# GEMM k-step body that issues the LDS-DMA pair runs at s_setprio 2 (other body at 1)
# speedup vs baseline: 1.0799x; 1.0068x over previous
; DEVI f32x4 mfma16(bf16x8 a, bf16x8 b, f32x4 c) { return __builtin_amdgcn_mfma_f32_16x16x32_bf16(a, b, c, 0, 0, 0); }
; DEVI void gemm_core3(f32x4 (&acc)[8][4], const bf* __restrict__ A, int lda, const bf* __restrict__ Bt, int ldb, int K, char* smem) {
;     ...
;   for (int kt = 0; kt < nk; ++kt) {
;     const int k1 = min((kt + 1) * 32, klast);
;     const int sn = ((kt + 1) & 1) * STG;
;     const int so = (kt & 1) * STG;
;     bf16x8 bfr[4], af[8];
; #pragma unroll
;     for (int n = 0; n < 4; ++n) bfr[n] = *reinterpret_cast<const bf16x8*>(bbase + so + n * 16 * 64);
; #pragma unroll
;     for (int m = 0; m < 8; ++m) af[m] = *reinterpret_cast<const bf16x8*>(abase + so + m * 16 * 64);
; #pragma unroll
;     for (int i = 0; i < 4; ++i) glds16(Ap + i * sa + k1, dbase + sn + i * 4096);
; #pragma unroll
;     for (int i = 0; i < 2; ++i) glds16(Bp + i * sb + k1, dbase + sn + ASZ + i * 4096);
;     __builtin_amdgcn_s_setprio(1);
; #pragma unroll
;     for (int m = 0; m < 8; ++m)
; #pragma unroll
;       for (int n = 0; n < 4; ++n) acc[m][n] = mfma16(af[m], bfr[n], acc[m][n]);
;     __builtin_amdgcn_s_setprio(0);
;     __syncthreads();
;   }
.Lg3_loop_173:
	v_add_u32_e32 v216, s10, v146
	v_add_u32_e32 v217, s10, v2
	ds_read_b128 v[148:151], v217 offset:16384
	ds_read_b128 v[166:169], v216
	ds_read_b128 v[154:157], v217 offset:17408
	ds_read_b128 v[158:161], v217 offset:18432
	ds_read_b128 v[162:165], v217 offset:19456
	ds_read_b128 v[170:173], v216 offset:1024
	ds_read_b128 v[174:177], v216 offset:2048
	ds_read_b128 v[192:195], v216 offset:3072
	ds_read_b128 v[196:199], v216 offset:4096
	ds_read_b128 v[204:207], v216 offset:5120
	ds_read_b128 v[208:211], v216 offset:6144
	ds_read_b128 v[212:215], v216 offset:7168
	s_setprio 1
	s_waitcnt lgkmcnt(10)
	v_mfma_f32_16x16x32_bf16 v[128:131], v[166:169], v[148:151], v[128:131]
	s_waitcnt lgkmcnt(9)
	v_mfma_f32_16x16x32_bf16 v[124:127], v[166:169], v[154:157], v[124:127]
	s_waitcnt lgkmcnt(8)
	v_mfma_f32_16x16x32_bf16 v[120:123], v[166:169], v[158:161], v[120:123]
	s_waitcnt lgkmcnt(7)
	v_mfma_f32_16x16x32_bf16 v[116:119], v[166:169], v[162:165], v[116:119]
	s_waitcnt lgkmcnt(6)
	v_mfma_f32_16x16x32_bf16 v[112:115], v[170:173], v[148:151], v[112:115]
	v_mfma_f32_16x16x32_bf16 v[108:111], v[170:173], v[154:157], v[108:111]
	v_mfma_f32_16x16x32_bf16 v[104:107], v[170:173], v[158:161], v[104:107]
	v_mfma_f32_16x16x32_bf16 v[100:103], v[170:173], v[162:165], v[100:103]
	s_waitcnt lgkmcnt(5)
	v_mfma_f32_16x16x32_bf16 v[96:99], v[174:177], v[148:151], v[96:99]
	v_mfma_f32_16x16x32_bf16 v[92:95], v[174:177], v[154:157], v[92:95]
	v_mfma_f32_16x16x32_bf16 v[88:91], v[174:177], v[158:161], v[88:91]
	v_mfma_f32_16x16x32_bf16 v[84:87], v[174:177], v[162:165], v[84:87]
	s_waitcnt lgkmcnt(4)
	v_mfma_f32_16x16x32_bf16 v[80:83], v[192:195], v[148:151], v[80:83]
	v_mfma_f32_16x16x32_bf16 v[76:79], v[192:195], v[154:157], v[76:79]
	v_mfma_f32_16x16x32_bf16 v[72:75], v[192:195], v[158:161], v[72:75]
	v_mfma_f32_16x16x32_bf16 v[68:71], v[192:195], v[162:165], v[68:71]
	s_waitcnt lgkmcnt(3)
	v_mfma_f32_16x16x32_bf16 v[64:67], v[196:199], v[148:151], v[64:67]
	v_mfma_f32_16x16x32_bf16 v[60:63], v[196:199], v[154:157], v[60:63]
	v_mfma_f32_16x16x32_bf16 v[56:59], v[196:199], v[158:161], v[56:59]
	v_mfma_f32_16x16x32_bf16 v[52:55], v[196:199], v[162:165], v[52:55]
	s_waitcnt lgkmcnt(2)
	v_mfma_f32_16x16x32_bf16 v[48:51], v[204:207], v[148:151], v[48:51]
	v_mfma_f32_16x16x32_bf16 v[44:47], v[204:207], v[154:157], v[44:47]
	v_mfma_f32_16x16x32_bf16 v[40:43], v[204:207], v[158:161], v[40:43]
	v_mfma_f32_16x16x32_bf16 v[36:39], v[204:207], v[162:165], v[36:39]
	s_waitcnt lgkmcnt(1)
	v_mfma_f32_16x16x32_bf16 v[32:35], v[208:211], v[148:151], v[32:35]
	v_mfma_f32_16x16x32_bf16 v[28:31], v[208:211], v[154:157], v[28:31]
	v_mfma_f32_16x16x32_bf16 v[24:27], v[208:211], v[158:161], v[24:27]
	v_mfma_f32_16x16x32_bf16 v[20:23], v[208:211], v[162:165], v[20:23]
	s_waitcnt lgkmcnt(0)
	v_mfma_f32_16x16x32_bf16 v[16:19], v[212:215], v[148:151], v[16:19]
	v_mfma_f32_16x16x32_bf16 v[12:15], v[212:215], v[154:157], v[12:15]
	v_mfma_f32_16x16x32_bf16 v[8:11], v[212:215], v[158:161], v[8:11]
	v_mfma_f32_16x16x32_bf16 v[4:7], v[212:215], v[162:165], v[4:7]
	s_setprio 0
	s_add_i32 s10, s10, 0x6000
	s_cmp_lg_u32 s10, 0x12000
	s_cselect_b32 s10, s10, 0
	s_waitcnt vmcnt(0)
	s_barrier
	v_add_u32_e32 v216, s10, v146
	v_add_u32_e32 v217, s10, v2
	ds_read_b128 v[148:151], v217 offset:16384
	ds_read_b128 v[166:169], v216
	ds_read_b128 v[154:157], v217 offset:17408
	ds_read_b128 v[158:161], v217 offset:18432
	ds_read_b128 v[162:165], v217 offset:19456
	ds_read_b128 v[170:173], v216 offset:1024
	ds_read_b128 v[174:177], v216 offset:2048
	ds_read_b128 v[192:195], v216 offset:3072
	ds_read_b128 v[196:199], v216 offset:4096
	ds_read_b128 v[204:207], v216 offset:5120
	ds_read_b128 v[208:211], v216 offset:6144
	ds_read_b128 v[212:215], v216 offset:7168
	v_readfirstlane_b32 s17, v140
	s_add_i32 s96, s11, 0x6000
	s_cmp_lg_u32 s96, 0x12000
	s_cselect_b32 s96, s96, 0
	s_add_i32 s96, s96, s17
	s_add_i32 s17, s17, s11
	s_setprio 2
	s_waitcnt lgkmcnt(10)
	s_mov_b32 m0, s17
	s_add_i32 s17, s17, 0x1000
	v_mfma_f32_16x16x32_bf16 v[128:131], v[166:169], v[148:151], v[128:131]
	s_waitcnt lgkmcnt(9)
	v_mfma_f32_16x16x32_bf16 v[124:127], v[166:169], v[154:157], v[124:127]
	global_load_lds_dwordx4 v[218:219], off
	v_lshl_add_u64 v[218:219], v[218:219], 0, 64
	s_waitcnt lgkmcnt(8)
	s_mov_b32 m0, s96
	s_add_i32 s96, s96, 0x1000
	v_mfma_f32_16x16x32_bf16 v[120:123], v[166:169], v[158:161], v[120:123]
	s_waitcnt lgkmcnt(7)
	v_mfma_f32_16x16x32_bf16 v[116:119], v[166:169], v[162:165], v[116:119]
	global_load_lds_dwordx4 v[218:219], off
	v_lshl_add_u64 v[218:219], v[218:219], 0, 64
	s_waitcnt lgkmcnt(6)
	v_mfma_f32_16x16x32_bf16 v[112:115], v[170:173], v[148:151], v[112:115]
	s_mov_b32 m0, s17
	s_add_i32 s17, s17, 0x1000
	v_mfma_f32_16x16x32_bf16 v[108:111], v[170:173], v[154:157], v[108:111]
	v_mfma_f32_16x16x32_bf16 v[104:107], v[170:173], v[158:161], v[104:107]
	global_load_lds_dwordx4 v[220:221], off
	v_lshl_add_u64 v[220:221], v[220:221], 0, 64
	s_mov_b32 m0, s96
	s_add_i32 s96, s96, 0x1000
	v_mfma_f32_16x16x32_bf16 v[100:103], v[170:173], v[162:165], v[100:103]
	s_waitcnt lgkmcnt(5)
	v_mfma_f32_16x16x32_bf16 v[96:99], v[174:177], v[148:151], v[96:99]
	global_load_lds_dwordx4 v[220:221], off
	v_lshl_add_u64 v[220:221], v[220:221], 0, 64
	v_mfma_f32_16x16x32_bf16 v[92:95], v[174:177], v[154:157], v[92:95]
	s_mov_b32 m0, s17
	s_add_i32 s17, s17, 0x1000
	v_mfma_f32_16x16x32_bf16 v[88:91], v[174:177], v[158:161], v[88:91]
	v_mfma_f32_16x16x32_bf16 v[84:87], v[174:177], v[162:165], v[84:87]
	global_load_lds_dwordx4 v[222:223], off
	v_lshl_add_u64 v[222:223], v[222:223], 0, 64
	s_waitcnt lgkmcnt(4)
; DEVI f32x4 mfma16(bf16x8 a, bf16x8 b, f32x4 c) { return __builtin_amdgcn_mfma_f32_16x16x32_bf16(a, b, c, 0, 0, 0); }
; DEVI void gemm_core3(f32x4 (&acc)[8][4], const bf* __restrict__ A, int lda, const bf* __restrict__ Bt, int ldb, int K, char* smem) {
;     ...
;   for (int kt = 0; kt < nk; ++kt) {
;     const int k1 = min((kt + 1) * 32, klast);
;     const int sn = ((kt + 1) & 1) * STG;
;     const int so = (kt & 1) * STG;
;     bf16x8 bfr[4], af[8];
; #pragma unroll
;     for (int n = 0; n < 4; ++n) bfr[n] = *reinterpret_cast<const bf16x8*>(bbase + so + n * 16 * 64);
; #pragma unroll
;     for (int m = 0; m < 8; ++m) af[m] = *reinterpret_cast<const bf16x8*>(abase + so + m * 16 * 64);
; #pragma unroll
;     for (int i = 0; i < 4; ++i) glds16(Ap + i * sa + k1, dbase + sn + i * 4096);
; #pragma unroll
;     for (int i = 0; i < 2; ++i) glds16(Bp + i * sb + k1, dbase + sn + ASZ + i * 4096);
;     __builtin_amdgcn_s_setprio(1);
; #pragma unroll
;     for (int m = 0; m < 8; ++m)
; #pragma unroll
;       for (int n = 0; n < 4; ++n) acc[m][n] = mfma16(af[m], bfr[n], acc[m][n]);
;     __builtin_amdgcn_s_setprio(0);
;     __syncthreads();
;   }
	s_mov_b32 m0, s96
	s_add_i32 s96, s96, 0x1000
	v_mfma_f32_16x16x32_bf16 v[80:83], v[192:195], v[148:151], v[80:83]
	v_mfma_f32_16x16x32_bf16 v[76:79], v[192:195], v[154:157], v[76:79]
	global_load_lds_dwordx4 v[222:223], off
	v_lshl_add_u64 v[222:223], v[222:223], 0, 64
	v_mfma_f32_16x16x32_bf16 v[72:75], v[192:195], v[158:161], v[72:75]
	s_mov_b32 m0, s17
	s_add_i32 s17, s17, 0x1000
	v_mfma_f32_16x16x32_bf16 v[68:71], v[192:195], v[162:165], v[68:71]
	s_waitcnt lgkmcnt(3)
	v_mfma_f32_16x16x32_bf16 v[64:67], v[196:199], v[148:151], v[64:67]
	global_load_lds_dwordx4 v[224:225], off
	v_lshl_add_u64 v[224:225], v[224:225], 0, 64
	s_mov_b32 m0, s96
	s_add_i32 s96, s96, 0x1000
	v_mfma_f32_16x16x32_bf16 v[60:63], v[196:199], v[154:157], v[60:63]
	v_mfma_f32_16x16x32_bf16 v[56:59], v[196:199], v[158:161], v[56:59]
	global_load_lds_dwordx4 v[224:225], off
	v_lshl_add_u64 v[224:225], v[224:225], 0, 64
	v_mfma_f32_16x16x32_bf16 v[52:55], v[196:199], v[162:165], v[52:55]
	s_waitcnt lgkmcnt(2)
	s_mov_b32 m0, s17
	s_add_i32 s17, s17, 0x1000
	v_mfma_f32_16x16x32_bf16 v[48:51], v[204:207], v[148:151], v[48:51]
	v_mfma_f32_16x16x32_bf16 v[44:47], v[204:207], v[154:157], v[44:47]
	global_load_lds_dwordx4 v[226:227], off
	v_lshl_add_u64 v[226:227], v[226:227], 0, 64
	s_mov_b32 m0, s96
	s_add_i32 s96, s96, 0x1000
	v_mfma_f32_16x16x32_bf16 v[40:43], v[204:207], v[158:161], v[40:43]
	v_mfma_f32_16x16x32_bf16 v[36:39], v[204:207], v[162:165], v[36:39]
	global_load_lds_dwordx4 v[226:227], off
	v_lshl_add_u64 v[226:227], v[226:227], 0, 64
	s_waitcnt lgkmcnt(1)
	v_mfma_f32_16x16x32_bf16 v[32:35], v[208:211], v[148:151], v[32:35]
	s_mov_b32 m0, s17
	s_add_i32 s17, s17, 0x1000
	v_mfma_f32_16x16x32_bf16 v[28:31], v[208:211], v[154:157], v[28:31]
	v_mfma_f32_16x16x32_bf16 v[24:27], v[208:211], v[158:161], v[24:27]
	global_load_lds_dwordx4 v[228:229], off
	v_lshl_add_u64 v[228:229], v[228:229], 0, 64
	s_mov_b32 m0, s96
	s_add_i32 s96, s96, 0x1000
	v_mfma_f32_16x16x32_bf16 v[20:23], v[208:211], v[162:165], v[20:23]
	s_waitcnt lgkmcnt(0)
	v_mfma_f32_16x16x32_bf16 v[16:19], v[212:215], v[148:151], v[16:19]
	global_load_lds_dwordx4 v[228:229], off
	v_lshl_add_u64 v[228:229], v[228:229], 0, 64
	v_mfma_f32_16x16x32_bf16 v[12:15], v[212:215], v[154:157], v[12:15]
	v_mfma_f32_16x16x32_bf16 v[8:11], v[212:215], v[158:161], v[8:11]
	v_mfma_f32_16x16x32_bf16 v[4:7], v[212:215], v[162:165], v[4:7]
	s_setprio 0
	s_add_i32 s10, s10, 0x6000
	s_cmp_lg_u32 s10, 0x12000
	s_cselect_b32 s10, s10, 0
	s_sub_i32 s11, s11, 0x6000
	s_cmp_lt_i32 s11, 0
	s_cselect_b32 s11, 0xc000, s11
	s_add_i32 s3, s3, 1
	s_cmp_lt_i32 s3, 43
	s_waitcnt vmcnt(1)
	s_barrier
	s_cbranch_scc1 .Lg3_loop_173
	v_add_u32_e32 v216, s10, v146
	v_add_u32_e32 v217, s10, v2
	ds_read_b128 v[148:151], v217 offset:16384
	ds_read_b128 v[166:169], v216
	ds_read_b128 v[154:157], v217 offset:17408
	ds_read_b128 v[158:161], v217 offset:18432
	ds_read_b128 v[162:165], v217 offset:19456
	ds_read_b128 v[170:173], v216 offset:1024
	ds_read_b128 v[174:177], v216 offset:2048
	ds_read_b128 v[192:195], v216 offset:3072
	ds_read_b128 v[196:199], v216 offset:4096
	ds_read_b128 v[204:207], v216 offset:5120
	ds_read_b128 v[208:211], v216 offset:6144
	ds_read_b128 v[212:215], v216 offset:7168
	s_setprio 1
	s_waitcnt lgkmcnt(10)
	v_mfma_f32_16x16x32_bf16 v[128:131], v[166:169], v[148:151], v[128:131]
	s_waitcnt lgkmcnt(9)
	v_mfma_f32_16x16x32_bf16 v[124:127], v[166:169], v[154:157], v[124:127]
	s_waitcnt lgkmcnt(8)
	v_mfma_f32_16x16x32_bf16 v[120:123], v[166:169], v[158:161], v[120:123]
	s_waitcnt lgkmcnt(7)
	v_mfma_f32_16x16x32_bf16 v[116:119], v[166:169], v[162:165], v[116:119]
	s_waitcnt lgkmcnt(6)
	v_mfma_f32_16x16x32_bf16 v[112:115], v[170:173], v[148:151], v[112:115]
	v_mfma_f32_16x16x32_bf16 v[108:111], v[170:173], v[154:157], v[108:111]
	v_mfma_f32_16x16x32_bf16 v[104:107], v[170:173], v[158:161], v[104:107]
	v_mfma_f32_16x16x32_bf16 v[100:103], v[170:173], v[162:165], v[100:103]
	s_waitcnt lgkmcnt(5)
	v_mfma_f32_16x16x32_bf16 v[96:99], v[174:177], v[148:151], v[96:99]
	v_mfma_f32_16x16x32_bf16 v[92:95], v[174:177], v[154:157], v[92:95]
	v_mfma_f32_16x16x32_bf16 v[88:91], v[174:177], v[158:161], v[88:91]
	v_mfma_f32_16x16x32_bf16 v[84:87], v[174:177], v[162:165], v[84:87]
	s_waitcnt lgkmcnt(4)
	v_mfma_f32_16x16x32_bf16 v[80:83], v[192:195], v[148:151], v[80:83]
	v_mfma_f32_16x16x32_bf16 v[76:79], v[192:195], v[154:157], v[76:79]
	v_mfma_f32_16x16x32_bf16 v[72:75], v[192:195], v[158:161], v[72:75]
	v_mfma_f32_16x16x32_bf16 v[68:71], v[192:195], v[162:165], v[68:71]
	s_waitcnt lgkmcnt(3)
	v_mfma_f32_16x16x32_bf16 v[64:67], v[196:199], v[148:151], v[64:67]
	v_mfma_f32_16x16x32_bf16 v[60:63], v[196:199], v[154:157], v[60:63]
	v_mfma_f32_16x16x32_bf16 v[56:59], v[196:199], v[158:161], v[56:59]
	v_mfma_f32_16x16x32_bf16 v[52:55], v[196:199], v[162:165], v[52:55]
	s_waitcnt lgkmcnt(2)
	v_mfma_f32_16x16x32_bf16 v[48:51], v[204:207], v[148:151], v[48:51]
	v_mfma_f32_16x16x32_bf16 v[44:47], v[204:207], v[154:157], v[44:47]
	v_mfma_f32_16x16x32_bf16 v[40:43], v[204:207], v[158:161], v[40:43]
	v_mfma_f32_16x16x32_bf16 v[36:39], v[204:207], v[162:165], v[36:39]
	s_waitcnt lgkmcnt(1)
	v_mfma_f32_16x16x32_bf16 v[32:35], v[208:211], v[148:151], v[32:35]
	v_mfma_f32_16x16x32_bf16 v[28:31], v[208:211], v[154:157], v[28:31]
	v_mfma_f32_16x16x32_bf16 v[24:27], v[208:211], v[158:161], v[24:27]
	v_mfma_f32_16x16x32_bf16 v[20:23], v[208:211], v[162:165], v[20:23]
	s_waitcnt lgkmcnt(0)
	v_mfma_f32_16x16x32_bf16 v[16:19], v[212:215], v[148:151], v[16:19]
	v_mfma_f32_16x16x32_bf16 v[12:15], v[212:215], v[154:157], v[12:15]
	v_mfma_f32_16x16x32_bf16 v[8:11], v[212:215], v[158:161], v[8:11]
	v_mfma_f32_16x16x32_bf16 v[4:7], v[212:215], v[162:165], v[4:7]
	s_setprio 0
	s_add_i32 s10, s10, 0x6000
	s_cmp_lg_u32 s10, 0x12000
	s_cselect_b32 s10, s10, 0
	s_waitcnt vmcnt(0)
	s_barrier
; DEVI f32x4 mfma16(bf16x8 a, bf16x8 b, f32x4 c) { return __builtin_amdgcn_mfma_f32_16x16x32_bf16(a, b, c, 0, 0, 0); }
; DEVI void gemm_core3(f32x4 (&acc)[8][4], const bf* __restrict__ A, int lda, const bf* __restrict__ Bt, int ldb, int K, char* smem) {
;     ...
; #pragma unroll
;     for (int n = 0; n < 4; ++n) bfr[n] = *reinterpret_cast<const bf16x8*>(bbase + so + n * 16 * 64);
; #pragma unroll
;     for (int m = 0; m < 8; ++m) af[m] = *reinterpret_cast<const bf16x8*>(abase + so + m * 16 * 64);
; #pragma unroll
;     for (int i = 0; i < 4; ++i) glds16(Ap + i * sa + k1, dbase + sn + i * 4096);
; #pragma unroll
;     for (int i = 0; i < 2; ++i) glds16(Bp + i * sb + k1, dbase + sn + ASZ + i * 4096);
;     __builtin_amdgcn_s_setprio(1);
; #pragma unroll
;     for (int m = 0; m < 8; ++m)
; #pragma unroll
;       for (int n = 0; n < 4; ++n) acc[m][n] = mfma16(af[m], bfr[n], acc[m][n]);
;     __builtin_amdgcn_s_setprio(0);
;     __syncthreads();
; DEVI void plain_tile256(const bf* A, int lda, const bf* Wt, int K, bf* C, int ldc, long row0, int n0, char* smem) {
;     ...
;   bf* tl = reinterpret_cast<bf*>(smem);
; #pragma unroll
;   for (int m = 0; m < 8; ++m)
; #pragma unroll
;     for (int n = 0; n < 4; ++n) {
;       const int cl = wc * 64 + n * 16 + l15;
; #pragma unroll
;       for (int j = 0; j < 4; ++j) tl[(wr * 128 + m * 16 + quad * 4 + j) * 136 + cl] = f2bf(acc[m][n][j]);
;     }
	v_add_u32_e32 v216, s10, v146
	v_add_u32_e32 v217, s10, v2
	ds_read_b128 v[148:151], v217 offset:16384
	ds_read_b128 v[166:169], v216
	ds_read_b128 v[154:157], v217 offset:17408
	ds_read_b128 v[158:161], v217 offset:18432
	ds_read_b128 v[162:165], v217 offset:19456
	ds_read_b128 v[170:173], v216 offset:1024
	ds_read_b128 v[174:177], v216 offset:2048
	ds_read_b128 v[192:195], v216 offset:3072
	ds_read_b128 v[196:199], v216 offset:4096
	ds_read_b128 v[204:207], v216 offset:5120
	ds_read_b128 v[208:211], v216 offset:6144
	ds_read_b128 v[212:215], v216 offset:7168
	s_setprio 1
	s_waitcnt lgkmcnt(10)
	v_mfma_f32_16x16x32_bf16 v[128:131], v[166:169], v[148:151], v[128:131]
	s_waitcnt lgkmcnt(9)
	v_mfma_f32_16x16x32_bf16 v[124:127], v[166:169], v[154:157], v[124:127]
	s_waitcnt lgkmcnt(8)
	v_mfma_f32_16x16x32_bf16 v[120:123], v[166:169], v[158:161], v[120:123]
	s_waitcnt lgkmcnt(7)
	v_mfma_f32_16x16x32_bf16 v[116:119], v[166:169], v[162:165], v[116:119]
	s_waitcnt lgkmcnt(6)
	v_mfma_f32_16x16x32_bf16 v[112:115], v[170:173], v[148:151], v[112:115]
	v_mfma_f32_16x16x32_bf16 v[108:111], v[170:173], v[154:157], v[108:111]
	v_mfma_f32_16x16x32_bf16 v[104:107], v[170:173], v[158:161], v[104:107]
	v_mfma_f32_16x16x32_bf16 v[100:103], v[170:173], v[162:165], v[100:103]
	s_waitcnt lgkmcnt(5)
	v_mfma_f32_16x16x32_bf16 v[96:99], v[174:177], v[148:151], v[96:99]
	v_mfma_f32_16x16x32_bf16 v[92:95], v[174:177], v[154:157], v[92:95]
	v_mfma_f32_16x16x32_bf16 v[88:91], v[174:177], v[158:161], v[88:91]
	v_mfma_f32_16x16x32_bf16 v[84:87], v[174:177], v[162:165], v[84:87]
	s_waitcnt lgkmcnt(4)
	v_mfma_f32_16x16x32_bf16 v[80:83], v[192:195], v[148:151], v[80:83]
	v_mfma_f32_16x16x32_bf16 v[76:79], v[192:195], v[154:157], v[76:79]
	v_mfma_f32_16x16x32_bf16 v[72:75], v[192:195], v[158:161], v[72:75]
	v_mfma_f32_16x16x32_bf16 v[68:71], v[192:195], v[162:165], v[68:71]
	s_waitcnt lgkmcnt(3)
	v_mfma_f32_16x16x32_bf16 v[64:67], v[196:199], v[148:151], v[64:67]
	v_mfma_f32_16x16x32_bf16 v[60:63], v[196:199], v[154:157], v[60:63]
	v_mfma_f32_16x16x32_bf16 v[56:59], v[196:199], v[158:161], v[56:59]
	v_mfma_f32_16x16x32_bf16 v[52:55], v[196:199], v[162:165], v[52:55]
	s_waitcnt lgkmcnt(2)
	v_mfma_f32_16x16x32_bf16 v[48:51], v[204:207], v[148:151], v[48:51]
	v_mfma_f32_16x16x32_bf16 v[44:47], v[204:207], v[154:157], v[44:47]
	v_mfma_f32_16x16x32_bf16 v[40:43], v[204:207], v[158:161], v[40:43]
	v_mfma_f32_16x16x32_bf16 v[36:39], v[204:207], v[162:165], v[36:39]
	s_waitcnt lgkmcnt(1)
	v_mfma_f32_16x16x32_bf16 v[32:35], v[208:211], v[148:151], v[32:35]
	v_mfma_f32_16x16x32_bf16 v[28:31], v[208:211], v[154:157], v[28:31]
	v_mfma_f32_16x16x32_bf16 v[24:27], v[208:211], v[158:161], v[24:27]
	v_mfma_f32_16x16x32_bf16 v[20:23], v[208:211], v[162:165], v[20:23]
	s_waitcnt lgkmcnt(0)
	v_mfma_f32_16x16x32_bf16 v[16:19], v[212:215], v[148:151], v[16:19]
	v_mfma_f32_16x16x32_bf16 v[12:15], v[212:215], v[154:157], v[12:15]
	v_mfma_f32_16x16x32_bf16 v[8:11], v[212:215], v[158:161], v[8:11]
	v_mfma_f32_16x16x32_bf16 v[4:7], v[212:215], v[162:165], v[4:7]
	s_setprio 0
	s_add_i32 s10, s10, 0x6000
	s_cmp_lg_u32 s10, 0x12000
	s_cselect_b32 s10, s10, 0
	s_waitcnt vmcnt(0)
	s_barrier
	v_and_b32_e32 v2, 0x4f, v1
	v_and_b32_e32 v132, 0xfffff80, v1
	v_lshrrev_b32_e32 v1, 2, v1
	v_and_or_b32 v1, v1, 12, v132
	v_mul_lo_u32 v1, v1, s16
	v_lshl_add_u32 v1, v2, 1, v1
	v_cvt_pk_bf16_f32 v2, v129, s0
	ds_write_b16 v1, v2 offset:272
	v_cvt_pk_bf16_f32 v2, v130, s0
	ds_write_b16 v1, v2 offset:544
	v_cvt_pk_bf16_f32 v2, v131, s0
	ds_write_b16 v1, v2 offset:816
	v_cvt_pk_bf16_f32 v2, v124, s0
	ds_write_b16 v1, v2 offset:32
	v_cvt_pk_bf16_f32 v2, v125, s0
	ds_write_b16 v1, v2 offset:304
	v_cvt_pk_bf16_f32 v2, v126, s0
	ds_write_b16 v1, v2 offset:576
	v_cvt_pk_bf16_f32 v2, v127, s0
	ds_write_b16 v1, v2 offset:848
	v_cvt_pk_bf16_f32 v2, v120, s0
	ds_write_b16 v1, v2 offset:64
	v_cvt_pk_bf16_f32 v2, v121, s0
	ds_write_b16 v1, v2 offset:336
	v_cvt_pk_bf16_f32 v2, v122, s0
	ds_write_b16 v1, v2 offset:608
	v_cvt_pk_bf16_f32 v2, v123, s0
	ds_write_b16 v1, v2 offset:880
	v_cvt_pk_bf16_f32 v2, v116, s0
	ds_write_b16 v1, v2 offset:96
	v_cvt_pk_bf16_f32 v2, v117, s0
	ds_write_b16 v1, v2 offset:368
	v_cvt_pk_bf16_f32 v2, v118, s0
	ds_write_b16 v1, v2 offset:640
	v_cvt_pk_bf16_f32 v2, v119, s0
	ds_write_b16 v1, v2 offset:912
	v_cvt_pk_bf16_f32 v2, v112, s0
	ds_write_b16 v1, v2 offset:4352
	v_cvt_pk_bf16_f32 v2, v113, s0
	ds_write_b16 v1, v2 offset:4624
	v_cvt_pk_bf16_f32 v2, v114, s0
	ds_write_b16 v1, v2 offset:4896
	v_cvt_pk_bf16_f32 v2, v115, s0
	ds_write_b16 v1, v2 offset:5168
	v_cvt_pk_bf16_f32 v2, v108, s0
	ds_write_b16 v1, v2 offset:4384
	v_cvt_pk_bf16_f32 v2, v109, s0
	ds_write_b16 v1, v2 offset:4656
	v_cvt_pk_bf16_f32 v2, v110, s0
	ds_write_b16 v1, v2 offset:4928
	v_cvt_pk_bf16_f32 v2, v111, s0
	ds_write_b16 v1, v2 offset:5200
	v_cvt_pk_bf16_f32 v2, v104, s0
	ds_write_b16 v1, v2 offset:4416
	v_cvt_pk_bf16_f32 v2, v105, s0
	ds_write_b16 v1, v2 offset:4688
	v_cvt_pk_bf16_f32 v2, v106, s0
	ds_write_b16 v1, v2 offset:4960
	v_cvt_pk_bf16_f32 v2, v107, s0
	ds_write_b16 v1, v2 offset:5232
	v_cvt_pk_bf16_f32 v2, v100, s0
	ds_write_b16 v1, v2 offset:4448
	v_cvt_pk_bf16_f32 v2, v101, s0
	ds_write_b16 v1, v2 offset:4720
	v_cvt_pk_bf16_f32 v2, v102, s0
	ds_write_b16 v1, v2 offset:4992
	v_cvt_pk_bf16_f32 v2, v103, s0
	ds_write_b16 v1, v2 offset:5264
	v_cvt_pk_bf16_f32 v2, v96, s0
	ds_write_b16 v1, v2 offset:8704
	v_cvt_pk_bf16_f32 v2, v97, s0
	ds_write_b16 v1, v2 offset:8976
	v_cvt_pk_bf16_f32 v2, v98, s0
	ds_write_b16 v1, v2 offset:9248
	v_cvt_pk_bf16_f32 v2, v99, s0
	ds_write_b16 v1, v2 offset:9520
	v_cvt_pk_bf16_f32 v2, v92, s0
; DEVI void plain_tile256(const bf* A, int lda, const bf* Wt, int K, bf* C, int ldc, long row0, int n0, char* smem) {
;     ...
; #pragma unroll
;   for (int m = 0; m < 8; ++m)
; #pragma unroll
;     for (int n = 0; n < 4; ++n) {
;       const int cl = wc * 64 + n * 16 + l15;
; #pragma unroll
;       for (int j = 0; j < 4; ++j) tl[(wr * 128 + m * 16 + quad * 4 + j) * 136 + cl] = f2bf(acc[m][n][j]);
;     }
;   __syncthreads();
	ds_write_b16 v1, v2 offset:8736
	v_cvt_pk_bf16_f32 v2, v93, s0
	ds_write_b16 v1, v2 offset:9008
	v_cvt_pk_bf16_f32 v2, v94, s0
	ds_write_b16 v1, v2 offset:9280
	v_cvt_pk_bf16_f32 v2, v95, s0
	ds_write_b16 v1, v2 offset:9552
	v_cvt_pk_bf16_f32 v2, v88, s0
	ds_write_b16 v1, v2 offset:8768
	v_cvt_pk_bf16_f32 v2, v89, s0
	ds_write_b16 v1, v2 offset:9040
	v_cvt_pk_bf16_f32 v2, v90, s0
	ds_write_b16 v1, v2 offset:9312
	v_cvt_pk_bf16_f32 v2, v91, s0
	ds_write_b16 v1, v2 offset:9584
	v_cvt_pk_bf16_f32 v2, v84, s0
	ds_write_b16 v1, v2 offset:8800
	v_cvt_pk_bf16_f32 v2, v85, s0
	ds_write_b16 v1, v2 offset:9072
	v_cvt_pk_bf16_f32 v2, v86, s0
	ds_write_b16 v1, v2 offset:9344
	v_cvt_pk_bf16_f32 v2, v87, s0
	ds_write_b16 v1, v2 offset:9616
	v_cvt_pk_bf16_f32 v2, v80, s0
	ds_write_b16 v1, v2 offset:13056
	v_cvt_pk_bf16_f32 v2, v81, s0
	ds_write_b16 v1, v2 offset:13328
	v_cvt_pk_bf16_f32 v2, v82, s0
	ds_write_b16 v1, v2 offset:13600
	v_cvt_pk_bf16_f32 v2, v83, s0
	ds_write_b16 v1, v2 offset:13872
	v_cvt_pk_bf16_f32 v2, v76, s0
	ds_write_b16 v1, v2 offset:13088
	v_cvt_pk_bf16_f32 v2, v77, s0
	ds_write_b16 v1, v2 offset:13360
	v_cvt_pk_bf16_f32 v2, v78, s0
	ds_write_b16 v1, v2 offset:13632
	v_cvt_pk_bf16_f32 v2, v79, s0
	ds_write_b16 v1, v2 offset:13904
	v_cvt_pk_bf16_f32 v2, v72, s0
	ds_write_b16 v1, v2 offset:13120
	v_cvt_pk_bf16_f32 v2, v73, s0
	ds_write_b16 v1, v2 offset:13392
	v_cvt_pk_bf16_f32 v2, v74, s0
	ds_write_b16 v1, v2 offset:13664
	v_cvt_pk_bf16_f32 v2, v75, s0
	ds_write_b16 v1, v2 offset:13936
	v_cvt_pk_bf16_f32 v2, v68, s0
	ds_write_b16 v1, v2 offset:13152
	v_cvt_pk_bf16_f32 v2, v69, s0
	ds_write_b16 v1, v2 offset:13424
	v_cvt_pk_bf16_f32 v2, v70, s0
	ds_write_b16 v1, v2 offset:13696
	v_cvt_pk_bf16_f32 v2, v71, s0
	ds_write_b16 v1, v2 offset:13968
	v_cvt_pk_bf16_f32 v2, v64, s0
	ds_write_b16 v1, v2 offset:17408
	v_cvt_pk_bf16_f32 v2, v65, s0
	ds_write_b16 v1, v2 offset:17680
	v_cvt_pk_bf16_f32 v2, v66, s0
	ds_write_b16 v1, v2 offset:17952
	v_cvt_pk_bf16_f32 v2, v67, s0
	ds_write_b16 v1, v2 offset:18224
	v_cvt_pk_bf16_f32 v2, v60, s0
	ds_write_b16 v1, v2 offset:17440
	v_cvt_pk_bf16_f32 v2, v61, s0
	ds_write_b16 v1, v2 offset:17712
	v_cvt_pk_bf16_f32 v2, v62, s0
	ds_write_b16 v1, v2 offset:17984
	v_cvt_pk_bf16_f32 v2, v63, s0
	ds_write_b16 v1, v2 offset:18256
	v_cvt_pk_bf16_f32 v2, v56, s0
	ds_write_b16 v1, v2 offset:17472
	v_cvt_pk_bf16_f32 v2, v57, s0
	ds_write_b16 v1, v2 offset:17744
	v_cvt_pk_bf16_f32 v2, v58, s0
	ds_write_b16 v1, v2 offset:18016
	v_cvt_pk_bf16_f32 v2, v59, s0
	ds_write_b16 v1, v2 offset:18288
	v_cvt_pk_bf16_f32 v2, v52, s0
	ds_write_b16 v1, v2 offset:17504
	v_cvt_pk_bf16_f32 v2, v53, s0
	ds_write_b16 v1, v2 offset:17776
	v_cvt_pk_bf16_f32 v2, v54, s0
	ds_write_b16 v1, v2 offset:18048
	v_cvt_pk_bf16_f32 v2, v55, s0
	ds_write_b16 v1, v2 offset:18320
	v_cvt_pk_bf16_f32 v2, v48, s0
	ds_write_b16 v1, v2 offset:21760
	v_cvt_pk_bf16_f32 v2, v49, s0
	ds_write_b16 v1, v2 offset:22032
	v_cvt_pk_bf16_f32 v2, v50, s0
	ds_write_b16 v1, v2 offset:22304
	v_cvt_pk_bf16_f32 v2, v51, s0
	ds_write_b16 v1, v2 offset:22576
	v_cvt_pk_bf16_f32 v2, v44, s0
	ds_write_b16 v1, v2 offset:21792
	v_cvt_pk_bf16_f32 v2, v45, s0
	ds_write_b16 v1, v2 offset:22064
	v_cvt_pk_bf16_f32 v2, v46, s0
	ds_write_b16 v1, v2 offset:22336
	v_cvt_pk_bf16_f32 v2, v47, s0
	ds_write_b16 v1, v2 offset:22608
	v_cvt_pk_bf16_f32 v2, v40, s0
	ds_write_b16 v1, v2 offset:21824
	v_cvt_pk_bf16_f32 v2, v41, s0
	ds_write_b16 v1, v2 offset:22096
	v_cvt_pk_bf16_f32 v2, v42, s0
	ds_write_b16 v1, v2 offset:22368
	v_cvt_pk_bf16_f32 v2, v43, s0
	ds_write_b16 v1, v2 offset:22640
	v_cvt_pk_bf16_f32 v2, v36, s0
	ds_write_b16 v1, v2 offset:21856
	v_cvt_pk_bf16_f32 v2, v37, s0
	ds_write_b16 v1, v2 offset:22128
	v_cvt_pk_bf16_f32 v2, v38, s0
	ds_write_b16 v1, v2 offset:22400
	v_cvt_pk_bf16_f32 v2, v39, s0
	ds_write_b16 v1, v2 offset:22672
	v_cvt_pk_bf16_f32 v2, v32, s0
	ds_write_b16 v1, v2 offset:26112
	v_cvt_pk_bf16_f32 v2, v33, s0
	ds_write_b16 v1, v2 offset:26384
	v_cvt_pk_bf16_f32 v2, v34, s0
	ds_write_b16 v1, v2 offset:26656
	v_cvt_pk_bf16_f32 v2, v35, s0
	ds_write_b16 v1, v2 offset:26928
	v_cvt_pk_bf16_f32 v2, v28, s0
	ds_write_b16 v1, v2 offset:26144
	v_cvt_pk_bf16_f32 v2, v29, s0
	ds_write_b16 v1, v2 offset:26416
	v_cvt_pk_bf16_f32 v2, v30, s0
	ds_write_b16 v1, v2 offset:26688
	v_cvt_pk_bf16_f32 v2, v31, s0
	ds_write_b16 v1, v2 offset:26960
	v_cvt_pk_bf16_f32 v2, v24, s0
	ds_write_b16 v1, v2 offset:26176
	v_cvt_pk_bf16_f32 v2, v25, s0
	ds_write_b16 v1, v2 offset:26448
	v_cvt_pk_bf16_f32 v2, v26, s0
	ds_write_b16 v1, v2 offset:26720
	v_cvt_pk_bf16_f32 v2, v27, s0
	ds_write_b16 v1, v2 offset:26992
	v_cvt_pk_bf16_f32 v2, v20, s0
	ds_write_b16 v1, v2 offset:26208
	v_cvt_pk_bf16_f32 v2, v21, s0
	ds_write_b16 v1, v2 offset:26480
	v_cvt_pk_bf16_f32 v2, v22, s0
	ds_write_b16 v1, v2 offset:26752
	v_cvt_pk_bf16_f32 v2, v23, s0
	ds_write_b16 v1, v2 offset:27024
	v_cvt_pk_bf16_f32 v2, v16, s0
	ds_write_b16 v1, v2 offset:30464
	v_cvt_pk_bf16_f32 v2, v17, s0
	ds_write_b16 v1, v2 offset:30736
	v_cvt_pk_bf16_f32 v2, v18, s0
	ds_write_b16 v1, v2 offset:31008
	v_cvt_pk_bf16_f32 v2, v19, s0
	ds_write_b16 v1, v2 offset:31280
	v_cvt_pk_bf16_f32 v2, v12, s0
	ds_write_b16 v1, v2 offset:30496
	v_cvt_pk_bf16_f32 v2, v13, s0
	ds_write_b16 v1, v2 offset:30768
	v_cvt_pk_bf16_f32 v2, v14, s0
	ds_write_b16 v1, v2 offset:31040
	v_cvt_pk_bf16_f32 v2, v15, s0
	ds_write_b16 v1, v2 offset:31312
	v_cvt_pk_bf16_f32 v2, v8, s0
	ds_write_b16 v1, v2 offset:30528
	v_cvt_pk_bf16_f32 v2, v9, s0
	ds_write_b16 v1, v2 offset:30800
	v_cvt_pk_bf16_f32 v2, v10, s0
	ds_write_b16 v1, v2 offset:31072
	v_cvt_pk_bf16_f32 v2, v11, s0
	ds_write_b16 v1, v2 offset:31344
	v_cvt_pk_bf16_f32 v2, v4, s0
	ds_write_b16 v1, v2 offset:30560
	v_cvt_pk_bf16_f32 v2, v5, s0
	ds_write_b16 v1, v2 offset:30832
	v_cvt_pk_bf16_f32 v2, v6, s0
	v_cvt_pk_bf16_f32 v128, v128, s0
	ds_write_b16 v1, v2 offset:31104
	v_cvt_pk_bf16_f32 v2, v7, s0
	ds_write_b16 v1, v128
	ds_write_b16 v1, v2 offset:31376
	v_mov_b32_e32 v1, v178
	s_waitcnt lgkmcnt(0)
	s_barrier
; DEVI int get_tid() { int t = threadIdx.x; asm volatile("" : "+v"(t)); return t; }
; template <int BN>
; DEVI void tile_store256(const char* smem, bf* __restrict__ C, long ldc, long row0, int col0) {
;   constexpr int LDT = BN + 8;
;   constexpr int CPR = BN / 8;
;   const int tid = get_tid();
; #pragma unroll
;   for (int i = 0; i < CPR; ++i) {
;     const int q = tid + 256 * i;
;     const int r = q / CPR, c = q - r * CPR;
;     u32x4 v = *reinterpret_cast<const u32x4*>(smem + (r * LDT + c * 8) * 2);
;     *reinterpret_cast<u32x4*>(C + (row0 + r) * ldc + col0 + c * 8) = v;
;   }
; }
	v_readlane_b32 s56, v251, 58
	v_ashrrev_i32_e32 v2, 31, v1
	v_lshrrev_b32_e32 v2, 28, v2
	v_add_u32_e32 v2, v1, v2
	v_ashrrev_i32_e32 v8, 4, v2
	s_lshl_b64 s[10:11], s[34:35], 1
	v_readlane_b32 s60, v251, 62
	v_lshlrev_b32_e32 v4, 7, v8
	v_lshlrev_b32_e32 v5, 3, v1
	v_ashrrev_i32_e32 v9, 31, v8
	v_readlane_b32 s61, v251, 63
	s_add_u32 s10, s60, s10
	v_mul_lo_u32 v2, v8, s39
	v_sub_u32_e32 v10, v5, v4
	v_lshl_add_u64 v[8:9], s[12:13], 0, v[8:9]
	s_addc_u32 s11, s61, s11
	v_add_lshl_u32 v2, v10, v2, 1
	v_lshlrev_b64 v[8:9], 11, v[8:9]
	ds_read_b128 v[4:7], v2
	v_lshl_add_u64 v[8:9], s[10:11], 0, v[8:9]
	v_ashrrev_i32_e32 v11, 31, v10
	v_add_u32_e32 v2, 0x100, v1
	v_lshl_add_u64 v[12:13], v[10:11], 1, v[8:9]
	v_ashrrev_i32_e32 v8, 31, v2
	v_lshrrev_b32_e32 v8, 28, v8
	v_add_u32_e32 v8, v2, v8
	v_ashrrev_i32_e32 v14, 4, v8
	v_lshlrev_b32_e32 v9, 7, v14
	v_lshlrev_b32_e32 v2, 3, v2
	v_mul_lo_u32 v8, v14, s39
	v_sub_u32_e32 v16, v2, v9
	v_add_lshl_u32 v2, v16, v8, 1
	ds_read_b128 v[8:11], v2
	v_ashrrev_i32_e32 v15, 31, v14
	s_waitcnt lgkmcnt(1)
	global_store_dwordx4 v[12:13], v[4:7], off
	v_ashrrev_i32_e32 v17, 31, v16
	v_add_u32_e32 v2, 0x200, v1
	v_lshl_add_u64 v[4:5], s[12:13], 0, v[14:15]
	v_lshlrev_b64 v[4:5], 11, v[4:5]
	v_lshl_add_u64 v[4:5], s[10:11], 0, v[4:5]
	v_lshl_add_u64 v[4:5], v[16:17], 1, v[4:5]
	s_waitcnt lgkmcnt(0)
	global_store_dwordx4 v[4:5], v[8:11], off
	v_ashrrev_i32_e32 v4, 31, v2
	v_lshrrev_b32_e32 v4, 28, v4
	v_add_u32_e32 v4, v2, v4
	v_ashrrev_i32_e32 v8, 4, v4
	v_lshlrev_b32_e32 v5, 7, v8
	v_lshlrev_b32_e32 v2, 3, v2
	v_ashrrev_i32_e32 v9, 31, v8
	v_mul_lo_u32 v4, v8, s39
	v_sub_u32_e32 v10, v2, v5
	v_lshl_add_u64 v[8:9], s[12:13], 0, v[8:9]
	v_add_lshl_u32 v2, v10, v4, 1
	v_lshlrev_b64 v[8:9], 11, v[8:9]
	ds_read_b128 v[4:7], v2
	v_lshl_add_u64 v[8:9], s[10:11], 0, v[8:9]
	v_ashrrev_i32_e32 v11, 31, v10
	v_add_u32_e32 v2, 0x300, v1
	v_lshl_add_u64 v[12:13], v[10:11], 1, v[8:9]
	v_ashrrev_i32_e32 v8, 31, v2
	v_lshrrev_b32_e32 v8, 28, v8
	v_add_u32_e32 v8, v2, v8
	v_ashrrev_i32_e32 v14, 4, v8
	v_lshlrev_b32_e32 v9, 7, v14
	v_lshlrev_b32_e32 v2, 3, v2
	v_mul_lo_u32 v8, v14, s39
	v_sub_u32_e32 v16, v2, v9
	v_add_lshl_u32 v2, v16, v8, 1
	ds_read_b128 v[8:11], v2
	v_ashrrev_i32_e32 v15, 31, v14
	s_waitcnt lgkmcnt(1)
	global_store_dwordx4 v[12:13], v[4:7], off
	v_ashrrev_i32_e32 v17, 31, v16
	v_add_u32_e32 v2, 0x400, v1
	v_lshl_add_u64 v[4:5], s[12:13], 0, v[14:15]
	v_lshlrev_b64 v[4:5], 11, v[4:5]
	v_lshl_add_u64 v[4:5], s[10:11], 0, v[4:5]
	v_lshl_add_u64 v[4:5], v[16:17], 1, v[4:5]
	s_waitcnt lgkmcnt(0)
	global_store_dwordx4 v[4:5], v[8:11], off
	v_ashrrev_i32_e32 v4, 31, v2
	v_lshrrev_b32_e32 v4, 28, v4
	v_add_u32_e32 v4, v2, v4
	v_ashrrev_i32_e32 v8, 4, v4
	v_lshlrev_b32_e32 v5, 7, v8
	v_lshlrev_b32_e32 v2, 3, v2
	v_ashrrev_i32_e32 v9, 31, v8
	v_mul_lo_u32 v4, v8, s39
	v_sub_u32_e32 v10, v2, v5
	v_lshl_add_u64 v[8:9], s[12:13], 0, v[8:9]
	v_add_lshl_u32 v2, v10, v4, 1
	v_lshlrev_b64 v[8:9], 11, v[8:9]
	ds_read_b128 v[4:7], v2
	v_lshl_add_u64 v[8:9], s[10:11], 0, v[8:9]
	v_ashrrev_i32_e32 v11, 31, v10
	v_add_u32_e32 v2, 0x500, v1
	v_lshl_add_u64 v[12:13], v[10:11], 1, v[8:9]
	v_ashrrev_i32_e32 v8, 31, v2
	v_lshrrev_b32_e32 v8, 28, v8
	v_add_u32_e32 v8, v2, v8
	v_ashrrev_i32_e32 v14, 4, v8
	v_lshlrev_b32_e32 v9, 7, v14
	v_lshlrev_b32_e32 v2, 3, v2
	v_mul_lo_u32 v8, v14, s39
	v_sub_u32_e32 v16, v2, v9
	v_add_lshl_u32 v2, v16, v8, 1
	ds_read_b128 v[8:11], v2
	v_ashrrev_i32_e32 v15, 31, v14
	s_waitcnt lgkmcnt(1)
	global_store_dwordx4 v[12:13], v[4:7], off
	v_ashrrev_i32_e32 v17, 31, v16
	v_add_u32_e32 v2, 0x600, v1
	v_lshl_add_u64 v[4:5], s[12:13], 0, v[14:15]
	v_lshlrev_b64 v[4:5], 11, v[4:5]
	v_lshl_add_u64 v[4:5], s[10:11], 0, v[4:5]
	v_lshl_add_u64 v[4:5], v[16:17], 1, v[4:5]
	s_waitcnt lgkmcnt(0)
	global_store_dwordx4 v[4:5], v[8:11], off
	v_ashrrev_i32_e32 v4, 31, v2
	v_lshrrev_b32_e32 v4, 28, v4
	v_add_u32_e32 v4, v2, v4
	v_ashrrev_i32_e32 v8, 4, v4
	v_lshlrev_b32_e32 v5, 7, v8
	v_lshlrev_b32_e32 v2, 3, v2
	v_ashrrev_i32_e32 v9, 31, v8
	v_mul_lo_u32 v4, v8, s39
	v_sub_u32_e32 v10, v2, v5
	v_lshl_add_u64 v[8:9], s[12:13], 0, v[8:9]
	v_add_lshl_u32 v2, v10, v4, 1
	v_lshlrev_b64 v[8:9], 11, v[8:9]
	ds_read_b128 v[4:7], v2
	v_lshl_add_u64 v[8:9], s[10:11], 0, v[8:9]
	v_ashrrev_i32_e32 v11, 31, v10
	v_add_u32_e32 v2, 0x700, v1
	v_lshl_add_u64 v[12:13], v[10:11], 1, v[8:9]
	v_ashrrev_i32_e32 v8, 31, v2
	v_lshrrev_b32_e32 v8, 28, v8
	v_add_u32_e32 v8, v2, v8
	v_ashrrev_i32_e32 v14, 4, v8
	v_lshlrev_b32_e32 v9, 7, v14
	v_lshlrev_b32_e32 v2, 3, v2
	v_mul_lo_u32 v8, v14, s39
	v_sub_u32_e32 v16, v2, v9
	v_add_lshl_u32 v2, v16, v8, 1
	ds_read_b128 v[8:11], v2
	v_ashrrev_i32_e32 v15, 31, v14
	s_waitcnt lgkmcnt(1)
	global_store_dwordx4 v[12:13], v[4:7], off
	v_ashrrev_i32_e32 v17, 31, v16
	v_add_u32_e32 v2, 0x800, v1
	v_lshl_add_u64 v[4:5], s[12:13], 0, v[14:15]
	v_lshlrev_b64 v[4:5], 11, v[4:5]
	v_lshl_add_u64 v[4:5], s[10:11], 0, v[4:5]
	v_lshl_add_u64 v[4:5], v[16:17], 1, v[4:5]
	s_waitcnt lgkmcnt(0)
; template <int BN>
; DEVI void tile_store256(const char* smem, bf* __restrict__ C, long ldc, long row0, int col0) {
;     ...
;   for (int i = 0; i < CPR; ++i) {
;     const int q = tid + 256 * i;
;     const int r = q / CPR, c = q - r * CPR;
;     u32x4 v = *reinterpret_cast<const u32x4*>(smem + (r * LDT + c * 8) * 2);
;     *reinterpret_cast<u32x4*>(C + (row0 + r) * ldc + col0 + c * 8) = v;
;   }
; DEVI void phase_gemm_plain128(const bf* A, int lda, const bf* Wt, int K, int N, bf* C, int ldc, char* smem) {
;     ...
;   for (int v = blockIdx.x; v < 128 * ntn; v += gridDim.x) {
;     int m2, nt;
;     lat_tile_map256(v, ntn, m2, nt);
;     plain_tile256(A, lda, Wt, K, C, ldc, lat_row0_256(m2), nt * 128, smem);
;   }
	global_store_dwordx4 v[4:5], v[8:11], off
	v_ashrrev_i32_e32 v4, 31, v2
	v_lshrrev_b32_e32 v4, 28, v4
	v_add_u32_e32 v4, v2, v4
	v_ashrrev_i32_e32 v8, 4, v4
	v_lshlrev_b32_e32 v5, 7, v8
	v_lshlrev_b32_e32 v2, 3, v2
	v_ashrrev_i32_e32 v9, 31, v8
	v_mul_lo_u32 v4, v8, s39
	v_sub_u32_e32 v10, v2, v5
	v_lshl_add_u64 v[8:9], s[12:13], 0, v[8:9]
	v_add_lshl_u32 v2, v10, v4, 1
	v_lshlrev_b64 v[8:9], 11, v[8:9]
	ds_read_b128 v[4:7], v2
	v_lshl_add_u64 v[8:9], s[10:11], 0, v[8:9]
	v_ashrrev_i32_e32 v11, 31, v10
	v_add_u32_e32 v2, 0x900, v1
	v_lshl_add_u64 v[12:13], v[10:11], 1, v[8:9]
	v_ashrrev_i32_e32 v8, 31, v2
	v_lshrrev_b32_e32 v8, 28, v8
	v_add_u32_e32 v8, v2, v8
	v_ashrrev_i32_e32 v14, 4, v8
	v_lshlrev_b32_e32 v9, 7, v14
	v_lshlrev_b32_e32 v2, 3, v2
	v_mul_lo_u32 v8, v14, s39
	v_sub_u32_e32 v16, v2, v9
	v_add_lshl_u32 v2, v16, v8, 1
	ds_read_b128 v[8:11], v2
	v_ashrrev_i32_e32 v15, 31, v14
	s_waitcnt lgkmcnt(1)
	global_store_dwordx4 v[12:13], v[4:7], off
	v_ashrrev_i32_e32 v17, 31, v16
	v_add_u32_e32 v2, 0xa00, v1
	v_lshl_add_u64 v[4:5], s[12:13], 0, v[14:15]
	v_lshlrev_b64 v[4:5], 11, v[4:5]
	v_lshl_add_u64 v[4:5], s[10:11], 0, v[4:5]
	v_lshl_add_u64 v[4:5], v[16:17], 1, v[4:5]
	s_waitcnt lgkmcnt(0)
	global_store_dwordx4 v[4:5], v[8:11], off
	v_ashrrev_i32_e32 v4, 31, v2
	v_lshrrev_b32_e32 v4, 28, v4
	v_add_u32_e32 v4, v2, v4
	v_ashrrev_i32_e32 v8, 4, v4
	v_lshlrev_b32_e32 v5, 7, v8
	v_lshlrev_b32_e32 v2, 3, v2
	v_ashrrev_i32_e32 v9, 31, v8
	v_mul_lo_u32 v4, v8, s39
	v_sub_u32_e32 v10, v2, v5
	v_lshl_add_u64 v[8:9], s[12:13], 0, v[8:9]
	v_add_lshl_u32 v2, v10, v4, 1
	v_lshlrev_b64 v[8:9], 11, v[8:9]
	ds_read_b128 v[4:7], v2
	v_lshl_add_u64 v[8:9], s[10:11], 0, v[8:9]
	v_ashrrev_i32_e32 v11, 31, v10
	v_add_u32_e32 v2, 0xb00, v1
	v_lshl_add_u64 v[12:13], v[10:11], 1, v[8:9]
	v_ashrrev_i32_e32 v8, 31, v2
	v_lshrrev_b32_e32 v8, 28, v8
	v_add_u32_e32 v8, v2, v8
	v_ashrrev_i32_e32 v14, 4, v8
	v_lshlrev_b32_e32 v9, 7, v14
	v_lshlrev_b32_e32 v2, 3, v2
	v_mul_lo_u32 v8, v14, s39
	v_sub_u32_e32 v16, v2, v9
	v_add_lshl_u32 v2, v16, v8, 1
	ds_read_b128 v[8:11], v2
	v_ashrrev_i32_e32 v15, 31, v14
	s_waitcnt lgkmcnt(1)
	global_store_dwordx4 v[12:13], v[4:7], off
	v_ashrrev_i32_e32 v17, 31, v16
	v_add_u32_e32 v2, 0xc00, v1
	v_lshl_add_u64 v[4:5], s[12:13], 0, v[14:15]
	v_lshlrev_b64 v[4:5], 11, v[4:5]
	v_lshl_add_u64 v[4:5], s[10:11], 0, v[4:5]
	v_lshl_add_u64 v[4:5], v[16:17], 1, v[4:5]
	s_waitcnt lgkmcnt(0)
	global_store_dwordx4 v[4:5], v[8:11], off
	v_ashrrev_i32_e32 v4, 31, v2
	v_lshrrev_b32_e32 v4, 28, v4
	v_add_u32_e32 v4, v2, v4
	v_ashrrev_i32_e32 v8, 4, v4
	v_lshlrev_b32_e32 v5, 7, v8
	v_lshlrev_b32_e32 v2, 3, v2
	v_ashrrev_i32_e32 v9, 31, v8
	v_mul_lo_u32 v4, v8, s39
	v_sub_u32_e32 v10, v2, v5
	v_lshl_add_u64 v[8:9], s[12:13], 0, v[8:9]
	v_add_lshl_u32 v2, v10, v4, 1
	v_lshlrev_b64 v[8:9], 11, v[8:9]
	ds_read_b128 v[4:7], v2
	v_lshl_add_u64 v[8:9], s[10:11], 0, v[8:9]
	v_ashrrev_i32_e32 v11, 31, v10
	v_add_u32_e32 v2, 0xd00, v1
	v_lshl_add_u64 v[12:13], v[10:11], 1, v[8:9]
	v_ashrrev_i32_e32 v8, 31, v2
	v_lshrrev_b32_e32 v8, 28, v8
	v_add_u32_e32 v8, v2, v8
	v_ashrrev_i32_e32 v14, 4, v8
	v_lshlrev_b32_e32 v9, 7, v14
	v_lshlrev_b32_e32 v2, 3, v2
	v_mul_lo_u32 v8, v14, s39
	v_sub_u32_e32 v16, v2, v9
	v_add_lshl_u32 v2, v16, v8, 1
	ds_read_b128 v[8:11], v2
	v_ashrrev_i32_e32 v15, 31, v14
	s_waitcnt lgkmcnt(1)
	global_store_dwordx4 v[12:13], v[4:7], off
	v_ashrrev_i32_e32 v17, 31, v16
	v_add_u32_e32 v2, 0xe00, v1
	v_lshl_add_u64 v[4:5], s[12:13], 0, v[14:15]
	v_lshlrev_b64 v[4:5], 11, v[4:5]
	v_lshl_add_u64 v[4:5], s[10:11], 0, v[4:5]
	v_lshl_add_u64 v[4:5], v[16:17], 1, v[4:5]
	s_waitcnt lgkmcnt(0)
	global_store_dwordx4 v[4:5], v[8:11], off
	v_ashrrev_i32_e32 v4, 31, v2
	v_lshrrev_b32_e32 v4, 28, v4
	v_add_u32_e32 v4, v2, v4
	v_ashrrev_i32_e32 v8, 4, v4
	v_lshlrev_b32_e32 v5, 7, v8
	v_lshlrev_b32_e32 v2, 3, v2
	v_mul_lo_u32 v4, v8, s39
	v_sub_u32_e32 v10, v2, v5
	v_add_lshl_u32 v2, v10, v4, 1
	v_add_u32_e32 v1, 0xf00, v1
	ds_read_b128 v[4:7], v2
	v_ashrrev_i32_e32 v9, 31, v8
	v_ashrrev_i32_e32 v2, 31, v1
	v_lshl_add_u64 v[8:9], s[12:13], 0, v[8:9]
	v_lshrrev_b32_e32 v2, 28, v2
	v_lshlrev_b64 v[8:9], 11, v[8:9]
	v_add_u32_e32 v2, v1, v2
	v_lshl_add_u64 v[8:9], s[10:11], 0, v[8:9]
	v_ashrrev_i32_e32 v11, 31, v10
	v_ashrrev_i32_e32 v14, 4, v2
	v_lshl_add_u64 v[12:13], v[10:11], 1, v[8:9]
	v_lshlrev_b32_e32 v8, 7, v14
	v_lshlrev_b32_e32 v1, 3, v1
	v_mul_lo_u32 v2, v14, s39
	v_sub_u32_e32 v16, v1, v8
	v_add_lshl_u32 v1, v16, v2, 1
	v_ashrrev_i32_e32 v15, 31, v14
	ds_read_b128 v[8:11], v1
	s_waitcnt lgkmcnt(1)
	global_store_dwordx4 v[12:13], v[4:7], off
	v_ashrrev_i32_e32 v17, 31, v16
	v_readlane_b32 s58, v251, 60
	v_lshl_add_u64 v[4:5], s[12:13], 0, v[14:15]
	v_lshlrev_b64 v[4:5], 11, v[4:5]
	v_lshl_add_u64 v[4:5], s[10:11], 0, v[4:5]
	v_readlane_b32 s10, v252, 59
	s_add_i32 s2, s2, s10
	v_readlane_b32 s59, v251, 61
	v_lshl_add_u64 v[4:5], v[16:17], 1, v[4:5]
	s_cmpk_gt_i32 s2, 0x3ff
	v_readlane_b32 s57, v251, 59
	v_readlane_b32 s62, v252, 0
	v_readlane_b32 s63, v252, 1
	v_readlane_b32 s64, v252, 2
	v_readlane_b32 s65, v252, 3
	v_readlane_b32 s66, v252, 4
	v_readlane_b32 s67, v252, 5
	v_readlane_b32 s68, v252, 6
	v_readlane_b32 s69, v252, 7
	v_readlane_b32 s70, v252, 8
	v_readlane_b32 s71, v252, 9
	s_waitcnt lgkmcnt(0)
	global_store_dwordx4 v[4:5], v[8:11], off
	s_barrier
	v_readlane_b32 s11, v252, 60
	s_cbranch_scc0 .LBB0_172

; DEVI f32x4 mfma16(bf16x8 a, bf16x8 b, f32x4 c) { return __builtin_amdgcn_mfma_f32_16x16x32_bf16(a, b, c, 0, 0, 0); }
; DEVI void gemm_core3(f32x4 (&acc)[8][4], const bf* __restrict__ A, int lda, const bf* __restrict__ Bt, int ldb, int K, char* smem) {
;     ...
;   for (int kt = 0; kt < nk; ++kt) {
;     const int k1 = min((kt + 1) * 32, klast);
;     const int sn = ((kt + 1) & 1) * STG;
;     const int so = (kt & 1) * STG;
;     bf16x8 bfr[4], af[8];
; #pragma unroll
;     for (int n = 0; n < 4; ++n) bfr[n] = *reinterpret_cast<const bf16x8*>(bbase + so + n * 16 * 64);
; #pragma unroll
;     for (int m = 0; m < 8; ++m) af[m] = *reinterpret_cast<const bf16x8*>(abase + so + m * 16 * 64);
; #pragma unroll
;     for (int i = 0; i < 4; ++i) glds16(Ap + i * sa + k1, dbase + sn + i * 4096);
; #pragma unroll
;     for (int i = 0; i < 2; ++i) glds16(Bp + i * sb + k1, dbase + sn + ASZ + i * 4096);
;     __builtin_amdgcn_s_setprio(1);
; #pragma unroll
;     for (int m = 0; m < 8; ++m)
; #pragma unroll
;       for (int n = 0; n < 4; ++n) acc[m][n] = mfma16(af[m], bfr[n], acc[m][n]);
;     __builtin_amdgcn_s_setprio(0);
;     __syncthreads();
;   }
.Lg3_loop_184:
	v_add_u32_e32 v216, s10, v146
	v_add_u32_e32 v217, s10, v2
	ds_read_b128 v[148:151], v217 offset:16384
	ds_read_b128 v[166:169], v216
	ds_read_b128 v[154:157], v217 offset:17408
	ds_read_b128 v[158:161], v217 offset:18432
	ds_read_b128 v[162:165], v217 offset:19456
	ds_read_b128 v[170:173], v216 offset:1024
	ds_read_b128 v[174:177], v216 offset:2048
	ds_read_b128 v[192:195], v216 offset:3072
	ds_read_b128 v[196:199], v216 offset:4096
	ds_read_b128 v[204:207], v216 offset:5120
	ds_read_b128 v[208:211], v216 offset:6144
	ds_read_b128 v[212:215], v216 offset:7168
	s_setprio 1
	s_waitcnt lgkmcnt(10)
	v_mfma_f32_16x16x32_bf16 v[128:131], v[166:169], v[148:151], v[128:131]
	s_waitcnt lgkmcnt(9)
	v_mfma_f32_16x16x32_bf16 v[124:127], v[166:169], v[154:157], v[124:127]
	s_waitcnt lgkmcnt(8)
	v_mfma_f32_16x16x32_bf16 v[120:123], v[166:169], v[158:161], v[120:123]
	s_waitcnt lgkmcnt(7)
	v_mfma_f32_16x16x32_bf16 v[116:119], v[166:169], v[162:165], v[116:119]
	s_waitcnt lgkmcnt(6)
	v_mfma_f32_16x16x32_bf16 v[112:115], v[170:173], v[148:151], v[112:115]
	v_mfma_f32_16x16x32_bf16 v[108:111], v[170:173], v[154:157], v[108:111]
	v_mfma_f32_16x16x32_bf16 v[104:107], v[170:173], v[158:161], v[104:107]
	v_mfma_f32_16x16x32_bf16 v[100:103], v[170:173], v[162:165], v[100:103]
	s_waitcnt lgkmcnt(5)
	v_mfma_f32_16x16x32_bf16 v[96:99], v[174:177], v[148:151], v[96:99]
	v_mfma_f32_16x16x32_bf16 v[92:95], v[174:177], v[154:157], v[92:95]
	v_mfma_f32_16x16x32_bf16 v[88:91], v[174:177], v[158:161], v[88:91]
	v_mfma_f32_16x16x32_bf16 v[84:87], v[174:177], v[162:165], v[84:87]
	s_waitcnt lgkmcnt(4)
	v_mfma_f32_16x16x32_bf16 v[80:83], v[192:195], v[148:151], v[80:83]
	v_mfma_f32_16x16x32_bf16 v[76:79], v[192:195], v[154:157], v[76:79]
	v_mfma_f32_16x16x32_bf16 v[72:75], v[192:195], v[158:161], v[72:75]
	v_mfma_f32_16x16x32_bf16 v[68:71], v[192:195], v[162:165], v[68:71]
	s_waitcnt lgkmcnt(3)
	v_mfma_f32_16x16x32_bf16 v[64:67], v[196:199], v[148:151], v[64:67]
	v_mfma_f32_16x16x32_bf16 v[60:63], v[196:199], v[154:157], v[60:63]
	v_mfma_f32_16x16x32_bf16 v[56:59], v[196:199], v[158:161], v[56:59]
	v_mfma_f32_16x16x32_bf16 v[52:55], v[196:199], v[162:165], v[52:55]
	s_waitcnt lgkmcnt(2)
	v_mfma_f32_16x16x32_bf16 v[48:51], v[204:207], v[148:151], v[48:51]
	v_mfma_f32_16x16x32_bf16 v[44:47], v[204:207], v[154:157], v[44:47]
	v_mfma_f32_16x16x32_bf16 v[40:43], v[204:207], v[158:161], v[40:43]
	v_mfma_f32_16x16x32_bf16 v[36:39], v[204:207], v[162:165], v[36:39]
	s_waitcnt lgkmcnt(1)
	v_mfma_f32_16x16x32_bf16 v[32:35], v[208:211], v[148:151], v[32:35]
	v_mfma_f32_16x16x32_bf16 v[28:31], v[208:211], v[154:157], v[28:31]
	v_mfma_f32_16x16x32_bf16 v[24:27], v[208:211], v[158:161], v[24:27]
	v_mfma_f32_16x16x32_bf16 v[20:23], v[208:211], v[162:165], v[20:23]
	s_waitcnt lgkmcnt(0)
	v_mfma_f32_16x16x32_bf16 v[16:19], v[212:215], v[148:151], v[16:19]
	v_mfma_f32_16x16x32_bf16 v[12:15], v[212:215], v[154:157], v[12:15]
	v_mfma_f32_16x16x32_bf16 v[8:11], v[212:215], v[158:161], v[8:11]
	v_mfma_f32_16x16x32_bf16 v[4:7], v[212:215], v[162:165], v[4:7]
	s_setprio 0
	s_add_i32 s10, s10, 0x6000
	s_cmp_lg_u32 s10, 0x12000
	s_cselect_b32 s10, s10, 0
	s_waitcnt vmcnt(0)
	s_barrier
	v_add_u32_e32 v216, s10, v146
	v_add_u32_e32 v217, s10, v2
	ds_read_b128 v[148:151], v217 offset:16384
	ds_read_b128 v[166:169], v216
	ds_read_b128 v[154:157], v217 offset:17408
	ds_read_b128 v[158:161], v217 offset:18432
	ds_read_b128 v[162:165], v217 offset:19456
	ds_read_b128 v[170:173], v216 offset:1024
	ds_read_b128 v[174:177], v216 offset:2048
	ds_read_b128 v[192:195], v216 offset:3072
	ds_read_b128 v[196:199], v216 offset:4096
	ds_read_b128 v[204:207], v216 offset:5120
	ds_read_b128 v[208:211], v216 offset:6144
	ds_read_b128 v[212:215], v216 offset:7168
	v_readfirstlane_b32 s17, v140
	s_add_i32 s96, s11, 0x6000
	s_cmp_lg_u32 s96, 0x12000
	s_cselect_b32 s96, s96, 0
	s_add_i32 s96, s96, s17
	s_add_i32 s17, s17, s11
	s_setprio 2
	s_waitcnt lgkmcnt(10)
	s_mov_b32 m0, s17
	s_add_i32 s17, s17, 0x1000
	v_mfma_f32_16x16x32_bf16 v[128:131], v[166:169], v[148:151], v[128:131]
	s_waitcnt lgkmcnt(9)
	v_mfma_f32_16x16x32_bf16 v[124:127], v[166:169], v[154:157], v[124:127]
	global_load_lds_dwordx4 v[218:219], off
	v_lshl_add_u64 v[218:219], v[218:219], 0, 64
	s_waitcnt lgkmcnt(8)
	s_mov_b32 m0, s96
	s_add_i32 s96, s96, 0x1000
	v_mfma_f32_16x16x32_bf16 v[120:123], v[166:169], v[158:161], v[120:123]
	s_waitcnt lgkmcnt(7)
	v_mfma_f32_16x16x32_bf16 v[116:119], v[166:169], v[162:165], v[116:119]
	global_load_lds_dwordx4 v[218:219], off
	v_lshl_add_u64 v[218:219], v[218:219], 0, 64
	s_waitcnt lgkmcnt(6)
	v_mfma_f32_16x16x32_bf16 v[112:115], v[170:173], v[148:151], v[112:115]
	s_mov_b32 m0, s17
	s_add_i32 s17, s17, 0x1000
	v_mfma_f32_16x16x32_bf16 v[108:111], v[170:173], v[154:157], v[108:111]
	v_mfma_f32_16x16x32_bf16 v[104:107], v[170:173], v[158:161], v[104:107]
	global_load_lds_dwordx4 v[220:221], off
	v_lshl_add_u64 v[220:221], v[220:221], 0, 64
	s_mov_b32 m0, s96
	s_add_i32 s96, s96, 0x1000
	v_mfma_f32_16x16x32_bf16 v[100:103], v[170:173], v[162:165], v[100:103]
	s_waitcnt lgkmcnt(5)
	v_mfma_f32_16x16x32_bf16 v[96:99], v[174:177], v[148:151], v[96:99]
	global_load_lds_dwordx4 v[220:221], off
	v_lshl_add_u64 v[220:221], v[220:221], 0, 64
	v_mfma_f32_16x16x32_bf16 v[92:95], v[174:177], v[154:157], v[92:95]
	s_mov_b32 m0, s17
	s_add_i32 s17, s17, 0x1000
	v_mfma_f32_16x16x32_bf16 v[88:91], v[174:177], v[158:161], v[88:91]
	v_mfma_f32_16x16x32_bf16 v[84:87], v[174:177], v[162:165], v[84:87]
	global_load_lds_dwordx4 v[222:223], off
	v_lshl_add_u64 v[222:223], v[222:223], 0, 64
	s_waitcnt lgkmcnt(4)
; DEVI f32x4 mfma16(bf16x8 a, bf16x8 b, f32x4 c) { return __builtin_amdgcn_mfma_f32_16x16x32_bf16(a, b, c, 0, 0, 0); }
; DEVI void gemm_core3(f32x4 (&acc)[8][4], const bf* __restrict__ A, int lda, const bf* __restrict__ Bt, int ldb, int K, char* smem) {
;     ...
;   for (int kt = 0; kt < nk; ++kt) {
;     const int k1 = min((kt + 1) * 32, klast);
;     const int sn = ((kt + 1) & 1) * STG;
;     const int so = (kt & 1) * STG;
;     bf16x8 bfr[4], af[8];
; #pragma unroll
;     for (int n = 0; n < 4; ++n) bfr[n] = *reinterpret_cast<const bf16x8*>(bbase + so + n * 16 * 64);
; #pragma unroll
;     for (int m = 0; m < 8; ++m) af[m] = *reinterpret_cast<const bf16x8*>(abase + so + m * 16 * 64);
; #pragma unroll
;     for (int i = 0; i < 4; ++i) glds16(Ap + i * sa + k1, dbase + sn + i * 4096);
; #pragma unroll
;     for (int i = 0; i < 2; ++i) glds16(Bp + i * sb + k1, dbase + sn + ASZ + i * 4096);
;     __builtin_amdgcn_s_setprio(1);
; #pragma unroll
;     for (int m = 0; m < 8; ++m)
; #pragma unroll
;       for (int n = 0; n < 4; ++n) acc[m][n] = mfma16(af[m], bfr[n], acc[m][n]);
;     __builtin_amdgcn_s_setprio(0);
;     __syncthreads();
;   }
	s_mov_b32 m0, s96
	s_add_i32 s96, s96, 0x1000
	v_mfma_f32_16x16x32_bf16 v[80:83], v[192:195], v[148:151], v[80:83]
	v_mfma_f32_16x16x32_bf16 v[76:79], v[192:195], v[154:157], v[76:79]
	global_load_lds_dwordx4 v[222:223], off
	v_lshl_add_u64 v[222:223], v[222:223], 0, 64
	v_mfma_f32_16x16x32_bf16 v[72:75], v[192:195], v[158:161], v[72:75]
	s_mov_b32 m0, s17
	s_add_i32 s17, s17, 0x1000
	v_mfma_f32_16x16x32_bf16 v[68:71], v[192:195], v[162:165], v[68:71]
	s_waitcnt lgkmcnt(3)
	v_mfma_f32_16x16x32_bf16 v[64:67], v[196:199], v[148:151], v[64:67]
	global_load_lds_dwordx4 v[224:225], off
	v_lshl_add_u64 v[224:225], v[224:225], 0, 64
	s_mov_b32 m0, s96
	s_add_i32 s96, s96, 0x1000
	v_mfma_f32_16x16x32_bf16 v[60:63], v[196:199], v[154:157], v[60:63]
	v_mfma_f32_16x16x32_bf16 v[56:59], v[196:199], v[158:161], v[56:59]
	global_load_lds_dwordx4 v[224:225], off
	v_lshl_add_u64 v[224:225], v[224:225], 0, 64
	v_mfma_f32_16x16x32_bf16 v[52:55], v[196:199], v[162:165], v[52:55]
	s_waitcnt lgkmcnt(2)
	s_mov_b32 m0, s17
	s_add_i32 s17, s17, 0x1000
	v_mfma_f32_16x16x32_bf16 v[48:51], v[204:207], v[148:151], v[48:51]
	v_mfma_f32_16x16x32_bf16 v[44:47], v[204:207], v[154:157], v[44:47]
	global_load_lds_dwordx4 v[226:227], off
	v_lshl_add_u64 v[226:227], v[226:227], 0, 64
	s_mov_b32 m0, s96
	s_add_i32 s96, s96, 0x1000
	v_mfma_f32_16x16x32_bf16 v[40:43], v[204:207], v[158:161], v[40:43]
	v_mfma_f32_16x16x32_bf16 v[36:39], v[204:207], v[162:165], v[36:39]
	global_load_lds_dwordx4 v[226:227], off
	v_lshl_add_u64 v[226:227], v[226:227], 0, 64
	s_waitcnt lgkmcnt(1)
	v_mfma_f32_16x16x32_bf16 v[32:35], v[208:211], v[148:151], v[32:35]
	s_mov_b32 m0, s17
	s_add_i32 s17, s17, 0x1000
	v_mfma_f32_16x16x32_bf16 v[28:31], v[208:211], v[154:157], v[28:31]
	v_mfma_f32_16x16x32_bf16 v[24:27], v[208:211], v[158:161], v[24:27]
	global_load_lds_dwordx4 v[228:229], off
	v_lshl_add_u64 v[228:229], v[228:229], 0, 64
	s_mov_b32 m0, s96
	s_add_i32 s96, s96, 0x1000
	v_mfma_f32_16x16x32_bf16 v[20:23], v[208:211], v[162:165], v[20:23]
	s_waitcnt lgkmcnt(0)
	v_mfma_f32_16x16x32_bf16 v[16:19], v[212:215], v[148:151], v[16:19]
	global_load_lds_dwordx4 v[228:229], off
	v_lshl_add_u64 v[228:229], v[228:229], 0, 64
	v_mfma_f32_16x16x32_bf16 v[12:15], v[212:215], v[154:157], v[12:15]
	v_mfma_f32_16x16x32_bf16 v[8:11], v[212:215], v[158:161], v[8:11]
	v_mfma_f32_16x16x32_bf16 v[4:7], v[212:215], v[162:165], v[4:7]
	s_setprio 0
	s_add_i32 s10, s10, 0x6000
	s_cmp_lg_u32 s10, 0x12000
	s_cselect_b32 s10, s10, 0
	s_sub_i32 s11, s11, 0x6000
	s_cmp_lt_i32 s11, 0
	s_cselect_b32 s11, 0xc000, s11
	s_add_i32 s3, s3, 1
	s_cmp_lt_i32 s3, 15
	s_waitcnt vmcnt(1)
	s_barrier
	s_cbranch_scc1 .Lg3_loop_184
	v_add_u32_e32 v216, s10, v146
	v_add_u32_e32 v217, s10, v2
	ds_read_b128 v[148:151], v217 offset:16384
	ds_read_b128 v[166:169], v216
	ds_read_b128 v[154:157], v217 offset:17408
	ds_read_b128 v[158:161], v217 offset:18432
	ds_read_b128 v[162:165], v217 offset:19456
	ds_read_b128 v[170:173], v216 offset:1024
	ds_read_b128 v[174:177], v216 offset:2048
	ds_read_b128 v[192:195], v216 offset:3072
	ds_read_b128 v[196:199], v216 offset:4096
	ds_read_b128 v[204:207], v216 offset:5120
	ds_read_b128 v[208:211], v216 offset:6144
	ds_read_b128 v[212:215], v216 offset:7168
	s_setprio 1
	s_waitcnt lgkmcnt(10)
	v_mfma_f32_16x16x32_bf16 v[128:131], v[166:169], v[148:151], v[128:131]
	s_waitcnt lgkmcnt(9)
	v_mfma_f32_16x16x32_bf16 v[124:127], v[166:169], v[154:157], v[124:127]
	s_waitcnt lgkmcnt(8)
	v_mfma_f32_16x16x32_bf16 v[120:123], v[166:169], v[158:161], v[120:123]
	s_waitcnt lgkmcnt(7)
	v_mfma_f32_16x16x32_bf16 v[116:119], v[166:169], v[162:165], v[116:119]
	s_waitcnt lgkmcnt(6)
	v_mfma_f32_16x16x32_bf16 v[112:115], v[170:173], v[148:151], v[112:115]
	v_mfma_f32_16x16x32_bf16 v[108:111], v[170:173], v[154:157], v[108:111]
	v_mfma_f32_16x16x32_bf16 v[104:107], v[170:173], v[158:161], v[104:107]
	v_mfma_f32_16x16x32_bf16 v[100:103], v[170:173], v[162:165], v[100:103]
	s_waitcnt lgkmcnt(5)
	v_mfma_f32_16x16x32_bf16 v[96:99], v[174:177], v[148:151], v[96:99]
	v_mfma_f32_16x16x32_bf16 v[92:95], v[174:177], v[154:157], v[92:95]
	v_mfma_f32_16x16x32_bf16 v[88:91], v[174:177], v[158:161], v[88:91]
	v_mfma_f32_16x16x32_bf16 v[84:87], v[174:177], v[162:165], v[84:87]
	s_waitcnt lgkmcnt(4)
	v_mfma_f32_16x16x32_bf16 v[80:83], v[192:195], v[148:151], v[80:83]
	v_mfma_f32_16x16x32_bf16 v[76:79], v[192:195], v[154:157], v[76:79]
	v_mfma_f32_16x16x32_bf16 v[72:75], v[192:195], v[158:161], v[72:75]
	v_mfma_f32_16x16x32_bf16 v[68:71], v[192:195], v[162:165], v[68:71]
	s_waitcnt lgkmcnt(3)
	v_mfma_f32_16x16x32_bf16 v[64:67], v[196:199], v[148:151], v[64:67]
	v_mfma_f32_16x16x32_bf16 v[60:63], v[196:199], v[154:157], v[60:63]
	v_mfma_f32_16x16x32_bf16 v[56:59], v[196:199], v[158:161], v[56:59]
	v_mfma_f32_16x16x32_bf16 v[52:55], v[196:199], v[162:165], v[52:55]
	s_waitcnt lgkmcnt(2)
	v_mfma_f32_16x16x32_bf16 v[48:51], v[204:207], v[148:151], v[48:51]
	v_mfma_f32_16x16x32_bf16 v[44:47], v[204:207], v[154:157], v[44:47]
	v_mfma_f32_16x16x32_bf16 v[40:43], v[204:207], v[158:161], v[40:43]
	v_mfma_f32_16x16x32_bf16 v[36:39], v[204:207], v[162:165], v[36:39]
	s_waitcnt lgkmcnt(1)
	v_mfma_f32_16x16x32_bf16 v[32:35], v[208:211], v[148:151], v[32:35]
	v_mfma_f32_16x16x32_bf16 v[28:31], v[208:211], v[154:157], v[28:31]
	v_mfma_f32_16x16x32_bf16 v[24:27], v[208:211], v[158:161], v[24:27]
	v_mfma_f32_16x16x32_bf16 v[20:23], v[208:211], v[162:165], v[20:23]
	s_waitcnt lgkmcnt(0)
	v_mfma_f32_16x16x32_bf16 v[16:19], v[212:215], v[148:151], v[16:19]
	v_mfma_f32_16x16x32_bf16 v[12:15], v[212:215], v[154:157], v[12:15]
	v_mfma_f32_16x16x32_bf16 v[8:11], v[212:215], v[158:161], v[8:11]
	v_mfma_f32_16x16x32_bf16 v[4:7], v[212:215], v[162:165], v[4:7]
	s_setprio 0
	s_add_i32 s10, s10, 0x6000
	s_cmp_lg_u32 s10, 0x12000
	s_cselect_b32 s10, s10, 0
	s_waitcnt vmcnt(0)
	s_barrier
; DEVI float silu_(float x) { return x / (1.f + __expf(-x)); }
; DEVI f32x4 mfma16(bf16x8 a, bf16x8 b, f32x4 c) { return __builtin_amdgcn_mfma_f32_16x16x32_bf16(a, b, c, 0, 0, 0); }
; DEVI void gemm_core3(f32x4 (&acc)[8][4], const bf* __restrict__ A, int lda, const bf* __restrict__ Bt, int ldb, int K, char* smem) {
;     ...
; #pragma unroll
;     for (int n = 0; n < 4; ++n) bfr[n] = *reinterpret_cast<const bf16x8*>(bbase + so + n * 16 * 64);
; #pragma unroll
;     for (int m = 0; m < 8; ++m) af[m] = *reinterpret_cast<const bf16x8*>(abase + so + m * 16 * 64);
; #pragma unroll
;     for (int i = 0; i < 4; ++i) glds16(Ap + i * sa + k1, dbase + sn + i * 4096);
; #pragma unroll
;     for (int i = 0; i < 2; ++i) glds16(Bp + i * sb + k1, dbase + sn + ASZ + i * 4096);
;     __builtin_amdgcn_s_setprio(1);
; #pragma unroll
;     for (int m = 0; m < 8; ++m)
; #pragma unroll
;       for (int n = 0; n < 4; ++n) acc[m][n] = mfma16(af[m], bfr[n], acc[m][n]);
;     __builtin_amdgcn_s_setprio(0);
;     __syncthreads();
; DEVI void ffn1_tile256(const P& p, const bf* W, long row0, int n0  , char* smem) {
;     ...
;   bf* tl = reinterpret_cast<bf*>(smem);
; #pragma unroll
;   for (int m = 0; m < 8; ++m)
; #pragma unroll
;     for (int pr = 0; pr < 2; ++pr) {
;       const int cl = (wc * 2 + pr) * 16 + l15;
; #pragma unroll
;       for (int j = 0; j < 4; ++j) {
;         const int rl = wr * 128 + m * 16 + quad * 4 + j;
;         float a = acc[m][2 * pr][j], b = acc[m][2 * pr + 1][j];
;         tl[rl * 72 + cl] = f2bf(silu_(a) * b);
;       }
;     }
	v_add_u32_e32 v216, s10, v146
	v_add_u32_e32 v217, s10, v2
	ds_read_b128 v[148:151], v217 offset:16384
	ds_read_b128 v[166:169], v216
	ds_read_b128 v[154:157], v217 offset:17408
	ds_read_b128 v[158:161], v217 offset:18432
	ds_read_b128 v[162:165], v217 offset:19456
	ds_read_b128 v[170:173], v216 offset:1024
	ds_read_b128 v[174:177], v216 offset:2048
	ds_read_b128 v[192:195], v216 offset:3072
	ds_read_b128 v[196:199], v216 offset:4096
	ds_read_b128 v[204:207], v216 offset:5120
	ds_read_b128 v[208:211], v216 offset:6144
	ds_read_b128 v[212:215], v216 offset:7168
	s_setprio 1
	s_waitcnt lgkmcnt(10)
	v_mfma_f32_16x16x32_bf16 v[128:131], v[166:169], v[148:151], v[128:131]
	s_waitcnt lgkmcnt(9)
	v_mfma_f32_16x16x32_bf16 v[124:127], v[166:169], v[154:157], v[124:127]
	s_waitcnt lgkmcnt(8)
	v_mfma_f32_16x16x32_bf16 v[120:123], v[166:169], v[158:161], v[120:123]
	s_waitcnt lgkmcnt(7)
	v_mfma_f32_16x16x32_bf16 v[116:119], v[166:169], v[162:165], v[116:119]
	s_waitcnt lgkmcnt(6)
	v_mfma_f32_16x16x32_bf16 v[112:115], v[170:173], v[148:151], v[112:115]
	v_mfma_f32_16x16x32_bf16 v[108:111], v[170:173], v[154:157], v[108:111]
	v_mfma_f32_16x16x32_bf16 v[104:107], v[170:173], v[158:161], v[104:107]
	v_mfma_f32_16x16x32_bf16 v[100:103], v[170:173], v[162:165], v[100:103]
	s_waitcnt lgkmcnt(5)
	v_mfma_f32_16x16x32_bf16 v[96:99], v[174:177], v[148:151], v[96:99]
	v_mfma_f32_16x16x32_bf16 v[92:95], v[174:177], v[154:157], v[92:95]
	v_mfma_f32_16x16x32_bf16 v[88:91], v[174:177], v[158:161], v[88:91]
	v_mfma_f32_16x16x32_bf16 v[84:87], v[174:177], v[162:165], v[84:87]
	s_waitcnt lgkmcnt(4)
	v_mfma_f32_16x16x32_bf16 v[80:83], v[192:195], v[148:151], v[80:83]
	v_mfma_f32_16x16x32_bf16 v[76:79], v[192:195], v[154:157], v[76:79]
	v_mfma_f32_16x16x32_bf16 v[72:75], v[192:195], v[158:161], v[72:75]
	v_mfma_f32_16x16x32_bf16 v[68:71], v[192:195], v[162:165], v[68:71]
	s_waitcnt lgkmcnt(3)
	v_mfma_f32_16x16x32_bf16 v[64:67], v[196:199], v[148:151], v[64:67]
	v_mfma_f32_16x16x32_bf16 v[60:63], v[196:199], v[154:157], v[60:63]
	v_mfma_f32_16x16x32_bf16 v[56:59], v[196:199], v[158:161], v[56:59]
	v_mfma_f32_16x16x32_bf16 v[52:55], v[196:199], v[162:165], v[52:55]
	s_waitcnt lgkmcnt(2)
	v_mfma_f32_16x16x32_bf16 v[48:51], v[204:207], v[148:151], v[48:51]
	v_mfma_f32_16x16x32_bf16 v[44:47], v[204:207], v[154:157], v[44:47]
	v_mfma_f32_16x16x32_bf16 v[40:43], v[204:207], v[158:161], v[40:43]
	v_mfma_f32_16x16x32_bf16 v[36:39], v[204:207], v[162:165], v[36:39]
	s_waitcnt lgkmcnt(1)
	v_mfma_f32_16x16x32_bf16 v[32:35], v[208:211], v[148:151], v[32:35]
	v_mfma_f32_16x16x32_bf16 v[28:31], v[208:211], v[154:157], v[28:31]
	v_mfma_f32_16x16x32_bf16 v[24:27], v[208:211], v[158:161], v[24:27]
	v_mfma_f32_16x16x32_bf16 v[20:23], v[208:211], v[162:165], v[20:23]
	s_waitcnt lgkmcnt(0)
	v_mfma_f32_16x16x32_bf16 v[16:19], v[212:215], v[148:151], v[16:19]
	v_mfma_f32_16x16x32_bf16 v[12:15], v[212:215], v[154:157], v[12:15]
	v_mfma_f32_16x16x32_bf16 v[8:11], v[212:215], v[158:161], v[8:11]
	v_mfma_f32_16x16x32_bf16 v[4:7], v[212:215], v[162:165], v[4:7]
	s_setprio 0
	s_add_i32 s10, s10, 0x6000
	s_cmp_lg_u32 s10, 0x12000
	s_cselect_b32 s10, s10, 0
	s_waitcnt vmcnt(0)
	s_barrier
	v_mul_f32_e32 v2, 0xbfb8aa3b, v128
	v_exp_f32_e32 v2, v2
	v_and_b32_e32 v132, 15, v1
	v_and_b32_e32 v133, 0xfffff80, v1
	v_lshrrev_b32_e32 v134, 2, v1
	v_add_f32_e32 v135, 1.0, v2
	v_div_scale_f32 v136, s[10:11], v135, v135, v128
	v_rcp_f32_e32 v137, v136
	v_lshlrev_b32_e32 v2, 1, v132
	v_and_or_b32 v2, v1, 64, v2
	v_and_or_b32 v133, v134, 12, v133
	v_fma_f32 v1, -v136, v137, 1.0
	v_fmac_f32_e32 v137, v1, v137
	v_div_scale_f32 v1, vcc, v128, v135, v128
	v_mul_f32_e32 v132, v1, v137
	v_fma_f32 v134, -v136, v132, v1
	v_fmac_f32_e32 v132, v134, v137
	v_fma_f32 v1, -v136, v132, v1
	v_div_fmas_f32 v1, v1, v137, v132
	v_mul_f32_e32 v132, 0xbfb8aa3b, v129
	v_exp_f32_e32 v132, v132
	v_div_fixup_f32 v1, v1, v135, v128
	v_mul_f32_e32 v1, v124, v1
	s_movk_i32 s3, 0x90
	v_add_f32_e32 v124, 1.0, v132
	v_div_scale_f32 v128, s[10:11], v124, v124, v129
	v_rcp_f32_e32 v134, v128
	v_cvt_pk_bf16_f32 v1, v1, s0
	v_mad_u64_u32 v[132:133], s[10:11], v133, s3, v[2:3]
	ds_write_b16 v132, v1
	v_fma_f32 v1, -v128, v134, 1.0
	v_fmac_f32_e32 v134, v1, v134
	v_div_scale_f32 v1, vcc, v129, v124, v129
	v_mul_f32_e32 v2, v1, v134
	v_fma_f32 v133, -v128, v2, v1
	v_fmac_f32_e32 v2, v133, v134
	v_fma_f32 v1, -v128, v2, v1
	v_mul_f32_e32 v128, 0xbfb8aa3b, v130
	v_exp_f32_e32 v128, v128
	v_div_fmas_f32 v1, v1, v134, v2
	v_div_fixup_f32 v1, v1, v124, v129
	v_mul_f32_e32 v1, v125, v1
	v_add_f32_e32 v2, 1.0, v128
	v_div_scale_f32 v124, s[10:11], v2, v2, v130
	v_rcp_f32_e32 v128, v124
	v_cvt_pk_bf16_f32 v1, v1, s0
	ds_write_b16 v132, v1 offset:144
	v_readlane_b32 s56, v251, 58
	v_fma_f32 v1, -v124, v128, 1.0
	v_fmac_f32_e32 v128, v1, v128
	v_div_scale_f32 v1, vcc, v130, v2, v130
	v_mul_f32_e32 v125, v1, v128
	v_fma_f32 v129, -v124, v125, v1
	v_fmac_f32_e32 v125, v129, v128
	v_fma_f32 v1, -v124, v125, v1
	v_mul_f32_e32 v124, 0xbfb8aa3b, v131
	v_exp_f32_e32 v124, v124
	v_div_fmas_f32 v1, v1, v128, v125
	v_div_fixup_f32 v1, v1, v2, v130
	v_mul_f32_e32 v1, v126, v1
	v_add_f32_e32 v2, 1.0, v124
	v_div_scale_f32 v124, s[10:11], v2, v2, v131
	v_rcp_f32_e32 v125, v124
	v_cvt_pk_bf16_f32 v1, v1, s0
	ds_write_b16 v132, v1 offset:288
	v_readlane_b32 s58, v251, 60
	v_fma_f32 v1, -v124, v125, 1.0
	v_fmac_f32_e32 v125, v1, v125
	v_div_scale_f32 v1, vcc, v131, v2, v131
	v_mul_f32_e32 v126, v1, v125
	v_fma_f32 v128, -v124, v126, v1
	v_fmac_f32_e32 v126, v128, v125
	v_fma_f32 v1, -v124, v126, v1
	v_mul_f32_e32 v124, 0xbfb8aa3b, v120
	v_exp_f32_e32 v124, v124
; DEVI float silu_(float x) { return x / (1.f + __expf(-x)); }
; DEVI void ffn1_tile256(const P& p, const bf* W, long row0, int n0  , char* smem) {
;     ...
; #pragma unroll
;   for (int m = 0; m < 8; ++m)
; #pragma unroll
;     for (int pr = 0; pr < 2; ++pr) {
;       const int cl = (wc * 2 + pr) * 16 + l15;
; #pragma unroll
;       for (int j = 0; j < 4; ++j) {
;         const int rl = wr * 128 + m * 16 + quad * 4 + j;
;         float a = acc[m][2 * pr][j], b = acc[m][2 * pr + 1][j];
;         tl[rl * 72 + cl] = f2bf(silu_(a) * b);
;       }
;     }
	v_div_fmas_f32 v1, v1, v125, v126
	v_div_fixup_f32 v1, v1, v2, v131
	v_mul_f32_e32 v1, v127, v1
	v_add_f32_e32 v2, 1.0, v124
	v_div_scale_f32 v124, s[10:11], v2, v2, v120
	v_rcp_f32_e32 v125, v124
	v_cvt_pk_bf16_f32 v1, v1, s0
	ds_write_b16 v132, v1 offset:432
	v_readlane_b32 s59, v251, 61
	v_fma_f32 v1, -v124, v125, 1.0
	v_fmac_f32_e32 v125, v1, v125
	v_div_scale_f32 v1, vcc, v120, v2, v120
	v_mul_f32_e32 v126, v1, v125
	v_fma_f32 v127, -v124, v126, v1
	v_fmac_f32_e32 v126, v127, v125
	v_fma_f32 v1, -v124, v126, v1
	v_mul_f32_e32 v124, 0xbfb8aa3b, v121
	v_exp_f32_e32 v124, v124
	v_div_fmas_f32 v1, v1, v125, v126
	v_div_fixup_f32 v1, v1, v2, v120
	v_mul_f32_e32 v1, v116, v1
	v_add_f32_e32 v2, 1.0, v124
	v_div_scale_f32 v120, s[10:11], v2, v2, v121
	v_rcp_f32_e32 v124, v120
	v_cvt_pk_bf16_f32 v1, v1, s0
	ds_write_b16 v132, v1 offset:32
	v_readlane_b32 s57, v251, 59
	v_fma_f32 v1, -v120, v124, 1.0
	v_fmac_f32_e32 v124, v1, v124
	v_div_scale_f32 v1, vcc, v121, v2, v121
	v_mul_f32_e32 v116, v1, v124
	v_fma_f32 v125, -v120, v116, v1
	v_fmac_f32_e32 v116, v125, v124
	v_fma_f32 v1, -v120, v116, v1
	v_mul_f32_e32 v120, 0xbfb8aa3b, v122
	v_exp_f32_e32 v120, v120
	v_div_fmas_f32 v1, v1, v124, v116
	v_div_fixup_f32 v1, v1, v2, v121
	v_mul_f32_e32 v1, v117, v1
	v_add_f32_e32 v2, 1.0, v120
	v_div_scale_f32 v116, s[10:11], v2, v2, v122
	v_rcp_f32_e32 v120, v116
	v_cvt_pk_bf16_f32 v1, v1, s0
	ds_write_b16 v132, v1 offset:176
	v_readlane_b32 s60, v251, 62
	v_fma_f32 v1, -v116, v120, 1.0
	v_fmac_f32_e32 v120, v1, v120
	v_div_scale_f32 v1, vcc, v122, v2, v122
	v_mul_f32_e32 v117, v1, v120
	v_fma_f32 v121, -v116, v117, v1
	v_fmac_f32_e32 v117, v121, v120
	v_fma_f32 v1, -v116, v117, v1
	v_mul_f32_e32 v116, 0xbfb8aa3b, v123
	v_exp_f32_e32 v116, v116
	v_div_fmas_f32 v1, v1, v120, v117
	v_div_fixup_f32 v1, v1, v2, v122
	v_mul_f32_e32 v1, v118, v1
	v_add_f32_e32 v2, 1.0, v116
	v_div_scale_f32 v116, s[10:11], v2, v2, v123
	v_rcp_f32_e32 v117, v116
	v_cvt_pk_bf16_f32 v1, v1, s0
	ds_write_b16 v132, v1 offset:320
	v_readlane_b32 s61, v251, 63
	v_fma_f32 v1, -v116, v117, 1.0
	v_fmac_f32_e32 v117, v1, v117
	v_div_scale_f32 v1, vcc, v123, v2, v123
	v_mul_f32_e32 v118, v1, v117
	v_fma_f32 v120, -v116, v118, v1
	v_fmac_f32_e32 v118, v120, v117
	v_fma_f32 v1, -v116, v118, v1
	v_mul_f32_e32 v116, 0xbfb8aa3b, v112
	v_exp_f32_e32 v116, v116
	v_div_fmas_f32 v1, v1, v117, v118
	v_div_fixup_f32 v1, v1, v2, v123
	v_mul_f32_e32 v1, v119, v1
	v_add_f32_e32 v2, 1.0, v116
	v_div_scale_f32 v116, s[10:11], v2, v2, v112
	v_rcp_f32_e32 v117, v116
	v_cvt_pk_bf16_f32 v1, v1, s0
	ds_write_b16 v132, v1 offset:464
	v_readlane_b32 s62, v252, 0
	v_fma_f32 v1, -v116, v117, 1.0
	v_fmac_f32_e32 v117, v1, v117
	v_div_scale_f32 v1, vcc, v112, v2, v112
	v_mul_f32_e32 v118, v1, v117
	v_fma_f32 v119, -v116, v118, v1
	v_fmac_f32_e32 v118, v119, v117
	v_fma_f32 v1, -v116, v118, v1
	v_mul_f32_e32 v116, 0xbfb8aa3b, v113
	v_exp_f32_e32 v116, v116
	v_div_fmas_f32 v1, v1, v117, v118
	v_div_fixup_f32 v1, v1, v2, v112
	v_mul_f32_e32 v1, v108, v1
	v_add_f32_e32 v2, 1.0, v116
	v_div_scale_f32 v112, s[10:11], v2, v2, v113
	v_rcp_f32_e32 v116, v112
	v_cvt_pk_bf16_f32 v1, v1, s0
	ds_write_b16 v132, v1 offset:2304
	v_readlane_b32 s63, v252, 1
	v_fma_f32 v1, -v112, v116, 1.0
	v_fmac_f32_e32 v116, v1, v116
	v_div_scale_f32 v1, vcc, v113, v2, v113
	v_mul_f32_e32 v108, v1, v116
	v_fma_f32 v117, -v112, v108, v1
	v_fmac_f32_e32 v108, v117, v116
	v_fma_f32 v1, -v112, v108, v1
	v_mul_f32_e32 v112, 0xbfb8aa3b, v114
	v_exp_f32_e32 v112, v112
	v_div_fmas_f32 v1, v1, v116, v108
	v_div_fixup_f32 v1, v1, v2, v113
	v_mul_f32_e32 v1, v109, v1
	v_add_f32_e32 v2, 1.0, v112
	v_div_scale_f32 v108, s[10:11], v2, v2, v114
	v_rcp_f32_e32 v112, v108
	v_cvt_pk_bf16_f32 v1, v1, s0
	ds_write_b16 v132, v1 offset:2448
	v_readlane_b32 s64, v252, 2
	v_fma_f32 v1, -v108, v112, 1.0
	v_fmac_f32_e32 v112, v1, v112
	v_div_scale_f32 v1, vcc, v114, v2, v114
	v_mul_f32_e32 v109, v1, v112
	v_fma_f32 v113, -v108, v109, v1
	v_fmac_f32_e32 v109, v113, v112
	v_fma_f32 v1, -v108, v109, v1
	v_mul_f32_e32 v108, 0xbfb8aa3b, v115
	v_exp_f32_e32 v108, v108
	v_div_fmas_f32 v1, v1, v112, v109
	v_div_fixup_f32 v1, v1, v2, v114
	v_mul_f32_e32 v1, v110, v1
	v_add_f32_e32 v2, 1.0, v108
	v_div_scale_f32 v108, s[10:11], v2, v2, v115
	v_rcp_f32_e32 v109, v108
	v_cvt_pk_bf16_f32 v1, v1, s0
	ds_write_b16 v132, v1 offset:2592
	v_readlane_b32 s65, v252, 3
	v_fma_f32 v1, -v108, v109, 1.0
	v_fmac_f32_e32 v109, v1, v109
	v_div_scale_f32 v1, vcc, v115, v2, v115
	v_mul_f32_e32 v110, v1, v109
	v_fma_f32 v112, -v108, v110, v1
	v_fmac_f32_e32 v110, v112, v109
	v_fma_f32 v1, -v108, v110, v1
	v_mul_f32_e32 v108, 0xbfb8aa3b, v104
	v_exp_f32_e32 v108, v108
	v_div_fmas_f32 v1, v1, v109, v110
	v_div_fixup_f32 v1, v1, v2, v115
	v_mul_f32_e32 v1, v111, v1
	v_add_f32_e32 v2, 1.0, v108
	v_div_scale_f32 v108, s[10:11], v2, v2, v104
	v_rcp_f32_e32 v109, v108
	v_cvt_pk_bf16_f32 v1, v1, s0
	ds_write_b16 v132, v1 offset:2736
	v_readlane_b32 s66, v252, 4
	v_fma_f32 v1, -v108, v109, 1.0
	v_fmac_f32_e32 v109, v1, v109
	v_div_scale_f32 v1, vcc, v104, v2, v104
	v_mul_f32_e32 v110, v1, v109
	v_fma_f32 v111, -v108, v110, v1
	v_fmac_f32_e32 v110, v111, v109
	v_fma_f32 v1, -v108, v110, v1
	v_mul_f32_e32 v108, 0xbfb8aa3b, v105
	v_exp_f32_e32 v108, v108
	v_div_fmas_f32 v1, v1, v109, v110
	v_div_fixup_f32 v1, v1, v2, v104
	v_mul_f32_e32 v1, v100, v1
	v_add_f32_e32 v2, 1.0, v108
	v_div_scale_f32 v104, s[10:11], v2, v2, v105
	v_rcp_f32_e32 v108, v104
	v_cvt_pk_bf16_f32 v1, v1, s0
	ds_write_b16 v132, v1 offset:2336
	v_readlane_b32 s67, v252, 5
	v_fma_f32 v1, -v104, v108, 1.0
	v_fmac_f32_e32 v108, v1, v108
; DEVI float silu_(float x) { return x / (1.f + __expf(-x)); }
; DEVI void ffn1_tile256(const P& p, const bf* W, long row0, int n0  , char* smem) {
;     ...
; #pragma unroll
;   for (int m = 0; m < 8; ++m)
; #pragma unroll
;     for (int pr = 0; pr < 2; ++pr) {
;       const int cl = (wc * 2 + pr) * 16 + l15;
; #pragma unroll
;       for (int j = 0; j < 4; ++j) {
;         const int rl = wr * 128 + m * 16 + quad * 4 + j;
;         float a = acc[m][2 * pr][j], b = acc[m][2 * pr + 1][j];
;         tl[rl * 72 + cl] = f2bf(silu_(a) * b);
;       }
;     }
	v_div_scale_f32 v1, vcc, v105, v2, v105
	v_mul_f32_e32 v100, v1, v108
	v_fma_f32 v109, -v104, v100, v1
	v_fmac_f32_e32 v100, v109, v108
	v_fma_f32 v1, -v104, v100, v1
	v_mul_f32_e32 v104, 0xbfb8aa3b, v106
	v_exp_f32_e32 v104, v104
	v_div_fmas_f32 v1, v1, v108, v100
	v_div_fixup_f32 v1, v1, v2, v105
	v_mul_f32_e32 v1, v101, v1
	v_add_f32_e32 v2, 1.0, v104
	v_div_scale_f32 v100, s[10:11], v2, v2, v106
	v_rcp_f32_e32 v104, v100
	v_cvt_pk_bf16_f32 v1, v1, s0
	ds_write_b16 v132, v1 offset:2480
	v_readlane_b32 s68, v252, 6
	v_fma_f32 v1, -v100, v104, 1.0
	v_fmac_f32_e32 v104, v1, v104
	v_div_scale_f32 v1, vcc, v106, v2, v106
	v_mul_f32_e32 v101, v1, v104
	v_fma_f32 v105, -v100, v101, v1
	v_fmac_f32_e32 v101, v105, v104
	v_fma_f32 v1, -v100, v101, v1
	v_mul_f32_e32 v100, 0xbfb8aa3b, v107
	v_exp_f32_e32 v100, v100
	v_div_fmas_f32 v1, v1, v104, v101
	v_div_fixup_f32 v1, v1, v2, v106
	v_mul_f32_e32 v1, v102, v1
	v_add_f32_e32 v2, 1.0, v100
	v_div_scale_f32 v100, s[10:11], v2, v2, v107
	v_rcp_f32_e32 v101, v100
	v_cvt_pk_bf16_f32 v1, v1, s0
	ds_write_b16 v132, v1 offset:2624
	v_readlane_b32 s69, v252, 7
	v_fma_f32 v1, -v100, v101, 1.0
	v_fmac_f32_e32 v101, v1, v101
	v_div_scale_f32 v1, vcc, v107, v2, v107
	v_mul_f32_e32 v102, v1, v101
	v_fma_f32 v104, -v100, v102, v1
	v_fmac_f32_e32 v102, v104, v101
	v_fma_f32 v1, -v100, v102, v1
	v_mul_f32_e32 v100, 0xbfb8aa3b, v96
	v_exp_f32_e32 v100, v100
	v_div_fmas_f32 v1, v1, v101, v102
	v_div_fixup_f32 v1, v1, v2, v107
	v_mul_f32_e32 v1, v103, v1
	v_add_f32_e32 v2, 1.0, v100
	v_div_scale_f32 v100, s[10:11], v2, v2, v96
	v_rcp_f32_e32 v101, v100
	v_cvt_pk_bf16_f32 v1, v1, s0
	ds_write_b16 v132, v1 offset:2768
	v_readlane_b32 s70, v252, 8
	v_fma_f32 v1, -v100, v101, 1.0
	v_fmac_f32_e32 v101, v1, v101
	v_div_scale_f32 v1, vcc, v96, v2, v96
	v_mul_f32_e32 v102, v1, v101
	v_fma_f32 v103, -v100, v102, v1
	v_fmac_f32_e32 v102, v103, v101
	v_fma_f32 v1, -v100, v102, v1
	v_mul_f32_e32 v100, 0xbfb8aa3b, v97
	v_exp_f32_e32 v100, v100
	v_div_fmas_f32 v1, v1, v101, v102
	v_div_fixup_f32 v1, v1, v2, v96
	v_mul_f32_e32 v1, v92, v1
	v_add_f32_e32 v2, 1.0, v100
	v_div_scale_f32 v96, s[10:11], v2, v2, v97
	v_rcp_f32_e32 v100, v96
	v_cvt_pk_bf16_f32 v1, v1, s0
	ds_write_b16 v132, v1 offset:4608
	v_readlane_b32 s71, v252, 9
	v_fma_f32 v1, -v96, v100, 1.0
	v_fmac_f32_e32 v100, v1, v100
	v_div_scale_f32 v1, vcc, v97, v2, v97
	v_mul_f32_e32 v92, v1, v100
	v_fma_f32 v101, -v96, v92, v1
	v_fmac_f32_e32 v92, v101, v100
	v_fma_f32 v1, -v96, v92, v1
	v_mul_f32_e32 v96, 0xbfb8aa3b, v98
	v_exp_f32_e32 v96, v96
	v_div_fmas_f32 v1, v1, v100, v92
	v_div_fixup_f32 v1, v1, v2, v97
	v_mul_f32_e32 v1, v93, v1
	v_add_f32_e32 v2, 1.0, v96
	v_div_scale_f32 v92, s[10:11], v2, v2, v98
	v_rcp_f32_e32 v96, v92
	v_cvt_pk_bf16_f32 v1, v1, s0
	ds_write_b16 v132, v1 offset:4752
	v_fma_f32 v1, -v92, v96, 1.0
	v_fmac_f32_e32 v96, v1, v96
	v_div_scale_f32 v1, vcc, v98, v2, v98
	v_mul_f32_e32 v93, v1, v96
	v_fma_f32 v97, -v92, v93, v1
	v_fmac_f32_e32 v93, v97, v96
	v_fma_f32 v1, -v92, v93, v1
	v_mul_f32_e32 v92, 0xbfb8aa3b, v99
	v_exp_f32_e32 v92, v92
	v_div_fmas_f32 v1, v1, v96, v93
	v_div_fixup_f32 v1, v1, v2, v98
	v_mul_f32_e32 v1, v94, v1
	v_add_f32_e32 v2, 1.0, v92
	v_div_scale_f32 v92, s[10:11], v2, v2, v99
	v_rcp_f32_e32 v93, v92
	v_cvt_pk_bf16_f32 v1, v1, s0
	ds_write_b16 v132, v1 offset:4896
	v_fma_f32 v1, -v92, v93, 1.0
	v_fmac_f32_e32 v93, v1, v93
	v_div_scale_f32 v1, vcc, v99, v2, v99
	v_mul_f32_e32 v94, v1, v93
	v_fma_f32 v96, -v92, v94, v1
	v_fmac_f32_e32 v94, v96, v93
	v_fma_f32 v1, -v92, v94, v1
	v_mul_f32_e32 v92, 0xbfb8aa3b, v88
	v_exp_f32_e32 v92, v92
	v_div_fmas_f32 v1, v1, v93, v94
	v_div_fixup_f32 v1, v1, v2, v99
	v_mul_f32_e32 v1, v95, v1
	v_add_f32_e32 v2, 1.0, v92
	v_div_scale_f32 v92, s[10:11], v2, v2, v88
	v_rcp_f32_e32 v93, v92
	v_cvt_pk_bf16_f32 v1, v1, s0
	ds_write_b16 v132, v1 offset:5040
	v_fma_f32 v1, -v92, v93, 1.0
	v_fmac_f32_e32 v93, v1, v93
	v_div_scale_f32 v1, vcc, v88, v2, v88
	v_mul_f32_e32 v94, v1, v93
	v_fma_f32 v95, -v92, v94, v1
	v_fmac_f32_e32 v94, v95, v93
	v_fma_f32 v1, -v92, v94, v1
	v_mul_f32_e32 v92, 0xbfb8aa3b, v89
	v_exp_f32_e32 v92, v92
	v_div_fmas_f32 v1, v1, v93, v94
	v_div_fixup_f32 v1, v1, v2, v88
	v_mul_f32_e32 v1, v84, v1
	v_add_f32_e32 v2, 1.0, v92
	v_div_scale_f32 v88, s[10:11], v2, v2, v89
	v_rcp_f32_e32 v92, v88
	v_cvt_pk_bf16_f32 v1, v1, s0
	ds_write_b16 v132, v1 offset:4640
	v_fma_f32 v1, -v88, v92, 1.0
	v_fmac_f32_e32 v92, v1, v92
	v_div_scale_f32 v1, vcc, v89, v2, v89
	v_mul_f32_e32 v84, v1, v92
	v_fma_f32 v93, -v88, v84, v1
	v_fmac_f32_e32 v84, v93, v92
	v_fma_f32 v1, -v88, v84, v1
	v_mul_f32_e32 v88, 0xbfb8aa3b, v90
	v_exp_f32_e32 v88, v88
	v_div_fmas_f32 v1, v1, v92, v84
	v_div_fixup_f32 v1, v1, v2, v89
	v_mul_f32_e32 v1, v85, v1
	v_add_f32_e32 v2, 1.0, v88
	v_div_scale_f32 v84, s[10:11], v2, v2, v90
	v_rcp_f32_e32 v88, v84
	v_cvt_pk_bf16_f32 v1, v1, s0
	ds_write_b16 v132, v1 offset:4784
	v_fma_f32 v1, -v84, v88, 1.0
	v_fmac_f32_e32 v88, v1, v88
	v_div_scale_f32 v1, vcc, v90, v2, v90
	v_mul_f32_e32 v85, v1, v88
	v_fma_f32 v89, -v84, v85, v1
	v_fmac_f32_e32 v85, v89, v88
	v_fma_f32 v1, -v84, v85, v1
	v_mul_f32_e32 v84, 0xbfb8aa3b, v91
	v_exp_f32_e32 v84, v84
	v_div_fmas_f32 v1, v1, v88, v85
	v_div_fixup_f32 v1, v1, v2, v90
	v_mul_f32_e32 v1, v86, v1
	v_add_f32_e32 v2, 1.0, v84
	v_div_scale_f32 v84, s[10:11], v2, v2, v91
	v_rcp_f32_e32 v85, v84
	v_cvt_pk_bf16_f32 v1, v1, s0
	ds_write_b16 v132, v1 offset:4928
	v_fma_f32 v1, -v84, v85, 1.0
	v_fmac_f32_e32 v85, v1, v85
	v_div_scale_f32 v1, vcc, v91, v2, v91
	v_mul_f32_e32 v86, v1, v85
	v_fma_f32 v88, -v84, v86, v1
	v_fmac_f32_e32 v86, v88, v85
; DEVI float silu_(float x) { return x / (1.f + __expf(-x)); }
; DEVI void ffn1_tile256(const P& p, const bf* W, long row0, int n0  , char* smem) {
;     ...
; #pragma unroll
;   for (int m = 0; m < 8; ++m)
; #pragma unroll
;     for (int pr = 0; pr < 2; ++pr) {
;       const int cl = (wc * 2 + pr) * 16 + l15;
; #pragma unroll
;       for (int j = 0; j < 4; ++j) {
;         const int rl = wr * 128 + m * 16 + quad * 4 + j;
;         float a = acc[m][2 * pr][j], b = acc[m][2 * pr + 1][j];
;         tl[rl * 72 + cl] = f2bf(silu_(a) * b);
;       }
;     }
	v_fma_f32 v1, -v84, v86, v1
	v_mul_f32_e32 v84, 0xbfb8aa3b, v80
	v_exp_f32_e32 v84, v84
	v_div_fmas_f32 v1, v1, v85, v86
	v_div_fixup_f32 v1, v1, v2, v91
	v_mul_f32_e32 v1, v87, v1
	v_add_f32_e32 v2, 1.0, v84
	v_div_scale_f32 v84, s[10:11], v2, v2, v80
	v_rcp_f32_e32 v85, v84
	v_cvt_pk_bf16_f32 v1, v1, s0
	ds_write_b16 v132, v1 offset:5072
	v_fma_f32 v1, -v84, v85, 1.0
	v_fmac_f32_e32 v85, v1, v85
	v_div_scale_f32 v1, vcc, v80, v2, v80
	v_mul_f32_e32 v86, v1, v85
	v_fma_f32 v87, -v84, v86, v1
	v_fmac_f32_e32 v86, v87, v85
	v_fma_f32 v1, -v84, v86, v1
	v_mul_f32_e32 v84, 0xbfb8aa3b, v81
	v_exp_f32_e32 v84, v84
	v_div_fmas_f32 v1, v1, v85, v86
	v_div_fixup_f32 v1, v1, v2, v80
	v_mul_f32_e32 v1, v76, v1
	v_add_f32_e32 v2, 1.0, v84
	v_div_scale_f32 v80, s[10:11], v2, v2, v81
	v_rcp_f32_e32 v84, v80
	v_cvt_pk_bf16_f32 v1, v1, s0
	ds_write_b16 v132, v1 offset:6912
	v_fma_f32 v1, -v80, v84, 1.0
	v_fmac_f32_e32 v84, v1, v84
	v_div_scale_f32 v1, vcc, v81, v2, v81
	v_mul_f32_e32 v76, v1, v84
	v_fma_f32 v85, -v80, v76, v1
	v_fmac_f32_e32 v76, v85, v84
	v_fma_f32 v1, -v80, v76, v1
	v_mul_f32_e32 v80, 0xbfb8aa3b, v82
	v_exp_f32_e32 v80, v80
	v_div_fmas_f32 v1, v1, v84, v76
	v_div_fixup_f32 v1, v1, v2, v81
	v_mul_f32_e32 v1, v77, v1
	v_add_f32_e32 v2, 1.0, v80
	v_div_scale_f32 v76, s[10:11], v2, v2, v82
	v_rcp_f32_e32 v80, v76
	v_cvt_pk_bf16_f32 v1, v1, s0
	ds_write_b16 v132, v1 offset:7056
	v_fma_f32 v1, -v76, v80, 1.0
	v_fmac_f32_e32 v80, v1, v80
	v_div_scale_f32 v1, vcc, v82, v2, v82
	v_mul_f32_e32 v77, v1, v80
	v_fma_f32 v81, -v76, v77, v1
	v_fmac_f32_e32 v77, v81, v80
	v_fma_f32 v1, -v76, v77, v1
	v_mul_f32_e32 v76, 0xbfb8aa3b, v83
	v_exp_f32_e32 v76, v76
	v_div_fmas_f32 v1, v1, v80, v77
	v_div_fixup_f32 v1, v1, v2, v82
	v_mul_f32_e32 v1, v78, v1
	v_add_f32_e32 v2, 1.0, v76
	v_div_scale_f32 v76, s[10:11], v2, v2, v83
	v_rcp_f32_e32 v77, v76
	v_cvt_pk_bf16_f32 v1, v1, s0
	ds_write_b16 v132, v1 offset:7200
	v_fma_f32 v1, -v76, v77, 1.0
	v_fmac_f32_e32 v77, v1, v77
	v_div_scale_f32 v1, vcc, v83, v2, v83
	v_mul_f32_e32 v78, v1, v77
	v_fma_f32 v80, -v76, v78, v1
	v_fmac_f32_e32 v78, v80, v77
	v_fma_f32 v1, -v76, v78, v1
	v_mul_f32_e32 v76, 0xbfb8aa3b, v72
	v_exp_f32_e32 v76, v76
	v_div_fmas_f32 v1, v1, v77, v78
	v_div_fixup_f32 v1, v1, v2, v83
	v_mul_f32_e32 v1, v79, v1
	v_add_f32_e32 v2, 1.0, v76
	v_div_scale_f32 v76, s[10:11], v2, v2, v72
	v_rcp_f32_e32 v77, v76
	v_cvt_pk_bf16_f32 v1, v1, s0
	ds_write_b16 v132, v1 offset:7344
	v_fma_f32 v1, -v76, v77, 1.0
	v_fmac_f32_e32 v77, v1, v77
	v_div_scale_f32 v1, vcc, v72, v2, v72
	v_mul_f32_e32 v78, v1, v77
	v_fma_f32 v79, -v76, v78, v1
	v_fmac_f32_e32 v78, v79, v77
	v_fma_f32 v1, -v76, v78, v1
	v_mul_f32_e32 v76, 0xbfb8aa3b, v73
	v_exp_f32_e32 v76, v76
	v_div_fmas_f32 v1, v1, v77, v78
	v_div_fixup_f32 v1, v1, v2, v72
	v_mul_f32_e32 v1, v68, v1
	v_add_f32_e32 v2, 1.0, v76
	v_div_scale_f32 v72, s[10:11], v2, v2, v73
	v_rcp_f32_e32 v76, v72
	v_cvt_pk_bf16_f32 v1, v1, s0
	ds_write_b16 v132, v1 offset:6944
	v_fma_f32 v1, -v72, v76, 1.0
	v_fmac_f32_e32 v76, v1, v76
	v_div_scale_f32 v1, vcc, v73, v2, v73
	v_mul_f32_e32 v68, v1, v76
	v_fma_f32 v77, -v72, v68, v1
	v_fmac_f32_e32 v68, v77, v76
	v_fma_f32 v1, -v72, v68, v1
	v_mul_f32_e32 v72, 0xbfb8aa3b, v74
	v_exp_f32_e32 v72, v72
	v_div_fmas_f32 v1, v1, v76, v68
	v_div_fixup_f32 v1, v1, v2, v73
	v_mul_f32_e32 v1, v69, v1
	v_add_f32_e32 v2, 1.0, v72
	v_div_scale_f32 v68, s[10:11], v2, v2, v74
	v_rcp_f32_e32 v72, v68
	v_cvt_pk_bf16_f32 v1, v1, s0
	ds_write_b16 v132, v1 offset:7088
	v_fma_f32 v1, -v68, v72, 1.0
	v_fmac_f32_e32 v72, v1, v72
	v_div_scale_f32 v1, vcc, v74, v2, v74
	v_mul_f32_e32 v69, v1, v72
	v_fma_f32 v73, -v68, v69, v1
	v_fmac_f32_e32 v69, v73, v72
	v_fma_f32 v1, -v68, v69, v1
	v_mul_f32_e32 v68, 0xbfb8aa3b, v75
	v_exp_f32_e32 v68, v68
	v_div_fmas_f32 v1, v1, v72, v69
	v_div_fixup_f32 v1, v1, v2, v74
	v_mul_f32_e32 v1, v70, v1
	v_add_f32_e32 v2, 1.0, v68
	v_div_scale_f32 v68, s[10:11], v2, v2, v75
	v_rcp_f32_e32 v69, v68
	v_cvt_pk_bf16_f32 v1, v1, s0
	ds_write_b16 v132, v1 offset:7232
	v_fma_f32 v1, -v68, v69, 1.0
	v_fmac_f32_e32 v69, v1, v69
	v_div_scale_f32 v1, vcc, v75, v2, v75
	v_mul_f32_e32 v70, v1, v69
	v_fma_f32 v72, -v68, v70, v1
	v_fmac_f32_e32 v70, v72, v69
	v_fma_f32 v1, -v68, v70, v1
	v_mul_f32_e32 v68, 0xbfb8aa3b, v64
	v_exp_f32_e32 v68, v68
	v_div_fmas_f32 v1, v1, v69, v70
	v_div_fixup_f32 v1, v1, v2, v75
	v_mul_f32_e32 v1, v71, v1
	v_add_f32_e32 v2, 1.0, v68
	v_div_scale_f32 v68, s[10:11], v2, v2, v64
	v_rcp_f32_e32 v69, v68
	v_cvt_pk_bf16_f32 v1, v1, s0
	ds_write_b16 v132, v1 offset:7376
	v_fma_f32 v1, -v68, v69, 1.0
	v_fmac_f32_e32 v69, v1, v69
	v_div_scale_f32 v1, vcc, v64, v2, v64
	v_mul_f32_e32 v70, v1, v69
	v_fma_f32 v71, -v68, v70, v1
	v_fmac_f32_e32 v70, v71, v69
	v_fma_f32 v1, -v68, v70, v1
	v_mul_f32_e32 v68, 0xbfb8aa3b, v65
	v_exp_f32_e32 v68, v68
	v_div_fmas_f32 v1, v1, v69, v70
	v_div_fixup_f32 v1, v1, v2, v64
	v_mul_f32_e32 v1, v60, v1
	v_add_f32_e32 v2, 1.0, v68
	v_div_scale_f32 v64, s[10:11], v2, v2, v65
	v_rcp_f32_e32 v68, v64
	v_cvt_pk_bf16_f32 v1, v1, s0
	ds_write_b16 v132, v1 offset:9216
	v_fma_f32 v1, -v64, v68, 1.0
	v_fmac_f32_e32 v68, v1, v68
	v_div_scale_f32 v1, vcc, v65, v2, v65
	v_mul_f32_e32 v60, v1, v68
	v_fma_f32 v69, -v64, v60, v1
	v_fmac_f32_e32 v60, v69, v68
	v_fma_f32 v1, -v64, v60, v1
	v_mul_f32_e32 v64, 0xbfb8aa3b, v66
	v_exp_f32_e32 v64, v64
	v_div_fmas_f32 v1, v1, v68, v60
	v_div_fixup_f32 v1, v1, v2, v65
	v_mul_f32_e32 v1, v61, v1
	v_add_f32_e32 v2, 1.0, v64
	v_div_scale_f32 v60, s[10:11], v2, v2, v66
	v_rcp_f32_e32 v64, v60
	v_cvt_pk_bf16_f32 v1, v1, s0
	ds_write_b16 v132, v1 offset:9360
; DEVI float silu_(float x) { return x / (1.f + __expf(-x)); }
; DEVI void ffn1_tile256(const P& p, const bf* W, long row0, int n0  , char* smem) {
;     ...
; #pragma unroll
;   for (int m = 0; m < 8; ++m)
; #pragma unroll
;     for (int pr = 0; pr < 2; ++pr) {
;       const int cl = (wc * 2 + pr) * 16 + l15;
; #pragma unroll
;       for (int j = 0; j < 4; ++j) {
;         const int rl = wr * 128 + m * 16 + quad * 4 + j;
;         float a = acc[m][2 * pr][j], b = acc[m][2 * pr + 1][j];
;         tl[rl * 72 + cl] = f2bf(silu_(a) * b);
;       }
;     }
	v_fma_f32 v1, -v60, v64, 1.0
	v_fmac_f32_e32 v64, v1, v64
	v_div_scale_f32 v1, vcc, v66, v2, v66
	v_mul_f32_e32 v61, v1, v64
	v_fma_f32 v65, -v60, v61, v1
	v_fmac_f32_e32 v61, v65, v64
	v_fma_f32 v1, -v60, v61, v1
	v_mul_f32_e32 v60, 0xbfb8aa3b, v67
	v_exp_f32_e32 v60, v60
	v_div_fmas_f32 v1, v1, v64, v61
	v_div_fixup_f32 v1, v1, v2, v66
	v_mul_f32_e32 v1, v62, v1
	v_add_f32_e32 v2, 1.0, v60
	v_div_scale_f32 v60, s[10:11], v2, v2, v67
	v_rcp_f32_e32 v61, v60
	v_cvt_pk_bf16_f32 v1, v1, s0
	ds_write_b16 v132, v1 offset:9504
	v_fma_f32 v1, -v60, v61, 1.0
	v_fmac_f32_e32 v61, v1, v61
	v_div_scale_f32 v1, vcc, v67, v2, v67
	v_mul_f32_e32 v62, v1, v61
	v_fma_f32 v64, -v60, v62, v1
	v_fmac_f32_e32 v62, v64, v61
	v_fma_f32 v1, -v60, v62, v1
	v_mul_f32_e32 v60, 0xbfb8aa3b, v56
	v_exp_f32_e32 v60, v60
	v_div_fmas_f32 v1, v1, v61, v62
	v_div_fixup_f32 v1, v1, v2, v67
	v_mul_f32_e32 v1, v63, v1
	v_add_f32_e32 v2, 1.0, v60
	v_div_scale_f32 v60, s[10:11], v2, v2, v56
	v_rcp_f32_e32 v61, v60
	v_cvt_pk_bf16_f32 v1, v1, s0
	ds_write_b16 v132, v1 offset:9648
	v_fma_f32 v1, -v60, v61, 1.0
	v_fmac_f32_e32 v61, v1, v61
	v_div_scale_f32 v1, vcc, v56, v2, v56
	v_mul_f32_e32 v62, v1, v61
	v_fma_f32 v63, -v60, v62, v1
	v_fmac_f32_e32 v62, v63, v61
	v_fma_f32 v1, -v60, v62, v1
	v_mul_f32_e32 v60, 0xbfb8aa3b, v57
	v_exp_f32_e32 v60, v60
	v_div_fmas_f32 v1, v1, v61, v62
	v_div_fixup_f32 v1, v1, v2, v56
	v_mul_f32_e32 v1, v52, v1
	v_add_f32_e32 v2, 1.0, v60
	v_div_scale_f32 v56, s[10:11], v2, v2, v57
	v_rcp_f32_e32 v60, v56
	v_cvt_pk_bf16_f32 v1, v1, s0
	ds_write_b16 v132, v1 offset:9248
	v_fma_f32 v1, -v56, v60, 1.0
	v_fmac_f32_e32 v60, v1, v60
	v_div_scale_f32 v1, vcc, v57, v2, v57
	v_mul_f32_e32 v52, v1, v60
	v_fma_f32 v61, -v56, v52, v1
	v_fmac_f32_e32 v52, v61, v60
	v_fma_f32 v1, -v56, v52, v1
	v_mul_f32_e32 v56, 0xbfb8aa3b, v58
	v_exp_f32_e32 v56, v56
	v_div_fmas_f32 v1, v1, v60, v52
	v_div_fixup_f32 v1, v1, v2, v57
	v_mul_f32_e32 v1, v53, v1
	v_add_f32_e32 v2, 1.0, v56
	v_div_scale_f32 v52, s[10:11], v2, v2, v58
	v_rcp_f32_e32 v56, v52
	v_cvt_pk_bf16_f32 v1, v1, s0
	ds_write_b16 v132, v1 offset:9392
	v_fma_f32 v1, -v52, v56, 1.0
	v_fmac_f32_e32 v56, v1, v56
	v_div_scale_f32 v1, vcc, v58, v2, v58
	v_mul_f32_e32 v53, v1, v56
	v_fma_f32 v57, -v52, v53, v1
	v_fmac_f32_e32 v53, v57, v56
	v_fma_f32 v1, -v52, v53, v1
	v_mul_f32_e32 v52, 0xbfb8aa3b, v59
	v_exp_f32_e32 v52, v52
	v_div_fmas_f32 v1, v1, v56, v53
	v_div_fixup_f32 v1, v1, v2, v58
	v_mul_f32_e32 v1, v54, v1
	v_add_f32_e32 v2, 1.0, v52
	v_div_scale_f32 v52, s[10:11], v2, v2, v59
	v_rcp_f32_e32 v53, v52
	v_cvt_pk_bf16_f32 v1, v1, s0
	ds_write_b16 v132, v1 offset:9536
	v_fma_f32 v1, -v52, v53, 1.0
	v_fmac_f32_e32 v53, v1, v53
	v_div_scale_f32 v1, vcc, v59, v2, v59
	v_mul_f32_e32 v54, v1, v53
	v_fma_f32 v56, -v52, v54, v1
	v_fmac_f32_e32 v54, v56, v53
	v_fma_f32 v1, -v52, v54, v1
	v_mul_f32_e32 v52, 0xbfb8aa3b, v48
	v_exp_f32_e32 v52, v52
	v_div_fmas_f32 v1, v1, v53, v54
	v_div_fixup_f32 v1, v1, v2, v59
	v_mul_f32_e32 v1, v55, v1
	v_add_f32_e32 v2, 1.0, v52
	v_div_scale_f32 v52, s[10:11], v2, v2, v48
	v_rcp_f32_e32 v53, v52
	v_cvt_pk_bf16_f32 v1, v1, s0
	ds_write_b16 v132, v1 offset:9680
	v_fma_f32 v1, -v52, v53, 1.0
	v_fmac_f32_e32 v53, v1, v53
	v_div_scale_f32 v1, vcc, v48, v2, v48
	v_mul_f32_e32 v54, v1, v53
	v_fma_f32 v55, -v52, v54, v1
	v_fmac_f32_e32 v54, v55, v53
	v_fma_f32 v1, -v52, v54, v1
	v_mul_f32_e32 v52, 0xbfb8aa3b, v49
	v_exp_f32_e32 v52, v52
	v_div_fmas_f32 v1, v1, v53, v54
	v_div_fixup_f32 v1, v1, v2, v48
	v_mul_f32_e32 v1, v44, v1
	v_add_f32_e32 v2, 1.0, v52
	v_div_scale_f32 v48, s[10:11], v2, v2, v49
	v_rcp_f32_e32 v52, v48
	v_cvt_pk_bf16_f32 v1, v1, s0
	ds_write_b16 v132, v1 offset:11520
	v_fma_f32 v1, -v48, v52, 1.0
	v_fmac_f32_e32 v52, v1, v52
	v_div_scale_f32 v1, vcc, v49, v2, v49
	v_mul_f32_e32 v44, v1, v52
	v_fma_f32 v53, -v48, v44, v1
	v_fmac_f32_e32 v44, v53, v52
	v_fma_f32 v1, -v48, v44, v1
	v_mul_f32_e32 v48, 0xbfb8aa3b, v50
	v_exp_f32_e32 v48, v48
	v_div_fmas_f32 v1, v1, v52, v44
	v_div_fixup_f32 v1, v1, v2, v49
	v_mul_f32_e32 v1, v45, v1
	v_add_f32_e32 v2, 1.0, v48
	v_div_scale_f32 v44, s[10:11], v2, v2, v50
	v_rcp_f32_e32 v48, v44
	v_cvt_pk_bf16_f32 v1, v1, s0
	ds_write_b16 v132, v1 offset:11664
	v_fma_f32 v1, -v44, v48, 1.0
	v_fmac_f32_e32 v48, v1, v48
	v_div_scale_f32 v1, vcc, v50, v2, v50
	v_mul_f32_e32 v45, v1, v48
	v_fma_f32 v49, -v44, v45, v1
	v_fmac_f32_e32 v45, v49, v48
	v_fma_f32 v1, -v44, v45, v1
	v_mul_f32_e32 v44, 0xbfb8aa3b, v51
	v_exp_f32_e32 v44, v44
	v_div_fmas_f32 v1, v1, v48, v45
	v_div_fixup_f32 v1, v1, v2, v50
	v_mul_f32_e32 v1, v46, v1
	v_add_f32_e32 v2, 1.0, v44
	v_div_scale_f32 v44, s[10:11], v2, v2, v51
	v_rcp_f32_e32 v45, v44
	v_cvt_pk_bf16_f32 v1, v1, s0
	ds_write_b16 v132, v1 offset:11808
	v_fma_f32 v1, -v44, v45, 1.0
	v_fmac_f32_e32 v45, v1, v45
	v_div_scale_f32 v1, vcc, v51, v2, v51
	v_mul_f32_e32 v46, v1, v45
	v_fma_f32 v48, -v44, v46, v1
	v_fmac_f32_e32 v46, v48, v45
	v_fma_f32 v1, -v44, v46, v1
	v_mul_f32_e32 v44, 0xbfb8aa3b, v40
	v_exp_f32_e32 v44, v44
	v_div_fmas_f32 v1, v1, v45, v46
	v_div_fixup_f32 v1, v1, v2, v51
	v_mul_f32_e32 v1, v47, v1
	v_add_f32_e32 v2, 1.0, v44
	v_div_scale_f32 v44, s[10:11], v2, v2, v40
	v_rcp_f32_e32 v45, v44
	v_cvt_pk_bf16_f32 v1, v1, s0
	ds_write_b16 v132, v1 offset:11952
	v_fma_f32 v1, -v44, v45, 1.0
	v_fmac_f32_e32 v45, v1, v45
	v_div_scale_f32 v1, vcc, v40, v2, v40
	v_mul_f32_e32 v46, v1, v45
	v_fma_f32 v47, -v44, v46, v1
	v_fmac_f32_e32 v46, v47, v45
	v_fma_f32 v1, -v44, v46, v1
	v_mul_f32_e32 v44, 0xbfb8aa3b, v41
	v_exp_f32_e32 v44, v44
	v_div_fmas_f32 v1, v1, v45, v46
	v_div_fixup_f32 v1, v1, v2, v40
; DEVI float silu_(float x) { return x / (1.f + __expf(-x)); }
; DEVI void ffn1_tile256(const P& p, const bf* W, long row0, int n0  , char* smem) {
;     ...
; #pragma unroll
;   for (int m = 0; m < 8; ++m)
; #pragma unroll
;     for (int pr = 0; pr < 2; ++pr) {
;       const int cl = (wc * 2 + pr) * 16 + l15;
; #pragma unroll
;       for (int j = 0; j < 4; ++j) {
;         const int rl = wr * 128 + m * 16 + quad * 4 + j;
;         float a = acc[m][2 * pr][j], b = acc[m][2 * pr + 1][j];
;         tl[rl * 72 + cl] = f2bf(silu_(a) * b);
;       }
;     }
	v_mul_f32_e32 v1, v36, v1
	v_add_f32_e32 v2, 1.0, v44
	v_div_scale_f32 v40, s[10:11], v2, v2, v41
	v_rcp_f32_e32 v44, v40
	v_cvt_pk_bf16_f32 v1, v1, s0
	ds_write_b16 v132, v1 offset:11552
	v_fma_f32 v1, -v40, v44, 1.0
	v_fmac_f32_e32 v44, v1, v44
	v_div_scale_f32 v1, vcc, v41, v2, v41
	v_mul_f32_e32 v36, v1, v44
	v_fma_f32 v45, -v40, v36, v1
	v_fmac_f32_e32 v36, v45, v44
	v_fma_f32 v1, -v40, v36, v1
	v_mul_f32_e32 v40, 0xbfb8aa3b, v42
	v_exp_f32_e32 v40, v40
	v_div_fmas_f32 v1, v1, v44, v36
	v_div_fixup_f32 v1, v1, v2, v41
	v_mul_f32_e32 v1, v37, v1
	v_add_f32_e32 v2, 1.0, v40
	v_div_scale_f32 v36, s[10:11], v2, v2, v42
	v_rcp_f32_e32 v40, v36
	v_cvt_pk_bf16_f32 v1, v1, s0
	ds_write_b16 v132, v1 offset:11696
	v_fma_f32 v1, -v36, v40, 1.0
	v_fmac_f32_e32 v40, v1, v40
	v_div_scale_f32 v1, vcc, v42, v2, v42
	v_mul_f32_e32 v37, v1, v40
	v_fma_f32 v41, -v36, v37, v1
	v_fmac_f32_e32 v37, v41, v40
	v_fma_f32 v1, -v36, v37, v1
	v_mul_f32_e32 v36, 0xbfb8aa3b, v43
	v_exp_f32_e32 v36, v36
	v_div_fmas_f32 v1, v1, v40, v37
	v_div_fixup_f32 v1, v1, v2, v42
	v_mul_f32_e32 v1, v38, v1
	v_add_f32_e32 v2, 1.0, v36
	v_div_scale_f32 v36, s[10:11], v2, v2, v43
	v_rcp_f32_e32 v37, v36
	v_cvt_pk_bf16_f32 v1, v1, s0
	ds_write_b16 v132, v1 offset:11840
	v_fma_f32 v1, -v36, v37, 1.0
	v_fmac_f32_e32 v37, v1, v37
	v_div_scale_f32 v1, vcc, v43, v2, v43
	v_mul_f32_e32 v38, v1, v37
	v_fma_f32 v40, -v36, v38, v1
	v_fmac_f32_e32 v38, v40, v37
	v_fma_f32 v1, -v36, v38, v1
	v_mul_f32_e32 v36, 0xbfb8aa3b, v32
	v_exp_f32_e32 v36, v36
	v_div_fmas_f32 v1, v1, v37, v38
	v_div_fixup_f32 v1, v1, v2, v43
	v_mul_f32_e32 v1, v39, v1
	v_add_f32_e32 v2, 1.0, v36
	v_div_scale_f32 v36, s[10:11], v2, v2, v32
	v_rcp_f32_e32 v37, v36
	v_cvt_pk_bf16_f32 v1, v1, s0
	ds_write_b16 v132, v1 offset:11984
	v_fma_f32 v1, -v36, v37, 1.0
	v_fmac_f32_e32 v37, v1, v37
	v_div_scale_f32 v1, vcc, v32, v2, v32
	v_mul_f32_e32 v38, v1, v37
	v_fma_f32 v39, -v36, v38, v1
	v_fmac_f32_e32 v38, v39, v37
	v_fma_f32 v1, -v36, v38, v1
	v_mul_f32_e32 v36, 0xbfb8aa3b, v33
	v_exp_f32_e32 v36, v36
	v_div_fmas_f32 v1, v1, v37, v38
	v_div_fixup_f32 v1, v1, v2, v32
	v_mul_f32_e32 v1, v28, v1
	v_add_f32_e32 v2, 1.0, v36
	v_div_scale_f32 v32, s[10:11], v2, v2, v33
	v_rcp_f32_e32 v36, v32
	v_cvt_pk_bf16_f32 v1, v1, s0
	ds_write_b16 v132, v1 offset:13824
	v_fma_f32 v1, -v32, v36, 1.0
	v_fmac_f32_e32 v36, v1, v36
	v_div_scale_f32 v1, vcc, v33, v2, v33
	v_mul_f32_e32 v28, v1, v36
	v_fma_f32 v37, -v32, v28, v1
	v_fmac_f32_e32 v28, v37, v36
	v_fma_f32 v1, -v32, v28, v1
	v_mul_f32_e32 v32, 0xbfb8aa3b, v34
	v_exp_f32_e32 v32, v32
	v_div_fmas_f32 v1, v1, v36, v28
	v_div_fixup_f32 v1, v1, v2, v33
	v_mul_f32_e32 v1, v29, v1
	v_add_f32_e32 v2, 1.0, v32
	v_div_scale_f32 v28, s[10:11], v2, v2, v34
	v_rcp_f32_e32 v32, v28
	v_cvt_pk_bf16_f32 v1, v1, s0
	ds_write_b16 v132, v1 offset:13968
	v_fma_f32 v1, -v28, v32, 1.0
	v_fmac_f32_e32 v32, v1, v32
	v_div_scale_f32 v1, vcc, v34, v2, v34
	v_mul_f32_e32 v29, v1, v32
	v_fma_f32 v33, -v28, v29, v1
	v_fmac_f32_e32 v29, v33, v32
	v_fma_f32 v1, -v28, v29, v1
	v_mul_f32_e32 v28, 0xbfb8aa3b, v35
	v_exp_f32_e32 v28, v28
	v_div_fmas_f32 v1, v1, v32, v29
	v_div_fixup_f32 v1, v1, v2, v34
	v_mul_f32_e32 v1, v30, v1
	v_add_f32_e32 v2, 1.0, v28
	v_div_scale_f32 v28, s[10:11], v2, v2, v35
	v_rcp_f32_e32 v29, v28
	v_cvt_pk_bf16_f32 v1, v1, s0
	ds_write_b16 v132, v1 offset:14112
	v_fma_f32 v1, -v28, v29, 1.0
	v_fmac_f32_e32 v29, v1, v29
	v_div_scale_f32 v1, vcc, v35, v2, v35
	v_mul_f32_e32 v30, v1, v29
	v_fma_f32 v32, -v28, v30, v1
	v_fmac_f32_e32 v30, v32, v29
	v_fma_f32 v1, -v28, v30, v1
	v_mul_f32_e32 v28, 0xbfb8aa3b, v24
	v_exp_f32_e32 v28, v28
	v_div_fmas_f32 v1, v1, v29, v30
	v_div_fixup_f32 v1, v1, v2, v35
	v_mul_f32_e32 v1, v31, v1
	v_add_f32_e32 v2, 1.0, v28
	v_div_scale_f32 v28, s[10:11], v2, v2, v24
	v_rcp_f32_e32 v29, v28
	v_cvt_pk_bf16_f32 v1, v1, s0
	ds_write_b16 v132, v1 offset:14256
	v_fma_f32 v1, -v28, v29, 1.0
	v_fmac_f32_e32 v29, v1, v29
	v_div_scale_f32 v1, vcc, v24, v2, v24
	v_mul_f32_e32 v30, v1, v29
	v_fma_f32 v31, -v28, v30, v1
	v_fmac_f32_e32 v30, v31, v29
	v_fma_f32 v1, -v28, v30, v1
	v_mul_f32_e32 v28, 0xbfb8aa3b, v25
	v_exp_f32_e32 v28, v28
	v_div_fmas_f32 v1, v1, v29, v30
	v_div_fixup_f32 v1, v1, v2, v24
	v_mul_f32_e32 v1, v20, v1
	v_add_f32_e32 v2, 1.0, v28
	v_div_scale_f32 v24, s[10:11], v2, v2, v25
	v_rcp_f32_e32 v28, v24
	v_cvt_pk_bf16_f32 v1, v1, s0
	ds_write_b16 v132, v1 offset:13856
	v_fma_f32 v1, -v24, v28, 1.0
	v_fmac_f32_e32 v28, v1, v28
	v_div_scale_f32 v1, vcc, v25, v2, v25
	v_mul_f32_e32 v20, v1, v28
	v_fma_f32 v29, -v24, v20, v1
	v_fmac_f32_e32 v20, v29, v28
	v_fma_f32 v1, -v24, v20, v1
	v_mul_f32_e32 v24, 0xbfb8aa3b, v26
	v_exp_f32_e32 v24, v24
	v_div_fmas_f32 v1, v1, v28, v20
	v_div_fixup_f32 v1, v1, v2, v25
	v_mul_f32_e32 v1, v21, v1
	v_add_f32_e32 v2, 1.0, v24
	v_div_scale_f32 v20, s[10:11], v2, v2, v26
	v_rcp_f32_e32 v24, v20
	v_cvt_pk_bf16_f32 v1, v1, s0
	ds_write_b16 v132, v1 offset:14000
	v_fma_f32 v1, -v20, v24, 1.0
	v_fmac_f32_e32 v24, v1, v24
	v_div_scale_f32 v1, vcc, v26, v2, v26
	v_mul_f32_e32 v21, v1, v24
	v_fma_f32 v25, -v20, v21, v1
	v_fmac_f32_e32 v21, v25, v24
	v_fma_f32 v1, -v20, v21, v1
	v_mul_f32_e32 v20, 0xbfb8aa3b, v27
	v_exp_f32_e32 v20, v20
	v_div_fmas_f32 v1, v1, v24, v21
	v_div_fixup_f32 v1, v1, v2, v26
	v_mul_f32_e32 v1, v22, v1
	v_add_f32_e32 v2, 1.0, v20
	v_div_scale_f32 v20, s[10:11], v2, v2, v27
	v_rcp_f32_e32 v21, v20
	v_cvt_pk_bf16_f32 v1, v1, s0
	ds_write_b16 v132, v1 offset:14144
	v_fma_f32 v1, -v20, v21, 1.0
	v_fmac_f32_e32 v21, v1, v21
	v_div_scale_f32 v1, vcc, v27, v2, v27
	v_mul_f32_e32 v22, v1, v21
	v_fma_f32 v24, -v20, v22, v1
; DEVI float silu_(float x) { return x / (1.f + __expf(-x)); }
; DEVI void ffn1_tile256(const P& p, const bf* W, long row0, int n0  , char* smem) {
;     ...
; #pragma unroll
;   for (int m = 0; m < 8; ++m)
; #pragma unroll
;     for (int pr = 0; pr < 2; ++pr) {
;       const int cl = (wc * 2 + pr) * 16 + l15;
; #pragma unroll
;       for (int j = 0; j < 4; ++j) {
;         const int rl = wr * 128 + m * 16 + quad * 4 + j;
;         float a = acc[m][2 * pr][j], b = acc[m][2 * pr + 1][j];
;         tl[rl * 72 + cl] = f2bf(silu_(a) * b);
;       }
;     }
;   __syncthreads();
	v_fmac_f32_e32 v22, v24, v21
	v_fma_f32 v1, -v20, v22, v1
	v_mul_f32_e32 v20, 0xbfb8aa3b, v16
	v_exp_f32_e32 v20, v20
	v_div_fmas_f32 v1, v1, v21, v22
	v_div_fixup_f32 v1, v1, v2, v27
	v_mul_f32_e32 v1, v23, v1
	v_add_f32_e32 v2, 1.0, v20
	v_div_scale_f32 v20, s[10:11], v2, v2, v16
	v_rcp_f32_e32 v21, v20
	v_cvt_pk_bf16_f32 v1, v1, s0
	ds_write_b16 v132, v1 offset:14288
	v_fma_f32 v1, -v20, v21, 1.0
	v_fmac_f32_e32 v21, v1, v21
	v_div_scale_f32 v1, vcc, v16, v2, v16
	v_mul_f32_e32 v22, v1, v21
	v_fma_f32 v23, -v20, v22, v1
	v_fmac_f32_e32 v22, v23, v21
	v_fma_f32 v1, -v20, v22, v1
	v_mul_f32_e32 v20, 0xbfb8aa3b, v17
	v_exp_f32_e32 v20, v20
	v_div_fmas_f32 v1, v1, v21, v22
	v_div_fixup_f32 v1, v1, v2, v16
	v_mul_f32_e32 v1, v12, v1
	v_add_f32_e32 v2, 1.0, v20
	v_div_scale_f32 v16, s[10:11], v2, v2, v17
	v_rcp_f32_e32 v20, v16
	v_cvt_pk_bf16_f32 v1, v1, s0
	ds_write_b16 v132, v1 offset:16128
	v_fma_f32 v1, -v16, v20, 1.0
	v_fmac_f32_e32 v20, v1, v20
	v_div_scale_f32 v1, vcc, v17, v2, v17
	v_mul_f32_e32 v12, v1, v20
	v_fma_f32 v21, -v16, v12, v1
	v_fmac_f32_e32 v12, v21, v20
	v_fma_f32 v1, -v16, v12, v1
	v_mul_f32_e32 v16, 0xbfb8aa3b, v18
	v_exp_f32_e32 v16, v16
	v_div_fmas_f32 v1, v1, v20, v12
	v_div_fixup_f32 v1, v1, v2, v17
	v_mul_f32_e32 v1, v13, v1
	v_add_f32_e32 v2, 1.0, v16
	v_div_scale_f32 v12, s[10:11], v2, v2, v18
	v_rcp_f32_e32 v16, v12
	v_cvt_pk_bf16_f32 v1, v1, s0
	ds_write_b16 v132, v1 offset:16272
	v_fma_f32 v1, -v12, v16, 1.0
	v_fmac_f32_e32 v16, v1, v16
	v_div_scale_f32 v1, vcc, v18, v2, v18
	v_mul_f32_e32 v13, v1, v16
	v_fma_f32 v17, -v12, v13, v1
	v_fmac_f32_e32 v13, v17, v16
	v_fma_f32 v1, -v12, v13, v1
	v_mul_f32_e32 v12, 0xbfb8aa3b, v19
	v_exp_f32_e32 v12, v12
	v_div_fmas_f32 v1, v1, v16, v13
	v_div_fixup_f32 v1, v1, v2, v18
	v_mul_f32_e32 v1, v14, v1
	v_add_f32_e32 v2, 1.0, v12
	v_div_scale_f32 v12, s[10:11], v2, v2, v19
	v_rcp_f32_e32 v13, v12
	v_cvt_pk_bf16_f32 v1, v1, s0
	ds_write_b16 v132, v1 offset:16416
	v_fma_f32 v1, -v12, v13, 1.0
	v_fmac_f32_e32 v13, v1, v13
	v_div_scale_f32 v1, vcc, v19, v2, v19
	v_mul_f32_e32 v14, v1, v13
	v_fma_f32 v16, -v12, v14, v1
	v_fmac_f32_e32 v14, v16, v13
	v_fma_f32 v1, -v12, v14, v1
	v_mul_f32_e32 v12, 0xbfb8aa3b, v8
	v_exp_f32_e32 v12, v12
	v_div_fmas_f32 v1, v1, v13, v14
	v_div_fixup_f32 v1, v1, v2, v19
	v_mul_f32_e32 v1, v15, v1
	v_add_f32_e32 v2, 1.0, v12
	v_div_scale_f32 v12, s[10:11], v2, v2, v8
	v_rcp_f32_e32 v13, v12
	v_cvt_pk_bf16_f32 v1, v1, s0
	ds_write_b16 v132, v1 offset:16560
	v_fma_f32 v1, -v12, v13, 1.0
	v_fmac_f32_e32 v13, v1, v13
	v_div_scale_f32 v1, vcc, v8, v2, v8
	v_mul_f32_e32 v14, v1, v13
	v_fma_f32 v15, -v12, v14, v1
	v_fmac_f32_e32 v14, v15, v13
	v_fma_f32 v1, -v12, v14, v1
	v_mul_f32_e32 v12, 0xbfb8aa3b, v9
	v_exp_f32_e32 v12, v12
	v_div_fmas_f32 v1, v1, v13, v14
	v_div_fixup_f32 v1, v1, v2, v8
	v_mul_f32_e32 v1, v4, v1
	v_add_f32_e32 v2, 1.0, v12
	v_div_scale_f32 v8, s[10:11], v2, v2, v9
	v_rcp_f32_e32 v12, v8
	v_cvt_pk_bf16_f32 v1, v1, s0
	ds_write_b16 v132, v1 offset:16160
	v_fma_f32 v1, -v8, v12, 1.0
	v_fmac_f32_e32 v12, v1, v12
	v_div_scale_f32 v1, vcc, v9, v2, v9
	v_mul_f32_e32 v4, v1, v12
	v_fma_f32 v13, -v8, v4, v1
	v_fmac_f32_e32 v4, v13, v12
	v_fma_f32 v1, -v8, v4, v1
	v_mul_f32_e32 v8, 0xbfb8aa3b, v10
	v_exp_f32_e32 v8, v8
	v_div_fmas_f32 v1, v1, v12, v4
	v_div_fixup_f32 v1, v1, v2, v9
	v_mul_f32_e32 v1, v5, v1
	v_add_f32_e32 v2, 1.0, v8
	v_div_scale_f32 v4, s[10:11], v2, v2, v10
	v_rcp_f32_e32 v8, v4
	v_cvt_pk_bf16_f32 v1, v1, s0
	ds_write_b16 v132, v1 offset:16304
	v_fma_f32 v1, -v4, v8, 1.0
	v_fmac_f32_e32 v8, v1, v8
	v_div_scale_f32 v1, vcc, v10, v2, v10
	v_mul_f32_e32 v5, v1, v8
	v_fma_f32 v9, -v4, v5, v1
	v_fmac_f32_e32 v5, v9, v8
	v_fma_f32 v1, -v4, v5, v1
	v_mul_f32_e32 v4, 0xbfb8aa3b, v11
	v_exp_f32_e32 v4, v4
	v_div_fmas_f32 v1, v1, v8, v5
	v_div_fixup_f32 v1, v1, v2, v10
	v_mul_f32_e32 v1, v6, v1
	v_add_f32_e32 v2, 1.0, v4
	v_div_scale_f32 v4, s[10:11], v2, v2, v11
	v_rcp_f32_e32 v5, v4
	v_cvt_pk_bf16_f32 v1, v1, s0
	ds_write_b16 v132, v1 offset:16448
	s_ashr_i32 s10, s38, 1
	v_fma_f32 v1, -v4, v5, 1.0
	v_fmac_f32_e32 v5, v1, v5
	v_div_scale_f32 v1, vcc, v11, v2, v11
	v_mul_f32_e32 v6, v1, v5
	v_fma_f32 v8, -v4, v6, v1
	v_fmac_f32_e32 v6, v8, v5
	v_fma_f32 v1, -v4, v6, v1
	v_div_fmas_f32 v1, v1, v5, v6
	v_div_fixup_f32 v1, v1, v2, v11
	v_mul_f32_e32 v1, v7, v1
	v_cvt_pk_bf16_f32 v1, v1, s0
	ds_write_b16 v132, v1 offset:16592
	v_mov_b32_e32 v1, v178
	s_waitcnt lgkmcnt(0)
	s_barrier
; DEVI int get_tid() { int t = threadIdx.x; asm volatile("" : "+v"(t)); return t; }
; template <int BN>
; DEVI void tile_store256(const char* smem, bf* __restrict__ C, long ldc, long row0, int col0) {
;   constexpr int LDT = BN + 8;
;   constexpr int CPR = BN / 8;
;   const int tid = get_tid();
; #pragma unroll
;   for (int i = 0; i < CPR; ++i) {
;     const int q = tid + 256 * i;
;     const int r = q / CPR, c = q - r * CPR;
;     u32x4 v = *reinterpret_cast<const u32x4*>(smem + (r * LDT + c * 8) * 2);
;     *reinterpret_cast<u32x4*>(C + (row0 + r) * ldc + col0 + c * 8) = v;
;   }
; }
; DEVI void phase_ffn1(const P& p, int f, char* smem) {
;     ...
;   for (int v = blockIdx.x; v < 128 * 44; v += gridDim.x) {
;     int m2, nt;
;     lat_tile_map256(v, 44, m2, nt);
;     ffn1_tile256(p, W, lat_row0_256(m2), nt * 128, smem);
;   }
	s_ashr_i32 s11, s10, 31
	v_ashrrev_i32_e32 v2, 31, v1
	v_lshrrev_b32_e32 v2, 29, v2
	s_lshl_b64 s[10:11], s[10:11], 1
	v_add_u32_e32 v2, v1, v2
	s_add_u32 s10, s58, s10
	v_ashrrev_i32_e32 v8, 3, v2
	s_addc_u32 s11, s59, s11
	v_lshlrev_b32_e32 v4, 6, v8
	v_lshlrev_b32_e32 v5, 3, v1
	v_ashrrev_i32_e32 v9, 31, v8
	v_mul_lo_u32 v2, v8, s25
	v_sub_u32_e32 v10, v5, v4
	v_lshl_add_u64 v[8:9], s[34:35], 0, v[8:9]
	v_mov_b64_e32 v[12:13], s[10:11]
	v_add_lshl_u32 v2, v10, v2, 1
	v_mad_u64_u32 v[14:15], s[10:11], v8, s73, v[12:13]
	ds_read_b128 v[4:7], v2
	v_mov_b32_e32 v2, v15
	v_mad_u64_u32 v[8:9], s[10:11], v9, s73, v[2:3]
	v_add_u32_e32 v2, 0x100, v1
	v_mov_b32_e32 v15, v8
	v_ashrrev_i32_e32 v8, 31, v2
	v_lshrrev_b32_e32 v8, 29, v8
	v_add_u32_e32 v8, v2, v8
	v_ashrrev_i32_e32 v16, 3, v8
	v_ashrrev_i32_e32 v11, 31, v10
	v_lshlrev_b32_e32 v9, 6, v16
	v_lshlrev_b32_e32 v2, 3, v2
	v_lshl_add_u64 v[14:15], v[10:11], 1, v[14:15]
	v_mul_lo_u32 v8, v16, s25
	v_sub_u32_e32 v18, v2, v9
	v_ashrrev_i32_e32 v17, 31, v16
	v_add_lshl_u32 v2, v18, v8, 1
	s_waitcnt lgkmcnt(0)
	global_store_dwordx4 v[14:15], v[4:7], off
	ds_read_b128 v[8:11], v2
	v_ashrrev_i32_e32 v19, 31, v18
	v_lshl_add_u64 v[4:5], s[34:35], 0, v[16:17]
	v_mad_u64_u32 v[6:7], s[10:11], v4, s73, v[12:13]
	v_mov_b32_e32 v2, v7
	v_mad_u64_u32 v[4:5], s[10:11], v5, s73, v[2:3]
	v_mov_b32_e32 v7, v4
	v_lshl_add_u64 v[4:5], v[18:19], 1, v[6:7]
	v_add_u32_e32 v2, 0x200, v1
	s_waitcnt lgkmcnt(0)
	global_store_dwordx4 v[4:5], v[8:11], off
	v_ashrrev_i32_e32 v4, 31, v2
	v_lshrrev_b32_e32 v4, 29, v4
	v_add_u32_e32 v4, v2, v4
	v_ashrrev_i32_e32 v8, 3, v4
	v_lshlrev_b32_e32 v5, 6, v8
	v_lshlrev_b32_e32 v2, 3, v2
	v_ashrrev_i32_e32 v9, 31, v8
	v_mul_lo_u32 v4, v8, s25
	v_sub_u32_e32 v10, v2, v5
	v_lshl_add_u64 v[8:9], s[34:35], 0, v[8:9]
	v_add_lshl_u32 v2, v10, v4, 1
	v_mad_u64_u32 v[14:15], s[10:11], v8, s73, v[12:13]
	ds_read_b128 v[4:7], v2
	v_mov_b32_e32 v2, v15
	v_mad_u64_u32 v[8:9], s[10:11], v9, s73, v[2:3]
	v_add_u32_e32 v2, 0x300, v1
	v_mov_b32_e32 v15, v8
	v_ashrrev_i32_e32 v8, 31, v2
	v_lshrrev_b32_e32 v8, 29, v8
	v_add_u32_e32 v8, v2, v8
	v_ashrrev_i32_e32 v16, 3, v8
	v_ashrrev_i32_e32 v11, 31, v10
	v_lshlrev_b32_e32 v9, 6, v16
	v_lshlrev_b32_e32 v2, 3, v2
	v_lshl_add_u64 v[14:15], v[10:11], 1, v[14:15]
	v_mul_lo_u32 v8, v16, s25
	v_sub_u32_e32 v18, v2, v9
	v_ashrrev_i32_e32 v17, 31, v16
	v_add_lshl_u32 v2, v18, v8, 1
	s_waitcnt lgkmcnt(0)
	global_store_dwordx4 v[14:15], v[4:7], off
	ds_read_b128 v[8:11], v2
	v_ashrrev_i32_e32 v19, 31, v18
	v_lshl_add_u64 v[4:5], s[34:35], 0, v[16:17]
	v_mad_u64_u32 v[6:7], s[10:11], v4, s73, v[12:13]
	v_mov_b32_e32 v2, v7
	v_mad_u64_u32 v[4:5], s[10:11], v5, s73, v[2:3]
	v_mov_b32_e32 v7, v4
	v_lshl_add_u64 v[4:5], v[18:19], 1, v[6:7]
	v_add_u32_e32 v2, 0x400, v1
	s_waitcnt lgkmcnt(0)
	global_store_dwordx4 v[4:5], v[8:11], off
	v_ashrrev_i32_e32 v4, 31, v2
	v_lshrrev_b32_e32 v4, 29, v4
	v_add_u32_e32 v4, v2, v4
	v_ashrrev_i32_e32 v8, 3, v4
	v_lshlrev_b32_e32 v5, 6, v8
	v_lshlrev_b32_e32 v2, 3, v2
	v_ashrrev_i32_e32 v9, 31, v8
	v_mul_lo_u32 v4, v8, s25
	v_sub_u32_e32 v10, v2, v5
	v_lshl_add_u64 v[8:9], s[34:35], 0, v[8:9]
	v_add_lshl_u32 v2, v10, v4, 1
	v_mad_u64_u32 v[14:15], s[10:11], v8, s73, v[12:13]
	ds_read_b128 v[4:7], v2
	v_mov_b32_e32 v2, v15
	v_mad_u64_u32 v[8:9], s[10:11], v9, s73, v[2:3]
	v_add_u32_e32 v2, 0x500, v1
	v_mov_b32_e32 v15, v8
	v_ashrrev_i32_e32 v8, 31, v2
	v_lshrrev_b32_e32 v8, 29, v8
	v_add_u32_e32 v8, v2, v8
	v_ashrrev_i32_e32 v16, 3, v8
	v_ashrrev_i32_e32 v11, 31, v10
	v_lshlrev_b32_e32 v9, 6, v16
	v_lshlrev_b32_e32 v2, 3, v2
	v_lshl_add_u64 v[14:15], v[10:11], 1, v[14:15]
	v_mul_lo_u32 v8, v16, s25
	v_sub_u32_e32 v18, v2, v9
	v_ashrrev_i32_e32 v17, 31, v16
	v_add_lshl_u32 v2, v18, v8, 1
	s_waitcnt lgkmcnt(0)
	global_store_dwordx4 v[14:15], v[4:7], off
	ds_read_b128 v[8:11], v2
	v_ashrrev_i32_e32 v19, 31, v18
	v_lshl_add_u64 v[4:5], s[34:35], 0, v[16:17]
	v_mad_u64_u32 v[6:7], s[10:11], v4, s73, v[12:13]
	v_mov_b32_e32 v2, v7
	v_mad_u64_u32 v[4:5], s[10:11], v5, s73, v[2:3]
	v_mov_b32_e32 v7, v4
	v_lshl_add_u64 v[4:5], v[18:19], 1, v[6:7]
	v_add_u32_e32 v2, 0x600, v1
	s_waitcnt lgkmcnt(0)
	global_store_dwordx4 v[4:5], v[8:11], off
	v_ashrrev_i32_e32 v4, 31, v2
	v_lshrrev_b32_e32 v4, 29, v4
	v_add_u32_e32 v4, v2, v4
	v_ashrrev_i32_e32 v8, 3, v4
	v_lshlrev_b32_e32 v5, 6, v8
	v_lshlrev_b32_e32 v2, 3, v2
	v_ashrrev_i32_e32 v9, 31, v8
	v_mul_lo_u32 v4, v8, s25
	v_sub_u32_e32 v10, v2, v5
	v_lshl_add_u64 v[8:9], s[34:35], 0, v[8:9]
	v_add_lshl_u32 v2, v10, v4, 1
	v_mad_u64_u32 v[14:15], s[10:11], v8, s73, v[12:13]
	ds_read_b128 v[4:7], v2
	v_mov_b32_e32 v2, v15
	v_add_u32_e32 v1, 0x700, v1
	v_mad_u64_u32 v[8:9], s[10:11], v9, s73, v[2:3]
	v_ashrrev_i32_e32 v2, 31, v1
	v_lshrrev_b32_e32 v2, 29, v2
	v_add_u32_e32 v2, v1, v2
	v_mov_b32_e32 v15, v8
	v_ashrrev_i32_e32 v11, 31, v10
	v_ashrrev_i32_e32 v16, 3, v2
	v_lshl_add_u64 v[14:15], v[10:11], 1, v[14:15]
	v_lshlrev_b32_e32 v8, 6, v16
	v_lshlrev_b32_e32 v1, 3, v1
	v_ashrrev_i32_e32 v17, 31, v16
	v_mul_lo_u32 v2, v16, s25
	v_sub_u32_e32 v18, v1, v8
	s_waitcnt lgkmcnt(0)
	global_store_dwordx4 v[14:15], v[4:7], off
	v_add_lshl_u32 v1, v18, v2, 1
	ds_read_b128 v[8:11], v1
	v_lshl_add_u64 v[4:5], s[34:35], 0, v[16:17]
	v_mad_u64_u32 v[6:7], s[10:11], v4, s73, v[12:13]
	v_mov_b32_e32 v2, v7
	v_mad_u64_u32 v[4:5], s[10:11], v5, s73, v[2:3]
	v_readlane_b32 s10, v252, 59
	v_mov_b32_e32 v7, v4
	v_ashrrev_i32_e32 v19, 31, v18
	s_add_i32 s2, s2, s10
	v_lshl_add_u64 v[4:5], v[18:19], 1, v[6:7]
	s_cmpk_gt_i32 s2, 0x15ff
	s_waitcnt lgkmcnt(0)
	global_store_dwordx4 v[4:5], v[8:11], off
	s_barrier
	v_readlane_b32 s11, v252, 60
	s_cbranch_scc0 .LBB0_183

; DEVI f32x4 mfma16(bf16x8 a, bf16x8 b, f32x4 c) { return __builtin_amdgcn_mfma_f32_16x16x32_bf16(a, b, c, 0, 0, 0); }
; DEVI void gemm_core3(f32x4 (&acc)[8][4], const bf* __restrict__ A, int lda, const bf* __restrict__ Bt, int ldb, int K, char* smem) {
;     ...
;   for (int kt = 0; kt < nk; ++kt) {
;     const int k1 = min((kt + 1) * 32, klast);
;     const int sn = ((kt + 1) & 1) * STG;
;     const int so = (kt & 1) * STG;
;     bf16x8 bfr[4], af[8];
; #pragma unroll
;     for (int n = 0; n < 4; ++n) bfr[n] = *reinterpret_cast<const bf16x8*>(bbase + so + n * 16 * 64);
; #pragma unroll
;     for (int m = 0; m < 8; ++m) af[m] = *reinterpret_cast<const bf16x8*>(abase + so + m * 16 * 64);
; #pragma unroll
;     for (int i = 0; i < 4; ++i) glds16(Ap + i * sa + k1, dbase + sn + i * 4096);
; #pragma unroll
;     for (int i = 0; i < 2; ++i) glds16(Bp + i * sb + k1, dbase + sn + ASZ + i * 4096);
;     __builtin_amdgcn_s_setprio(1);
; #pragma unroll
;     for (int m = 0; m < 8; ++m)
; #pragma unroll
;       for (int n = 0; n < 4; ++n) acc[m][n] = mfma16(af[m], bfr[n], acc[m][n]);
;     __builtin_amdgcn_s_setprio(0);
;     __syncthreads();
;   }
.Lg3_loop_206:
	v_add_u32_e32 v216, s10, v146
	v_add_u32_e32 v217, s10, v2
	ds_read_b128 v[148:151], v217 offset:16384
	ds_read_b128 v[166:169], v216
	ds_read_b128 v[154:157], v217 offset:17408
	ds_read_b128 v[158:161], v217 offset:18432
	ds_read_b128 v[162:165], v217 offset:19456
	ds_read_b128 v[170:173], v216 offset:1024
	ds_read_b128 v[174:177], v216 offset:2048
	ds_read_b128 v[192:195], v216 offset:3072
	ds_read_b128 v[196:199], v216 offset:4096
	ds_read_b128 v[204:207], v216 offset:5120
	ds_read_b128 v[208:211], v216 offset:6144
	ds_read_b128 v[212:215], v216 offset:7168
	s_setprio 1
	s_waitcnt lgkmcnt(10)
	v_mfma_f32_16x16x32_bf16 v[128:131], v[166:169], v[148:151], v[128:131]
	s_waitcnt lgkmcnt(9)
	v_mfma_f32_16x16x32_bf16 v[124:127], v[166:169], v[154:157], v[124:127]
	s_waitcnt lgkmcnt(8)
	v_mfma_f32_16x16x32_bf16 v[120:123], v[166:169], v[158:161], v[120:123]
	s_waitcnt lgkmcnt(7)
	v_mfma_f32_16x16x32_bf16 v[116:119], v[166:169], v[162:165], v[116:119]
	s_waitcnt lgkmcnt(6)
	v_mfma_f32_16x16x32_bf16 v[112:115], v[170:173], v[148:151], v[112:115]
	v_mfma_f32_16x16x32_bf16 v[108:111], v[170:173], v[154:157], v[108:111]
	v_mfma_f32_16x16x32_bf16 v[104:107], v[170:173], v[158:161], v[104:107]
	v_mfma_f32_16x16x32_bf16 v[100:103], v[170:173], v[162:165], v[100:103]
	s_waitcnt lgkmcnt(5)
	v_mfma_f32_16x16x32_bf16 v[96:99], v[174:177], v[148:151], v[96:99]
	v_mfma_f32_16x16x32_bf16 v[92:95], v[174:177], v[154:157], v[92:95]
	v_mfma_f32_16x16x32_bf16 v[88:91], v[174:177], v[158:161], v[88:91]
	v_mfma_f32_16x16x32_bf16 v[84:87], v[174:177], v[162:165], v[84:87]
	s_waitcnt lgkmcnt(4)
	v_mfma_f32_16x16x32_bf16 v[80:83], v[192:195], v[148:151], v[80:83]
	v_mfma_f32_16x16x32_bf16 v[76:79], v[192:195], v[154:157], v[76:79]
	v_mfma_f32_16x16x32_bf16 v[72:75], v[192:195], v[158:161], v[72:75]
	v_mfma_f32_16x16x32_bf16 v[68:71], v[192:195], v[162:165], v[68:71]
	s_waitcnt lgkmcnt(3)
	v_mfma_f32_16x16x32_bf16 v[64:67], v[196:199], v[148:151], v[64:67]
	v_mfma_f32_16x16x32_bf16 v[60:63], v[196:199], v[154:157], v[60:63]
	v_mfma_f32_16x16x32_bf16 v[56:59], v[196:199], v[158:161], v[56:59]
	v_mfma_f32_16x16x32_bf16 v[52:55], v[196:199], v[162:165], v[52:55]
	s_waitcnt lgkmcnt(2)
	v_mfma_f32_16x16x32_bf16 v[48:51], v[204:207], v[148:151], v[48:51]
	v_mfma_f32_16x16x32_bf16 v[44:47], v[204:207], v[154:157], v[44:47]
	v_mfma_f32_16x16x32_bf16 v[40:43], v[204:207], v[158:161], v[40:43]
	v_mfma_f32_16x16x32_bf16 v[36:39], v[204:207], v[162:165], v[36:39]
	s_waitcnt lgkmcnt(1)
	v_mfma_f32_16x16x32_bf16 v[32:35], v[208:211], v[148:151], v[32:35]
	v_mfma_f32_16x16x32_bf16 v[28:31], v[208:211], v[154:157], v[28:31]
	v_mfma_f32_16x16x32_bf16 v[24:27], v[208:211], v[158:161], v[24:27]
	v_mfma_f32_16x16x32_bf16 v[20:23], v[208:211], v[162:165], v[20:23]
	s_waitcnt lgkmcnt(0)
	v_mfma_f32_16x16x32_bf16 v[16:19], v[212:215], v[148:151], v[16:19]
	v_mfma_f32_16x16x32_bf16 v[12:15], v[212:215], v[154:157], v[12:15]
	v_mfma_f32_16x16x32_bf16 v[8:11], v[212:215], v[158:161], v[8:11]
	v_mfma_f32_16x16x32_bf16 v[4:7], v[212:215], v[162:165], v[4:7]
	s_setprio 0
	s_add_i32 s10, s10, 0x6000
	s_cmp_lg_u32 s10, 0x12000
	s_cselect_b32 s10, s10, 0
	s_waitcnt vmcnt(0)
	s_barrier
	v_add_u32_e32 v216, s10, v146
	v_add_u32_e32 v217, s10, v2
	ds_read_b128 v[148:151], v217 offset:16384
	ds_read_b128 v[166:169], v216
	ds_read_b128 v[154:157], v217 offset:17408
	ds_read_b128 v[158:161], v217 offset:18432
	ds_read_b128 v[162:165], v217 offset:19456
	ds_read_b128 v[170:173], v216 offset:1024
	ds_read_b128 v[174:177], v216 offset:2048
	ds_read_b128 v[192:195], v216 offset:3072
	ds_read_b128 v[196:199], v216 offset:4096
	ds_read_b128 v[204:207], v216 offset:5120
	ds_read_b128 v[208:211], v216 offset:6144
	ds_read_b128 v[212:215], v216 offset:7168
	v_readfirstlane_b32 s17, v140
	s_add_i32 s96, s11, 0x6000
	s_cmp_lg_u32 s96, 0x12000
	s_cselect_b32 s96, s96, 0
	s_add_i32 s96, s96, s17
	s_add_i32 s17, s17, s11
	s_setprio 2
	s_waitcnt lgkmcnt(10)
	s_mov_b32 m0, s17
	s_add_i32 s17, s17, 0x1000
	v_mfma_f32_16x16x32_bf16 v[128:131], v[166:169], v[148:151], v[128:131]
	s_waitcnt lgkmcnt(9)
	v_mfma_f32_16x16x32_bf16 v[124:127], v[166:169], v[154:157], v[124:127]
	global_load_lds_dwordx4 v[218:219], off
	v_lshl_add_u64 v[218:219], v[218:219], 0, 64
	s_waitcnt lgkmcnt(8)
	s_mov_b32 m0, s96
	s_add_i32 s96, s96, 0x1000
	v_mfma_f32_16x16x32_bf16 v[120:123], v[166:169], v[158:161], v[120:123]
	s_waitcnt lgkmcnt(7)
	v_mfma_f32_16x16x32_bf16 v[116:119], v[166:169], v[162:165], v[116:119]
	global_load_lds_dwordx4 v[218:219], off
	v_lshl_add_u64 v[218:219], v[218:219], 0, 64
	s_waitcnt lgkmcnt(6)
	v_mfma_f32_16x16x32_bf16 v[112:115], v[170:173], v[148:151], v[112:115]
	s_mov_b32 m0, s17
	s_add_i32 s17, s17, 0x1000
	v_mfma_f32_16x16x32_bf16 v[108:111], v[170:173], v[154:157], v[108:111]
	v_mfma_f32_16x16x32_bf16 v[104:107], v[170:173], v[158:161], v[104:107]
	global_load_lds_dwordx4 v[220:221], off
	v_lshl_add_u64 v[220:221], v[220:221], 0, 64
	s_mov_b32 m0, s96
	s_add_i32 s96, s96, 0x1000
	v_mfma_f32_16x16x32_bf16 v[100:103], v[170:173], v[162:165], v[100:103]
	s_waitcnt lgkmcnt(5)
	v_mfma_f32_16x16x32_bf16 v[96:99], v[174:177], v[148:151], v[96:99]
	global_load_lds_dwordx4 v[220:221], off
	v_lshl_add_u64 v[220:221], v[220:221], 0, 64
	v_mfma_f32_16x16x32_bf16 v[92:95], v[174:177], v[154:157], v[92:95]
	s_mov_b32 m0, s17
	s_add_i32 s17, s17, 0x1000
	v_mfma_f32_16x16x32_bf16 v[88:91], v[174:177], v[158:161], v[88:91]
	v_mfma_f32_16x16x32_bf16 v[84:87], v[174:177], v[162:165], v[84:87]
	global_load_lds_dwordx4 v[222:223], off
	v_lshl_add_u64 v[222:223], v[222:223], 0, 64
	s_waitcnt lgkmcnt(4)
; DEVI f32x4 mfma16(bf16x8 a, bf16x8 b, f32x4 c) { return __builtin_amdgcn_mfma_f32_16x16x32_bf16(a, b, c, 0, 0, 0); }
; DEVI void gemm_core3(f32x4 (&acc)[8][4], const bf* __restrict__ A, int lda, const bf* __restrict__ Bt, int ldb, int K, char* smem) {
;     ...
;   for (int kt = 0; kt < nk; ++kt) {
;     const int k1 = min((kt + 1) * 32, klast);
;     const int sn = ((kt + 1) & 1) * STG;
;     const int so = (kt & 1) * STG;
;     bf16x8 bfr[4], af[8];
; #pragma unroll
;     for (int n = 0; n < 4; ++n) bfr[n] = *reinterpret_cast<const bf16x8*>(bbase + so + n * 16 * 64);
; #pragma unroll
;     for (int m = 0; m < 8; ++m) af[m] = *reinterpret_cast<const bf16x8*>(abase + so + m * 16 * 64);
; #pragma unroll
;     for (int i = 0; i < 4; ++i) glds16(Ap + i * sa + k1, dbase + sn + i * 4096);
; #pragma unroll
;     for (int i = 0; i < 2; ++i) glds16(Bp + i * sb + k1, dbase + sn + ASZ + i * 4096);
;     __builtin_amdgcn_s_setprio(1);
; #pragma unroll
;     for (int m = 0; m < 8; ++m)
; #pragma unroll
;       for (int n = 0; n < 4; ++n) acc[m][n] = mfma16(af[m], bfr[n], acc[m][n]);
;     __builtin_amdgcn_s_setprio(0);
;     __syncthreads();
;   }
	s_mov_b32 m0, s96
	s_add_i32 s96, s96, 0x1000
	v_mfma_f32_16x16x32_bf16 v[80:83], v[192:195], v[148:151], v[80:83]
	v_mfma_f32_16x16x32_bf16 v[76:79], v[192:195], v[154:157], v[76:79]
	global_load_lds_dwordx4 v[222:223], off
	v_lshl_add_u64 v[222:223], v[222:223], 0, 64
	v_mfma_f32_16x16x32_bf16 v[72:75], v[192:195], v[158:161], v[72:75]
	s_mov_b32 m0, s17
	s_add_i32 s17, s17, 0x1000
	v_mfma_f32_16x16x32_bf16 v[68:71], v[192:195], v[162:165], v[68:71]
	s_waitcnt lgkmcnt(3)
	v_mfma_f32_16x16x32_bf16 v[64:67], v[196:199], v[148:151], v[64:67]
	global_load_lds_dwordx4 v[224:225], off
	v_lshl_add_u64 v[224:225], v[224:225], 0, 64
	s_mov_b32 m0, s96
	s_add_i32 s96, s96, 0x1000
	v_mfma_f32_16x16x32_bf16 v[60:63], v[196:199], v[154:157], v[60:63]
	v_mfma_f32_16x16x32_bf16 v[56:59], v[196:199], v[158:161], v[56:59]
	global_load_lds_dwordx4 v[224:225], off
	v_lshl_add_u64 v[224:225], v[224:225], 0, 64
	v_mfma_f32_16x16x32_bf16 v[52:55], v[196:199], v[162:165], v[52:55]
	s_waitcnt lgkmcnt(2)
	s_mov_b32 m0, s17
	s_add_i32 s17, s17, 0x1000
	v_mfma_f32_16x16x32_bf16 v[48:51], v[204:207], v[148:151], v[48:51]
	v_mfma_f32_16x16x32_bf16 v[44:47], v[204:207], v[154:157], v[44:47]
	global_load_lds_dwordx4 v[226:227], off
	v_lshl_add_u64 v[226:227], v[226:227], 0, 64
	s_mov_b32 m0, s96
	s_add_i32 s96, s96, 0x1000
	v_mfma_f32_16x16x32_bf16 v[40:43], v[204:207], v[158:161], v[40:43]
	v_mfma_f32_16x16x32_bf16 v[36:39], v[204:207], v[162:165], v[36:39]
	global_load_lds_dwordx4 v[226:227], off
	v_lshl_add_u64 v[226:227], v[226:227], 0, 64
	s_waitcnt lgkmcnt(1)
	v_mfma_f32_16x16x32_bf16 v[32:35], v[208:211], v[148:151], v[32:35]
	s_mov_b32 m0, s17
	s_add_i32 s17, s17, 0x1000
	v_mfma_f32_16x16x32_bf16 v[28:31], v[208:211], v[154:157], v[28:31]
	v_mfma_f32_16x16x32_bf16 v[24:27], v[208:211], v[158:161], v[24:27]
	global_load_lds_dwordx4 v[228:229], off
	v_lshl_add_u64 v[228:229], v[228:229], 0, 64
	s_mov_b32 m0, s96
	s_add_i32 s96, s96, 0x1000
	v_mfma_f32_16x16x32_bf16 v[20:23], v[208:211], v[162:165], v[20:23]
	s_waitcnt lgkmcnt(0)
	v_mfma_f32_16x16x32_bf16 v[16:19], v[212:215], v[148:151], v[16:19]
	global_load_lds_dwordx4 v[228:229], off
	v_lshl_add_u64 v[228:229], v[228:229], 0, 64
	v_mfma_f32_16x16x32_bf16 v[12:15], v[212:215], v[154:157], v[12:15]
	v_mfma_f32_16x16x32_bf16 v[8:11], v[212:215], v[158:161], v[8:11]
	v_mfma_f32_16x16x32_bf16 v[4:7], v[212:215], v[162:165], v[4:7]
	s_setprio 0
	s_add_i32 s10, s10, 0x6000
	s_cmp_lg_u32 s10, 0x12000
	s_cselect_b32 s10, s10, 0
	s_sub_i32 s11, s11, 0x6000
	s_cmp_lt_i32 s11, 0
	s_cselect_b32 s11, 0xc000, s11
	s_add_i32 s3, s3, 1
	s_cmp_lt_i32 s3, 15
	s_waitcnt vmcnt(1)
	s_barrier
	s_cbranch_scc1 .Lg3_loop_206
	v_add_u32_e32 v216, s10, v146
	v_add_u32_e32 v217, s10, v2
	ds_read_b128 v[148:151], v217 offset:16384
	ds_read_b128 v[166:169], v216
	ds_read_b128 v[154:157], v217 offset:17408
	ds_read_b128 v[158:161], v217 offset:18432
	ds_read_b128 v[162:165], v217 offset:19456
	ds_read_b128 v[170:173], v216 offset:1024
	ds_read_b128 v[174:177], v216 offset:2048
	ds_read_b128 v[192:195], v216 offset:3072
	ds_read_b128 v[196:199], v216 offset:4096
	ds_read_b128 v[204:207], v216 offset:5120
	ds_read_b128 v[208:211], v216 offset:6144
	ds_read_b128 v[212:215], v216 offset:7168
	s_setprio 1
	s_waitcnt lgkmcnt(10)
	v_mfma_f32_16x16x32_bf16 v[128:131], v[166:169], v[148:151], v[128:131]
	s_waitcnt lgkmcnt(9)
	v_mfma_f32_16x16x32_bf16 v[124:127], v[166:169], v[154:157], v[124:127]
	s_waitcnt lgkmcnt(8)
	v_mfma_f32_16x16x32_bf16 v[120:123], v[166:169], v[158:161], v[120:123]
	s_waitcnt lgkmcnt(7)
	v_mfma_f32_16x16x32_bf16 v[116:119], v[166:169], v[162:165], v[116:119]
	s_waitcnt lgkmcnt(6)
	v_mfma_f32_16x16x32_bf16 v[112:115], v[170:173], v[148:151], v[112:115]
	v_mfma_f32_16x16x32_bf16 v[108:111], v[170:173], v[154:157], v[108:111]
	v_mfma_f32_16x16x32_bf16 v[104:107], v[170:173], v[158:161], v[104:107]
	v_mfma_f32_16x16x32_bf16 v[100:103], v[170:173], v[162:165], v[100:103]
	s_waitcnt lgkmcnt(5)
	v_mfma_f32_16x16x32_bf16 v[96:99], v[174:177], v[148:151], v[96:99]
	v_mfma_f32_16x16x32_bf16 v[92:95], v[174:177], v[154:157], v[92:95]
	v_mfma_f32_16x16x32_bf16 v[88:91], v[174:177], v[158:161], v[88:91]
	v_mfma_f32_16x16x32_bf16 v[84:87], v[174:177], v[162:165], v[84:87]
	s_waitcnt lgkmcnt(4)
	v_mfma_f32_16x16x32_bf16 v[80:83], v[192:195], v[148:151], v[80:83]
	v_mfma_f32_16x16x32_bf16 v[76:79], v[192:195], v[154:157], v[76:79]
	v_mfma_f32_16x16x32_bf16 v[72:75], v[192:195], v[158:161], v[72:75]
	v_mfma_f32_16x16x32_bf16 v[68:71], v[192:195], v[162:165], v[68:71]
	s_waitcnt lgkmcnt(3)
	v_mfma_f32_16x16x32_bf16 v[64:67], v[196:199], v[148:151], v[64:67]
	v_mfma_f32_16x16x32_bf16 v[60:63], v[196:199], v[154:157], v[60:63]
	v_mfma_f32_16x16x32_bf16 v[56:59], v[196:199], v[158:161], v[56:59]
	v_mfma_f32_16x16x32_bf16 v[52:55], v[196:199], v[162:165], v[52:55]
	s_waitcnt lgkmcnt(2)
	v_mfma_f32_16x16x32_bf16 v[48:51], v[204:207], v[148:151], v[48:51]
	v_mfma_f32_16x16x32_bf16 v[44:47], v[204:207], v[154:157], v[44:47]
	v_mfma_f32_16x16x32_bf16 v[40:43], v[204:207], v[158:161], v[40:43]
	v_mfma_f32_16x16x32_bf16 v[36:39], v[204:207], v[162:165], v[36:39]
	s_waitcnt lgkmcnt(1)
	v_mfma_f32_16x16x32_bf16 v[32:35], v[208:211], v[148:151], v[32:35]
	v_mfma_f32_16x16x32_bf16 v[28:31], v[208:211], v[154:157], v[28:31]
	v_mfma_f32_16x16x32_bf16 v[24:27], v[208:211], v[158:161], v[24:27]
	v_mfma_f32_16x16x32_bf16 v[20:23], v[208:211], v[162:165], v[20:23]
	s_waitcnt lgkmcnt(0)
	v_mfma_f32_16x16x32_bf16 v[16:19], v[212:215], v[148:151], v[16:19]
	v_mfma_f32_16x16x32_bf16 v[12:15], v[212:215], v[154:157], v[12:15]
	v_mfma_f32_16x16x32_bf16 v[8:11], v[212:215], v[158:161], v[8:11]
	v_mfma_f32_16x16x32_bf16 v[4:7], v[212:215], v[162:165], v[4:7]
	s_setprio 0
	s_add_i32 s10, s10, 0x6000
	s_cmp_lg_u32 s10, 0x12000
	s_cselect_b32 s10, s10, 0
	s_waitcnt vmcnt(0)
	s_barrier
; DEVI f32x4 mfma16(bf16x8 a, bf16x8 b, f32x4 c) { return __builtin_amdgcn_mfma_f32_16x16x32_bf16(a, b, c, 0, 0, 0); }
; DEVI void gemm_core3(f32x4 (&acc)[8][4], const bf* __restrict__ A, int lda, const bf* __restrict__ Bt, int ldb, int K, char* smem) {
;     ...
;     bf16x8 bfr[4], af[8];
; #pragma unroll
;     for (int n = 0; n < 4; ++n) bfr[n] = *reinterpret_cast<const bf16x8*>(bbase + so + n * 16 * 64);
; #pragma unroll
;     for (int m = 0; m < 8; ++m) af[m] = *reinterpret_cast<const bf16x8*>(abase + so + m * 16 * 64);
; #pragma unroll
;     for (int i = 0; i < 4; ++i) glds16(Ap + i * sa + k1, dbase + sn + i * 4096);
; #pragma unroll
;     for (int i = 0; i < 2; ++i) glds16(Bp + i * sb + k1, dbase + sn + ASZ + i * 4096);
;     __builtin_amdgcn_s_setprio(1);
; #pragma unroll
;     for (int m = 0; m < 8; ++m)
; #pragma unroll
;       for (int n = 0; n < 4; ++n) acc[m][n] = mfma16(af[m], bfr[n], acc[m][n]);
;     __builtin_amdgcn_s_setprio(0);
; DEVI void plain_tile256(const bf* A, int lda, const bf* Wt, int K, bf* C, int ldc, long row0, int n0, char* smem) {
;     ...
;   bf* tl = reinterpret_cast<bf*>(smem);
; #pragma unroll
;   for (int m = 0; m < 8; ++m)
; #pragma unroll
;     for (int n = 0; n < 4; ++n) {
;       const int cl = wc * 64 + n * 16 + l15;
; #pragma unroll
;       for (int j = 0; j < 4; ++j) tl[(wr * 128 + m * 16 + quad * 4 + j) * 136 + cl] = f2bf(acc[m][n][j]);
;     }
	v_add_u32_e32 v216, s10, v146
	v_add_u32_e32 v217, s10, v2
	ds_read_b128 v[148:151], v217 offset:16384
	ds_read_b128 v[166:169], v216
	ds_read_b128 v[154:157], v217 offset:17408
	ds_read_b128 v[158:161], v217 offset:18432
	ds_read_b128 v[162:165], v217 offset:19456
	ds_read_b128 v[170:173], v216 offset:1024
	ds_read_b128 v[174:177], v216 offset:2048
	ds_read_b128 v[192:195], v216 offset:3072
	ds_read_b128 v[196:199], v216 offset:4096
	ds_read_b128 v[204:207], v216 offset:5120
	ds_read_b128 v[208:211], v216 offset:6144
	ds_read_b128 v[212:215], v216 offset:7168
	s_setprio 1
	s_waitcnt lgkmcnt(10)
	v_mfma_f32_16x16x32_bf16 v[128:131], v[166:169], v[148:151], v[128:131]
	s_waitcnt lgkmcnt(9)
	v_mfma_f32_16x16x32_bf16 v[124:127], v[166:169], v[154:157], v[124:127]
	s_waitcnt lgkmcnt(8)
	v_mfma_f32_16x16x32_bf16 v[120:123], v[166:169], v[158:161], v[120:123]
	s_waitcnt lgkmcnt(7)
	v_mfma_f32_16x16x32_bf16 v[116:119], v[166:169], v[162:165], v[116:119]
	s_waitcnt lgkmcnt(6)
	v_mfma_f32_16x16x32_bf16 v[112:115], v[170:173], v[148:151], v[112:115]
	v_mfma_f32_16x16x32_bf16 v[108:111], v[170:173], v[154:157], v[108:111]
	v_mfma_f32_16x16x32_bf16 v[104:107], v[170:173], v[158:161], v[104:107]
	v_mfma_f32_16x16x32_bf16 v[100:103], v[170:173], v[162:165], v[100:103]
	s_waitcnt lgkmcnt(5)
	v_mfma_f32_16x16x32_bf16 v[96:99], v[174:177], v[148:151], v[96:99]
	v_mfma_f32_16x16x32_bf16 v[92:95], v[174:177], v[154:157], v[92:95]
	v_mfma_f32_16x16x32_bf16 v[88:91], v[174:177], v[158:161], v[88:91]
	v_mfma_f32_16x16x32_bf16 v[84:87], v[174:177], v[162:165], v[84:87]
	s_waitcnt lgkmcnt(4)
	v_mfma_f32_16x16x32_bf16 v[80:83], v[192:195], v[148:151], v[80:83]
	v_mfma_f32_16x16x32_bf16 v[76:79], v[192:195], v[154:157], v[76:79]
	v_mfma_f32_16x16x32_bf16 v[72:75], v[192:195], v[158:161], v[72:75]
	v_mfma_f32_16x16x32_bf16 v[68:71], v[192:195], v[162:165], v[68:71]
	s_waitcnt lgkmcnt(3)
	v_mfma_f32_16x16x32_bf16 v[64:67], v[196:199], v[148:151], v[64:67]
	v_mfma_f32_16x16x32_bf16 v[60:63], v[196:199], v[154:157], v[60:63]
	v_mfma_f32_16x16x32_bf16 v[56:59], v[196:199], v[158:161], v[56:59]
	v_mfma_f32_16x16x32_bf16 v[52:55], v[196:199], v[162:165], v[52:55]
	s_waitcnt lgkmcnt(2)
	v_mfma_f32_16x16x32_bf16 v[48:51], v[204:207], v[148:151], v[48:51]
	v_mfma_f32_16x16x32_bf16 v[44:47], v[204:207], v[154:157], v[44:47]
	v_mfma_f32_16x16x32_bf16 v[40:43], v[204:207], v[158:161], v[40:43]
	v_mfma_f32_16x16x32_bf16 v[36:39], v[204:207], v[162:165], v[36:39]
	s_waitcnt lgkmcnt(1)
	v_mfma_f32_16x16x32_bf16 v[32:35], v[208:211], v[148:151], v[32:35]
	v_mfma_f32_16x16x32_bf16 v[28:31], v[208:211], v[154:157], v[28:31]
	v_mfma_f32_16x16x32_bf16 v[24:27], v[208:211], v[158:161], v[24:27]
	v_mfma_f32_16x16x32_bf16 v[20:23], v[208:211], v[162:165], v[20:23]
	s_waitcnt lgkmcnt(0)
	v_mfma_f32_16x16x32_bf16 v[16:19], v[212:215], v[148:151], v[16:19]
	v_mfma_f32_16x16x32_bf16 v[12:15], v[212:215], v[154:157], v[12:15]
	v_mfma_f32_16x16x32_bf16 v[8:11], v[212:215], v[158:161], v[8:11]
	v_mfma_f32_16x16x32_bf16 v[4:7], v[212:215], v[162:165], v[4:7]
	s_setprio 0
	s_add_i32 s10, s10, 0x6000
	s_cmp_lg_u32 s10, 0x12000
	s_cselect_b32 s10, s10, 0
	s_waitcnt vmcnt(0)
	s_barrier
	v_and_b32_e32 v2, 0x4f, v1
	v_and_b32_e32 v132, 0xfffff80, v1
	v_lshrrev_b32_e32 v1, 2, v1
	v_and_or_b32 v1, v1, 12, v132
	v_mul_lo_u32 v1, v1, s16
	v_lshl_add_u32 v1, v2, 1, v1
	v_cvt_pk_bf16_f32 v2, v129, s0
	ds_write_b16 v1, v2 offset:272
	v_cvt_pk_bf16_f32 v2, v130, s0
	ds_write_b16 v1, v2 offset:544
	v_cvt_pk_bf16_f32 v2, v131, s0
	ds_write_b16 v1, v2 offset:816
	v_cvt_pk_bf16_f32 v2, v124, s0
	ds_write_b16 v1, v2 offset:32
	v_cvt_pk_bf16_f32 v2, v125, s0
	ds_write_b16 v1, v2 offset:304
	v_cvt_pk_bf16_f32 v2, v126, s0
	ds_write_b16 v1, v2 offset:576
	v_cvt_pk_bf16_f32 v2, v127, s0
	ds_write_b16 v1, v2 offset:848
	v_cvt_pk_bf16_f32 v2, v120, s0
	ds_write_b16 v1, v2 offset:64
	v_cvt_pk_bf16_f32 v2, v121, s0
	ds_write_b16 v1, v2 offset:336
	v_cvt_pk_bf16_f32 v2, v122, s0
	ds_write_b16 v1, v2 offset:608
	v_cvt_pk_bf16_f32 v2, v123, s0
	ds_write_b16 v1, v2 offset:880
	v_cvt_pk_bf16_f32 v2, v116, s0
	ds_write_b16 v1, v2 offset:96
	v_cvt_pk_bf16_f32 v2, v117, s0
	ds_write_b16 v1, v2 offset:368
	v_cvt_pk_bf16_f32 v2, v118, s0
	ds_write_b16 v1, v2 offset:640
	v_cvt_pk_bf16_f32 v2, v119, s0
	ds_write_b16 v1, v2 offset:912
	v_cvt_pk_bf16_f32 v2, v112, s0
	ds_write_b16 v1, v2 offset:4352
	v_cvt_pk_bf16_f32 v2, v113, s0
	ds_write_b16 v1, v2 offset:4624
	v_cvt_pk_bf16_f32 v2, v114, s0
	ds_write_b16 v1, v2 offset:4896
	v_cvt_pk_bf16_f32 v2, v115, s0
	ds_write_b16 v1, v2 offset:5168
	v_cvt_pk_bf16_f32 v2, v108, s0
	ds_write_b16 v1, v2 offset:4384
	v_cvt_pk_bf16_f32 v2, v109, s0
	ds_write_b16 v1, v2 offset:4656
	v_cvt_pk_bf16_f32 v2, v110, s0
	ds_write_b16 v1, v2 offset:4928
	v_cvt_pk_bf16_f32 v2, v111, s0
	ds_write_b16 v1, v2 offset:5200
	v_cvt_pk_bf16_f32 v2, v104, s0
	ds_write_b16 v1, v2 offset:4416
	v_cvt_pk_bf16_f32 v2, v105, s0
	ds_write_b16 v1, v2 offset:4688
	v_cvt_pk_bf16_f32 v2, v106, s0
	ds_write_b16 v1, v2 offset:4960
	v_cvt_pk_bf16_f32 v2, v107, s0
	ds_write_b16 v1, v2 offset:5232
	v_cvt_pk_bf16_f32 v2, v100, s0
	ds_write_b16 v1, v2 offset:4448
	v_cvt_pk_bf16_f32 v2, v101, s0
	ds_write_b16 v1, v2 offset:4720
	v_cvt_pk_bf16_f32 v2, v102, s0
	ds_write_b16 v1, v2 offset:4992
	v_cvt_pk_bf16_f32 v2, v103, s0
	ds_write_b16 v1, v2 offset:5264
	v_cvt_pk_bf16_f32 v2, v96, s0
	ds_write_b16 v1, v2 offset:8704
	v_cvt_pk_bf16_f32 v2, v97, s0
	ds_write_b16 v1, v2 offset:8976
	v_cvt_pk_bf16_f32 v2, v98, s0
	ds_write_b16 v1, v2 offset:9248
	v_cvt_pk_bf16_f32 v2, v99, s0
	ds_write_b16 v1, v2 offset:9520
	v_cvt_pk_bf16_f32 v2, v92, s0
; DEVI void plain_tile256(const bf* A, int lda, const bf* Wt, int K, bf* C, int ldc, long row0, int n0, char* smem) {
;     ...
; #pragma unroll
;   for (int m = 0; m < 8; ++m)
; #pragma unroll
;     for (int n = 0; n < 4; ++n) {
;       const int cl = wc * 64 + n * 16 + l15;
; #pragma unroll
;       for (int j = 0; j < 4; ++j) tl[(wr * 128 + m * 16 + quad * 4 + j) * 136 + cl] = f2bf(acc[m][n][j]);
;     }
;   __syncthreads();
	ds_write_b16 v1, v2 offset:8736
	v_cvt_pk_bf16_f32 v2, v93, s0
	ds_write_b16 v1, v2 offset:9008
	v_cvt_pk_bf16_f32 v2, v94, s0
	ds_write_b16 v1, v2 offset:9280
	v_cvt_pk_bf16_f32 v2, v95, s0
	ds_write_b16 v1, v2 offset:9552
	v_cvt_pk_bf16_f32 v2, v88, s0
	ds_write_b16 v1, v2 offset:8768
	v_cvt_pk_bf16_f32 v2, v89, s0
	ds_write_b16 v1, v2 offset:9040
	v_cvt_pk_bf16_f32 v2, v90, s0
	ds_write_b16 v1, v2 offset:9312
	v_cvt_pk_bf16_f32 v2, v91, s0
	ds_write_b16 v1, v2 offset:9584
	v_cvt_pk_bf16_f32 v2, v84, s0
	ds_write_b16 v1, v2 offset:8800
	v_cvt_pk_bf16_f32 v2, v85, s0
	ds_write_b16 v1, v2 offset:9072
	v_cvt_pk_bf16_f32 v2, v86, s0
	ds_write_b16 v1, v2 offset:9344
	v_cvt_pk_bf16_f32 v2, v87, s0
	ds_write_b16 v1, v2 offset:9616
	v_cvt_pk_bf16_f32 v2, v80, s0
	ds_write_b16 v1, v2 offset:13056
	v_cvt_pk_bf16_f32 v2, v81, s0
	ds_write_b16 v1, v2 offset:13328
	v_cvt_pk_bf16_f32 v2, v82, s0
	ds_write_b16 v1, v2 offset:13600
	v_cvt_pk_bf16_f32 v2, v83, s0
	ds_write_b16 v1, v2 offset:13872
	v_cvt_pk_bf16_f32 v2, v76, s0
	ds_write_b16 v1, v2 offset:13088
	v_cvt_pk_bf16_f32 v2, v77, s0
	ds_write_b16 v1, v2 offset:13360
	v_cvt_pk_bf16_f32 v2, v78, s0
	ds_write_b16 v1, v2 offset:13632
	v_cvt_pk_bf16_f32 v2, v79, s0
	ds_write_b16 v1, v2 offset:13904
	v_cvt_pk_bf16_f32 v2, v72, s0
	ds_write_b16 v1, v2 offset:13120
	v_cvt_pk_bf16_f32 v2, v73, s0
	ds_write_b16 v1, v2 offset:13392
	v_cvt_pk_bf16_f32 v2, v74, s0
	ds_write_b16 v1, v2 offset:13664
	v_cvt_pk_bf16_f32 v2, v75, s0
	ds_write_b16 v1, v2 offset:13936
	v_cvt_pk_bf16_f32 v2, v68, s0
	ds_write_b16 v1, v2 offset:13152
	v_cvt_pk_bf16_f32 v2, v69, s0
	ds_write_b16 v1, v2 offset:13424
	v_cvt_pk_bf16_f32 v2, v70, s0
	ds_write_b16 v1, v2 offset:13696
	v_cvt_pk_bf16_f32 v2, v71, s0
	ds_write_b16 v1, v2 offset:13968
	v_cvt_pk_bf16_f32 v2, v64, s0
	ds_write_b16 v1, v2 offset:17408
	v_cvt_pk_bf16_f32 v2, v65, s0
	ds_write_b16 v1, v2 offset:17680
	v_cvt_pk_bf16_f32 v2, v66, s0
	ds_write_b16 v1, v2 offset:17952
	v_cvt_pk_bf16_f32 v2, v67, s0
	ds_write_b16 v1, v2 offset:18224
	v_cvt_pk_bf16_f32 v2, v60, s0
	ds_write_b16 v1, v2 offset:17440
	v_cvt_pk_bf16_f32 v2, v61, s0
	ds_write_b16 v1, v2 offset:17712
	v_cvt_pk_bf16_f32 v2, v62, s0
	ds_write_b16 v1, v2 offset:17984
	v_cvt_pk_bf16_f32 v2, v63, s0
	ds_write_b16 v1, v2 offset:18256
	v_cvt_pk_bf16_f32 v2, v56, s0
	ds_write_b16 v1, v2 offset:17472
	v_cvt_pk_bf16_f32 v2, v57, s0
	ds_write_b16 v1, v2 offset:17744
	v_cvt_pk_bf16_f32 v2, v58, s0
	ds_write_b16 v1, v2 offset:18016
	v_cvt_pk_bf16_f32 v2, v59, s0
	ds_write_b16 v1, v2 offset:18288
	v_cvt_pk_bf16_f32 v2, v52, s0
	ds_write_b16 v1, v2 offset:17504
	v_cvt_pk_bf16_f32 v2, v53, s0
	ds_write_b16 v1, v2 offset:17776
	v_cvt_pk_bf16_f32 v2, v54, s0
	ds_write_b16 v1, v2 offset:18048
	v_cvt_pk_bf16_f32 v2, v55, s0
	ds_write_b16 v1, v2 offset:18320
	v_cvt_pk_bf16_f32 v2, v48, s0
	ds_write_b16 v1, v2 offset:21760
	v_cvt_pk_bf16_f32 v2, v49, s0
	ds_write_b16 v1, v2 offset:22032
	v_cvt_pk_bf16_f32 v2, v50, s0
	ds_write_b16 v1, v2 offset:22304
	v_cvt_pk_bf16_f32 v2, v51, s0
	ds_write_b16 v1, v2 offset:22576
	v_cvt_pk_bf16_f32 v2, v44, s0
	ds_write_b16 v1, v2 offset:21792
	v_cvt_pk_bf16_f32 v2, v45, s0
	ds_write_b16 v1, v2 offset:22064
	v_cvt_pk_bf16_f32 v2, v46, s0
	ds_write_b16 v1, v2 offset:22336
	v_cvt_pk_bf16_f32 v2, v47, s0
	ds_write_b16 v1, v2 offset:22608
	v_cvt_pk_bf16_f32 v2, v40, s0
	ds_write_b16 v1, v2 offset:21824
	v_cvt_pk_bf16_f32 v2, v41, s0
	ds_write_b16 v1, v2 offset:22096
	v_cvt_pk_bf16_f32 v2, v42, s0
	ds_write_b16 v1, v2 offset:22368
	v_cvt_pk_bf16_f32 v2, v43, s0
	ds_write_b16 v1, v2 offset:22640
	v_cvt_pk_bf16_f32 v2, v36, s0
	ds_write_b16 v1, v2 offset:21856
	v_cvt_pk_bf16_f32 v2, v37, s0
	ds_write_b16 v1, v2 offset:22128
	v_cvt_pk_bf16_f32 v2, v38, s0
	ds_write_b16 v1, v2 offset:22400
	v_cvt_pk_bf16_f32 v2, v39, s0
	ds_write_b16 v1, v2 offset:22672
	v_cvt_pk_bf16_f32 v2, v32, s0
	ds_write_b16 v1, v2 offset:26112
	v_cvt_pk_bf16_f32 v2, v33, s0
	ds_write_b16 v1, v2 offset:26384
	v_cvt_pk_bf16_f32 v2, v34, s0
	ds_write_b16 v1, v2 offset:26656
	v_cvt_pk_bf16_f32 v2, v35, s0
	ds_write_b16 v1, v2 offset:26928
	v_cvt_pk_bf16_f32 v2, v28, s0
	ds_write_b16 v1, v2 offset:26144
	v_cvt_pk_bf16_f32 v2, v29, s0
	ds_write_b16 v1, v2 offset:26416
	v_cvt_pk_bf16_f32 v2, v30, s0
	ds_write_b16 v1, v2 offset:26688
	v_cvt_pk_bf16_f32 v2, v31, s0
	ds_write_b16 v1, v2 offset:26960
	v_cvt_pk_bf16_f32 v2, v24, s0
	ds_write_b16 v1, v2 offset:26176
	v_cvt_pk_bf16_f32 v2, v25, s0
	ds_write_b16 v1, v2 offset:26448
	v_cvt_pk_bf16_f32 v2, v26, s0
	ds_write_b16 v1, v2 offset:26720
	v_cvt_pk_bf16_f32 v2, v27, s0
	ds_write_b16 v1, v2 offset:26992
	v_cvt_pk_bf16_f32 v2, v20, s0
	ds_write_b16 v1, v2 offset:26208
	v_cvt_pk_bf16_f32 v2, v21, s0
	ds_write_b16 v1, v2 offset:26480
	v_cvt_pk_bf16_f32 v2, v22, s0
	ds_write_b16 v1, v2 offset:26752
	v_cvt_pk_bf16_f32 v2, v23, s0
	ds_write_b16 v1, v2 offset:27024
	v_cvt_pk_bf16_f32 v2, v16, s0
	ds_write_b16 v1, v2 offset:30464
	v_cvt_pk_bf16_f32 v2, v17, s0
	ds_write_b16 v1, v2 offset:30736
	v_cvt_pk_bf16_f32 v2, v18, s0
	ds_write_b16 v1, v2 offset:31008
	v_cvt_pk_bf16_f32 v2, v19, s0
	ds_write_b16 v1, v2 offset:31280
	v_cvt_pk_bf16_f32 v2, v12, s0
	ds_write_b16 v1, v2 offset:30496
	v_cvt_pk_bf16_f32 v2, v13, s0
	ds_write_b16 v1, v2 offset:30768
	v_cvt_pk_bf16_f32 v2, v14, s0
	ds_write_b16 v1, v2 offset:31040
	v_cvt_pk_bf16_f32 v2, v15, s0
	ds_write_b16 v1, v2 offset:31312
	v_cvt_pk_bf16_f32 v2, v8, s0
	ds_write_b16 v1, v2 offset:30528
	v_cvt_pk_bf16_f32 v2, v9, s0
	ds_write_b16 v1, v2 offset:30800
	v_cvt_pk_bf16_f32 v2, v10, s0
	ds_write_b16 v1, v2 offset:31072
	v_cvt_pk_bf16_f32 v2, v11, s0
	ds_write_b16 v1, v2 offset:31344
	v_cvt_pk_bf16_f32 v2, v4, s0
	ds_write_b16 v1, v2 offset:30560
	v_cvt_pk_bf16_f32 v2, v5, s0
	ds_write_b16 v1, v2 offset:30832
	v_cvt_pk_bf16_f32 v2, v6, s0
	v_cvt_pk_bf16_f32 v128, v128, s0
	ds_write_b16 v1, v2 offset:31104
	v_cvt_pk_bf16_f32 v2, v7, s0
	ds_write_b16 v1, v128
	ds_write_b16 v1, v2 offset:31376
	v_mov_b32_e32 v1, v178
	s_waitcnt lgkmcnt(0)
	s_barrier
; DEVI int get_tid() { int t = threadIdx.x; asm volatile("" : "+v"(t)); return t; }
; template <int BN>
; DEVI void tile_store256(const char* smem, bf* __restrict__ C, long ldc, long row0, int col0) {
;   constexpr int LDT = BN + 8;
;   constexpr int CPR = BN / 8;
;   const int tid = get_tid();
; #pragma unroll
;   for (int i = 0; i < CPR; ++i) {
;     const int q = tid + 256 * i;
;     const int r = q / CPR, c = q - r * CPR;
;     u32x4 v = *reinterpret_cast<const u32x4*>(smem + (r * LDT + c * 8) * 2);
;     *reinterpret_cast<u32x4*>(C + (row0 + r) * ldc + col0 + c * 8) = v;
;   }
; }
; DEVI void phase_gemm_plain128(const bf* A, int lda, const bf* Wt, int K, int N, bf* C, int ldc, char* smem) {
;     ...
;   for (int v = blockIdx.x; v < 128 * ntn; v += gridDim.x) {
;     int m2, nt;
;     lat_tile_map256(v, ntn, m2, nt);
;     plain_tile256(A, lda, Wt, K, C, ldc, lat_row0_256(m2), nt * 128, smem);
	v_readlane_b32 s56, v251, 58
	v_ashrrev_i32_e32 v2, 31, v1
	v_lshrrev_b32_e32 v2, 28, v2
	v_add_u32_e32 v2, v1, v2
	v_ashrrev_i32_e32 v8, 4, v2
	s_lshl_b64 s[10:11], s[34:35], 1
	v_readlane_b32 s60, v251, 62
	v_lshlrev_b32_e32 v4, 7, v8
	v_lshlrev_b32_e32 v5, 3, v1
	v_ashrrev_i32_e32 v9, 31, v8
	v_readlane_b32 s61, v251, 63
	s_add_u32 s10, s60, s10
	v_mul_lo_u32 v2, v8, s83
	v_sub_u32_e32 v10, v5, v4
	v_lshl_add_u64 v[8:9], s[12:13], 0, v[8:9]
	s_addc_u32 s11, s61, s11
	v_add_lshl_u32 v2, v10, v2, 1
	v_lshlrev_b64 v[8:9], 11, v[8:9]
	ds_read_b128 v[4:7], v2
	v_lshl_add_u64 v[8:9], s[10:11], 0, v[8:9]
	v_ashrrev_i32_e32 v11, 31, v10
	v_add_u32_e32 v2, 0x100, v1
	v_lshl_add_u64 v[12:13], v[10:11], 1, v[8:9]
	v_ashrrev_i32_e32 v8, 31, v2
	v_lshrrev_b32_e32 v8, 28, v8
	v_add_u32_e32 v8, v2, v8
	v_ashrrev_i32_e32 v14, 4, v8
	v_lshlrev_b32_e32 v9, 7, v14
	v_lshlrev_b32_e32 v2, 3, v2
	v_mul_lo_u32 v8, v14, s83
	v_sub_u32_e32 v16, v2, v9
	v_add_lshl_u32 v2, v16, v8, 1
	ds_read_b128 v[8:11], v2
	v_ashrrev_i32_e32 v15, 31, v14
	s_waitcnt lgkmcnt(1)
	global_store_dwordx4 v[12:13], v[4:7], off
	v_ashrrev_i32_e32 v17, 31, v16
	v_add_u32_e32 v2, 0x200, v1
	v_lshl_add_u64 v[4:5], s[12:13], 0, v[14:15]
	v_lshlrev_b64 v[4:5], 11, v[4:5]
	v_lshl_add_u64 v[4:5], s[10:11], 0, v[4:5]
	v_lshl_add_u64 v[4:5], v[16:17], 1, v[4:5]
	s_waitcnt lgkmcnt(0)
	global_store_dwordx4 v[4:5], v[8:11], off
	v_ashrrev_i32_e32 v4, 31, v2
	v_lshrrev_b32_e32 v4, 28, v4
	v_add_u32_e32 v4, v2, v4
	v_ashrrev_i32_e32 v8, 4, v4
	v_lshlrev_b32_e32 v5, 7, v8
	v_lshlrev_b32_e32 v2, 3, v2
	v_ashrrev_i32_e32 v9, 31, v8
	v_mul_lo_u32 v4, v8, s83
	v_sub_u32_e32 v10, v2, v5
	v_lshl_add_u64 v[8:9], s[12:13], 0, v[8:9]
	v_add_lshl_u32 v2, v10, v4, 1
	v_lshlrev_b64 v[8:9], 11, v[8:9]
	ds_read_b128 v[4:7], v2
	v_lshl_add_u64 v[8:9], s[10:11], 0, v[8:9]
	v_ashrrev_i32_e32 v11, 31, v10
	v_add_u32_e32 v2, 0x300, v1
	v_lshl_add_u64 v[12:13], v[10:11], 1, v[8:9]
	v_ashrrev_i32_e32 v8, 31, v2
	v_lshrrev_b32_e32 v8, 28, v8
	v_add_u32_e32 v8, v2, v8
	v_ashrrev_i32_e32 v14, 4, v8
	v_lshlrev_b32_e32 v9, 7, v14
	v_lshlrev_b32_e32 v2, 3, v2
	v_mul_lo_u32 v8, v14, s83
	v_sub_u32_e32 v16, v2, v9
	v_add_lshl_u32 v2, v16, v8, 1
	ds_read_b128 v[8:11], v2
	v_ashrrev_i32_e32 v15, 31, v14
	s_waitcnt lgkmcnt(1)
	global_store_dwordx4 v[12:13], v[4:7], off
	v_ashrrev_i32_e32 v17, 31, v16
	v_add_u32_e32 v2, 0x400, v1
	v_lshl_add_u64 v[4:5], s[12:13], 0, v[14:15]
	v_lshlrev_b64 v[4:5], 11, v[4:5]
	v_lshl_add_u64 v[4:5], s[10:11], 0, v[4:5]
	v_lshl_add_u64 v[4:5], v[16:17], 1, v[4:5]
	s_waitcnt lgkmcnt(0)
	global_store_dwordx4 v[4:5], v[8:11], off
	v_ashrrev_i32_e32 v4, 31, v2
	v_lshrrev_b32_e32 v4, 28, v4
	v_add_u32_e32 v4, v2, v4
	v_ashrrev_i32_e32 v8, 4, v4
	v_lshlrev_b32_e32 v5, 7, v8
	v_lshlrev_b32_e32 v2, 3, v2
	v_ashrrev_i32_e32 v9, 31, v8
	v_mul_lo_u32 v4, v8, s83
	v_sub_u32_e32 v10, v2, v5
	v_lshl_add_u64 v[8:9], s[12:13], 0, v[8:9]
	v_add_lshl_u32 v2, v10, v4, 1
	v_lshlrev_b64 v[8:9], 11, v[8:9]
	ds_read_b128 v[4:7], v2
	v_lshl_add_u64 v[8:9], s[10:11], 0, v[8:9]
	v_ashrrev_i32_e32 v11, 31, v10
	v_add_u32_e32 v2, 0x500, v1
	v_lshl_add_u64 v[12:13], v[10:11], 1, v[8:9]
	v_ashrrev_i32_e32 v8, 31, v2
	v_lshrrev_b32_e32 v8, 28, v8
	v_add_u32_e32 v8, v2, v8
	v_ashrrev_i32_e32 v14, 4, v8
	v_lshlrev_b32_e32 v9, 7, v14
	v_lshlrev_b32_e32 v2, 3, v2
	v_mul_lo_u32 v8, v14, s83
	v_sub_u32_e32 v16, v2, v9
	v_add_lshl_u32 v2, v16, v8, 1
	ds_read_b128 v[8:11], v2
	v_ashrrev_i32_e32 v15, 31, v14
	s_waitcnt lgkmcnt(1)
	global_store_dwordx4 v[12:13], v[4:7], off
	v_ashrrev_i32_e32 v17, 31, v16
	v_add_u32_e32 v2, 0x600, v1
	v_lshl_add_u64 v[4:5], s[12:13], 0, v[14:15]
	v_lshlrev_b64 v[4:5], 11, v[4:5]
	v_lshl_add_u64 v[4:5], s[10:11], 0, v[4:5]
	v_lshl_add_u64 v[4:5], v[16:17], 1, v[4:5]
	s_waitcnt lgkmcnt(0)
	global_store_dwordx4 v[4:5], v[8:11], off
	v_ashrrev_i32_e32 v4, 31, v2
	v_lshrrev_b32_e32 v4, 28, v4
	v_add_u32_e32 v4, v2, v4
	v_ashrrev_i32_e32 v8, 4, v4
	v_lshlrev_b32_e32 v5, 7, v8
	v_lshlrev_b32_e32 v2, 3, v2
	v_ashrrev_i32_e32 v9, 31, v8
	v_mul_lo_u32 v4, v8, s83
	v_sub_u32_e32 v10, v2, v5
	v_lshl_add_u64 v[8:9], s[12:13], 0, v[8:9]
	v_add_lshl_u32 v2, v10, v4, 1
	v_lshlrev_b64 v[8:9], 11, v[8:9]
	ds_read_b128 v[4:7], v2
	v_lshl_add_u64 v[8:9], s[10:11], 0, v[8:9]
	v_ashrrev_i32_e32 v11, 31, v10
	v_add_u32_e32 v2, 0x700, v1
	v_lshl_add_u64 v[12:13], v[10:11], 1, v[8:9]
	v_ashrrev_i32_e32 v8, 31, v2
	v_lshrrev_b32_e32 v8, 28, v8
	v_add_u32_e32 v8, v2, v8
	v_ashrrev_i32_e32 v14, 4, v8
	v_lshlrev_b32_e32 v9, 7, v14
	v_lshlrev_b32_e32 v2, 3, v2
	v_mul_lo_u32 v8, v14, s83
	v_sub_u32_e32 v16, v2, v9
	v_add_lshl_u32 v2, v16, v8, 1
	ds_read_b128 v[8:11], v2
	v_ashrrev_i32_e32 v15, 31, v14
	s_waitcnt lgkmcnt(1)
	global_store_dwordx4 v[12:13], v[4:7], off
	v_ashrrev_i32_e32 v17, 31, v16
	v_add_u32_e32 v2, 0x800, v1
	v_lshl_add_u64 v[4:5], s[12:13], 0, v[14:15]
	v_lshlrev_b64 v[4:5], 11, v[4:5]
	v_lshl_add_u64 v[4:5], s[10:11], 0, v[4:5]
	v_lshl_add_u64 v[4:5], v[16:17], 1, v[4:5]
	s_waitcnt lgkmcnt(0)
; DEVI int get_tid() { int t = threadIdx.x; asm volatile("" : "+v"(t)); return t; }
; template <int BN>
; DEVI void tile_store256(const char* smem, bf* __restrict__ C, long ldc, long row0, int col0) {
;   constexpr int LDT = BN + 8;
;   constexpr int CPR = BN / 8;
;   const int tid = get_tid();
; #pragma unroll
;   for (int i = 0; i < CPR; ++i) {
;     const int q = tid + 256 * i;
;     const int r = q / CPR, c = q - r * CPR;
;     u32x4 v = *reinterpret_cast<const u32x4*>(smem + (r * LDT + c * 8) * 2);
;     *reinterpret_cast<u32x4*>(C + (row0 + r) * ldc + col0 + c * 8) = v;
;   }
; }
; DEVI void phase_gemm_plain128(const bf* A, int lda, const bf* Wt, int K, int N, bf* C, int ldc, char* smem) {
;     ...
;   for (int v = blockIdx.x; v < 128 * ntn; v += gridDim.x) {
;     int m2, nt;
;     lat_tile_map256(v, ntn, m2, nt);
;     plain_tile256(A, lda, Wt, K, C, ldc, lat_row0_256(m2), nt * 128, smem);
	global_store_dwordx4 v[4:5], v[8:11], off
	v_ashrrev_i32_e32 v4, 31, v2
	v_lshrrev_b32_e32 v4, 28, v4
	v_add_u32_e32 v4, v2, v4
	v_ashrrev_i32_e32 v8, 4, v4
	v_lshlrev_b32_e32 v5, 7, v8
	v_lshlrev_b32_e32 v2, 3, v2
	v_ashrrev_i32_e32 v9, 31, v8
	v_mul_lo_u32 v4, v8, s83
	v_sub_u32_e32 v10, v2, v5
	v_lshl_add_u64 v[8:9], s[12:13], 0, v[8:9]
	v_add_lshl_u32 v2, v10, v4, 1
	v_lshlrev_b64 v[8:9], 11, v[8:9]
	ds_read_b128 v[4:7], v2
	v_lshl_add_u64 v[8:9], s[10:11], 0, v[8:9]
	v_ashrrev_i32_e32 v11, 31, v10
	v_add_u32_e32 v2, 0x900, v1
	v_lshl_add_u64 v[12:13], v[10:11], 1, v[8:9]
	v_ashrrev_i32_e32 v8, 31, v2
	v_lshrrev_b32_e32 v8, 28, v8
	v_add_u32_e32 v8, v2, v8
	v_ashrrev_i32_e32 v14, 4, v8
	v_lshlrev_b32_e32 v9, 7, v14
	v_lshlrev_b32_e32 v2, 3, v2
	v_mul_lo_u32 v8, v14, s83
	v_sub_u32_e32 v16, v2, v9
	v_add_lshl_u32 v2, v16, v8, 1
	ds_read_b128 v[8:11], v2
	v_ashrrev_i32_e32 v15, 31, v14
	s_waitcnt lgkmcnt(1)
	global_store_dwordx4 v[12:13], v[4:7], off
	v_ashrrev_i32_e32 v17, 31, v16
	v_add_u32_e32 v2, 0xa00, v1
	v_lshl_add_u64 v[4:5], s[12:13], 0, v[14:15]
	v_lshlrev_b64 v[4:5], 11, v[4:5]
	v_lshl_add_u64 v[4:5], s[10:11], 0, v[4:5]
	v_lshl_add_u64 v[4:5], v[16:17], 1, v[4:5]
	s_waitcnt lgkmcnt(0)
	global_store_dwordx4 v[4:5], v[8:11], off
	v_ashrrev_i32_e32 v4, 31, v2
	v_lshrrev_b32_e32 v4, 28, v4
	v_add_u32_e32 v4, v2, v4
	v_ashrrev_i32_e32 v8, 4, v4
	v_lshlrev_b32_e32 v5, 7, v8
	v_lshlrev_b32_e32 v2, 3, v2
	v_ashrrev_i32_e32 v9, 31, v8
	v_mul_lo_u32 v4, v8, s83
	v_sub_u32_e32 v10, v2, v5
	v_lshl_add_u64 v[8:9], s[12:13], 0, v[8:9]
	v_add_lshl_u32 v2, v10, v4, 1
	v_lshlrev_b64 v[8:9], 11, v[8:9]
	ds_read_b128 v[4:7], v2
	v_lshl_add_u64 v[8:9], s[10:11], 0, v[8:9]
	v_ashrrev_i32_e32 v11, 31, v10
	v_add_u32_e32 v2, 0xb00, v1
	v_lshl_add_u64 v[12:13], v[10:11], 1, v[8:9]
	v_ashrrev_i32_e32 v8, 31, v2
	v_lshrrev_b32_e32 v8, 28, v8
	v_add_u32_e32 v8, v2, v8
	v_ashrrev_i32_e32 v14, 4, v8
	v_lshlrev_b32_e32 v9, 7, v14
	v_lshlrev_b32_e32 v2, 3, v2
	v_mul_lo_u32 v8, v14, s83
	v_sub_u32_e32 v16, v2, v9
	v_add_lshl_u32 v2, v16, v8, 1
	ds_read_b128 v[8:11], v2
	v_ashrrev_i32_e32 v15, 31, v14
	s_waitcnt lgkmcnt(1)
	global_store_dwordx4 v[12:13], v[4:7], off
	v_ashrrev_i32_e32 v17, 31, v16
	v_add_u32_e32 v2, 0xc00, v1
	v_lshl_add_u64 v[4:5], s[12:13], 0, v[14:15]
	v_lshlrev_b64 v[4:5], 11, v[4:5]
	v_lshl_add_u64 v[4:5], s[10:11], 0, v[4:5]
	v_lshl_add_u64 v[4:5], v[16:17], 1, v[4:5]
	s_waitcnt lgkmcnt(0)
	global_store_dwordx4 v[4:5], v[8:11], off
	v_ashrrev_i32_e32 v4, 31, v2
	v_lshrrev_b32_e32 v4, 28, v4
	v_add_u32_e32 v4, v2, v4
	v_ashrrev_i32_e32 v8, 4, v4
	v_lshlrev_b32_e32 v5, 7, v8
	v_lshlrev_b32_e32 v2, 3, v2
	v_ashrrev_i32_e32 v9, 31, v8
	v_mul_lo_u32 v4, v8, s83
	v_sub_u32_e32 v10, v2, v5
	v_lshl_add_u64 v[8:9], s[12:13], 0, v[8:9]
	v_add_lshl_u32 v2, v10, v4, 1
	v_lshlrev_b64 v[8:9], 11, v[8:9]
	ds_read_b128 v[4:7], v2
	v_lshl_add_u64 v[8:9], s[10:11], 0, v[8:9]
	v_ashrrev_i32_e32 v11, 31, v10
	v_add_u32_e32 v2, 0xd00, v1
	v_lshl_add_u64 v[12:13], v[10:11], 1, v[8:9]
	v_ashrrev_i32_e32 v8, 31, v2
	v_lshrrev_b32_e32 v8, 28, v8
	v_add_u32_e32 v8, v2, v8
	v_ashrrev_i32_e32 v14, 4, v8
	v_lshlrev_b32_e32 v9, 7, v14
	v_lshlrev_b32_e32 v2, 3, v2
	v_mul_lo_u32 v8, v14, s83
	v_sub_u32_e32 v16, v2, v9
	v_add_lshl_u32 v2, v16, v8, 1
	ds_read_b128 v[8:11], v2
	v_ashrrev_i32_e32 v15, 31, v14
	s_waitcnt lgkmcnt(1)
	global_store_dwordx4 v[12:13], v[4:7], off
	v_ashrrev_i32_e32 v17, 31, v16
	v_add_u32_e32 v2, 0xe00, v1
	v_lshl_add_u64 v[4:5], s[12:13], 0, v[14:15]
	v_lshlrev_b64 v[4:5], 11, v[4:5]
	v_lshl_add_u64 v[4:5], s[10:11], 0, v[4:5]
	v_lshl_add_u64 v[4:5], v[16:17], 1, v[4:5]
	s_waitcnt lgkmcnt(0)
	global_store_dwordx4 v[4:5], v[8:11], off
	v_ashrrev_i32_e32 v4, 31, v2
	v_lshrrev_b32_e32 v4, 28, v4
	v_add_u32_e32 v4, v2, v4
	v_ashrrev_i32_e32 v8, 4, v4
	v_lshlrev_b32_e32 v5, 7, v8
	v_lshlrev_b32_e32 v2, 3, v2
	v_mul_lo_u32 v4, v8, s83
	v_sub_u32_e32 v10, v2, v5
	v_add_lshl_u32 v2, v10, v4, 1
	v_add_u32_e32 v1, 0xf00, v1
	ds_read_b128 v[4:7], v2
	v_ashrrev_i32_e32 v9, 31, v8
	v_ashrrev_i32_e32 v2, 31, v1
	v_lshl_add_u64 v[8:9], s[12:13], 0, v[8:9]
	v_lshrrev_b32_e32 v2, 28, v2
	v_lshlrev_b64 v[8:9], 11, v[8:9]
	v_add_u32_e32 v2, v1, v2
	v_lshl_add_u64 v[8:9], s[10:11], 0, v[8:9]
	v_ashrrev_i32_e32 v11, 31, v10
	v_ashrrev_i32_e32 v14, 4, v2
	v_lshl_add_u64 v[12:13], v[10:11], 1, v[8:9]
	v_lshlrev_b32_e32 v8, 7, v14
	v_lshlrev_b32_e32 v1, 3, v1
	v_mul_lo_u32 v2, v14, s83
	v_sub_u32_e32 v16, v1, v8
	v_add_lshl_u32 v1, v16, v2, 1
	v_ashrrev_i32_e32 v15, 31, v14
	ds_read_b128 v[8:11], v1
	s_waitcnt lgkmcnt(1)
	global_store_dwordx4 v[12:13], v[4:7], off
	v_ashrrev_i32_e32 v17, 31, v16
	v_readlane_b32 s58, v251, 60
	v_lshl_add_u64 v[4:5], s[12:13], 0, v[14:15]
	v_lshlrev_b64 v[4:5], 11, v[4:5]
	v_lshl_add_u64 v[4:5], s[10:11], 0, v[4:5]
	v_readlane_b32 s10, v252, 59
	s_add_i32 s2, s2, s10
	v_readlane_b32 s59, v251, 61
	v_lshl_add_u64 v[4:5], v[16:17], 1, v[4:5]
	s_cmpk_gt_i32 s2, 0x3ff
	s_movk_i32 s27, 0x100
	v_readlane_b32 s57, v251, 59
	v_readlane_b32 s62, v252, 0
	v_readlane_b32 s63, v252, 1
	v_readlane_b32 s64, v252, 2
	v_readlane_b32 s65, v252, 3
	v_readlane_b32 s66, v252, 4
	v_readlane_b32 s67, v252, 5
	v_readlane_b32 s68, v252, 6
	v_readlane_b32 s69, v252, 7
	v_readlane_b32 s70, v252, 8
	v_readlane_b32 s71, v252, 9
	s_waitcnt lgkmcnt(0)
	global_store_dwordx4 v[4:5], v[8:11], off
	s_barrier
	v_readlane_b32 s11, v252, 60
	s_cbranch_scc0 .LBB0_205

; DEVI f32x4 mfma16(bf16x8 a, bf16x8 b, f32x4 c) { return __builtin_amdgcn_mfma_f32_16x16x32_bf16(a, b, c, 0, 0, 0); }
; DEVI void gemm_core3(f32x4 (&acc)[8][4], const bf* __restrict__ A, int lda, const bf* __restrict__ Bt, int ldb, int K, char* smem) {
;     ...
;   for (int kt = 0; kt < nk; ++kt) {
;     const int k1 = min((kt + 1) * 32, klast);
;     const int sn = ((kt + 1) & 1) * STG;
;     const int so = (kt & 1) * STG;
;     bf16x8 bfr[4], af[8];
; #pragma unroll
;     for (int n = 0; n < 4; ++n) bfr[n] = *reinterpret_cast<const bf16x8*>(bbase + so + n * 16 * 64);
; #pragma unroll
;     for (int m = 0; m < 8; ++m) af[m] = *reinterpret_cast<const bf16x8*>(abase + so + m * 16 * 64);
; #pragma unroll
;     for (int i = 0; i < 4; ++i) glds16(Ap + i * sa + k1, dbase + sn + i * 4096);
; #pragma unroll
;     for (int i = 0; i < 2; ++i) glds16(Bp + i * sb + k1, dbase + sn + ASZ + i * 4096);
;     __builtin_amdgcn_s_setprio(1);
; #pragma unroll
;     for (int m = 0; m < 8; ++m)
; #pragma unroll
;       for (int n = 0; n < 4; ++n) acc[m][n] = mfma16(af[m], bfr[n], acc[m][n]);
;     __builtin_amdgcn_s_setprio(0);
;     __syncthreads();
;   }
.Lg3_loop_904:
	v_add_u32_e32 v216, s10, v146
	v_add_u32_e32 v217, s10, v2
	ds_read_b128 v[148:151], v217 offset:16384
	ds_read_b128 v[166:169], v216
	ds_read_b128 v[154:157], v217 offset:17408
	ds_read_b128 v[158:161], v217 offset:18432
	ds_read_b128 v[162:165], v217 offset:19456
	ds_read_b128 v[170:173], v216 offset:1024
	ds_read_b128 v[174:177], v216 offset:2048
	ds_read_b128 v[192:195], v216 offset:3072
	ds_read_b128 v[196:199], v216 offset:4096
	ds_read_b128 v[204:207], v216 offset:5120
	ds_read_b128 v[208:211], v216 offset:6144
	ds_read_b128 v[212:215], v216 offset:7168
	s_setprio 1
	s_waitcnt lgkmcnt(10)
	v_mfma_f32_16x16x32_bf16 v[128:131], v[166:169], v[148:151], v[128:131]
	s_waitcnt lgkmcnt(9)
	v_mfma_f32_16x16x32_bf16 v[124:127], v[166:169], v[154:157], v[124:127]
	s_waitcnt lgkmcnt(8)
	v_mfma_f32_16x16x32_bf16 v[120:123], v[166:169], v[158:161], v[120:123]
	s_waitcnt lgkmcnt(7)
	v_mfma_f32_16x16x32_bf16 v[116:119], v[166:169], v[162:165], v[116:119]
	s_waitcnt lgkmcnt(6)
	v_mfma_f32_16x16x32_bf16 v[112:115], v[170:173], v[148:151], v[112:115]
	v_mfma_f32_16x16x32_bf16 v[108:111], v[170:173], v[154:157], v[108:111]
	v_mfma_f32_16x16x32_bf16 v[104:107], v[170:173], v[158:161], v[104:107]
	v_mfma_f32_16x16x32_bf16 v[100:103], v[170:173], v[162:165], v[100:103]
	s_waitcnt lgkmcnt(5)
	v_mfma_f32_16x16x32_bf16 v[96:99], v[174:177], v[148:151], v[96:99]
	v_mfma_f32_16x16x32_bf16 v[92:95], v[174:177], v[154:157], v[92:95]
	v_mfma_f32_16x16x32_bf16 v[88:91], v[174:177], v[158:161], v[88:91]
	v_mfma_f32_16x16x32_bf16 v[84:87], v[174:177], v[162:165], v[84:87]
	s_waitcnt lgkmcnt(4)
	v_mfma_f32_16x16x32_bf16 v[80:83], v[192:195], v[148:151], v[80:83]
	v_mfma_f32_16x16x32_bf16 v[76:79], v[192:195], v[154:157], v[76:79]
	v_mfma_f32_16x16x32_bf16 v[72:75], v[192:195], v[158:161], v[72:75]
	v_mfma_f32_16x16x32_bf16 v[68:71], v[192:195], v[162:165], v[68:71]
	s_waitcnt lgkmcnt(3)
	v_mfma_f32_16x16x32_bf16 v[64:67], v[196:199], v[148:151], v[64:67]
	v_mfma_f32_16x16x32_bf16 v[60:63], v[196:199], v[154:157], v[60:63]
	v_mfma_f32_16x16x32_bf16 v[56:59], v[196:199], v[158:161], v[56:59]
	v_mfma_f32_16x16x32_bf16 v[52:55], v[196:199], v[162:165], v[52:55]
	s_waitcnt lgkmcnt(2)
	v_mfma_f32_16x16x32_bf16 v[48:51], v[204:207], v[148:151], v[48:51]
	v_mfma_f32_16x16x32_bf16 v[44:47], v[204:207], v[154:157], v[44:47]
	v_mfma_f32_16x16x32_bf16 v[40:43], v[204:207], v[158:161], v[40:43]
	v_mfma_f32_16x16x32_bf16 v[36:39], v[204:207], v[162:165], v[36:39]
	s_waitcnt lgkmcnt(1)
	v_mfma_f32_16x16x32_bf16 v[32:35], v[208:211], v[148:151], v[32:35]
	v_mfma_f32_16x16x32_bf16 v[28:31], v[208:211], v[154:157], v[28:31]
	v_mfma_f32_16x16x32_bf16 v[24:27], v[208:211], v[158:161], v[24:27]
	v_mfma_f32_16x16x32_bf16 v[20:23], v[208:211], v[162:165], v[20:23]
	s_waitcnt lgkmcnt(0)
	v_mfma_f32_16x16x32_bf16 v[16:19], v[212:215], v[148:151], v[16:19]
	v_mfma_f32_16x16x32_bf16 v[12:15], v[212:215], v[154:157], v[12:15]
	v_mfma_f32_16x16x32_bf16 v[8:11], v[212:215], v[158:161], v[8:11]
	v_mfma_f32_16x16x32_bf16 v[4:7], v[212:215], v[162:165], v[4:7]
	s_setprio 0
	s_add_i32 s10, s10, 0x6000
	s_cmp_lg_u32 s10, 0x12000
	s_cselect_b32 s10, s10, 0
	s_waitcnt vmcnt(0)
	s_barrier
	v_add_u32_e32 v216, s10, v146
	v_add_u32_e32 v217, s10, v2
	ds_read_b128 v[148:151], v217 offset:16384
	ds_read_b128 v[166:169], v216
	ds_read_b128 v[154:157], v217 offset:17408
	ds_read_b128 v[158:161], v217 offset:18432
	ds_read_b128 v[162:165], v217 offset:19456
	ds_read_b128 v[170:173], v216 offset:1024
	ds_read_b128 v[174:177], v216 offset:2048
	ds_read_b128 v[192:195], v216 offset:3072
	ds_read_b128 v[196:199], v216 offset:4096
	ds_read_b128 v[204:207], v216 offset:5120
	ds_read_b128 v[208:211], v216 offset:6144
	ds_read_b128 v[212:215], v216 offset:7168
	v_readfirstlane_b32 s17, v140
	s_add_i32 s96, s11, 0x6000
	s_cmp_lg_u32 s96, 0x12000
	s_cselect_b32 s96, s96, 0
	s_add_i32 s96, s96, s17
	s_add_i32 s17, s17, s11
	s_setprio 2
	s_waitcnt lgkmcnt(10)
	s_mov_b32 m0, s17
	s_add_i32 s17, s17, 0x1000
	v_mfma_f32_16x16x32_bf16 v[128:131], v[166:169], v[148:151], v[128:131]
	s_waitcnt lgkmcnt(9)
	v_mfma_f32_16x16x32_bf16 v[124:127], v[166:169], v[154:157], v[124:127]
	global_load_lds_dwordx4 v[218:219], off
	v_lshl_add_u64 v[218:219], v[218:219], 0, 64
	s_waitcnt lgkmcnt(8)
	s_mov_b32 m0, s96
	s_add_i32 s96, s96, 0x1000
	v_mfma_f32_16x16x32_bf16 v[120:123], v[166:169], v[158:161], v[120:123]
	s_waitcnt lgkmcnt(7)
	v_mfma_f32_16x16x32_bf16 v[116:119], v[166:169], v[162:165], v[116:119]
	global_load_lds_dwordx4 v[218:219], off
	v_lshl_add_u64 v[218:219], v[218:219], 0, 64
	s_waitcnt lgkmcnt(6)
	v_mfma_f32_16x16x32_bf16 v[112:115], v[170:173], v[148:151], v[112:115]
	s_mov_b32 m0, s17
	s_add_i32 s17, s17, 0x1000
	v_mfma_f32_16x16x32_bf16 v[108:111], v[170:173], v[154:157], v[108:111]
	v_mfma_f32_16x16x32_bf16 v[104:107], v[170:173], v[158:161], v[104:107]
	global_load_lds_dwordx4 v[220:221], off
	v_lshl_add_u64 v[220:221], v[220:221], 0, 64
	s_mov_b32 m0, s96
	s_add_i32 s96, s96, 0x1000
	v_mfma_f32_16x16x32_bf16 v[100:103], v[170:173], v[162:165], v[100:103]
	s_waitcnt lgkmcnt(5)
	v_mfma_f32_16x16x32_bf16 v[96:99], v[174:177], v[148:151], v[96:99]
	global_load_lds_dwordx4 v[220:221], off
	v_lshl_add_u64 v[220:221], v[220:221], 0, 64
	v_mfma_f32_16x16x32_bf16 v[92:95], v[174:177], v[154:157], v[92:95]
	s_mov_b32 m0, s17
	s_add_i32 s17, s17, 0x1000
	v_mfma_f32_16x16x32_bf16 v[88:91], v[174:177], v[158:161], v[88:91]
	v_mfma_f32_16x16x32_bf16 v[84:87], v[174:177], v[162:165], v[84:87]
	global_load_lds_dwordx4 v[222:223], off
	v_lshl_add_u64 v[222:223], v[222:223], 0, 64
	s_waitcnt lgkmcnt(4)
; DEVI f32x4 mfma16(bf16x8 a, bf16x8 b, f32x4 c) { return __builtin_amdgcn_mfma_f32_16x16x32_bf16(a, b, c, 0, 0, 0); }
; DEVI void gemm_core3(f32x4 (&acc)[8][4], const bf* __restrict__ A, int lda, const bf* __restrict__ Bt, int ldb, int K, char* smem) {
;     ...
;   for (int kt = 0; kt < nk; ++kt) {
;     const int k1 = min((kt + 1) * 32, klast);
;     const int sn = ((kt + 1) & 1) * STG;
;     const int so = (kt & 1) * STG;
;     bf16x8 bfr[4], af[8];
; #pragma unroll
;     for (int n = 0; n < 4; ++n) bfr[n] = *reinterpret_cast<const bf16x8*>(bbase + so + n * 16 * 64);
; #pragma unroll
;     for (int m = 0; m < 8; ++m) af[m] = *reinterpret_cast<const bf16x8*>(abase + so + m * 16 * 64);
; #pragma unroll
;     for (int i = 0; i < 4; ++i) glds16(Ap + i * sa + k1, dbase + sn + i * 4096);
; #pragma unroll
;     for (int i = 0; i < 2; ++i) glds16(Bp + i * sb + k1, dbase + sn + ASZ + i * 4096);
;     __builtin_amdgcn_s_setprio(1);
; #pragma unroll
;     for (int m = 0; m < 8; ++m)
; #pragma unroll
;       for (int n = 0; n < 4; ++n) acc[m][n] = mfma16(af[m], bfr[n], acc[m][n]);
;     __builtin_amdgcn_s_setprio(0);
;     __syncthreads();
;   }
	s_mov_b32 m0, s96
	s_add_i32 s96, s96, 0x1000
	v_mfma_f32_16x16x32_bf16 v[80:83], v[192:195], v[148:151], v[80:83]
	v_mfma_f32_16x16x32_bf16 v[76:79], v[192:195], v[154:157], v[76:79]
	global_load_lds_dwordx4 v[222:223], off
	v_lshl_add_u64 v[222:223], v[222:223], 0, 64
	v_mfma_f32_16x16x32_bf16 v[72:75], v[192:195], v[158:161], v[72:75]
	s_mov_b32 m0, s17
	s_add_i32 s17, s17, 0x1000
	v_mfma_f32_16x16x32_bf16 v[68:71], v[192:195], v[162:165], v[68:71]
	s_waitcnt lgkmcnt(3)
	v_mfma_f32_16x16x32_bf16 v[64:67], v[196:199], v[148:151], v[64:67]
	global_load_lds_dwordx4 v[224:225], off
	v_lshl_add_u64 v[224:225], v[224:225], 0, 64
	s_mov_b32 m0, s96
	s_add_i32 s96, s96, 0x1000
	v_mfma_f32_16x16x32_bf16 v[60:63], v[196:199], v[154:157], v[60:63]
	v_mfma_f32_16x16x32_bf16 v[56:59], v[196:199], v[158:161], v[56:59]
	global_load_lds_dwordx4 v[224:225], off
	v_lshl_add_u64 v[224:225], v[224:225], 0, 64
	v_mfma_f32_16x16x32_bf16 v[52:55], v[196:199], v[162:165], v[52:55]
	s_waitcnt lgkmcnt(2)
	s_mov_b32 m0, s17
	s_add_i32 s17, s17, 0x1000
	v_mfma_f32_16x16x32_bf16 v[48:51], v[204:207], v[148:151], v[48:51]
	v_mfma_f32_16x16x32_bf16 v[44:47], v[204:207], v[154:157], v[44:47]
	global_load_lds_dwordx4 v[226:227], off
	v_lshl_add_u64 v[226:227], v[226:227], 0, 64
	s_mov_b32 m0, s96
	s_add_i32 s96, s96, 0x1000
	v_mfma_f32_16x16x32_bf16 v[40:43], v[204:207], v[158:161], v[40:43]
	v_mfma_f32_16x16x32_bf16 v[36:39], v[204:207], v[162:165], v[36:39]
	global_load_lds_dwordx4 v[226:227], off
	v_lshl_add_u64 v[226:227], v[226:227], 0, 64
	s_waitcnt lgkmcnt(1)
	v_mfma_f32_16x16x32_bf16 v[32:35], v[208:211], v[148:151], v[32:35]
	s_mov_b32 m0, s17
	s_add_i32 s17, s17, 0x1000
	v_mfma_f32_16x16x32_bf16 v[28:31], v[208:211], v[154:157], v[28:31]
	v_mfma_f32_16x16x32_bf16 v[24:27], v[208:211], v[158:161], v[24:27]
	global_load_lds_dwordx4 v[228:229], off
	v_lshl_add_u64 v[228:229], v[228:229], 0, 64
	s_mov_b32 m0, s96
	s_add_i32 s96, s96, 0x1000
	v_mfma_f32_16x16x32_bf16 v[20:23], v[208:211], v[162:165], v[20:23]
	s_waitcnt lgkmcnt(0)
	v_mfma_f32_16x16x32_bf16 v[16:19], v[212:215], v[148:151], v[16:19]
	global_load_lds_dwordx4 v[228:229], off
	v_lshl_add_u64 v[228:229], v[228:229], 0, 64
	v_mfma_f32_16x16x32_bf16 v[12:15], v[212:215], v[154:157], v[12:15]
	v_mfma_f32_16x16x32_bf16 v[8:11], v[212:215], v[158:161], v[8:11]
	v_mfma_f32_16x16x32_bf16 v[4:7], v[212:215], v[162:165], v[4:7]
	s_setprio 0
	s_add_i32 s10, s10, 0x6000
	s_cmp_lg_u32 s10, 0x12000
	s_cselect_b32 s10, s10, 0
	s_sub_i32 s11, s11, 0x6000
	s_cmp_lt_i32 s11, 0
	s_cselect_b32 s11, 0xc000, s11
	s_add_i32 s3, s3, 1
	s_cmp_lt_i32 s3, 15
	s_waitcnt vmcnt(1)
	s_barrier
	s_cbranch_scc1 .Lg3_loop_904
	v_add_u32_e32 v216, s10, v146
	v_add_u32_e32 v217, s10, v2
	ds_read_b128 v[148:151], v217 offset:16384
	ds_read_b128 v[166:169], v216
	ds_read_b128 v[154:157], v217 offset:17408
	ds_read_b128 v[158:161], v217 offset:18432
	ds_read_b128 v[162:165], v217 offset:19456
	ds_read_b128 v[170:173], v216 offset:1024
	ds_read_b128 v[174:177], v216 offset:2048
	ds_read_b128 v[192:195], v216 offset:3072
	ds_read_b128 v[196:199], v216 offset:4096
	ds_read_b128 v[204:207], v216 offset:5120
	ds_read_b128 v[208:211], v216 offset:6144
	ds_read_b128 v[212:215], v216 offset:7168
	s_setprio 1
	s_waitcnt lgkmcnt(10)
	v_mfma_f32_16x16x32_bf16 v[128:131], v[166:169], v[148:151], v[128:131]
	s_waitcnt lgkmcnt(9)
	v_mfma_f32_16x16x32_bf16 v[124:127], v[166:169], v[154:157], v[124:127]
	s_waitcnt lgkmcnt(8)
	v_mfma_f32_16x16x32_bf16 v[120:123], v[166:169], v[158:161], v[120:123]
	s_waitcnt lgkmcnt(7)
	v_mfma_f32_16x16x32_bf16 v[116:119], v[166:169], v[162:165], v[116:119]
	s_waitcnt lgkmcnt(6)
	v_mfma_f32_16x16x32_bf16 v[112:115], v[170:173], v[148:151], v[112:115]
	v_mfma_f32_16x16x32_bf16 v[108:111], v[170:173], v[154:157], v[108:111]
	v_mfma_f32_16x16x32_bf16 v[104:107], v[170:173], v[158:161], v[104:107]
	v_mfma_f32_16x16x32_bf16 v[100:103], v[170:173], v[162:165], v[100:103]
	s_waitcnt lgkmcnt(5)
	v_mfma_f32_16x16x32_bf16 v[96:99], v[174:177], v[148:151], v[96:99]
	v_mfma_f32_16x16x32_bf16 v[92:95], v[174:177], v[154:157], v[92:95]
	v_mfma_f32_16x16x32_bf16 v[88:91], v[174:177], v[158:161], v[88:91]
	v_mfma_f32_16x16x32_bf16 v[84:87], v[174:177], v[162:165], v[84:87]
	s_waitcnt lgkmcnt(4)
	v_mfma_f32_16x16x32_bf16 v[80:83], v[192:195], v[148:151], v[80:83]
	v_mfma_f32_16x16x32_bf16 v[76:79], v[192:195], v[154:157], v[76:79]
	v_mfma_f32_16x16x32_bf16 v[72:75], v[192:195], v[158:161], v[72:75]
	v_mfma_f32_16x16x32_bf16 v[68:71], v[192:195], v[162:165], v[68:71]
	s_waitcnt lgkmcnt(3)
	v_mfma_f32_16x16x32_bf16 v[64:67], v[196:199], v[148:151], v[64:67]
	v_mfma_f32_16x16x32_bf16 v[60:63], v[196:199], v[154:157], v[60:63]
	v_mfma_f32_16x16x32_bf16 v[56:59], v[196:199], v[158:161], v[56:59]
	v_mfma_f32_16x16x32_bf16 v[52:55], v[196:199], v[162:165], v[52:55]
	s_waitcnt lgkmcnt(2)
	v_mfma_f32_16x16x32_bf16 v[48:51], v[204:207], v[148:151], v[48:51]
	v_mfma_f32_16x16x32_bf16 v[44:47], v[204:207], v[154:157], v[44:47]
	v_mfma_f32_16x16x32_bf16 v[40:43], v[204:207], v[158:161], v[40:43]
	v_mfma_f32_16x16x32_bf16 v[36:39], v[204:207], v[162:165], v[36:39]
	s_waitcnt lgkmcnt(1)
	v_mfma_f32_16x16x32_bf16 v[32:35], v[208:211], v[148:151], v[32:35]
	v_mfma_f32_16x16x32_bf16 v[28:31], v[208:211], v[154:157], v[28:31]
	v_mfma_f32_16x16x32_bf16 v[24:27], v[208:211], v[158:161], v[24:27]
	v_mfma_f32_16x16x32_bf16 v[20:23], v[208:211], v[162:165], v[20:23]
	s_waitcnt lgkmcnt(0)
	v_mfma_f32_16x16x32_bf16 v[16:19], v[212:215], v[148:151], v[16:19]
	v_mfma_f32_16x16x32_bf16 v[12:15], v[212:215], v[154:157], v[12:15]
	v_mfma_f32_16x16x32_bf16 v[8:11], v[212:215], v[158:161], v[8:11]
	v_mfma_f32_16x16x32_bf16 v[4:7], v[212:215], v[162:165], v[4:7]
	s_setprio 0
	s_add_i32 s10, s10, 0x6000
	s_cmp_lg_u32 s10, 0x12000
	s_cselect_b32 s10, s10, 0
	s_waitcnt vmcnt(0)
	s_barrier
; DEVI f32x4 mfma16(bf16x8 a, bf16x8 b, f32x4 c) { return __builtin_amdgcn_mfma_f32_16x16x32_bf16(a, b, c, 0, 0, 0); }
; DEVI void gemm_core3(f32x4 (&acc)[8][4], const bf* __restrict__ A, int lda, const bf* __restrict__ Bt, int ldb, int K, char* smem) {
;     ...
;     bf16x8 bfr[4], af[8];
; #pragma unroll
;     for (int n = 0; n < 4; ++n) bfr[n] = *reinterpret_cast<const bf16x8*>(bbase + so + n * 16 * 64);
; #pragma unroll
;     for (int m = 0; m < 8; ++m) af[m] = *reinterpret_cast<const bf16x8*>(abase + so + m * 16 * 64);
; #pragma unroll
;     for (int i = 0; i < 4; ++i) glds16(Ap + i * sa + k1, dbase + sn + i * 4096);
; #pragma unroll
;     for (int i = 0; i < 2; ++i) glds16(Bp + i * sb + k1, dbase + sn + ASZ + i * 4096);
;     __builtin_amdgcn_s_setprio(1);
; #pragma unroll
;     for (int m = 0; m < 8; ++m)
; #pragma unroll
;       for (int n = 0; n < 4; ++n) acc[m][n] = mfma16(af[m], bfr[n], acc[m][n]);
;     __builtin_amdgcn_s_setprio(0);
; DEVI void plain_tile256(const bf* A, int lda, const bf* Wt, int K, bf* C, int ldc, long row0, int n0, char* smem) {
;     ...
;   bf* tl = reinterpret_cast<bf*>(smem);
; #pragma unroll
;   for (int m = 0; m < 8; ++m)
; #pragma unroll
;     for (int n = 0; n < 4; ++n) {
;       const int cl = wc * 64 + n * 16 + l15;
; #pragma unroll
;       for (int j = 0; j < 4; ++j) tl[(wr * 128 + m * 16 + quad * 4 + j) * 136 + cl] = f2bf(acc[m][n][j]);
;     }
	v_add_u32_e32 v216, s10, v146
	v_add_u32_e32 v217, s10, v2
	ds_read_b128 v[148:151], v217 offset:16384
	ds_read_b128 v[166:169], v216
	ds_read_b128 v[154:157], v217 offset:17408
	ds_read_b128 v[158:161], v217 offset:18432
	ds_read_b128 v[162:165], v217 offset:19456
	ds_read_b128 v[170:173], v216 offset:1024
	ds_read_b128 v[174:177], v216 offset:2048
	ds_read_b128 v[192:195], v216 offset:3072
	ds_read_b128 v[196:199], v216 offset:4096
	ds_read_b128 v[204:207], v216 offset:5120
	ds_read_b128 v[208:211], v216 offset:6144
	ds_read_b128 v[212:215], v216 offset:7168
	s_setprio 1
	s_waitcnt lgkmcnt(10)
	v_mfma_f32_16x16x32_bf16 v[128:131], v[166:169], v[148:151], v[128:131]
	s_waitcnt lgkmcnt(9)
	v_mfma_f32_16x16x32_bf16 v[124:127], v[166:169], v[154:157], v[124:127]
	s_waitcnt lgkmcnt(8)
	v_mfma_f32_16x16x32_bf16 v[120:123], v[166:169], v[158:161], v[120:123]
	s_waitcnt lgkmcnt(7)
	v_mfma_f32_16x16x32_bf16 v[116:119], v[166:169], v[162:165], v[116:119]
	s_waitcnt lgkmcnt(6)
	v_mfma_f32_16x16x32_bf16 v[112:115], v[170:173], v[148:151], v[112:115]
	v_mfma_f32_16x16x32_bf16 v[108:111], v[170:173], v[154:157], v[108:111]
	v_mfma_f32_16x16x32_bf16 v[104:107], v[170:173], v[158:161], v[104:107]
	v_mfma_f32_16x16x32_bf16 v[100:103], v[170:173], v[162:165], v[100:103]
	s_waitcnt lgkmcnt(5)
	v_mfma_f32_16x16x32_bf16 v[96:99], v[174:177], v[148:151], v[96:99]
	v_mfma_f32_16x16x32_bf16 v[92:95], v[174:177], v[154:157], v[92:95]
	v_mfma_f32_16x16x32_bf16 v[88:91], v[174:177], v[158:161], v[88:91]
	v_mfma_f32_16x16x32_bf16 v[84:87], v[174:177], v[162:165], v[84:87]
	s_waitcnt lgkmcnt(4)
	v_mfma_f32_16x16x32_bf16 v[80:83], v[192:195], v[148:151], v[80:83]
	v_mfma_f32_16x16x32_bf16 v[76:79], v[192:195], v[154:157], v[76:79]
	v_mfma_f32_16x16x32_bf16 v[72:75], v[192:195], v[158:161], v[72:75]
	v_mfma_f32_16x16x32_bf16 v[68:71], v[192:195], v[162:165], v[68:71]
	s_waitcnt lgkmcnt(3)
	v_mfma_f32_16x16x32_bf16 v[64:67], v[196:199], v[148:151], v[64:67]
	v_mfma_f32_16x16x32_bf16 v[60:63], v[196:199], v[154:157], v[60:63]
	v_mfma_f32_16x16x32_bf16 v[56:59], v[196:199], v[158:161], v[56:59]
	v_mfma_f32_16x16x32_bf16 v[52:55], v[196:199], v[162:165], v[52:55]
	s_waitcnt lgkmcnt(2)
	v_mfma_f32_16x16x32_bf16 v[48:51], v[204:207], v[148:151], v[48:51]
	v_mfma_f32_16x16x32_bf16 v[44:47], v[204:207], v[154:157], v[44:47]
	v_mfma_f32_16x16x32_bf16 v[40:43], v[204:207], v[158:161], v[40:43]
	v_mfma_f32_16x16x32_bf16 v[36:39], v[204:207], v[162:165], v[36:39]
	s_waitcnt lgkmcnt(1)
	v_mfma_f32_16x16x32_bf16 v[32:35], v[208:211], v[148:151], v[32:35]
	v_mfma_f32_16x16x32_bf16 v[28:31], v[208:211], v[154:157], v[28:31]
	v_mfma_f32_16x16x32_bf16 v[24:27], v[208:211], v[158:161], v[24:27]
	v_mfma_f32_16x16x32_bf16 v[20:23], v[208:211], v[162:165], v[20:23]
	s_waitcnt lgkmcnt(0)
	v_mfma_f32_16x16x32_bf16 v[16:19], v[212:215], v[148:151], v[16:19]
	v_mfma_f32_16x16x32_bf16 v[12:15], v[212:215], v[154:157], v[12:15]
	v_mfma_f32_16x16x32_bf16 v[8:11], v[212:215], v[158:161], v[8:11]
	v_mfma_f32_16x16x32_bf16 v[4:7], v[212:215], v[162:165], v[4:7]
	s_setprio 0
	s_add_i32 s10, s10, 0x6000
	s_cmp_lg_u32 s10, 0x12000
	s_cselect_b32 s10, s10, 0
	s_waitcnt vmcnt(0)
	s_barrier
	v_and_b32_e32 v2, 0x4f, v1
	v_and_b32_e32 v132, 0xfffff80, v1
	v_lshrrev_b32_e32 v1, 2, v1
	v_and_or_b32 v1, v1, 12, v132
	v_mul_lo_u32 v1, v1, s16
	v_lshl_add_u32 v1, v2, 1, v1
	v_cvt_pk_bf16_f32 v2, v129, s0
	ds_write_b16 v1, v2 offset:272
	v_cvt_pk_bf16_f32 v2, v130, s0
	ds_write_b16 v1, v2 offset:544
	v_cvt_pk_bf16_f32 v2, v131, s0
	ds_write_b16 v1, v2 offset:816
	v_cvt_pk_bf16_f32 v2, v124, s0
	ds_write_b16 v1, v2 offset:32
	v_cvt_pk_bf16_f32 v2, v125, s0
	ds_write_b16 v1, v2 offset:304
	v_cvt_pk_bf16_f32 v2, v126, s0
	ds_write_b16 v1, v2 offset:576
	v_cvt_pk_bf16_f32 v2, v127, s0
	ds_write_b16 v1, v2 offset:848
	v_cvt_pk_bf16_f32 v2, v120, s0
	ds_write_b16 v1, v2 offset:64
	v_cvt_pk_bf16_f32 v2, v121, s0
	ds_write_b16 v1, v2 offset:336
	v_cvt_pk_bf16_f32 v2, v122, s0
	ds_write_b16 v1, v2 offset:608
	v_cvt_pk_bf16_f32 v2, v123, s0
	ds_write_b16 v1, v2 offset:880
	v_cvt_pk_bf16_f32 v2, v116, s0
	ds_write_b16 v1, v2 offset:96
	v_cvt_pk_bf16_f32 v2, v117, s0
	ds_write_b16 v1, v2 offset:368
	v_cvt_pk_bf16_f32 v2, v118, s0
	ds_write_b16 v1, v2 offset:640
	v_cvt_pk_bf16_f32 v2, v119, s0
	ds_write_b16 v1, v2 offset:912
	v_cvt_pk_bf16_f32 v2, v112, s0
	ds_write_b16 v1, v2 offset:4352
	v_cvt_pk_bf16_f32 v2, v113, s0
	ds_write_b16 v1, v2 offset:4624
	v_cvt_pk_bf16_f32 v2, v114, s0
	ds_write_b16 v1, v2 offset:4896
	v_cvt_pk_bf16_f32 v2, v115, s0
	ds_write_b16 v1, v2 offset:5168
	v_cvt_pk_bf16_f32 v2, v108, s0
	ds_write_b16 v1, v2 offset:4384
	v_cvt_pk_bf16_f32 v2, v109, s0
	ds_write_b16 v1, v2 offset:4656
	v_cvt_pk_bf16_f32 v2, v110, s0
	ds_write_b16 v1, v2 offset:4928
	v_cvt_pk_bf16_f32 v2, v111, s0
	ds_write_b16 v1, v2 offset:5200
	v_cvt_pk_bf16_f32 v2, v104, s0
	ds_write_b16 v1, v2 offset:4416
	v_cvt_pk_bf16_f32 v2, v105, s0
	ds_write_b16 v1, v2 offset:4688
	v_cvt_pk_bf16_f32 v2, v106, s0
	ds_write_b16 v1, v2 offset:4960
	v_cvt_pk_bf16_f32 v2, v107, s0
	ds_write_b16 v1, v2 offset:5232
	v_cvt_pk_bf16_f32 v2, v100, s0
	ds_write_b16 v1, v2 offset:4448
	v_cvt_pk_bf16_f32 v2, v101, s0
	ds_write_b16 v1, v2 offset:4720
	v_cvt_pk_bf16_f32 v2, v102, s0
	ds_write_b16 v1, v2 offset:4992
	v_cvt_pk_bf16_f32 v2, v103, s0
	ds_write_b16 v1, v2 offset:5264
	v_cvt_pk_bf16_f32 v2, v96, s0
	ds_write_b16 v1, v2 offset:8704
	v_cvt_pk_bf16_f32 v2, v97, s0
	ds_write_b16 v1, v2 offset:8976
	v_cvt_pk_bf16_f32 v2, v98, s0
	ds_write_b16 v1, v2 offset:9248
	v_cvt_pk_bf16_f32 v2, v99, s0
	ds_write_b16 v1, v2 offset:9520
	v_cvt_pk_bf16_f32 v2, v92, s0
; DEVI void plain_tile256(const bf* A, int lda, const bf* Wt, int K, bf* C, int ldc, long row0, int n0, char* smem) {
;     ...
; #pragma unroll
;   for (int m = 0; m < 8; ++m)
; #pragma unroll
;     for (int n = 0; n < 4; ++n) {
;       const int cl = wc * 64 + n * 16 + l15;
; #pragma unroll
;       for (int j = 0; j < 4; ++j) tl[(wr * 128 + m * 16 + quad * 4 + j) * 136 + cl] = f2bf(acc[m][n][j]);
;     }
;   __syncthreads();
	ds_write_b16 v1, v2 offset:8736
	v_cvt_pk_bf16_f32 v2, v93, s0
	ds_write_b16 v1, v2 offset:9008
	v_cvt_pk_bf16_f32 v2, v94, s0
	ds_write_b16 v1, v2 offset:9280
	v_cvt_pk_bf16_f32 v2, v95, s0
	ds_write_b16 v1, v2 offset:9552
	v_cvt_pk_bf16_f32 v2, v88, s0
	ds_write_b16 v1, v2 offset:8768
	v_cvt_pk_bf16_f32 v2, v89, s0
	ds_write_b16 v1, v2 offset:9040
	v_cvt_pk_bf16_f32 v2, v90, s0
	ds_write_b16 v1, v2 offset:9312
	v_cvt_pk_bf16_f32 v2, v91, s0
	ds_write_b16 v1, v2 offset:9584
	v_cvt_pk_bf16_f32 v2, v84, s0
	ds_write_b16 v1, v2 offset:8800
	v_cvt_pk_bf16_f32 v2, v85, s0
	ds_write_b16 v1, v2 offset:9072
	v_cvt_pk_bf16_f32 v2, v86, s0
	ds_write_b16 v1, v2 offset:9344
	v_cvt_pk_bf16_f32 v2, v87, s0
	ds_write_b16 v1, v2 offset:9616
	v_cvt_pk_bf16_f32 v2, v80, s0
	ds_write_b16 v1, v2 offset:13056
	v_cvt_pk_bf16_f32 v2, v81, s0
	ds_write_b16 v1, v2 offset:13328
	v_cvt_pk_bf16_f32 v2, v82, s0
	ds_write_b16 v1, v2 offset:13600
	v_cvt_pk_bf16_f32 v2, v83, s0
	ds_write_b16 v1, v2 offset:13872
	v_cvt_pk_bf16_f32 v2, v76, s0
	ds_write_b16 v1, v2 offset:13088
	v_cvt_pk_bf16_f32 v2, v77, s0
	ds_write_b16 v1, v2 offset:13360
	v_cvt_pk_bf16_f32 v2, v78, s0
	ds_write_b16 v1, v2 offset:13632
	v_cvt_pk_bf16_f32 v2, v79, s0
	ds_write_b16 v1, v2 offset:13904
	v_cvt_pk_bf16_f32 v2, v72, s0
	ds_write_b16 v1, v2 offset:13120
	v_cvt_pk_bf16_f32 v2, v73, s0
	ds_write_b16 v1, v2 offset:13392
	v_cvt_pk_bf16_f32 v2, v74, s0
	ds_write_b16 v1, v2 offset:13664
	v_cvt_pk_bf16_f32 v2, v75, s0
	ds_write_b16 v1, v2 offset:13936
	v_cvt_pk_bf16_f32 v2, v68, s0
	ds_write_b16 v1, v2 offset:13152
	v_cvt_pk_bf16_f32 v2, v69, s0
	ds_write_b16 v1, v2 offset:13424
	v_cvt_pk_bf16_f32 v2, v70, s0
	ds_write_b16 v1, v2 offset:13696
	v_cvt_pk_bf16_f32 v2, v71, s0
	ds_write_b16 v1, v2 offset:13968
	v_cvt_pk_bf16_f32 v2, v64, s0
	ds_write_b16 v1, v2 offset:17408
	v_cvt_pk_bf16_f32 v2, v65, s0
	ds_write_b16 v1, v2 offset:17680
	v_cvt_pk_bf16_f32 v2, v66, s0
	ds_write_b16 v1, v2 offset:17952
	v_cvt_pk_bf16_f32 v2, v67, s0
	ds_write_b16 v1, v2 offset:18224
	v_cvt_pk_bf16_f32 v2, v60, s0
	ds_write_b16 v1, v2 offset:17440
	v_cvt_pk_bf16_f32 v2, v61, s0
	ds_write_b16 v1, v2 offset:17712
	v_cvt_pk_bf16_f32 v2, v62, s0
	ds_write_b16 v1, v2 offset:17984
	v_cvt_pk_bf16_f32 v2, v63, s0
	ds_write_b16 v1, v2 offset:18256
	v_cvt_pk_bf16_f32 v2, v56, s0
	ds_write_b16 v1, v2 offset:17472
	v_cvt_pk_bf16_f32 v2, v57, s0
	ds_write_b16 v1, v2 offset:17744
	v_cvt_pk_bf16_f32 v2, v58, s0
	ds_write_b16 v1, v2 offset:18016
	v_cvt_pk_bf16_f32 v2, v59, s0
	ds_write_b16 v1, v2 offset:18288
	v_cvt_pk_bf16_f32 v2, v52, s0
	ds_write_b16 v1, v2 offset:17504
	v_cvt_pk_bf16_f32 v2, v53, s0
	ds_write_b16 v1, v2 offset:17776
	v_cvt_pk_bf16_f32 v2, v54, s0
	ds_write_b16 v1, v2 offset:18048
	v_cvt_pk_bf16_f32 v2, v55, s0
	ds_write_b16 v1, v2 offset:18320
	v_cvt_pk_bf16_f32 v2, v48, s0
	ds_write_b16 v1, v2 offset:21760
	v_cvt_pk_bf16_f32 v2, v49, s0
	ds_write_b16 v1, v2 offset:22032
	v_cvt_pk_bf16_f32 v2, v50, s0
	ds_write_b16 v1, v2 offset:22304
	v_cvt_pk_bf16_f32 v2, v51, s0
	ds_write_b16 v1, v2 offset:22576
	v_cvt_pk_bf16_f32 v2, v44, s0
	ds_write_b16 v1, v2 offset:21792
	v_cvt_pk_bf16_f32 v2, v45, s0
	ds_write_b16 v1, v2 offset:22064
	v_cvt_pk_bf16_f32 v2, v46, s0
	ds_write_b16 v1, v2 offset:22336
	v_cvt_pk_bf16_f32 v2, v47, s0
	ds_write_b16 v1, v2 offset:22608
	v_cvt_pk_bf16_f32 v2, v40, s0
	ds_write_b16 v1, v2 offset:21824
	v_cvt_pk_bf16_f32 v2, v41, s0
	ds_write_b16 v1, v2 offset:22096
	v_cvt_pk_bf16_f32 v2, v42, s0
	ds_write_b16 v1, v2 offset:22368
	v_cvt_pk_bf16_f32 v2, v43, s0
	ds_write_b16 v1, v2 offset:22640
	v_cvt_pk_bf16_f32 v2, v36, s0
	ds_write_b16 v1, v2 offset:21856
	v_cvt_pk_bf16_f32 v2, v37, s0
	ds_write_b16 v1, v2 offset:22128
	v_cvt_pk_bf16_f32 v2, v38, s0
	ds_write_b16 v1, v2 offset:22400
	v_cvt_pk_bf16_f32 v2, v39, s0
	ds_write_b16 v1, v2 offset:22672
	v_cvt_pk_bf16_f32 v2, v32, s0
	ds_write_b16 v1, v2 offset:26112
	v_cvt_pk_bf16_f32 v2, v33, s0
	ds_write_b16 v1, v2 offset:26384
	v_cvt_pk_bf16_f32 v2, v34, s0
	ds_write_b16 v1, v2 offset:26656
	v_cvt_pk_bf16_f32 v2, v35, s0
	ds_write_b16 v1, v2 offset:26928
	v_cvt_pk_bf16_f32 v2, v28, s0
	ds_write_b16 v1, v2 offset:26144
	v_cvt_pk_bf16_f32 v2, v29, s0
	ds_write_b16 v1, v2 offset:26416
	v_cvt_pk_bf16_f32 v2, v30, s0
	ds_write_b16 v1, v2 offset:26688
	v_cvt_pk_bf16_f32 v2, v31, s0
	ds_write_b16 v1, v2 offset:26960
	v_cvt_pk_bf16_f32 v2, v24, s0
	ds_write_b16 v1, v2 offset:26176
	v_cvt_pk_bf16_f32 v2, v25, s0
	ds_write_b16 v1, v2 offset:26448
	v_cvt_pk_bf16_f32 v2, v26, s0
	ds_write_b16 v1, v2 offset:26720
	v_cvt_pk_bf16_f32 v2, v27, s0
	ds_write_b16 v1, v2 offset:26992
	v_cvt_pk_bf16_f32 v2, v20, s0
	ds_write_b16 v1, v2 offset:26208
	v_cvt_pk_bf16_f32 v2, v21, s0
	ds_write_b16 v1, v2 offset:26480
	v_cvt_pk_bf16_f32 v2, v22, s0
	ds_write_b16 v1, v2 offset:26752
	v_cvt_pk_bf16_f32 v2, v23, s0
	ds_write_b16 v1, v2 offset:27024
	v_cvt_pk_bf16_f32 v2, v16, s0
	ds_write_b16 v1, v2 offset:30464
	v_cvt_pk_bf16_f32 v2, v17, s0
	ds_write_b16 v1, v2 offset:30736
	v_cvt_pk_bf16_f32 v2, v18, s0
	ds_write_b16 v1, v2 offset:31008
	v_cvt_pk_bf16_f32 v2, v19, s0
	ds_write_b16 v1, v2 offset:31280
	v_cvt_pk_bf16_f32 v2, v12, s0
	ds_write_b16 v1, v2 offset:30496
	v_cvt_pk_bf16_f32 v2, v13, s0
	ds_write_b16 v1, v2 offset:30768
	v_cvt_pk_bf16_f32 v2, v14, s0
	ds_write_b16 v1, v2 offset:31040
	v_cvt_pk_bf16_f32 v2, v15, s0
	ds_write_b16 v1, v2 offset:31312
	v_cvt_pk_bf16_f32 v2, v8, s0
	ds_write_b16 v1, v2 offset:30528
	v_cvt_pk_bf16_f32 v2, v9, s0
	ds_write_b16 v1, v2 offset:30800
	v_cvt_pk_bf16_f32 v2, v10, s0
	ds_write_b16 v1, v2 offset:31072
	v_cvt_pk_bf16_f32 v2, v11, s0
	ds_write_b16 v1, v2 offset:31344
	v_cvt_pk_bf16_f32 v2, v4, s0
	ds_write_b16 v1, v2 offset:30560
	v_cvt_pk_bf16_f32 v2, v5, s0
	ds_write_b16 v1, v2 offset:30832
	v_cvt_pk_bf16_f32 v2, v6, s0
	v_cvt_pk_bf16_f32 v128, v128, s0
	ds_write_b16 v1, v2 offset:31104
	v_cvt_pk_bf16_f32 v2, v7, s0
	ds_write_b16 v1, v128
	ds_write_b16 v1, v2 offset:31376
	v_mov_b32_e32 v1, v178
	s_waitcnt lgkmcnt(0)
	s_barrier
; DEVI int get_tid() { int t = threadIdx.x; asm volatile("" : "+v"(t)); return t; }
; template <int BN>
; DEVI void tile_store256(const char* smem, bf* __restrict__ C, long ldc, long row0, int col0) {
;   constexpr int LDT = BN + 8;
;   constexpr int CPR = BN / 8;
;   const int tid = get_tid();
; #pragma unroll
;   for (int i = 0; i < CPR; ++i) {
;     const int q = tid + 256 * i;
;     const int r = q / CPR, c = q - r * CPR;
;     u32x4 v = *reinterpret_cast<const u32x4*>(smem + (r * LDT + c * 8) * 2);
;     *reinterpret_cast<u32x4*>(C + (row0 + r) * ldc + col0 + c * 8) = v;
;   }
; }
; DEVI void phase_gemm_plain128(const bf* A, int lda, const bf* Wt, int K, int N, bf* C, int ldc, char* smem) {
;     ...
;   for (int v = blockIdx.x; v < 128 * ntn; v += gridDim.x) {
;     int m2, nt;
;     lat_tile_map256(v, ntn, m2, nt);
;     plain_tile256(A, lda, Wt, K, C, ldc, lat_row0_256(m2), nt * 128, smem);
	v_readlane_b32 s56, v251, 58
	v_ashrrev_i32_e32 v2, 31, v1
	v_lshrrev_b32_e32 v2, 28, v2
	v_add_u32_e32 v2, v1, v2
	s_lshl_b64 s[10:11], s[34:35], 1
	v_readlane_b32 s58, v251, 60
	v_ashrrev_i32_e32 v4, 4, v2
	v_readlane_b32 s59, v251, 61
	s_add_u32 s10, s58, s10
	v_lshlrev_b32_e32 v5, 7, v4
	v_lshlrev_b32_e32 v6, 3, v1
	s_addc_u32 s11, s59, s11
	v_sub_u32_e32 v10, v6, v5
	v_ashrrev_i32_e32 v5, 31, v4
	v_mul_lo_u32 v2, v4, s29
	v_lshl_add_u64 v[12:13], s[12:13], 0, v[4:5]
	v_mov_b64_e32 v[4:5], s[10:11]
	v_add_lshl_u32 v2, v10, v2, 1
	v_mad_u64_u32 v[14:15], s[10:11], v12, s39, v[4:5]
	ds_read_b128 v[6:9], v2
	v_mov_b32_e32 v2, v15
	v_mad_u64_u32 v[12:13], s[10:11], v13, s39, v[2:3]
	v_mov_b32_e32 v15, v12
	v_ashrrev_i32_e32 v11, 31, v10
	v_add_u32_e32 v2, 0x100, v1
	v_lshl_add_u64 v[14:15], v[10:11], 1, v[14:15]
	v_ashrrev_i32_e32 v10, 31, v2
	v_lshrrev_b32_e32 v10, 28, v10
	v_add_u32_e32 v10, v2, v10
	v_ashrrev_i32_e32 v16, 4, v10
	v_lshlrev_b32_e32 v11, 7, v16
	v_lshlrev_b32_e32 v2, 3, v2
	v_mul_lo_u32 v10, v16, s29
	v_sub_u32_e32 v18, v2, v11
	v_ashrrev_i32_e32 v17, 31, v16
	v_add_lshl_u32 v2, v18, v10, 1
	s_waitcnt lgkmcnt(0)
	global_store_dwordx4 v[14:15], v[6:9], off
	ds_read_b128 v[10:13], v2
	v_ashrrev_i32_e32 v19, 31, v18
	v_lshl_add_u64 v[6:7], s[12:13], 0, v[16:17]
	v_mad_u64_u32 v[8:9], s[10:11], v6, s39, v[4:5]
	v_mov_b32_e32 v2, v9
	v_mad_u64_u32 v[6:7], s[10:11], v7, s39, v[2:3]
	v_mov_b32_e32 v9, v6
	v_lshl_add_u64 v[6:7], v[18:19], 1, v[8:9]
	v_add_u32_e32 v2, 0x200, v1
	s_waitcnt lgkmcnt(0)
	global_store_dwordx4 v[6:7], v[10:13], off
	v_ashrrev_i32_e32 v6, 31, v2
	v_lshrrev_b32_e32 v6, 28, v6
	v_add_u32_e32 v6, v2, v6
	v_ashrrev_i32_e32 v10, 4, v6
	v_lshlrev_b32_e32 v7, 7, v10
	v_lshlrev_b32_e32 v2, 3, v2
	v_ashrrev_i32_e32 v11, 31, v10
	v_mul_lo_u32 v6, v10, s29
	v_sub_u32_e32 v12, v2, v7
	v_lshl_add_u64 v[10:11], s[12:13], 0, v[10:11]
	v_add_lshl_u32 v2, v12, v6, 1
	v_mad_u64_u32 v[14:15], s[10:11], v10, s39, v[4:5]
	ds_read_b128 v[6:9], v2
	v_mov_b32_e32 v2, v15
	v_mad_u64_u32 v[10:11], s[10:11], v11, s39, v[2:3]
	v_add_u32_e32 v2, 0x300, v1
	v_mov_b32_e32 v15, v10
	v_ashrrev_i32_e32 v10, 31, v2
	v_lshrrev_b32_e32 v10, 28, v10
	v_add_u32_e32 v10, v2, v10
	v_ashrrev_i32_e32 v16, 4, v10
	v_ashrrev_i32_e32 v13, 31, v12
	v_lshlrev_b32_e32 v11, 7, v16
	v_lshlrev_b32_e32 v2, 3, v2
	v_lshl_add_u64 v[14:15], v[12:13], 1, v[14:15]
	v_mul_lo_u32 v10, v16, s29
	v_sub_u32_e32 v18, v2, v11
	v_ashrrev_i32_e32 v17, 31, v16
	v_add_lshl_u32 v2, v18, v10, 1
	s_waitcnt lgkmcnt(0)
	global_store_dwordx4 v[14:15], v[6:9], off
	ds_read_b128 v[10:13], v2
	v_ashrrev_i32_e32 v19, 31, v18
	v_lshl_add_u64 v[6:7], s[12:13], 0, v[16:17]
	v_mad_u64_u32 v[8:9], s[10:11], v6, s39, v[4:5]
	v_mov_b32_e32 v2, v9
	v_mad_u64_u32 v[6:7], s[10:11], v7, s39, v[2:3]
	v_mov_b32_e32 v9, v6
	v_lshl_add_u64 v[6:7], v[18:19], 1, v[8:9]
	v_add_u32_e32 v2, 0x400, v1
	s_waitcnt lgkmcnt(0)
	global_store_dwordx4 v[6:7], v[10:13], off
	v_ashrrev_i32_e32 v6, 31, v2
	v_lshrrev_b32_e32 v6, 28, v6
	v_add_u32_e32 v6, v2, v6
	v_ashrrev_i32_e32 v10, 4, v6
	v_lshlrev_b32_e32 v7, 7, v10
	v_lshlrev_b32_e32 v2, 3, v2
	v_ashrrev_i32_e32 v11, 31, v10
	v_mul_lo_u32 v6, v10, s29
	v_sub_u32_e32 v12, v2, v7
	v_lshl_add_u64 v[10:11], s[12:13], 0, v[10:11]
	v_add_lshl_u32 v2, v12, v6, 1
	v_mad_u64_u32 v[14:15], s[10:11], v10, s39, v[4:5]
	ds_read_b128 v[6:9], v2
	v_mov_b32_e32 v2, v15
	v_mad_u64_u32 v[10:11], s[10:11], v11, s39, v[2:3]
	v_add_u32_e32 v2, 0x500, v1
	v_mov_b32_e32 v15, v10
	v_ashrrev_i32_e32 v10, 31, v2
	v_lshrrev_b32_e32 v10, 28, v10
	v_add_u32_e32 v10, v2, v10
	v_ashrrev_i32_e32 v16, 4, v10
	v_ashrrev_i32_e32 v13, 31, v12
	v_lshlrev_b32_e32 v11, 7, v16
	v_lshlrev_b32_e32 v2, 3, v2
	v_lshl_add_u64 v[14:15], v[12:13], 1, v[14:15]
	v_mul_lo_u32 v10, v16, s29
	v_sub_u32_e32 v18, v2, v11
	v_ashrrev_i32_e32 v17, 31, v16
	v_add_lshl_u32 v2, v18, v10, 1
	s_waitcnt lgkmcnt(0)
	global_store_dwordx4 v[14:15], v[6:9], off
	ds_read_b128 v[10:13], v2
	v_ashrrev_i32_e32 v19, 31, v18
	v_lshl_add_u64 v[6:7], s[12:13], 0, v[16:17]
	v_mad_u64_u32 v[8:9], s[10:11], v6, s39, v[4:5]
	v_mov_b32_e32 v2, v9
	v_mad_u64_u32 v[6:7], s[10:11], v7, s39, v[2:3]
	v_mov_b32_e32 v9, v6
	v_lshl_add_u64 v[6:7], v[18:19], 1, v[8:9]
	v_add_u32_e32 v2, 0x600, v1
	s_waitcnt lgkmcnt(0)
	global_store_dwordx4 v[6:7], v[10:13], off
	v_ashrrev_i32_e32 v6, 31, v2
	v_lshrrev_b32_e32 v6, 28, v6
	v_add_u32_e32 v6, v2, v6
	v_ashrrev_i32_e32 v10, 4, v6
	v_lshlrev_b32_e32 v7, 7, v10
	v_lshlrev_b32_e32 v2, 3, v2
	v_ashrrev_i32_e32 v11, 31, v10
	v_mul_lo_u32 v6, v10, s29
	v_sub_u32_e32 v12, v2, v7
	v_lshl_add_u64 v[10:11], s[12:13], 0, v[10:11]
	v_add_lshl_u32 v2, v12, v6, 1
	v_mad_u64_u32 v[14:15], s[10:11], v10, s39, v[4:5]
	ds_read_b128 v[6:9], v2
	v_mov_b32_e32 v2, v15
	v_mad_u64_u32 v[10:11], s[10:11], v11, s39, v[2:3]
	v_add_u32_e32 v2, 0x700, v1
	v_mov_b32_e32 v15, v10
	v_ashrrev_i32_e32 v10, 31, v2
	v_lshrrev_b32_e32 v10, 28, v10
	v_add_u32_e32 v10, v2, v10
	v_ashrrev_i32_e32 v16, 4, v10
	v_ashrrev_i32_e32 v13, 31, v12
	v_lshlrev_b32_e32 v11, 7, v16
	v_lshlrev_b32_e32 v2, 3, v2
	v_lshl_add_u64 v[14:15], v[12:13], 1, v[14:15]
	v_mul_lo_u32 v10, v16, s29
	v_sub_u32_e32 v18, v2, v11
	v_ashrrev_i32_e32 v17, 31, v16
	v_add_lshl_u32 v2, v18, v10, 1
	s_waitcnt lgkmcnt(0)
	global_store_dwordx4 v[14:15], v[6:9], off
	ds_read_b128 v[10:13], v2
	v_ashrrev_i32_e32 v19, 31, v18
	v_lshl_add_u64 v[6:7], s[12:13], 0, v[16:17]
	v_mad_u64_u32 v[8:9], s[10:11], v6, s39, v[4:5]
	v_mov_b32_e32 v2, v9
	v_mad_u64_u32 v[6:7], s[10:11], v7, s39, v[2:3]
	v_mov_b32_e32 v9, v6
	v_lshl_add_u64 v[6:7], v[18:19], 1, v[8:9]
	v_add_u32_e32 v2, 0x800, v1
	s_waitcnt lgkmcnt(0)
; DEVI int get_tid() { int t = threadIdx.x; asm volatile("" : "+v"(t)); return t; }
; template <int BN>
; DEVI void tile_store256(const char* smem, bf* __restrict__ C, long ldc, long row0, int col0) {
;   constexpr int LDT = BN + 8;
;   constexpr int CPR = BN / 8;
;   const int tid = get_tid();
; #pragma unroll
;   for (int i = 0; i < CPR; ++i) {
;     const int q = tid + 256 * i;
;     const int r = q / CPR, c = q - r * CPR;
;     u32x4 v = *reinterpret_cast<const u32x4*>(smem + (r * LDT + c * 8) * 2);
;     *reinterpret_cast<u32x4*>(C + (row0 + r) * ldc + col0 + c * 8) = v;
;   }
; }
; DEVI void phase_gemm_plain128(const bf* A, int lda, const bf* Wt, int K, int N, bf* C, int ldc, char* smem) {
;     ...
;   for (int v = blockIdx.x; v < 128 * ntn; v += gridDim.x) {
;     int m2, nt;
;     lat_tile_map256(v, ntn, m2, nt);
;     plain_tile256(A, lda, Wt, K, C, ldc, lat_row0_256(m2), nt * 128, smem);
	global_store_dwordx4 v[6:7], v[10:13], off
	v_ashrrev_i32_e32 v6, 31, v2
	v_lshrrev_b32_e32 v6, 28, v6
	v_add_u32_e32 v6, v2, v6
	v_ashrrev_i32_e32 v10, 4, v6
	v_lshlrev_b32_e32 v7, 7, v10
	v_lshlrev_b32_e32 v2, 3, v2
	v_ashrrev_i32_e32 v11, 31, v10
	v_mul_lo_u32 v6, v10, s29
	v_sub_u32_e32 v12, v2, v7
	v_lshl_add_u64 v[10:11], s[12:13], 0, v[10:11]
	v_add_lshl_u32 v2, v12, v6, 1
	v_mad_u64_u32 v[14:15], s[10:11], v10, s39, v[4:5]
	ds_read_b128 v[6:9], v2
	v_mov_b32_e32 v2, v15
	v_mad_u64_u32 v[10:11], s[10:11], v11, s39, v[2:3]
	v_add_u32_e32 v2, 0x900, v1
	v_mov_b32_e32 v15, v10
	v_ashrrev_i32_e32 v10, 31, v2
	v_lshrrev_b32_e32 v10, 28, v10
	v_add_u32_e32 v10, v2, v10
	v_ashrrev_i32_e32 v16, 4, v10
	v_ashrrev_i32_e32 v13, 31, v12
	v_lshlrev_b32_e32 v11, 7, v16
	v_lshlrev_b32_e32 v2, 3, v2
	v_lshl_add_u64 v[14:15], v[12:13], 1, v[14:15]
	v_mul_lo_u32 v10, v16, s29
	v_sub_u32_e32 v18, v2, v11
	v_ashrrev_i32_e32 v17, 31, v16
	v_add_lshl_u32 v2, v18, v10, 1
	s_waitcnt lgkmcnt(0)
	global_store_dwordx4 v[14:15], v[6:9], off
	ds_read_b128 v[10:13], v2
	v_ashrrev_i32_e32 v19, 31, v18
	v_lshl_add_u64 v[6:7], s[12:13], 0, v[16:17]
	v_mad_u64_u32 v[8:9], s[10:11], v6, s39, v[4:5]
	v_mov_b32_e32 v2, v9
	v_mad_u64_u32 v[6:7], s[10:11], v7, s39, v[2:3]
	v_mov_b32_e32 v9, v6
	v_lshl_add_u64 v[6:7], v[18:19], 1, v[8:9]
	v_add_u32_e32 v2, 0xa00, v1
	s_waitcnt lgkmcnt(0)
	global_store_dwordx4 v[6:7], v[10:13], off
	v_ashrrev_i32_e32 v6, 31, v2
	v_lshrrev_b32_e32 v6, 28, v6
	v_add_u32_e32 v6, v2, v6
	v_ashrrev_i32_e32 v10, 4, v6
	v_lshlrev_b32_e32 v7, 7, v10
	v_lshlrev_b32_e32 v2, 3, v2
	v_ashrrev_i32_e32 v11, 31, v10
	v_mul_lo_u32 v6, v10, s29
	v_sub_u32_e32 v12, v2, v7
	v_lshl_add_u64 v[10:11], s[12:13], 0, v[10:11]
	v_add_lshl_u32 v2, v12, v6, 1
	v_mad_u64_u32 v[14:15], s[10:11], v10, s39, v[4:5]
	ds_read_b128 v[6:9], v2
	v_mov_b32_e32 v2, v15
	v_mad_u64_u32 v[10:11], s[10:11], v11, s39, v[2:3]
	v_add_u32_e32 v2, 0xb00, v1
	v_mov_b32_e32 v15, v10
	v_ashrrev_i32_e32 v10, 31, v2
	v_lshrrev_b32_e32 v10, 28, v10
	v_add_u32_e32 v10, v2, v10
	v_ashrrev_i32_e32 v16, 4, v10
	v_ashrrev_i32_e32 v13, 31, v12
	v_lshlrev_b32_e32 v11, 7, v16
	v_lshlrev_b32_e32 v2, 3, v2
	v_lshl_add_u64 v[14:15], v[12:13], 1, v[14:15]
	v_mul_lo_u32 v10, v16, s29
	v_sub_u32_e32 v18, v2, v11
	v_ashrrev_i32_e32 v17, 31, v16
	v_add_lshl_u32 v2, v18, v10, 1
	s_waitcnt lgkmcnt(0)
	global_store_dwordx4 v[14:15], v[6:9], off
	ds_read_b128 v[10:13], v2
	v_ashrrev_i32_e32 v19, 31, v18
	v_lshl_add_u64 v[6:7], s[12:13], 0, v[16:17]
	v_mad_u64_u32 v[8:9], s[10:11], v6, s39, v[4:5]
	v_mov_b32_e32 v2, v9
	v_mad_u64_u32 v[6:7], s[10:11], v7, s39, v[2:3]
	v_mov_b32_e32 v9, v6
	v_lshl_add_u64 v[6:7], v[18:19], 1, v[8:9]
	v_add_u32_e32 v2, 0xc00, v1
	s_waitcnt lgkmcnt(0)
	global_store_dwordx4 v[6:7], v[10:13], off
	v_ashrrev_i32_e32 v6, 31, v2
	v_lshrrev_b32_e32 v6, 28, v6
	v_add_u32_e32 v6, v2, v6
	v_ashrrev_i32_e32 v10, 4, v6
	v_lshlrev_b32_e32 v7, 7, v10
	v_lshlrev_b32_e32 v2, 3, v2
	v_ashrrev_i32_e32 v11, 31, v10
	v_mul_lo_u32 v6, v10, s29
	v_sub_u32_e32 v12, v2, v7
	v_lshl_add_u64 v[10:11], s[12:13], 0, v[10:11]
	v_add_lshl_u32 v2, v12, v6, 1
	v_mad_u64_u32 v[14:15], s[10:11], v10, s39, v[4:5]
	ds_read_b128 v[6:9], v2
	v_mov_b32_e32 v2, v15
	v_mad_u64_u32 v[10:11], s[10:11], v11, s39, v[2:3]
	v_add_u32_e32 v2, 0xd00, v1
	v_mov_b32_e32 v15, v10
	v_ashrrev_i32_e32 v10, 31, v2
	v_lshrrev_b32_e32 v10, 28, v10
	v_add_u32_e32 v10, v2, v10
	v_ashrrev_i32_e32 v16, 4, v10
	v_ashrrev_i32_e32 v13, 31, v12
	v_lshlrev_b32_e32 v11, 7, v16
	v_lshlrev_b32_e32 v2, 3, v2
	v_lshl_add_u64 v[14:15], v[12:13], 1, v[14:15]
	v_mul_lo_u32 v10, v16, s29
	v_sub_u32_e32 v18, v2, v11
	v_ashrrev_i32_e32 v17, 31, v16
	v_add_lshl_u32 v2, v18, v10, 1
	s_waitcnt lgkmcnt(0)
	global_store_dwordx4 v[14:15], v[6:9], off
	ds_read_b128 v[10:13], v2
	v_ashrrev_i32_e32 v19, 31, v18
	v_lshl_add_u64 v[6:7], s[12:13], 0, v[16:17]
	v_mad_u64_u32 v[8:9], s[10:11], v6, s39, v[4:5]
	v_mov_b32_e32 v2, v9
	v_mad_u64_u32 v[6:7], s[10:11], v7, s39, v[2:3]
	v_mov_b32_e32 v9, v6
	v_lshl_add_u64 v[6:7], v[18:19], 1, v[8:9]
	v_add_u32_e32 v2, 0xe00, v1
	s_waitcnt lgkmcnt(0)
	global_store_dwordx4 v[6:7], v[10:13], off
	v_ashrrev_i32_e32 v6, 31, v2
	v_lshrrev_b32_e32 v6, 28, v6
	v_add_u32_e32 v6, v2, v6
	v_ashrrev_i32_e32 v10, 4, v6
	v_lshlrev_b32_e32 v7, 7, v10
	v_lshlrev_b32_e32 v2, 3, v2
	v_ashrrev_i32_e32 v11, 31, v10
	v_mul_lo_u32 v6, v10, s29
	v_sub_u32_e32 v12, v2, v7
	v_lshl_add_u64 v[10:11], s[12:13], 0, v[10:11]
	v_add_lshl_u32 v2, v12, v6, 1
	v_mad_u64_u32 v[14:15], s[10:11], v10, s39, v[4:5]
	ds_read_b128 v[6:9], v2
	v_mov_b32_e32 v2, v15
	v_add_u32_e32 v1, 0xf00, v1
	v_mad_u64_u32 v[10:11], s[10:11], v11, s39, v[2:3]
	v_ashrrev_i32_e32 v2, 31, v1
	v_lshrrev_b32_e32 v2, 28, v2
	v_add_u32_e32 v2, v1, v2
	v_mov_b32_e32 v15, v10
	v_ashrrev_i32_e32 v13, 31, v12
	v_ashrrev_i32_e32 v16, 4, v2
	v_lshl_add_u64 v[14:15], v[12:13], 1, v[14:15]
	v_lshlrev_b32_e32 v10, 7, v16
	v_lshlrev_b32_e32 v1, 3, v1
	v_ashrrev_i32_e32 v17, 31, v16
	v_mul_lo_u32 v2, v16, s29
	v_sub_u32_e32 v18, v1, v10
	s_waitcnt lgkmcnt(0)
	global_store_dwordx4 v[14:15], v[6:9], off
	v_add_lshl_u32 v1, v18, v2, 1
	ds_read_b128 v[10:13], v1
	v_lshl_add_u64 v[6:7], s[12:13], 0, v[16:17]
	v_mad_u64_u32 v[4:5], s[10:11], v6, s39, v[4:5]
	v_mov_b32_e32 v2, v5
	v_mad_u64_u32 v[6:7], s[10:11], v7, s39, v[2:3]
	v_readlane_b32 s10, v252, 59
	v_mov_b32_e32 v5, v6
	v_ashrrev_i32_e32 v19, 31, v18
	s_add_i32 s2, s2, s10
	v_readlane_b32 s57, v251, 59
	v_lshl_add_u64 v[4:5], v[18:19], 1, v[4:5]
	s_cmpk_gt_i32 s2, 0x97f
	v_readlane_b32 s60, v251, 62
	v_readlane_b32 s61, v251, 63
	v_readlane_b32 s62, v252, 0
	v_readlane_b32 s63, v252, 1
	v_readlane_b32 s64, v252, 2
	v_readlane_b32 s65, v252, 3
	v_readlane_b32 s66, v252, 4
	v_readlane_b32 s67, v252, 5
	v_readlane_b32 s68, v252, 6
	v_readlane_b32 s69, v252, 7
	v_readlane_b32 s70, v252, 8
	v_readlane_b32 s71, v252, 9
	s_waitcnt lgkmcnt(0)
	global_store_dwordx4 v[4:5], v[10:13], off
	s_barrier
	v_readlane_b32 s11, v252, 60
	s_cbranch_scc0 .LBB0_903

; DEVI f32x4 mfma16(bf16x8 a, bf16x8 b, f32x4 c) { return __builtin_amdgcn_mfma_f32_16x16x32_bf16(a, b, c, 0, 0, 0); }
; DEVI void gemm_core3(f32x4 (&acc)[8][4], const bf* __restrict__ A, int lda, const bf* __restrict__ Bt, int ldb, int K, char* smem) {
;     ...
;   for (int kt = 0; kt < nk; ++kt) {
;     const int k1 = min((kt + 1) * 32, klast);
;     const int sn = ((kt + 1) & 1) * STG;
;     const int so = (kt & 1) * STG;
;     bf16x8 bfr[4], af[8];
; #pragma unroll
;     for (int n = 0; n < 4; ++n) bfr[n] = *reinterpret_cast<const bf16x8*>(bbase + so + n * 16 * 64);
; #pragma unroll
;     for (int m = 0; m < 8; ++m) af[m] = *reinterpret_cast<const bf16x8*>(abase + so + m * 16 * 64);
; #pragma unroll
;     for (int i = 0; i < 4; ++i) glds16(Ap + i * sa + k1, dbase + sn + i * 4096);
; #pragma unroll
;     for (int i = 0; i < 2; ++i) glds16(Bp + i * sb + k1, dbase + sn + ASZ + i * 4096);
;     __builtin_amdgcn_s_setprio(1);
; #pragma unroll
;     for (int m = 0; m < 8; ++m)
; #pragma unroll
;       for (int n = 0; n < 4; ++n) acc[m][n] = mfma16(af[m], bfr[n], acc[m][n]);
;     __builtin_amdgcn_s_setprio(0);
;     __syncthreads();
;   }
.Lg3_loop_926:
	v_add_u32_e32 v216, s10, v146
	v_add_u32_e32 v217, s10, v2
	ds_read_b128 v[148:151], v217 offset:16384
	ds_read_b128 v[166:169], v216
	ds_read_b128 v[154:157], v217 offset:17408
	ds_read_b128 v[158:161], v217 offset:18432
	ds_read_b128 v[162:165], v217 offset:19456
	ds_read_b128 v[170:173], v216 offset:1024
	ds_read_b128 v[174:177], v216 offset:2048
	ds_read_b128 v[192:195], v216 offset:3072
	ds_read_b128 v[196:199], v216 offset:4096
	ds_read_b128 v[204:207], v216 offset:5120
	ds_read_b128 v[208:211], v216 offset:6144
	ds_read_b128 v[212:215], v216 offset:7168
	s_setprio 1
	s_waitcnt lgkmcnt(10)
	v_mfma_f32_16x16x32_bf16 v[128:131], v[166:169], v[148:151], v[128:131]
	s_waitcnt lgkmcnt(9)
	v_mfma_f32_16x16x32_bf16 v[124:127], v[166:169], v[154:157], v[124:127]
	s_waitcnt lgkmcnt(8)
	v_mfma_f32_16x16x32_bf16 v[120:123], v[166:169], v[158:161], v[120:123]
	s_waitcnt lgkmcnt(7)
	v_mfma_f32_16x16x32_bf16 v[116:119], v[166:169], v[162:165], v[116:119]
	s_waitcnt lgkmcnt(6)
	v_mfma_f32_16x16x32_bf16 v[112:115], v[170:173], v[148:151], v[112:115]
	v_mfma_f32_16x16x32_bf16 v[108:111], v[170:173], v[154:157], v[108:111]
	v_mfma_f32_16x16x32_bf16 v[104:107], v[170:173], v[158:161], v[104:107]
	v_mfma_f32_16x16x32_bf16 v[100:103], v[170:173], v[162:165], v[100:103]
	s_waitcnt lgkmcnt(5)
	v_mfma_f32_16x16x32_bf16 v[96:99], v[174:177], v[148:151], v[96:99]
	v_mfma_f32_16x16x32_bf16 v[92:95], v[174:177], v[154:157], v[92:95]
	v_mfma_f32_16x16x32_bf16 v[88:91], v[174:177], v[158:161], v[88:91]
	v_mfma_f32_16x16x32_bf16 v[84:87], v[174:177], v[162:165], v[84:87]
	s_waitcnt lgkmcnt(4)
	v_mfma_f32_16x16x32_bf16 v[80:83], v[192:195], v[148:151], v[80:83]
	v_mfma_f32_16x16x32_bf16 v[76:79], v[192:195], v[154:157], v[76:79]
	v_mfma_f32_16x16x32_bf16 v[72:75], v[192:195], v[158:161], v[72:75]
	v_mfma_f32_16x16x32_bf16 v[68:71], v[192:195], v[162:165], v[68:71]
	s_waitcnt lgkmcnt(3)
	v_mfma_f32_16x16x32_bf16 v[64:67], v[196:199], v[148:151], v[64:67]
	v_mfma_f32_16x16x32_bf16 v[60:63], v[196:199], v[154:157], v[60:63]
	v_mfma_f32_16x16x32_bf16 v[56:59], v[196:199], v[158:161], v[56:59]
	v_mfma_f32_16x16x32_bf16 v[52:55], v[196:199], v[162:165], v[52:55]
	s_waitcnt lgkmcnt(2)
	v_mfma_f32_16x16x32_bf16 v[48:51], v[204:207], v[148:151], v[48:51]
	v_mfma_f32_16x16x32_bf16 v[44:47], v[204:207], v[154:157], v[44:47]
	v_mfma_f32_16x16x32_bf16 v[40:43], v[204:207], v[158:161], v[40:43]
	v_mfma_f32_16x16x32_bf16 v[36:39], v[204:207], v[162:165], v[36:39]
	s_waitcnt lgkmcnt(1)
	v_mfma_f32_16x16x32_bf16 v[32:35], v[208:211], v[148:151], v[32:35]
	v_mfma_f32_16x16x32_bf16 v[28:31], v[208:211], v[154:157], v[28:31]
	v_mfma_f32_16x16x32_bf16 v[24:27], v[208:211], v[158:161], v[24:27]
	v_mfma_f32_16x16x32_bf16 v[20:23], v[208:211], v[162:165], v[20:23]
	s_waitcnt lgkmcnt(0)
	v_mfma_f32_16x16x32_bf16 v[16:19], v[212:215], v[148:151], v[16:19]
	v_mfma_f32_16x16x32_bf16 v[12:15], v[212:215], v[154:157], v[12:15]
	v_mfma_f32_16x16x32_bf16 v[8:11], v[212:215], v[158:161], v[8:11]
	v_mfma_f32_16x16x32_bf16 v[4:7], v[212:215], v[162:165], v[4:7]
	s_setprio 0
	s_add_i32 s10, s10, 0x6000
	s_cmp_lg_u32 s10, 0x12000
	s_cselect_b32 s10, s10, 0
	s_waitcnt vmcnt(0)
	s_barrier
	v_add_u32_e32 v216, s10, v146
	v_add_u32_e32 v217, s10, v2
	ds_read_b128 v[148:151], v217 offset:16384
	ds_read_b128 v[166:169], v216
	ds_read_b128 v[154:157], v217 offset:17408
	ds_read_b128 v[158:161], v217 offset:18432
	ds_read_b128 v[162:165], v217 offset:19456
	ds_read_b128 v[170:173], v216 offset:1024
	ds_read_b128 v[174:177], v216 offset:2048
	ds_read_b128 v[192:195], v216 offset:3072
	ds_read_b128 v[196:199], v216 offset:4096
	ds_read_b128 v[204:207], v216 offset:5120
	ds_read_b128 v[208:211], v216 offset:6144
	ds_read_b128 v[212:215], v216 offset:7168
	v_readfirstlane_b32 s17, v140
	s_add_i32 s96, s11, 0x6000
	s_cmp_lg_u32 s96, 0x12000
	s_cselect_b32 s96, s96, 0
	s_add_i32 s96, s96, s17
	s_add_i32 s17, s17, s11
	s_setprio 2
	s_waitcnt lgkmcnt(10)
	s_mov_b32 m0, s17
	s_add_i32 s17, s17, 0x1000
	v_mfma_f32_16x16x32_bf16 v[128:131], v[166:169], v[148:151], v[128:131]
	s_waitcnt lgkmcnt(9)
	v_mfma_f32_16x16x32_bf16 v[124:127], v[166:169], v[154:157], v[124:127]
	global_load_lds_dwordx4 v[218:219], off
	v_lshl_add_u64 v[218:219], v[218:219], 0, 64
	s_waitcnt lgkmcnt(8)
	s_mov_b32 m0, s96
	s_add_i32 s96, s96, 0x1000
	v_mfma_f32_16x16x32_bf16 v[120:123], v[166:169], v[158:161], v[120:123]
	s_waitcnt lgkmcnt(7)
	v_mfma_f32_16x16x32_bf16 v[116:119], v[166:169], v[162:165], v[116:119]
	global_load_lds_dwordx4 v[218:219], off
	v_lshl_add_u64 v[218:219], v[218:219], 0, 64
	s_waitcnt lgkmcnt(6)
	v_mfma_f32_16x16x32_bf16 v[112:115], v[170:173], v[148:151], v[112:115]
	s_mov_b32 m0, s17
	s_add_i32 s17, s17, 0x1000
	v_mfma_f32_16x16x32_bf16 v[108:111], v[170:173], v[154:157], v[108:111]
	v_mfma_f32_16x16x32_bf16 v[104:107], v[170:173], v[158:161], v[104:107]
	global_load_lds_dwordx4 v[220:221], off
	v_lshl_add_u64 v[220:221], v[220:221], 0, 64
	s_mov_b32 m0, s96
	s_add_i32 s96, s96, 0x1000
	v_mfma_f32_16x16x32_bf16 v[100:103], v[170:173], v[162:165], v[100:103]
	s_waitcnt lgkmcnt(5)
	v_mfma_f32_16x16x32_bf16 v[96:99], v[174:177], v[148:151], v[96:99]
	global_load_lds_dwordx4 v[220:221], off
	v_lshl_add_u64 v[220:221], v[220:221], 0, 64
	v_mfma_f32_16x16x32_bf16 v[92:95], v[174:177], v[154:157], v[92:95]
	s_mov_b32 m0, s17
	s_add_i32 s17, s17, 0x1000
	v_mfma_f32_16x16x32_bf16 v[88:91], v[174:177], v[158:161], v[88:91]
	v_mfma_f32_16x16x32_bf16 v[84:87], v[174:177], v[162:165], v[84:87]
	global_load_lds_dwordx4 v[222:223], off
	v_lshl_add_u64 v[222:223], v[222:223], 0, 64
	s_waitcnt lgkmcnt(4)
; DEVI f32x4 mfma16(bf16x8 a, bf16x8 b, f32x4 c) { return __builtin_amdgcn_mfma_f32_16x16x32_bf16(a, b, c, 0, 0, 0); }
; DEVI void gemm_core3(f32x4 (&acc)[8][4], const bf* __restrict__ A, int lda, const bf* __restrict__ Bt, int ldb, int K, char* smem) {
;     ...
;   for (int kt = 0; kt < nk; ++kt) {
;     const int k1 = min((kt + 1) * 32, klast);
;     const int sn = ((kt + 1) & 1) * STG;
;     const int so = (kt & 1) * STG;
;     bf16x8 bfr[4], af[8];
; #pragma unroll
;     for (int n = 0; n < 4; ++n) bfr[n] = *reinterpret_cast<const bf16x8*>(bbase + so + n * 16 * 64);
; #pragma unroll
;     for (int m = 0; m < 8; ++m) af[m] = *reinterpret_cast<const bf16x8*>(abase + so + m * 16 * 64);
; #pragma unroll
;     for (int i = 0; i < 4; ++i) glds16(Ap + i * sa + k1, dbase + sn + i * 4096);
; #pragma unroll
;     for (int i = 0; i < 2; ++i) glds16(Bp + i * sb + k1, dbase + sn + ASZ + i * 4096);
;     __builtin_amdgcn_s_setprio(1);
; #pragma unroll
;     for (int m = 0; m < 8; ++m)
; #pragma unroll
;       for (int n = 0; n < 4; ++n) acc[m][n] = mfma16(af[m], bfr[n], acc[m][n]);
;     __builtin_amdgcn_s_setprio(0);
;     __syncthreads();
;   }
	s_mov_b32 m0, s96
	s_add_i32 s96, s96, 0x1000
	v_mfma_f32_16x16x32_bf16 v[80:83], v[192:195], v[148:151], v[80:83]
	v_mfma_f32_16x16x32_bf16 v[76:79], v[192:195], v[154:157], v[76:79]
	global_load_lds_dwordx4 v[222:223], off
	v_lshl_add_u64 v[222:223], v[222:223], 0, 64
	v_mfma_f32_16x16x32_bf16 v[72:75], v[192:195], v[158:161], v[72:75]
	s_mov_b32 m0, s17
	s_add_i32 s17, s17, 0x1000
	v_mfma_f32_16x16x32_bf16 v[68:71], v[192:195], v[162:165], v[68:71]
	s_waitcnt lgkmcnt(3)
	v_mfma_f32_16x16x32_bf16 v[64:67], v[196:199], v[148:151], v[64:67]
	global_load_lds_dwordx4 v[224:225], off
	v_lshl_add_u64 v[224:225], v[224:225], 0, 64
	s_mov_b32 m0, s96
	s_add_i32 s96, s96, 0x1000
	v_mfma_f32_16x16x32_bf16 v[60:63], v[196:199], v[154:157], v[60:63]
	v_mfma_f32_16x16x32_bf16 v[56:59], v[196:199], v[158:161], v[56:59]
	global_load_lds_dwordx4 v[224:225], off
	v_lshl_add_u64 v[224:225], v[224:225], 0, 64
	v_mfma_f32_16x16x32_bf16 v[52:55], v[196:199], v[162:165], v[52:55]
	s_waitcnt lgkmcnt(2)
	s_mov_b32 m0, s17
	s_add_i32 s17, s17, 0x1000
	v_mfma_f32_16x16x32_bf16 v[48:51], v[204:207], v[148:151], v[48:51]
	v_mfma_f32_16x16x32_bf16 v[44:47], v[204:207], v[154:157], v[44:47]
	global_load_lds_dwordx4 v[226:227], off
	v_lshl_add_u64 v[226:227], v[226:227], 0, 64
	s_mov_b32 m0, s96
	s_add_i32 s96, s96, 0x1000
	v_mfma_f32_16x16x32_bf16 v[40:43], v[204:207], v[158:161], v[40:43]
	v_mfma_f32_16x16x32_bf16 v[36:39], v[204:207], v[162:165], v[36:39]
	global_load_lds_dwordx4 v[226:227], off
	v_lshl_add_u64 v[226:227], v[226:227], 0, 64
	s_waitcnt lgkmcnt(1)
	v_mfma_f32_16x16x32_bf16 v[32:35], v[208:211], v[148:151], v[32:35]
	s_mov_b32 m0, s17
	s_add_i32 s17, s17, 0x1000
	v_mfma_f32_16x16x32_bf16 v[28:31], v[208:211], v[154:157], v[28:31]
	v_mfma_f32_16x16x32_bf16 v[24:27], v[208:211], v[158:161], v[24:27]
	global_load_lds_dwordx4 v[228:229], off
	v_lshl_add_u64 v[228:229], v[228:229], 0, 64
	s_mov_b32 m0, s96
	s_add_i32 s96, s96, 0x1000
	v_mfma_f32_16x16x32_bf16 v[20:23], v[208:211], v[162:165], v[20:23]
	s_waitcnt lgkmcnt(0)
	v_mfma_f32_16x16x32_bf16 v[16:19], v[212:215], v[148:151], v[16:19]
	global_load_lds_dwordx4 v[228:229], off
	v_lshl_add_u64 v[228:229], v[228:229], 0, 64
	v_mfma_f32_16x16x32_bf16 v[12:15], v[212:215], v[154:157], v[12:15]
	v_mfma_f32_16x16x32_bf16 v[8:11], v[212:215], v[158:161], v[8:11]
	v_mfma_f32_16x16x32_bf16 v[4:7], v[212:215], v[162:165], v[4:7]
	s_setprio 0
	s_add_i32 s10, s10, 0x6000
	s_cmp_lg_u32 s10, 0x12000
	s_cselect_b32 s10, s10, 0
	s_sub_i32 s11, s11, 0x6000
	s_cmp_lt_i32 s11, 0
	s_cselect_b32 s11, 0xc000, s11
	s_add_i32 s3, s3, 1
	s_cmp_lt_i32 s3, 43
	s_waitcnt vmcnt(1)
	s_barrier
	s_cbranch_scc1 .Lg3_loop_926
	v_add_u32_e32 v216, s10, v146
	v_add_u32_e32 v217, s10, v2
	ds_read_b128 v[148:151], v217 offset:16384
	ds_read_b128 v[166:169], v216
	ds_read_b128 v[154:157], v217 offset:17408
	ds_read_b128 v[158:161], v217 offset:18432
	ds_read_b128 v[162:165], v217 offset:19456
	ds_read_b128 v[170:173], v216 offset:1024
	ds_read_b128 v[174:177], v216 offset:2048
	ds_read_b128 v[192:195], v216 offset:3072
	ds_read_b128 v[196:199], v216 offset:4096
	ds_read_b128 v[204:207], v216 offset:5120
	ds_read_b128 v[208:211], v216 offset:6144
	ds_read_b128 v[212:215], v216 offset:7168
	s_setprio 1
	s_waitcnt lgkmcnt(10)
	v_mfma_f32_16x16x32_bf16 v[128:131], v[166:169], v[148:151], v[128:131]
	s_waitcnt lgkmcnt(9)
	v_mfma_f32_16x16x32_bf16 v[124:127], v[166:169], v[154:157], v[124:127]
	s_waitcnt lgkmcnt(8)
	v_mfma_f32_16x16x32_bf16 v[120:123], v[166:169], v[158:161], v[120:123]
	s_waitcnt lgkmcnt(7)
	v_mfma_f32_16x16x32_bf16 v[116:119], v[166:169], v[162:165], v[116:119]
	s_waitcnt lgkmcnt(6)
	v_mfma_f32_16x16x32_bf16 v[112:115], v[170:173], v[148:151], v[112:115]
	v_mfma_f32_16x16x32_bf16 v[108:111], v[170:173], v[154:157], v[108:111]
	v_mfma_f32_16x16x32_bf16 v[104:107], v[170:173], v[158:161], v[104:107]
	v_mfma_f32_16x16x32_bf16 v[100:103], v[170:173], v[162:165], v[100:103]
	s_waitcnt lgkmcnt(5)
	v_mfma_f32_16x16x32_bf16 v[96:99], v[174:177], v[148:151], v[96:99]
	v_mfma_f32_16x16x32_bf16 v[92:95], v[174:177], v[154:157], v[92:95]
	v_mfma_f32_16x16x32_bf16 v[88:91], v[174:177], v[158:161], v[88:91]
	v_mfma_f32_16x16x32_bf16 v[84:87], v[174:177], v[162:165], v[84:87]
	s_waitcnt lgkmcnt(4)
	v_mfma_f32_16x16x32_bf16 v[80:83], v[192:195], v[148:151], v[80:83]
	v_mfma_f32_16x16x32_bf16 v[76:79], v[192:195], v[154:157], v[76:79]
	v_mfma_f32_16x16x32_bf16 v[72:75], v[192:195], v[158:161], v[72:75]
	v_mfma_f32_16x16x32_bf16 v[68:71], v[192:195], v[162:165], v[68:71]
	s_waitcnt lgkmcnt(3)
	v_mfma_f32_16x16x32_bf16 v[64:67], v[196:199], v[148:151], v[64:67]
	v_mfma_f32_16x16x32_bf16 v[60:63], v[196:199], v[154:157], v[60:63]
	v_mfma_f32_16x16x32_bf16 v[56:59], v[196:199], v[158:161], v[56:59]
	v_mfma_f32_16x16x32_bf16 v[52:55], v[196:199], v[162:165], v[52:55]
	s_waitcnt lgkmcnt(2)
	v_mfma_f32_16x16x32_bf16 v[48:51], v[204:207], v[148:151], v[48:51]
	v_mfma_f32_16x16x32_bf16 v[44:47], v[204:207], v[154:157], v[44:47]
	v_mfma_f32_16x16x32_bf16 v[40:43], v[204:207], v[158:161], v[40:43]
	v_mfma_f32_16x16x32_bf16 v[36:39], v[204:207], v[162:165], v[36:39]
	s_waitcnt lgkmcnt(1)
	v_mfma_f32_16x16x32_bf16 v[32:35], v[208:211], v[148:151], v[32:35]
	v_mfma_f32_16x16x32_bf16 v[28:31], v[208:211], v[154:157], v[28:31]
	v_mfma_f32_16x16x32_bf16 v[24:27], v[208:211], v[158:161], v[24:27]
	v_mfma_f32_16x16x32_bf16 v[20:23], v[208:211], v[162:165], v[20:23]
	s_waitcnt lgkmcnt(0)
	v_mfma_f32_16x16x32_bf16 v[16:19], v[212:215], v[148:151], v[16:19]
	v_mfma_f32_16x16x32_bf16 v[12:15], v[212:215], v[154:157], v[12:15]
	v_mfma_f32_16x16x32_bf16 v[8:11], v[212:215], v[158:161], v[8:11]
	v_mfma_f32_16x16x32_bf16 v[4:7], v[212:215], v[162:165], v[4:7]
	s_setprio 0
	s_add_i32 s10, s10, 0x6000
	s_cmp_lg_u32 s10, 0x12000
	s_cselect_b32 s10, s10, 0
	s_waitcnt vmcnt(0)
	s_barrier
; DEVI f32x4 mfma16(bf16x8 a, bf16x8 b, f32x4 c) { return __builtin_amdgcn_mfma_f32_16x16x32_bf16(a, b, c, 0, 0, 0); }
; DEVI void gemm_core3(f32x4 (&acc)[8][4], const bf* __restrict__ A, int lda, const bf* __restrict__ Bt, int ldb, int K, char* smem) {
;     ...
;     bf16x8 bfr[4], af[8];
; #pragma unroll
;     for (int n = 0; n < 4; ++n) bfr[n] = *reinterpret_cast<const bf16x8*>(bbase + so + n * 16 * 64);
; #pragma unroll
;     for (int m = 0; m < 8; ++m) af[m] = *reinterpret_cast<const bf16x8*>(abase + so + m * 16 * 64);
; #pragma unroll
;     for (int i = 0; i < 4; ++i) glds16(Ap + i * sa + k1, dbase + sn + i * 4096);
; #pragma unroll
;     for (int i = 0; i < 2; ++i) glds16(Bp + i * sb + k1, dbase + sn + ASZ + i * 4096);
;     __builtin_amdgcn_s_setprio(1);
; #pragma unroll
;     for (int m = 0; m < 8; ++m)
; #pragma unroll
;       for (int n = 0; n < 4; ++n) acc[m][n] = mfma16(af[m], bfr[n], acc[m][n]);
;     __builtin_amdgcn_s_setprio(0);
; DEVI void plain_tile256(const bf* A, int lda, const bf* Wt, int K, bf* C, int ldc, long row0, int n0, char* smem) {
;     ...
;   bf* tl = reinterpret_cast<bf*>(smem);
; #pragma unroll
;   for (int m = 0; m < 8; ++m)
; #pragma unroll
;     for (int n = 0; n < 4; ++n) {
;       const int cl = wc * 64 + n * 16 + l15;
; #pragma unroll
;       for (int j = 0; j < 4; ++j) tl[(wr * 128 + m * 16 + quad * 4 + j) * 136 + cl] = f2bf(acc[m][n][j]);
;     }
	v_add_u32_e32 v216, s10, v146
	v_add_u32_e32 v217, s10, v2
	ds_read_b128 v[148:151], v217 offset:16384
	ds_read_b128 v[166:169], v216
	ds_read_b128 v[154:157], v217 offset:17408
	ds_read_b128 v[158:161], v217 offset:18432
	ds_read_b128 v[162:165], v217 offset:19456
	ds_read_b128 v[170:173], v216 offset:1024
	ds_read_b128 v[174:177], v216 offset:2048
	ds_read_b128 v[192:195], v216 offset:3072
	ds_read_b128 v[196:199], v216 offset:4096
	ds_read_b128 v[204:207], v216 offset:5120
	ds_read_b128 v[208:211], v216 offset:6144
	ds_read_b128 v[212:215], v216 offset:7168
	s_setprio 1
	s_waitcnt lgkmcnt(10)
	v_mfma_f32_16x16x32_bf16 v[128:131], v[166:169], v[148:151], v[128:131]
	s_waitcnt lgkmcnt(9)
	v_mfma_f32_16x16x32_bf16 v[124:127], v[166:169], v[154:157], v[124:127]
	s_waitcnt lgkmcnt(8)
	v_mfma_f32_16x16x32_bf16 v[120:123], v[166:169], v[158:161], v[120:123]
	s_waitcnt lgkmcnt(7)
	v_mfma_f32_16x16x32_bf16 v[116:119], v[166:169], v[162:165], v[116:119]
	s_waitcnt lgkmcnt(6)
	v_mfma_f32_16x16x32_bf16 v[112:115], v[170:173], v[148:151], v[112:115]
	v_mfma_f32_16x16x32_bf16 v[108:111], v[170:173], v[154:157], v[108:111]
	v_mfma_f32_16x16x32_bf16 v[104:107], v[170:173], v[158:161], v[104:107]
	v_mfma_f32_16x16x32_bf16 v[100:103], v[170:173], v[162:165], v[100:103]
	s_waitcnt lgkmcnt(5)
	v_mfma_f32_16x16x32_bf16 v[96:99], v[174:177], v[148:151], v[96:99]
	v_mfma_f32_16x16x32_bf16 v[92:95], v[174:177], v[154:157], v[92:95]
	v_mfma_f32_16x16x32_bf16 v[88:91], v[174:177], v[158:161], v[88:91]
	v_mfma_f32_16x16x32_bf16 v[84:87], v[174:177], v[162:165], v[84:87]
	s_waitcnt lgkmcnt(4)
	v_mfma_f32_16x16x32_bf16 v[80:83], v[192:195], v[148:151], v[80:83]
	v_mfma_f32_16x16x32_bf16 v[76:79], v[192:195], v[154:157], v[76:79]
	v_mfma_f32_16x16x32_bf16 v[72:75], v[192:195], v[158:161], v[72:75]
	v_mfma_f32_16x16x32_bf16 v[68:71], v[192:195], v[162:165], v[68:71]
	s_waitcnt lgkmcnt(3)
	v_mfma_f32_16x16x32_bf16 v[64:67], v[196:199], v[148:151], v[64:67]
	v_mfma_f32_16x16x32_bf16 v[60:63], v[196:199], v[154:157], v[60:63]
	v_mfma_f32_16x16x32_bf16 v[56:59], v[196:199], v[158:161], v[56:59]
	v_mfma_f32_16x16x32_bf16 v[52:55], v[196:199], v[162:165], v[52:55]
	s_waitcnt lgkmcnt(2)
	v_mfma_f32_16x16x32_bf16 v[48:51], v[204:207], v[148:151], v[48:51]
	v_mfma_f32_16x16x32_bf16 v[44:47], v[204:207], v[154:157], v[44:47]
	v_mfma_f32_16x16x32_bf16 v[40:43], v[204:207], v[158:161], v[40:43]
	v_mfma_f32_16x16x32_bf16 v[36:39], v[204:207], v[162:165], v[36:39]
	s_waitcnt lgkmcnt(1)
	v_mfma_f32_16x16x32_bf16 v[32:35], v[208:211], v[148:151], v[32:35]
	v_mfma_f32_16x16x32_bf16 v[28:31], v[208:211], v[154:157], v[28:31]
	v_mfma_f32_16x16x32_bf16 v[24:27], v[208:211], v[158:161], v[24:27]
	v_mfma_f32_16x16x32_bf16 v[20:23], v[208:211], v[162:165], v[20:23]
	s_waitcnt lgkmcnt(0)
	v_mfma_f32_16x16x32_bf16 v[16:19], v[212:215], v[148:151], v[16:19]
	v_mfma_f32_16x16x32_bf16 v[12:15], v[212:215], v[154:157], v[12:15]
	v_mfma_f32_16x16x32_bf16 v[8:11], v[212:215], v[158:161], v[8:11]
	v_mfma_f32_16x16x32_bf16 v[4:7], v[212:215], v[162:165], v[4:7]
	s_setprio 0
	s_add_i32 s10, s10, 0x6000
	s_cmp_lg_u32 s10, 0x12000
	s_cselect_b32 s10, s10, 0
	s_waitcnt vmcnt(0)
	s_barrier
	v_and_b32_e32 v2, 0x4f, v1
	v_and_b32_e32 v132, 0xfffff80, v1
	v_lshrrev_b32_e32 v1, 2, v1
	v_and_or_b32 v1, v1, 12, v132
	v_mul_lo_u32 v1, v1, s16
	v_lshl_add_u32 v1, v2, 1, v1
	v_cvt_pk_bf16_f32 v2, v129, s0
	ds_write_b16 v1, v2 offset:272
	v_cvt_pk_bf16_f32 v2, v130, s0
	ds_write_b16 v1, v2 offset:544
	v_cvt_pk_bf16_f32 v2, v131, s0
	ds_write_b16 v1, v2 offset:816
	v_cvt_pk_bf16_f32 v2, v124, s0
	ds_write_b16 v1, v2 offset:32
	v_cvt_pk_bf16_f32 v2, v125, s0
	ds_write_b16 v1, v2 offset:304
	v_cvt_pk_bf16_f32 v2, v126, s0
	ds_write_b16 v1, v2 offset:576
	v_cvt_pk_bf16_f32 v2, v127, s0
	ds_write_b16 v1, v2 offset:848
	v_cvt_pk_bf16_f32 v2, v120, s0
	ds_write_b16 v1, v2 offset:64
	v_cvt_pk_bf16_f32 v2, v121, s0
	ds_write_b16 v1, v2 offset:336
	v_cvt_pk_bf16_f32 v2, v122, s0
	ds_write_b16 v1, v2 offset:608
	v_cvt_pk_bf16_f32 v2, v123, s0
	ds_write_b16 v1, v2 offset:880
	v_cvt_pk_bf16_f32 v2, v116, s0
	ds_write_b16 v1, v2 offset:96
	v_cvt_pk_bf16_f32 v2, v117, s0
	ds_write_b16 v1, v2 offset:368
	v_cvt_pk_bf16_f32 v2, v118, s0
	ds_write_b16 v1, v2 offset:640
	v_cvt_pk_bf16_f32 v2, v119, s0
	ds_write_b16 v1, v2 offset:912
	v_cvt_pk_bf16_f32 v2, v112, s0
	ds_write_b16 v1, v2 offset:4352
	v_cvt_pk_bf16_f32 v2, v113, s0
	ds_write_b16 v1, v2 offset:4624
	v_cvt_pk_bf16_f32 v2, v114, s0
	ds_write_b16 v1, v2 offset:4896
	v_cvt_pk_bf16_f32 v2, v115, s0
	ds_write_b16 v1, v2 offset:5168
	v_cvt_pk_bf16_f32 v2, v108, s0
	ds_write_b16 v1, v2 offset:4384
	v_cvt_pk_bf16_f32 v2, v109, s0
	ds_write_b16 v1, v2 offset:4656
	v_cvt_pk_bf16_f32 v2, v110, s0
	ds_write_b16 v1, v2 offset:4928
	v_cvt_pk_bf16_f32 v2, v111, s0
	ds_write_b16 v1, v2 offset:5200
	v_cvt_pk_bf16_f32 v2, v104, s0
	ds_write_b16 v1, v2 offset:4416
	v_cvt_pk_bf16_f32 v2, v105, s0
	ds_write_b16 v1, v2 offset:4688
	v_cvt_pk_bf16_f32 v2, v106, s0
	ds_write_b16 v1, v2 offset:4960
	v_cvt_pk_bf16_f32 v2, v107, s0
	ds_write_b16 v1, v2 offset:5232
	v_cvt_pk_bf16_f32 v2, v100, s0
	ds_write_b16 v1, v2 offset:4448
	v_cvt_pk_bf16_f32 v2, v101, s0
	ds_write_b16 v1, v2 offset:4720
	v_cvt_pk_bf16_f32 v2, v102, s0
	ds_write_b16 v1, v2 offset:4992
	v_cvt_pk_bf16_f32 v2, v103, s0
	ds_write_b16 v1, v2 offset:5264
	v_cvt_pk_bf16_f32 v2, v96, s0
	ds_write_b16 v1, v2 offset:8704
	v_cvt_pk_bf16_f32 v2, v97, s0
	ds_write_b16 v1, v2 offset:8976
	v_cvt_pk_bf16_f32 v2, v98, s0
	ds_write_b16 v1, v2 offset:9248
	v_cvt_pk_bf16_f32 v2, v99, s0
	ds_write_b16 v1, v2 offset:9520
	v_cvt_pk_bf16_f32 v2, v92, s0
; DEVI void plain_tile256(const bf* A, int lda, const bf* Wt, int K, bf* C, int ldc, long row0, int n0, char* smem) {
;     ...
; #pragma unroll
;   for (int m = 0; m < 8; ++m)
; #pragma unroll
;     for (int n = 0; n < 4; ++n) {
;       const int cl = wc * 64 + n * 16 + l15;
; #pragma unroll
;       for (int j = 0; j < 4; ++j) tl[(wr * 128 + m * 16 + quad * 4 + j) * 136 + cl] = f2bf(acc[m][n][j]);
;     }
;   __syncthreads();
	ds_write_b16 v1, v2 offset:8736
	v_cvt_pk_bf16_f32 v2, v93, s0
	ds_write_b16 v1, v2 offset:9008
	v_cvt_pk_bf16_f32 v2, v94, s0
	ds_write_b16 v1, v2 offset:9280
	v_cvt_pk_bf16_f32 v2, v95, s0
	ds_write_b16 v1, v2 offset:9552
	v_cvt_pk_bf16_f32 v2, v88, s0
	ds_write_b16 v1, v2 offset:8768
	v_cvt_pk_bf16_f32 v2, v89, s0
	ds_write_b16 v1, v2 offset:9040
	v_cvt_pk_bf16_f32 v2, v90, s0
	ds_write_b16 v1, v2 offset:9312
	v_cvt_pk_bf16_f32 v2, v91, s0
	ds_write_b16 v1, v2 offset:9584
	v_cvt_pk_bf16_f32 v2, v84, s0
	ds_write_b16 v1, v2 offset:8800
	v_cvt_pk_bf16_f32 v2, v85, s0
	ds_write_b16 v1, v2 offset:9072
	v_cvt_pk_bf16_f32 v2, v86, s0
	ds_write_b16 v1, v2 offset:9344
	v_cvt_pk_bf16_f32 v2, v87, s0
	ds_write_b16 v1, v2 offset:9616
	v_cvt_pk_bf16_f32 v2, v80, s0
	ds_write_b16 v1, v2 offset:13056
	v_cvt_pk_bf16_f32 v2, v81, s0
	ds_write_b16 v1, v2 offset:13328
	v_cvt_pk_bf16_f32 v2, v82, s0
	ds_write_b16 v1, v2 offset:13600
	v_cvt_pk_bf16_f32 v2, v83, s0
	ds_write_b16 v1, v2 offset:13872
	v_cvt_pk_bf16_f32 v2, v76, s0
	ds_write_b16 v1, v2 offset:13088
	v_cvt_pk_bf16_f32 v2, v77, s0
	ds_write_b16 v1, v2 offset:13360
	v_cvt_pk_bf16_f32 v2, v78, s0
	ds_write_b16 v1, v2 offset:13632
	v_cvt_pk_bf16_f32 v2, v79, s0
	ds_write_b16 v1, v2 offset:13904
	v_cvt_pk_bf16_f32 v2, v72, s0
	ds_write_b16 v1, v2 offset:13120
	v_cvt_pk_bf16_f32 v2, v73, s0
	ds_write_b16 v1, v2 offset:13392
	v_cvt_pk_bf16_f32 v2, v74, s0
	ds_write_b16 v1, v2 offset:13664
	v_cvt_pk_bf16_f32 v2, v75, s0
	ds_write_b16 v1, v2 offset:13936
	v_cvt_pk_bf16_f32 v2, v68, s0
	ds_write_b16 v1, v2 offset:13152
	v_cvt_pk_bf16_f32 v2, v69, s0
	ds_write_b16 v1, v2 offset:13424
	v_cvt_pk_bf16_f32 v2, v70, s0
	ds_write_b16 v1, v2 offset:13696
	v_cvt_pk_bf16_f32 v2, v71, s0
	ds_write_b16 v1, v2 offset:13968
	v_cvt_pk_bf16_f32 v2, v64, s0
	ds_write_b16 v1, v2 offset:17408
	v_cvt_pk_bf16_f32 v2, v65, s0
	ds_write_b16 v1, v2 offset:17680
	v_cvt_pk_bf16_f32 v2, v66, s0
	ds_write_b16 v1, v2 offset:17952
	v_cvt_pk_bf16_f32 v2, v67, s0
	ds_write_b16 v1, v2 offset:18224
	v_cvt_pk_bf16_f32 v2, v60, s0
	ds_write_b16 v1, v2 offset:17440
	v_cvt_pk_bf16_f32 v2, v61, s0
	ds_write_b16 v1, v2 offset:17712
	v_cvt_pk_bf16_f32 v2, v62, s0
	ds_write_b16 v1, v2 offset:17984
	v_cvt_pk_bf16_f32 v2, v63, s0
	ds_write_b16 v1, v2 offset:18256
	v_cvt_pk_bf16_f32 v2, v56, s0
	ds_write_b16 v1, v2 offset:17472
	v_cvt_pk_bf16_f32 v2, v57, s0
	ds_write_b16 v1, v2 offset:17744
	v_cvt_pk_bf16_f32 v2, v58, s0
	ds_write_b16 v1, v2 offset:18016
	v_cvt_pk_bf16_f32 v2, v59, s0
	ds_write_b16 v1, v2 offset:18288
	v_cvt_pk_bf16_f32 v2, v52, s0
	ds_write_b16 v1, v2 offset:17504
	v_cvt_pk_bf16_f32 v2, v53, s0
	ds_write_b16 v1, v2 offset:17776
	v_cvt_pk_bf16_f32 v2, v54, s0
	ds_write_b16 v1, v2 offset:18048
	v_cvt_pk_bf16_f32 v2, v55, s0
	ds_write_b16 v1, v2 offset:18320
	v_cvt_pk_bf16_f32 v2, v48, s0
	ds_write_b16 v1, v2 offset:21760
	v_cvt_pk_bf16_f32 v2, v49, s0
	ds_write_b16 v1, v2 offset:22032
	v_cvt_pk_bf16_f32 v2, v50, s0
	ds_write_b16 v1, v2 offset:22304
	v_cvt_pk_bf16_f32 v2, v51, s0
	ds_write_b16 v1, v2 offset:22576
	v_cvt_pk_bf16_f32 v2, v44, s0
	ds_write_b16 v1, v2 offset:21792
	v_cvt_pk_bf16_f32 v2, v45, s0
	ds_write_b16 v1, v2 offset:22064
	v_cvt_pk_bf16_f32 v2, v46, s0
	ds_write_b16 v1, v2 offset:22336
	v_cvt_pk_bf16_f32 v2, v47, s0
	ds_write_b16 v1, v2 offset:22608
	v_cvt_pk_bf16_f32 v2, v40, s0
	ds_write_b16 v1, v2 offset:21824
	v_cvt_pk_bf16_f32 v2, v41, s0
	ds_write_b16 v1, v2 offset:22096
	v_cvt_pk_bf16_f32 v2, v42, s0
	ds_write_b16 v1, v2 offset:22368
	v_cvt_pk_bf16_f32 v2, v43, s0
	ds_write_b16 v1, v2 offset:22640
	v_cvt_pk_bf16_f32 v2, v36, s0
	ds_write_b16 v1, v2 offset:21856
	v_cvt_pk_bf16_f32 v2, v37, s0
	ds_write_b16 v1, v2 offset:22128
	v_cvt_pk_bf16_f32 v2, v38, s0
	ds_write_b16 v1, v2 offset:22400
	v_cvt_pk_bf16_f32 v2, v39, s0
	ds_write_b16 v1, v2 offset:22672
	v_cvt_pk_bf16_f32 v2, v32, s0
	ds_write_b16 v1, v2 offset:26112
	v_cvt_pk_bf16_f32 v2, v33, s0
	ds_write_b16 v1, v2 offset:26384
	v_cvt_pk_bf16_f32 v2, v34, s0
	ds_write_b16 v1, v2 offset:26656
	v_cvt_pk_bf16_f32 v2, v35, s0
	ds_write_b16 v1, v2 offset:26928
	v_cvt_pk_bf16_f32 v2, v28, s0
	ds_write_b16 v1, v2 offset:26144
	v_cvt_pk_bf16_f32 v2, v29, s0
	ds_write_b16 v1, v2 offset:26416
	v_cvt_pk_bf16_f32 v2, v30, s0
	ds_write_b16 v1, v2 offset:26688
	v_cvt_pk_bf16_f32 v2, v31, s0
	ds_write_b16 v1, v2 offset:26960
	v_cvt_pk_bf16_f32 v2, v24, s0
	ds_write_b16 v1, v2 offset:26176
	v_cvt_pk_bf16_f32 v2, v25, s0
	ds_write_b16 v1, v2 offset:26448
	v_cvt_pk_bf16_f32 v2, v26, s0
	ds_write_b16 v1, v2 offset:26720
	v_cvt_pk_bf16_f32 v2, v27, s0
	ds_write_b16 v1, v2 offset:26992
	v_cvt_pk_bf16_f32 v2, v20, s0
	ds_write_b16 v1, v2 offset:26208
	v_cvt_pk_bf16_f32 v2, v21, s0
	ds_write_b16 v1, v2 offset:26480
	v_cvt_pk_bf16_f32 v2, v22, s0
	ds_write_b16 v1, v2 offset:26752
	v_cvt_pk_bf16_f32 v2, v23, s0
	ds_write_b16 v1, v2 offset:27024
	v_cvt_pk_bf16_f32 v2, v16, s0
	ds_write_b16 v1, v2 offset:30464
	v_cvt_pk_bf16_f32 v2, v17, s0
	ds_write_b16 v1, v2 offset:30736
	v_cvt_pk_bf16_f32 v2, v18, s0
	ds_write_b16 v1, v2 offset:31008
	v_cvt_pk_bf16_f32 v2, v19, s0
	ds_write_b16 v1, v2 offset:31280
	v_cvt_pk_bf16_f32 v2, v12, s0
	ds_write_b16 v1, v2 offset:30496
	v_cvt_pk_bf16_f32 v2, v13, s0
	ds_write_b16 v1, v2 offset:30768
	v_cvt_pk_bf16_f32 v2, v14, s0
	ds_write_b16 v1, v2 offset:31040
	v_cvt_pk_bf16_f32 v2, v15, s0
	ds_write_b16 v1, v2 offset:31312
	v_cvt_pk_bf16_f32 v2, v8, s0
	ds_write_b16 v1, v2 offset:30528
	v_cvt_pk_bf16_f32 v2, v9, s0
	ds_write_b16 v1, v2 offset:30800
	v_cvt_pk_bf16_f32 v2, v10, s0
	ds_write_b16 v1, v2 offset:31072
	v_cvt_pk_bf16_f32 v2, v11, s0
	ds_write_b16 v1, v2 offset:31344
	v_cvt_pk_bf16_f32 v2, v4, s0
	ds_write_b16 v1, v2 offset:30560
	v_cvt_pk_bf16_f32 v2, v5, s0
	ds_write_b16 v1, v2 offset:30832
	v_cvt_pk_bf16_f32 v2, v6, s0
	v_cvt_pk_bf16_f32 v128, v128, s0
	ds_write_b16 v1, v2 offset:31104
	v_cvt_pk_bf16_f32 v2, v7, s0
	ds_write_b16 v1, v128
	ds_write_b16 v1, v2 offset:31376
	v_mov_b32_e32 v1, v178
	s_waitcnt lgkmcnt(0)
	s_barrier
; DEVI int get_tid() { int t = threadIdx.x; asm volatile("" : "+v"(t)); return t; }
; template <int BN>
; DEVI void tile_store256(const char* smem, bf* __restrict__ C, long ldc, long row0, int col0) {
;   constexpr int LDT = BN + 8;
;   constexpr int CPR = BN / 8;
;   const int tid = get_tid();
; #pragma unroll
;   for (int i = 0; i < CPR; ++i) {
;     const int q = tid + 256 * i;
;     const int r = q / CPR, c = q - r * CPR;
;     u32x4 v = *reinterpret_cast<const u32x4*>(smem + (r * LDT + c * 8) * 2);
;     *reinterpret_cast<u32x4*>(C + (row0 + r) * ldc + col0 + c * 8) = v;
;   }
; }
; DEVI void phase_gemm_plain128(const bf* A, int lda, const bf* Wt, int K, int N, bf* C, int ldc, char* smem) {
;     ...
;   for (int v = blockIdx.x; v < 128 * ntn; v += gridDim.x) {
;     int m2, nt;
;     lat_tile_map256(v, ntn, m2, nt);
;     plain_tile256(A, lda, Wt, K, C, ldc, lat_row0_256(m2), nt * 128, smem);
	v_readlane_b32 s56, v251, 58
	v_ashrrev_i32_e32 v2, 31, v1
	v_lshrrev_b32_e32 v2, 28, v2
	v_add_u32_e32 v2, v1, v2
	v_ashrrev_i32_e32 v8, 4, v2
	s_lshl_b64 s[10:11], s[34:35], 1
	v_readlane_b32 s60, v251, 62
	v_lshlrev_b32_e32 v4, 7, v8
	v_lshlrev_b32_e32 v5, 3, v1
	v_ashrrev_i32_e32 v9, 31, v8
	v_readlane_b32 s61, v251, 63
	s_add_u32 s10, s60, s10
	v_mul_lo_u32 v2, v8, s38
	v_sub_u32_e32 v10, v5, v4
	v_lshl_add_u64 v[8:9], s[12:13], 0, v[8:9]
	s_addc_u32 s11, s61, s11
	v_add_lshl_u32 v2, v10, v2, 1
	v_lshlrev_b64 v[8:9], 11, v[8:9]
	ds_read_b128 v[4:7], v2
	v_lshl_add_u64 v[8:9], s[10:11], 0, v[8:9]
	v_ashrrev_i32_e32 v11, 31, v10
	v_add_u32_e32 v2, 0x100, v1
	v_lshl_add_u64 v[12:13], v[10:11], 1, v[8:9]
	v_ashrrev_i32_e32 v8, 31, v2
	v_lshrrev_b32_e32 v8, 28, v8
	v_add_u32_e32 v8, v2, v8
	v_ashrrev_i32_e32 v14, 4, v8
	v_lshlrev_b32_e32 v9, 7, v14
	v_lshlrev_b32_e32 v2, 3, v2
	v_mul_lo_u32 v8, v14, s38
	v_sub_u32_e32 v16, v2, v9
	v_add_lshl_u32 v2, v16, v8, 1
	ds_read_b128 v[8:11], v2
	v_ashrrev_i32_e32 v15, 31, v14
	s_waitcnt lgkmcnt(1)
	global_store_dwordx4 v[12:13], v[4:7], off
	v_ashrrev_i32_e32 v17, 31, v16
	v_add_u32_e32 v2, 0x200, v1
	v_lshl_add_u64 v[4:5], s[12:13], 0, v[14:15]
	v_lshlrev_b64 v[4:5], 11, v[4:5]
	v_lshl_add_u64 v[4:5], s[10:11], 0, v[4:5]
	v_lshl_add_u64 v[4:5], v[16:17], 1, v[4:5]
	s_waitcnt lgkmcnt(0)
	global_store_dwordx4 v[4:5], v[8:11], off
	v_ashrrev_i32_e32 v4, 31, v2
	v_lshrrev_b32_e32 v4, 28, v4
	v_add_u32_e32 v4, v2, v4
	v_ashrrev_i32_e32 v8, 4, v4
	v_lshlrev_b32_e32 v5, 7, v8
	v_lshlrev_b32_e32 v2, 3, v2
	v_ashrrev_i32_e32 v9, 31, v8
	v_mul_lo_u32 v4, v8, s38
	v_sub_u32_e32 v10, v2, v5
	v_lshl_add_u64 v[8:9], s[12:13], 0, v[8:9]
	v_add_lshl_u32 v2, v10, v4, 1
	v_lshlrev_b64 v[8:9], 11, v[8:9]
	ds_read_b128 v[4:7], v2
	v_lshl_add_u64 v[8:9], s[10:11], 0, v[8:9]
	v_ashrrev_i32_e32 v11, 31, v10
	v_add_u32_e32 v2, 0x300, v1
	v_lshl_add_u64 v[12:13], v[10:11], 1, v[8:9]
	v_ashrrev_i32_e32 v8, 31, v2
	v_lshrrev_b32_e32 v8, 28, v8
	v_add_u32_e32 v8, v2, v8
	v_ashrrev_i32_e32 v14, 4, v8
	v_lshlrev_b32_e32 v9, 7, v14
	v_lshlrev_b32_e32 v2, 3, v2
	v_mul_lo_u32 v8, v14, s38
	v_sub_u32_e32 v16, v2, v9
	v_add_lshl_u32 v2, v16, v8, 1
	ds_read_b128 v[8:11], v2
	v_ashrrev_i32_e32 v15, 31, v14
	s_waitcnt lgkmcnt(1)
	global_store_dwordx4 v[12:13], v[4:7], off
	v_ashrrev_i32_e32 v17, 31, v16
	v_add_u32_e32 v2, 0x400, v1
	v_lshl_add_u64 v[4:5], s[12:13], 0, v[14:15]
	v_lshlrev_b64 v[4:5], 11, v[4:5]
	v_lshl_add_u64 v[4:5], s[10:11], 0, v[4:5]
	v_lshl_add_u64 v[4:5], v[16:17], 1, v[4:5]
	s_waitcnt lgkmcnt(0)
	global_store_dwordx4 v[4:5], v[8:11], off
	v_ashrrev_i32_e32 v4, 31, v2
	v_lshrrev_b32_e32 v4, 28, v4
	v_add_u32_e32 v4, v2, v4
	v_ashrrev_i32_e32 v8, 4, v4
	v_lshlrev_b32_e32 v5, 7, v8
	v_lshlrev_b32_e32 v2, 3, v2
	v_ashrrev_i32_e32 v9, 31, v8
	v_mul_lo_u32 v4, v8, s38
	v_sub_u32_e32 v10, v2, v5
	v_lshl_add_u64 v[8:9], s[12:13], 0, v[8:9]
	v_add_lshl_u32 v2, v10, v4, 1
	v_lshlrev_b64 v[8:9], 11, v[8:9]
	ds_read_b128 v[4:7], v2
	v_lshl_add_u64 v[8:9], s[10:11], 0, v[8:9]
	v_ashrrev_i32_e32 v11, 31, v10
	v_add_u32_e32 v2, 0x500, v1
	v_lshl_add_u64 v[12:13], v[10:11], 1, v[8:9]
	v_ashrrev_i32_e32 v8, 31, v2
	v_lshrrev_b32_e32 v8, 28, v8
	v_add_u32_e32 v8, v2, v8
	v_ashrrev_i32_e32 v14, 4, v8
	v_lshlrev_b32_e32 v9, 7, v14
	v_lshlrev_b32_e32 v2, 3, v2
	v_mul_lo_u32 v8, v14, s38
	v_sub_u32_e32 v16, v2, v9
	v_add_lshl_u32 v2, v16, v8, 1
	ds_read_b128 v[8:11], v2
	v_ashrrev_i32_e32 v15, 31, v14
	s_waitcnt lgkmcnt(1)
	global_store_dwordx4 v[12:13], v[4:7], off
	v_ashrrev_i32_e32 v17, 31, v16
	v_add_u32_e32 v2, 0x600, v1
	v_lshl_add_u64 v[4:5], s[12:13], 0, v[14:15]
	v_lshlrev_b64 v[4:5], 11, v[4:5]
	v_lshl_add_u64 v[4:5], s[10:11], 0, v[4:5]
	v_lshl_add_u64 v[4:5], v[16:17], 1, v[4:5]
	s_waitcnt lgkmcnt(0)
	global_store_dwordx4 v[4:5], v[8:11], off
	v_ashrrev_i32_e32 v4, 31, v2
	v_lshrrev_b32_e32 v4, 28, v4
	v_add_u32_e32 v4, v2, v4
	v_ashrrev_i32_e32 v8, 4, v4
	v_lshlrev_b32_e32 v5, 7, v8
	v_lshlrev_b32_e32 v2, 3, v2
	v_ashrrev_i32_e32 v9, 31, v8
	v_mul_lo_u32 v4, v8, s38
	v_sub_u32_e32 v10, v2, v5
	v_lshl_add_u64 v[8:9], s[12:13], 0, v[8:9]
	v_add_lshl_u32 v2, v10, v4, 1
	v_lshlrev_b64 v[8:9], 11, v[8:9]
	ds_read_b128 v[4:7], v2
	v_lshl_add_u64 v[8:9], s[10:11], 0, v[8:9]
	v_ashrrev_i32_e32 v11, 31, v10
	v_add_u32_e32 v2, 0x700, v1
	v_lshl_add_u64 v[12:13], v[10:11], 1, v[8:9]
	v_ashrrev_i32_e32 v8, 31, v2
	v_lshrrev_b32_e32 v8, 28, v8
	v_add_u32_e32 v8, v2, v8
	v_ashrrev_i32_e32 v14, 4, v8
	v_lshlrev_b32_e32 v9, 7, v14
	v_lshlrev_b32_e32 v2, 3, v2
	v_mul_lo_u32 v8, v14, s38
	v_sub_u32_e32 v16, v2, v9
	v_add_lshl_u32 v2, v16, v8, 1
	ds_read_b128 v[8:11], v2
	v_ashrrev_i32_e32 v15, 31, v14
	s_waitcnt lgkmcnt(1)
	global_store_dwordx4 v[12:13], v[4:7], off
	v_ashrrev_i32_e32 v17, 31, v16
	v_add_u32_e32 v2, 0x800, v1
	v_lshl_add_u64 v[4:5], s[12:13], 0, v[14:15]
	v_lshlrev_b64 v[4:5], 11, v[4:5]
	v_lshl_add_u64 v[4:5], s[10:11], 0, v[4:5]
	v_lshl_add_u64 v[4:5], v[16:17], 1, v[4:5]
	s_waitcnt lgkmcnt(0)
; DEVI int get_tid() { int t = threadIdx.x; asm volatile("" : "+v"(t)); return t; }
; template <int BN>
; DEVI void tile_store256(const char* smem, bf* __restrict__ C, long ldc, long row0, int col0) {
;   constexpr int LDT = BN + 8;
;   constexpr int CPR = BN / 8;
;   const int tid = get_tid();
; #pragma unroll
;   for (int i = 0; i < CPR; ++i) {
;     const int q = tid + 256 * i;
;     const int r = q / CPR, c = q - r * CPR;
;     u32x4 v = *reinterpret_cast<const u32x4*>(smem + (r * LDT + c * 8) * 2);
;     *reinterpret_cast<u32x4*>(C + (row0 + r) * ldc + col0 + c * 8) = v;
;   }
; }
; DEVI void phase_gemm_plain128(const bf* A, int lda, const bf* Wt, int K, int N, bf* C, int ldc, char* smem) {
;     ...
;   for (int v = blockIdx.x; v < 128 * ntn; v += gridDim.x) {
;     int m2, nt;
;     lat_tile_map256(v, ntn, m2, nt);
;     plain_tile256(A, lda, Wt, K, C, ldc, lat_row0_256(m2), nt * 128, smem);
	global_store_dwordx4 v[4:5], v[8:11], off
	v_ashrrev_i32_e32 v4, 31, v2
	v_lshrrev_b32_e32 v4, 28, v4
	v_add_u32_e32 v4, v2, v4
	v_ashrrev_i32_e32 v8, 4, v4
	v_lshlrev_b32_e32 v5, 7, v8
	v_lshlrev_b32_e32 v2, 3, v2
	v_ashrrev_i32_e32 v9, 31, v8
	v_mul_lo_u32 v4, v8, s38
	v_sub_u32_e32 v10, v2, v5
	v_lshl_add_u64 v[8:9], s[12:13], 0, v[8:9]
	v_add_lshl_u32 v2, v10, v4, 1
	v_lshlrev_b64 v[8:9], 11, v[8:9]
	ds_read_b128 v[4:7], v2
	v_lshl_add_u64 v[8:9], s[10:11], 0, v[8:9]
	v_ashrrev_i32_e32 v11, 31, v10
	v_add_u32_e32 v2, 0x900, v1
	v_lshl_add_u64 v[12:13], v[10:11], 1, v[8:9]
	v_ashrrev_i32_e32 v8, 31, v2
	v_lshrrev_b32_e32 v8, 28, v8
	v_add_u32_e32 v8, v2, v8
	v_ashrrev_i32_e32 v14, 4, v8
	v_lshlrev_b32_e32 v9, 7, v14
	v_lshlrev_b32_e32 v2, 3, v2
	v_mul_lo_u32 v8, v14, s38
	v_sub_u32_e32 v16, v2, v9
	v_add_lshl_u32 v2, v16, v8, 1
	ds_read_b128 v[8:11], v2
	v_ashrrev_i32_e32 v15, 31, v14
	s_waitcnt lgkmcnt(1)
	global_store_dwordx4 v[12:13], v[4:7], off
	v_ashrrev_i32_e32 v17, 31, v16
	v_add_u32_e32 v2, 0xa00, v1
	v_lshl_add_u64 v[4:5], s[12:13], 0, v[14:15]
	v_lshlrev_b64 v[4:5], 11, v[4:5]
	v_lshl_add_u64 v[4:5], s[10:11], 0, v[4:5]
	v_lshl_add_u64 v[4:5], v[16:17], 1, v[4:5]
	s_waitcnt lgkmcnt(0)
	global_store_dwordx4 v[4:5], v[8:11], off
	v_ashrrev_i32_e32 v4, 31, v2
	v_lshrrev_b32_e32 v4, 28, v4
	v_add_u32_e32 v4, v2, v4
	v_ashrrev_i32_e32 v8, 4, v4
	v_lshlrev_b32_e32 v5, 7, v8
	v_lshlrev_b32_e32 v2, 3, v2
	v_ashrrev_i32_e32 v9, 31, v8
	v_mul_lo_u32 v4, v8, s38
	v_sub_u32_e32 v10, v2, v5
	v_lshl_add_u64 v[8:9], s[12:13], 0, v[8:9]
	v_add_lshl_u32 v2, v10, v4, 1
	v_lshlrev_b64 v[8:9], 11, v[8:9]
	ds_read_b128 v[4:7], v2
	v_lshl_add_u64 v[8:9], s[10:11], 0, v[8:9]
	v_ashrrev_i32_e32 v11, 31, v10
	v_add_u32_e32 v2, 0xb00, v1
	v_lshl_add_u64 v[12:13], v[10:11], 1, v[8:9]
	v_ashrrev_i32_e32 v8, 31, v2
	v_lshrrev_b32_e32 v8, 28, v8
	v_add_u32_e32 v8, v2, v8
	v_ashrrev_i32_e32 v14, 4, v8
	v_lshlrev_b32_e32 v9, 7, v14
	v_lshlrev_b32_e32 v2, 3, v2
	v_mul_lo_u32 v8, v14, s38
	v_sub_u32_e32 v16, v2, v9
	v_add_lshl_u32 v2, v16, v8, 1
	ds_read_b128 v[8:11], v2
	v_ashrrev_i32_e32 v15, 31, v14
	s_waitcnt lgkmcnt(1)
	global_store_dwordx4 v[12:13], v[4:7], off
	v_ashrrev_i32_e32 v17, 31, v16
	v_add_u32_e32 v2, 0xc00, v1
	v_lshl_add_u64 v[4:5], s[12:13], 0, v[14:15]
	v_lshlrev_b64 v[4:5], 11, v[4:5]
	v_lshl_add_u64 v[4:5], s[10:11], 0, v[4:5]
	v_lshl_add_u64 v[4:5], v[16:17], 1, v[4:5]
	s_waitcnt lgkmcnt(0)
	global_store_dwordx4 v[4:5], v[8:11], off
	v_ashrrev_i32_e32 v4, 31, v2
	v_lshrrev_b32_e32 v4, 28, v4
	v_add_u32_e32 v4, v2, v4
	v_ashrrev_i32_e32 v8, 4, v4
	v_lshlrev_b32_e32 v5, 7, v8
	v_lshlrev_b32_e32 v2, 3, v2
	v_ashrrev_i32_e32 v9, 31, v8
	v_mul_lo_u32 v4, v8, s38
	v_sub_u32_e32 v10, v2, v5
	v_lshl_add_u64 v[8:9], s[12:13], 0, v[8:9]
	v_add_lshl_u32 v2, v10, v4, 1
	v_lshlrev_b64 v[8:9], 11, v[8:9]
	ds_read_b128 v[4:7], v2
	v_lshl_add_u64 v[8:9], s[10:11], 0, v[8:9]
	v_ashrrev_i32_e32 v11, 31, v10
	v_add_u32_e32 v2, 0xd00, v1
	v_lshl_add_u64 v[12:13], v[10:11], 1, v[8:9]
	v_ashrrev_i32_e32 v8, 31, v2
	v_lshrrev_b32_e32 v8, 28, v8
	v_add_u32_e32 v8, v2, v8
	v_ashrrev_i32_e32 v14, 4, v8
	v_lshlrev_b32_e32 v9, 7, v14
	v_lshlrev_b32_e32 v2, 3, v2
	v_mul_lo_u32 v8, v14, s38
	v_sub_u32_e32 v16, v2, v9
	v_add_lshl_u32 v2, v16, v8, 1
	ds_read_b128 v[8:11], v2
	v_ashrrev_i32_e32 v15, 31, v14
	s_waitcnt lgkmcnt(1)
	global_store_dwordx4 v[12:13], v[4:7], off
	v_ashrrev_i32_e32 v17, 31, v16
	v_add_u32_e32 v2, 0xe00, v1
	v_lshl_add_u64 v[4:5], s[12:13], 0, v[14:15]
	v_lshlrev_b64 v[4:5], 11, v[4:5]
	v_lshl_add_u64 v[4:5], s[10:11], 0, v[4:5]
	v_lshl_add_u64 v[4:5], v[16:17], 1, v[4:5]
	s_waitcnt lgkmcnt(0)
	global_store_dwordx4 v[4:5], v[8:11], off
	v_ashrrev_i32_e32 v4, 31, v2
	v_lshrrev_b32_e32 v4, 28, v4
	v_add_u32_e32 v4, v2, v4
	v_ashrrev_i32_e32 v8, 4, v4
	v_lshlrev_b32_e32 v5, 7, v8
	v_lshlrev_b32_e32 v2, 3, v2
	v_mul_lo_u32 v4, v8, s38
	v_sub_u32_e32 v10, v2, v5
	v_add_lshl_u32 v2, v10, v4, 1
	v_add_u32_e32 v1, 0xf00, v1
	ds_read_b128 v[4:7], v2
	v_ashrrev_i32_e32 v9, 31, v8
	v_ashrrev_i32_e32 v2, 31, v1
	v_lshl_add_u64 v[8:9], s[12:13], 0, v[8:9]
	v_lshrrev_b32_e32 v2, 28, v2
	v_lshlrev_b64 v[8:9], 11, v[8:9]
	v_add_u32_e32 v2, v1, v2
	v_lshl_add_u64 v[8:9], s[10:11], 0, v[8:9]
	v_ashrrev_i32_e32 v11, 31, v10
	v_ashrrev_i32_e32 v14, 4, v2
	v_lshl_add_u64 v[12:13], v[10:11], 1, v[8:9]
	v_lshlrev_b32_e32 v8, 7, v14
	v_lshlrev_b32_e32 v1, 3, v1
	v_mul_lo_u32 v2, v14, s38
	v_sub_u32_e32 v16, v1, v8
	v_add_lshl_u32 v1, v16, v2, 1
	v_ashrrev_i32_e32 v15, 31, v14
	ds_read_b128 v[8:11], v1
	s_waitcnt lgkmcnt(1)
	global_store_dwordx4 v[12:13], v[4:7], off
	v_ashrrev_i32_e32 v17, 31, v16
	v_readlane_b32 s58, v251, 60
	v_lshl_add_u64 v[4:5], s[12:13], 0, v[14:15]
	v_lshlrev_b64 v[4:5], 11, v[4:5]
	v_lshl_add_u64 v[4:5], s[10:11], 0, v[4:5]
	v_readlane_b32 s10, v252, 59
	s_add_i32 s2, s2, s10
	v_readlane_b32 s59, v251, 61
	v_lshl_add_u64 v[4:5], v[16:17], 1, v[4:5]
	s_cmpk_gt_i32 s2, 0x3ff
	v_readlane_b32 s57, v251, 59
	v_readlane_b32 s62, v252, 0
	v_readlane_b32 s63, v252, 1
	v_readlane_b32 s64, v252, 2
	v_readlane_b32 s65, v252, 3
	v_readlane_b32 s66, v252, 4
	v_readlane_b32 s67, v252, 5
	v_readlane_b32 s68, v252, 6
	v_readlane_b32 s69, v252, 7
	v_readlane_b32 s70, v252, 8
	v_readlane_b32 s71, v252, 9
	s_waitcnt lgkmcnt(0)
	global_store_dwordx4 v[4:5], v[8:11], off
	s_barrier
	v_readlane_b32 s11, v252, 60
	s_cbranch_scc0 .LBB0_925

; DEVI f32x4 mfma16(bf16x8 a, bf16x8 b, f32x4 c) { return __builtin_amdgcn_mfma_f32_16x16x32_bf16(a, b, c, 0, 0, 0); }
; DEVI void gemm_core3(f32x4 (&acc)[8][4], const bf* __restrict__ A, int lda, const bf* __restrict__ Bt, int ldb, int K, char* smem) {
;     ...
;   for (int kt = 0; kt < nk; ++kt) {
;     const int k1 = min((kt + 1) * 32, klast);
;     const int sn = ((kt + 1) & 1) * STG;
;     const int so = (kt & 1) * STG;
;     bf16x8 bfr[4], af[8];
; #pragma unroll
;     for (int n = 0; n < 4; ++n) bfr[n] = *reinterpret_cast<const bf16x8*>(bbase + so + n * 16 * 64);
; #pragma unroll
;     for (int m = 0; m < 8; ++m) af[m] = *reinterpret_cast<const bf16x8*>(abase + so + m * 16 * 64);
; #pragma unroll
;     for (int i = 0; i < 4; ++i) glds16(Ap + i * sa + k1, dbase + sn + i * 4096);
; #pragma unroll
;     for (int i = 0; i < 2; ++i) glds16(Bp + i * sb + k1, dbase + sn + ASZ + i * 4096);
;     __builtin_amdgcn_s_setprio(1);
; #pragma unroll
;     for (int m = 0; m < 8; ++m)
; #pragma unroll
;       for (int n = 0; n < 4; ++n) acc[m][n] = mfma16(af[m], bfr[n], acc[m][n]);
;     __builtin_amdgcn_s_setprio(0);
;     __syncthreads();
;   }
.Lg3_loop_936:
	v_add_u32_e32 v216, s10, v146
	v_add_u32_e32 v217, s10, v2
	ds_read_b128 v[148:151], v217 offset:16384
	ds_read_b128 v[166:169], v216
	ds_read_b128 v[154:157], v217 offset:17408
	ds_read_b128 v[158:161], v217 offset:18432
	ds_read_b128 v[162:165], v217 offset:19456
	ds_read_b128 v[170:173], v216 offset:1024
	ds_read_b128 v[174:177], v216 offset:2048
	ds_read_b128 v[192:195], v216 offset:3072
	ds_read_b128 v[196:199], v216 offset:4096
	ds_read_b128 v[204:207], v216 offset:5120
	ds_read_b128 v[208:211], v216 offset:6144
	ds_read_b128 v[212:215], v216 offset:7168
	s_setprio 1
	s_waitcnt lgkmcnt(10)
	v_mfma_f32_16x16x32_bf16 v[128:131], v[166:169], v[148:151], v[128:131]
	s_waitcnt lgkmcnt(9)
	v_mfma_f32_16x16x32_bf16 v[124:127], v[166:169], v[154:157], v[124:127]
	s_waitcnt lgkmcnt(8)
	v_mfma_f32_16x16x32_bf16 v[120:123], v[166:169], v[158:161], v[120:123]
	s_waitcnt lgkmcnt(7)
	v_mfma_f32_16x16x32_bf16 v[116:119], v[166:169], v[162:165], v[116:119]
	s_waitcnt lgkmcnt(6)
	v_mfma_f32_16x16x32_bf16 v[112:115], v[170:173], v[148:151], v[112:115]
	v_mfma_f32_16x16x32_bf16 v[108:111], v[170:173], v[154:157], v[108:111]
	v_mfma_f32_16x16x32_bf16 v[104:107], v[170:173], v[158:161], v[104:107]
	v_mfma_f32_16x16x32_bf16 v[100:103], v[170:173], v[162:165], v[100:103]
	s_waitcnt lgkmcnt(5)
	v_mfma_f32_16x16x32_bf16 v[96:99], v[174:177], v[148:151], v[96:99]
	v_mfma_f32_16x16x32_bf16 v[92:95], v[174:177], v[154:157], v[92:95]
	v_mfma_f32_16x16x32_bf16 v[88:91], v[174:177], v[158:161], v[88:91]
	v_mfma_f32_16x16x32_bf16 v[84:87], v[174:177], v[162:165], v[84:87]
	s_waitcnt lgkmcnt(4)
	v_mfma_f32_16x16x32_bf16 v[80:83], v[192:195], v[148:151], v[80:83]
	v_mfma_f32_16x16x32_bf16 v[76:79], v[192:195], v[154:157], v[76:79]
	v_mfma_f32_16x16x32_bf16 v[72:75], v[192:195], v[158:161], v[72:75]
	v_mfma_f32_16x16x32_bf16 v[68:71], v[192:195], v[162:165], v[68:71]
	s_waitcnt lgkmcnt(3)
	v_mfma_f32_16x16x32_bf16 v[64:67], v[196:199], v[148:151], v[64:67]
	v_mfma_f32_16x16x32_bf16 v[60:63], v[196:199], v[154:157], v[60:63]
	v_mfma_f32_16x16x32_bf16 v[56:59], v[196:199], v[158:161], v[56:59]
	v_mfma_f32_16x16x32_bf16 v[52:55], v[196:199], v[162:165], v[52:55]
	s_waitcnt lgkmcnt(2)
	v_mfma_f32_16x16x32_bf16 v[48:51], v[204:207], v[148:151], v[48:51]
	v_mfma_f32_16x16x32_bf16 v[44:47], v[204:207], v[154:157], v[44:47]
	v_mfma_f32_16x16x32_bf16 v[40:43], v[204:207], v[158:161], v[40:43]
	v_mfma_f32_16x16x32_bf16 v[36:39], v[204:207], v[162:165], v[36:39]
	s_waitcnt lgkmcnt(1)
	v_mfma_f32_16x16x32_bf16 v[32:35], v[208:211], v[148:151], v[32:35]
	v_mfma_f32_16x16x32_bf16 v[28:31], v[208:211], v[154:157], v[28:31]
	v_mfma_f32_16x16x32_bf16 v[24:27], v[208:211], v[158:161], v[24:27]
	v_mfma_f32_16x16x32_bf16 v[20:23], v[208:211], v[162:165], v[20:23]
	s_waitcnt lgkmcnt(0)
	v_mfma_f32_16x16x32_bf16 v[16:19], v[212:215], v[148:151], v[16:19]
	v_mfma_f32_16x16x32_bf16 v[12:15], v[212:215], v[154:157], v[12:15]
	v_mfma_f32_16x16x32_bf16 v[8:11], v[212:215], v[158:161], v[8:11]
	v_mfma_f32_16x16x32_bf16 v[4:7], v[212:215], v[162:165], v[4:7]
	s_setprio 0
	s_add_i32 s10, s10, 0x6000
	s_cmp_lg_u32 s10, 0x12000
	s_cselect_b32 s10, s10, 0
	s_waitcnt vmcnt(0)
	s_barrier
	v_add_u32_e32 v216, s10, v146
	v_add_u32_e32 v217, s10, v2
	ds_read_b128 v[148:151], v217 offset:16384
	ds_read_b128 v[166:169], v216
	ds_read_b128 v[154:157], v217 offset:17408
	ds_read_b128 v[158:161], v217 offset:18432
	ds_read_b128 v[162:165], v217 offset:19456
	ds_read_b128 v[170:173], v216 offset:1024
	ds_read_b128 v[174:177], v216 offset:2048
	ds_read_b128 v[192:195], v216 offset:3072
	ds_read_b128 v[196:199], v216 offset:4096
	ds_read_b128 v[204:207], v216 offset:5120
	ds_read_b128 v[208:211], v216 offset:6144
	ds_read_b128 v[212:215], v216 offset:7168
	v_readfirstlane_b32 s17, v140
	s_add_i32 s96, s11, 0x6000
	s_cmp_lg_u32 s96, 0x12000
	s_cselect_b32 s96, s96, 0
	s_add_i32 s96, s96, s17
	s_add_i32 s17, s17, s11
	s_setprio 2
	s_waitcnt lgkmcnt(10)
	s_mov_b32 m0, s17
	s_add_i32 s17, s17, 0x1000
	v_mfma_f32_16x16x32_bf16 v[128:131], v[166:169], v[148:151], v[128:131]
	s_waitcnt lgkmcnt(9)
	v_mfma_f32_16x16x32_bf16 v[124:127], v[166:169], v[154:157], v[124:127]
	global_load_lds_dwordx4 v[218:219], off
	v_lshl_add_u64 v[218:219], v[218:219], 0, 64
	s_waitcnt lgkmcnt(8)
	s_mov_b32 m0, s96
	s_add_i32 s96, s96, 0x1000
	v_mfma_f32_16x16x32_bf16 v[120:123], v[166:169], v[158:161], v[120:123]
	s_waitcnt lgkmcnt(7)
	v_mfma_f32_16x16x32_bf16 v[116:119], v[166:169], v[162:165], v[116:119]
	global_load_lds_dwordx4 v[218:219], off
	v_lshl_add_u64 v[218:219], v[218:219], 0, 64
	s_waitcnt lgkmcnt(6)
	v_mfma_f32_16x16x32_bf16 v[112:115], v[170:173], v[148:151], v[112:115]
	s_mov_b32 m0, s17
	s_add_i32 s17, s17, 0x1000
	v_mfma_f32_16x16x32_bf16 v[108:111], v[170:173], v[154:157], v[108:111]
	v_mfma_f32_16x16x32_bf16 v[104:107], v[170:173], v[158:161], v[104:107]
	global_load_lds_dwordx4 v[220:221], off
	v_lshl_add_u64 v[220:221], v[220:221], 0, 64
	s_mov_b32 m0, s96
	s_add_i32 s96, s96, 0x1000
	v_mfma_f32_16x16x32_bf16 v[100:103], v[170:173], v[162:165], v[100:103]
	s_waitcnt lgkmcnt(5)
	v_mfma_f32_16x16x32_bf16 v[96:99], v[174:177], v[148:151], v[96:99]
	global_load_lds_dwordx4 v[220:221], off
	v_lshl_add_u64 v[220:221], v[220:221], 0, 64
	v_mfma_f32_16x16x32_bf16 v[92:95], v[174:177], v[154:157], v[92:95]
	s_mov_b32 m0, s17
	s_add_i32 s17, s17, 0x1000
	v_mfma_f32_16x16x32_bf16 v[88:91], v[174:177], v[158:161], v[88:91]
	v_mfma_f32_16x16x32_bf16 v[84:87], v[174:177], v[162:165], v[84:87]
	global_load_lds_dwordx4 v[222:223], off
	v_lshl_add_u64 v[222:223], v[222:223], 0, 64
	s_waitcnt lgkmcnt(4)
; DEVI f32x4 mfma16(bf16x8 a, bf16x8 b, f32x4 c) { return __builtin_amdgcn_mfma_f32_16x16x32_bf16(a, b, c, 0, 0, 0); }
; DEVI void gemm_core3(f32x4 (&acc)[8][4], const bf* __restrict__ A, int lda, const bf* __restrict__ Bt, int ldb, int K, char* smem) {
;     ...
;   for (int kt = 0; kt < nk; ++kt) {
;     const int k1 = min((kt + 1) * 32, klast);
;     const int sn = ((kt + 1) & 1) * STG;
;     const int so = (kt & 1) * STG;
;     bf16x8 bfr[4], af[8];
; #pragma unroll
;     for (int n = 0; n < 4; ++n) bfr[n] = *reinterpret_cast<const bf16x8*>(bbase + so + n * 16 * 64);
; #pragma unroll
;     for (int m = 0; m < 8; ++m) af[m] = *reinterpret_cast<const bf16x8*>(abase + so + m * 16 * 64);
; #pragma unroll
;     for (int i = 0; i < 4; ++i) glds16(Ap + i * sa + k1, dbase + sn + i * 4096);
; #pragma unroll
;     for (int i = 0; i < 2; ++i) glds16(Bp + i * sb + k1, dbase + sn + ASZ + i * 4096);
;     __builtin_amdgcn_s_setprio(1);
; #pragma unroll
;     for (int m = 0; m < 8; ++m)
; #pragma unroll
;       for (int n = 0; n < 4; ++n) acc[m][n] = mfma16(af[m], bfr[n], acc[m][n]);
;     __builtin_amdgcn_s_setprio(0);
;     __syncthreads();
;   }
	s_mov_b32 m0, s96
	s_add_i32 s96, s96, 0x1000
	v_mfma_f32_16x16x32_bf16 v[80:83], v[192:195], v[148:151], v[80:83]
	v_mfma_f32_16x16x32_bf16 v[76:79], v[192:195], v[154:157], v[76:79]
	global_load_lds_dwordx4 v[222:223], off
	v_lshl_add_u64 v[222:223], v[222:223], 0, 64
	v_mfma_f32_16x16x32_bf16 v[72:75], v[192:195], v[158:161], v[72:75]
	s_mov_b32 m0, s17
	s_add_i32 s17, s17, 0x1000
	v_mfma_f32_16x16x32_bf16 v[68:71], v[192:195], v[162:165], v[68:71]
	s_waitcnt lgkmcnt(3)
	v_mfma_f32_16x16x32_bf16 v[64:67], v[196:199], v[148:151], v[64:67]
	global_load_lds_dwordx4 v[224:225], off
	v_lshl_add_u64 v[224:225], v[224:225], 0, 64
	s_mov_b32 m0, s96
	s_add_i32 s96, s96, 0x1000
	v_mfma_f32_16x16x32_bf16 v[60:63], v[196:199], v[154:157], v[60:63]
	v_mfma_f32_16x16x32_bf16 v[56:59], v[196:199], v[158:161], v[56:59]
	global_load_lds_dwordx4 v[224:225], off
	v_lshl_add_u64 v[224:225], v[224:225], 0, 64
	v_mfma_f32_16x16x32_bf16 v[52:55], v[196:199], v[162:165], v[52:55]
	s_waitcnt lgkmcnt(2)
	s_mov_b32 m0, s17
	s_add_i32 s17, s17, 0x1000
	v_mfma_f32_16x16x32_bf16 v[48:51], v[204:207], v[148:151], v[48:51]
	v_mfma_f32_16x16x32_bf16 v[44:47], v[204:207], v[154:157], v[44:47]
	global_load_lds_dwordx4 v[226:227], off
	v_lshl_add_u64 v[226:227], v[226:227], 0, 64
	s_mov_b32 m0, s96
	s_add_i32 s96, s96, 0x1000
	v_mfma_f32_16x16x32_bf16 v[40:43], v[204:207], v[158:161], v[40:43]
	v_mfma_f32_16x16x32_bf16 v[36:39], v[204:207], v[162:165], v[36:39]
	global_load_lds_dwordx4 v[226:227], off
	v_lshl_add_u64 v[226:227], v[226:227], 0, 64
	s_waitcnt lgkmcnt(1)
	v_mfma_f32_16x16x32_bf16 v[32:35], v[208:211], v[148:151], v[32:35]
	s_mov_b32 m0, s17
	s_add_i32 s17, s17, 0x1000
	v_mfma_f32_16x16x32_bf16 v[28:31], v[208:211], v[154:157], v[28:31]
	v_mfma_f32_16x16x32_bf16 v[24:27], v[208:211], v[158:161], v[24:27]
	global_load_lds_dwordx4 v[228:229], off
	v_lshl_add_u64 v[228:229], v[228:229], 0, 64
	s_mov_b32 m0, s96
	s_add_i32 s96, s96, 0x1000
	v_mfma_f32_16x16x32_bf16 v[20:23], v[208:211], v[162:165], v[20:23]
	s_waitcnt lgkmcnt(0)
	v_mfma_f32_16x16x32_bf16 v[16:19], v[212:215], v[148:151], v[16:19]
	global_load_lds_dwordx4 v[228:229], off
	v_lshl_add_u64 v[228:229], v[228:229], 0, 64
	v_mfma_f32_16x16x32_bf16 v[12:15], v[212:215], v[154:157], v[12:15]
	v_mfma_f32_16x16x32_bf16 v[8:11], v[212:215], v[158:161], v[8:11]
	v_mfma_f32_16x16x32_bf16 v[4:7], v[212:215], v[162:165], v[4:7]
	s_setprio 0
	s_add_i32 s10, s10, 0x6000
	s_cmp_lg_u32 s10, 0x12000
	s_cselect_b32 s10, s10, 0
	s_sub_i32 s11, s11, 0x6000
	s_cmp_lt_i32 s11, 0
	s_cselect_b32 s11, 0xc000, s11
	s_add_i32 s3, s3, 1
	s_cmp_lt_i32 s3, 15
	s_waitcnt vmcnt(1)
	s_barrier
	s_cbranch_scc1 .Lg3_loop_936
	v_add_u32_e32 v216, s10, v146
	v_add_u32_e32 v217, s10, v2
	ds_read_b128 v[148:151], v217 offset:16384
	ds_read_b128 v[166:169], v216
	ds_read_b128 v[154:157], v217 offset:17408
	ds_read_b128 v[158:161], v217 offset:18432
	ds_read_b128 v[162:165], v217 offset:19456
	ds_read_b128 v[170:173], v216 offset:1024
	ds_read_b128 v[174:177], v216 offset:2048
	ds_read_b128 v[192:195], v216 offset:3072
	ds_read_b128 v[196:199], v216 offset:4096
	ds_read_b128 v[204:207], v216 offset:5120
	ds_read_b128 v[208:211], v216 offset:6144
	ds_read_b128 v[212:215], v216 offset:7168
	s_setprio 1
	s_waitcnt lgkmcnt(10)
	v_mfma_f32_16x16x32_bf16 v[128:131], v[166:169], v[148:151], v[128:131]
	s_waitcnt lgkmcnt(9)
	v_mfma_f32_16x16x32_bf16 v[124:127], v[166:169], v[154:157], v[124:127]
	s_waitcnt lgkmcnt(8)
	v_mfma_f32_16x16x32_bf16 v[120:123], v[166:169], v[158:161], v[120:123]
	s_waitcnt lgkmcnt(7)
	v_mfma_f32_16x16x32_bf16 v[116:119], v[166:169], v[162:165], v[116:119]
	s_waitcnt lgkmcnt(6)
	v_mfma_f32_16x16x32_bf16 v[112:115], v[170:173], v[148:151], v[112:115]
	v_mfma_f32_16x16x32_bf16 v[108:111], v[170:173], v[154:157], v[108:111]
	v_mfma_f32_16x16x32_bf16 v[104:107], v[170:173], v[158:161], v[104:107]
	v_mfma_f32_16x16x32_bf16 v[100:103], v[170:173], v[162:165], v[100:103]
	s_waitcnt lgkmcnt(5)
	v_mfma_f32_16x16x32_bf16 v[96:99], v[174:177], v[148:151], v[96:99]
	v_mfma_f32_16x16x32_bf16 v[92:95], v[174:177], v[154:157], v[92:95]
	v_mfma_f32_16x16x32_bf16 v[88:91], v[174:177], v[158:161], v[88:91]
	v_mfma_f32_16x16x32_bf16 v[84:87], v[174:177], v[162:165], v[84:87]
	s_waitcnt lgkmcnt(4)
	v_mfma_f32_16x16x32_bf16 v[80:83], v[192:195], v[148:151], v[80:83]
	v_mfma_f32_16x16x32_bf16 v[76:79], v[192:195], v[154:157], v[76:79]
	v_mfma_f32_16x16x32_bf16 v[72:75], v[192:195], v[158:161], v[72:75]
	v_mfma_f32_16x16x32_bf16 v[68:71], v[192:195], v[162:165], v[68:71]
	s_waitcnt lgkmcnt(3)
	v_mfma_f32_16x16x32_bf16 v[64:67], v[196:199], v[148:151], v[64:67]
	v_mfma_f32_16x16x32_bf16 v[60:63], v[196:199], v[154:157], v[60:63]
	v_mfma_f32_16x16x32_bf16 v[56:59], v[196:199], v[158:161], v[56:59]
	v_mfma_f32_16x16x32_bf16 v[52:55], v[196:199], v[162:165], v[52:55]
	s_waitcnt lgkmcnt(2)
	v_mfma_f32_16x16x32_bf16 v[48:51], v[204:207], v[148:151], v[48:51]
	v_mfma_f32_16x16x32_bf16 v[44:47], v[204:207], v[154:157], v[44:47]
	v_mfma_f32_16x16x32_bf16 v[40:43], v[204:207], v[158:161], v[40:43]
	v_mfma_f32_16x16x32_bf16 v[36:39], v[204:207], v[162:165], v[36:39]
	s_waitcnt lgkmcnt(1)
	v_mfma_f32_16x16x32_bf16 v[32:35], v[208:211], v[148:151], v[32:35]
	v_mfma_f32_16x16x32_bf16 v[28:31], v[208:211], v[154:157], v[28:31]
	v_mfma_f32_16x16x32_bf16 v[24:27], v[208:211], v[158:161], v[24:27]
	v_mfma_f32_16x16x32_bf16 v[20:23], v[208:211], v[162:165], v[20:23]
	s_waitcnt lgkmcnt(0)
	v_mfma_f32_16x16x32_bf16 v[16:19], v[212:215], v[148:151], v[16:19]
	v_mfma_f32_16x16x32_bf16 v[12:15], v[212:215], v[154:157], v[12:15]
	v_mfma_f32_16x16x32_bf16 v[8:11], v[212:215], v[158:161], v[8:11]
	v_mfma_f32_16x16x32_bf16 v[4:7], v[212:215], v[162:165], v[4:7]
	s_setprio 0
	s_add_i32 s10, s10, 0x6000
	s_cmp_lg_u32 s10, 0x12000
	s_cselect_b32 s10, s10, 0
	s_waitcnt vmcnt(0)
	s_barrier
; DEVI float silu_(float x) { return x / (1.f + __expf(-x)); }
; DEVI f32x4 mfma16(bf16x8 a, bf16x8 b, f32x4 c) { return __builtin_amdgcn_mfma_f32_16x16x32_bf16(a, b, c, 0, 0, 0); }
; DEVI void gemm_core3(f32x4 (&acc)[8][4], const bf* __restrict__ A, int lda, const bf* __restrict__ Bt, int ldb, int K, char* smem) {
;     ...
;     bf16x8 bfr[4], af[8];
; #pragma unroll
;     for (int n = 0; n < 4; ++n) bfr[n] = *reinterpret_cast<const bf16x8*>(bbase + so + n * 16 * 64);
; #pragma unroll
;     for (int m = 0; m < 8; ++m) af[m] = *reinterpret_cast<const bf16x8*>(abase + so + m * 16 * 64);
; #pragma unroll
;     for (int i = 0; i < 4; ++i) glds16(Ap + i * sa + k1, dbase + sn + i * 4096);
; #pragma unroll
;     for (int i = 0; i < 2; ++i) glds16(Bp + i * sb + k1, dbase + sn + ASZ + i * 4096);
;     __builtin_amdgcn_s_setprio(1);
; #pragma unroll
;     for (int m = 0; m < 8; ++m)
; #pragma unroll
;       for (int n = 0; n < 4; ++n) acc[m][n] = mfma16(af[m], bfr[n], acc[m][n]);
;     __builtin_amdgcn_s_setprio(0);
; DEVI void ffn1_tile256(const P& p, const bf* W, long row0, int n0  , char* smem) {
;     ...
;   bf* tl = reinterpret_cast<bf*>(smem);
; #pragma unroll
;   for (int m = 0; m < 8; ++m)
; #pragma unroll
;     for (int pr = 0; pr < 2; ++pr) {
;       const int cl = (wc * 2 + pr) * 16 + l15;
; #pragma unroll
;       for (int j = 0; j < 4; ++j) {
;         const int rl = wr * 128 + m * 16 + quad * 4 + j;
;         float a = acc[m][2 * pr][j], b = acc[m][2 * pr + 1][j];
;         tl[rl * 72 + cl] = f2bf(silu_(a) * b);
;       }
	v_add_u32_e32 v216, s10, v146
	v_add_u32_e32 v217, s10, v2
	ds_read_b128 v[148:151], v217 offset:16384
	ds_read_b128 v[166:169], v216
	ds_read_b128 v[154:157], v217 offset:17408
	ds_read_b128 v[158:161], v217 offset:18432
	ds_read_b128 v[162:165], v217 offset:19456
	ds_read_b128 v[170:173], v216 offset:1024
	ds_read_b128 v[174:177], v216 offset:2048
	ds_read_b128 v[192:195], v216 offset:3072
	ds_read_b128 v[196:199], v216 offset:4096
	ds_read_b128 v[204:207], v216 offset:5120
	ds_read_b128 v[208:211], v216 offset:6144
	ds_read_b128 v[212:215], v216 offset:7168
	s_setprio 1
	s_waitcnt lgkmcnt(10)
	v_mfma_f32_16x16x32_bf16 v[128:131], v[166:169], v[148:151], v[128:131]
	s_waitcnt lgkmcnt(9)
	v_mfma_f32_16x16x32_bf16 v[124:127], v[166:169], v[154:157], v[124:127]
	s_waitcnt lgkmcnt(8)
	v_mfma_f32_16x16x32_bf16 v[120:123], v[166:169], v[158:161], v[120:123]
	s_waitcnt lgkmcnt(7)
	v_mfma_f32_16x16x32_bf16 v[116:119], v[166:169], v[162:165], v[116:119]
	s_waitcnt lgkmcnt(6)
	v_mfma_f32_16x16x32_bf16 v[112:115], v[170:173], v[148:151], v[112:115]
	v_mfma_f32_16x16x32_bf16 v[108:111], v[170:173], v[154:157], v[108:111]
	v_mfma_f32_16x16x32_bf16 v[104:107], v[170:173], v[158:161], v[104:107]
	v_mfma_f32_16x16x32_bf16 v[100:103], v[170:173], v[162:165], v[100:103]
	s_waitcnt lgkmcnt(5)
	v_mfma_f32_16x16x32_bf16 v[96:99], v[174:177], v[148:151], v[96:99]
	v_mfma_f32_16x16x32_bf16 v[92:95], v[174:177], v[154:157], v[92:95]
	v_mfma_f32_16x16x32_bf16 v[88:91], v[174:177], v[158:161], v[88:91]
	v_mfma_f32_16x16x32_bf16 v[84:87], v[174:177], v[162:165], v[84:87]
	s_waitcnt lgkmcnt(4)
	v_mfma_f32_16x16x32_bf16 v[80:83], v[192:195], v[148:151], v[80:83]
	v_mfma_f32_16x16x32_bf16 v[76:79], v[192:195], v[154:157], v[76:79]
	v_mfma_f32_16x16x32_bf16 v[72:75], v[192:195], v[158:161], v[72:75]
	v_mfma_f32_16x16x32_bf16 v[68:71], v[192:195], v[162:165], v[68:71]
	s_waitcnt lgkmcnt(3)
	v_mfma_f32_16x16x32_bf16 v[64:67], v[196:199], v[148:151], v[64:67]
	v_mfma_f32_16x16x32_bf16 v[60:63], v[196:199], v[154:157], v[60:63]
	v_mfma_f32_16x16x32_bf16 v[56:59], v[196:199], v[158:161], v[56:59]
	v_mfma_f32_16x16x32_bf16 v[52:55], v[196:199], v[162:165], v[52:55]
	s_waitcnt lgkmcnt(2)
	v_mfma_f32_16x16x32_bf16 v[48:51], v[204:207], v[148:151], v[48:51]
	v_mfma_f32_16x16x32_bf16 v[44:47], v[204:207], v[154:157], v[44:47]
	v_mfma_f32_16x16x32_bf16 v[40:43], v[204:207], v[158:161], v[40:43]
	v_mfma_f32_16x16x32_bf16 v[36:39], v[204:207], v[162:165], v[36:39]
	s_waitcnt lgkmcnt(1)
	v_mfma_f32_16x16x32_bf16 v[32:35], v[208:211], v[148:151], v[32:35]
	v_mfma_f32_16x16x32_bf16 v[28:31], v[208:211], v[154:157], v[28:31]
	v_mfma_f32_16x16x32_bf16 v[24:27], v[208:211], v[158:161], v[24:27]
	v_mfma_f32_16x16x32_bf16 v[20:23], v[208:211], v[162:165], v[20:23]
	s_waitcnt lgkmcnt(0)
	v_mfma_f32_16x16x32_bf16 v[16:19], v[212:215], v[148:151], v[16:19]
	v_mfma_f32_16x16x32_bf16 v[12:15], v[212:215], v[154:157], v[12:15]
	v_mfma_f32_16x16x32_bf16 v[8:11], v[212:215], v[158:161], v[8:11]
	v_mfma_f32_16x16x32_bf16 v[4:7], v[212:215], v[162:165], v[4:7]
	s_setprio 0
	s_add_i32 s10, s10, 0x6000
	s_cmp_lg_u32 s10, 0x12000
	s_cselect_b32 s10, s10, 0
	s_waitcnt vmcnt(0)
	s_barrier
	v_mul_f32_e32 v2, 0xbfb8aa3b, v128
	v_exp_f32_e32 v2, v2
	v_and_b32_e32 v132, 15, v1
	v_and_b32_e32 v133, 0xfffff80, v1
	v_lshrrev_b32_e32 v134, 2, v1
	v_add_f32_e32 v135, 1.0, v2
	v_div_scale_f32 v136, s[10:11], v135, v135, v128
	v_rcp_f32_e32 v137, v136
	v_lshlrev_b32_e32 v2, 1, v132
	v_and_or_b32 v2, v1, 64, v2
	v_and_or_b32 v133, v134, 12, v133
	v_fma_f32 v1, -v136, v137, 1.0
	v_fmac_f32_e32 v137, v1, v137
	v_div_scale_f32 v1, vcc, v128, v135, v128
	v_mul_f32_e32 v132, v1, v137
	v_fma_f32 v134, -v136, v132, v1
	v_fmac_f32_e32 v132, v134, v137
	v_fma_f32 v1, -v136, v132, v1
	v_div_fmas_f32 v1, v1, v137, v132
	v_mul_f32_e32 v132, 0xbfb8aa3b, v129
	v_exp_f32_e32 v132, v132
	v_div_fixup_f32 v1, v1, v135, v128
	v_mul_f32_e32 v1, v124, v1
	s_movk_i32 s3, 0x90
	v_add_f32_e32 v124, 1.0, v132
	v_div_scale_f32 v128, s[10:11], v124, v124, v129
	v_rcp_f32_e32 v134, v128
	v_cvt_pk_bf16_f32 v1, v1, s0
	v_mad_u64_u32 v[132:133], s[10:11], v133, s3, v[2:3]
	ds_write_b16 v132, v1
	v_fma_f32 v1, -v128, v134, 1.0
	v_fmac_f32_e32 v134, v1, v134
	v_div_scale_f32 v1, vcc, v129, v124, v129
	v_mul_f32_e32 v2, v1, v134
	v_fma_f32 v133, -v128, v2, v1
	v_fmac_f32_e32 v2, v133, v134
	v_fma_f32 v1, -v128, v2, v1
	v_mul_f32_e32 v128, 0xbfb8aa3b, v130
	v_exp_f32_e32 v128, v128
	v_div_fmas_f32 v1, v1, v134, v2
	v_div_fixup_f32 v1, v1, v124, v129
	v_mul_f32_e32 v1, v125, v1
	v_add_f32_e32 v2, 1.0, v128
	v_div_scale_f32 v124, s[10:11], v2, v2, v130
	v_rcp_f32_e32 v128, v124
	v_cvt_pk_bf16_f32 v1, v1, s0
	ds_write_b16 v132, v1 offset:144
	v_readlane_b32 s56, v251, 58
	v_fma_f32 v1, -v124, v128, 1.0
	v_fmac_f32_e32 v128, v1, v128
	v_div_scale_f32 v1, vcc, v130, v2, v130
	v_mul_f32_e32 v125, v1, v128
	v_fma_f32 v129, -v124, v125, v1
	v_fmac_f32_e32 v125, v129, v128
	v_fma_f32 v1, -v124, v125, v1
	v_mul_f32_e32 v124, 0xbfb8aa3b, v131
	v_exp_f32_e32 v124, v124
	v_div_fmas_f32 v1, v1, v128, v125
	v_div_fixup_f32 v1, v1, v2, v130
	v_mul_f32_e32 v1, v126, v1
	v_add_f32_e32 v2, 1.0, v124
	v_div_scale_f32 v124, s[10:11], v2, v2, v131
	v_rcp_f32_e32 v125, v124
	v_cvt_pk_bf16_f32 v1, v1, s0
	ds_write_b16 v132, v1 offset:288
	v_readlane_b32 s58, v251, 60
	v_fma_f32 v1, -v124, v125, 1.0
	v_fmac_f32_e32 v125, v1, v125
	v_div_scale_f32 v1, vcc, v131, v2, v131
	v_mul_f32_e32 v126, v1, v125
	v_fma_f32 v128, -v124, v126, v1
	v_fmac_f32_e32 v126, v128, v125
	v_fma_f32 v1, -v124, v126, v1
	v_mul_f32_e32 v124, 0xbfb8aa3b, v120
	v_exp_f32_e32 v124, v124
; DEVI float silu_(float x) { return x / (1.f + __expf(-x)); }
; DEVI void ffn1_tile256(const P& p, const bf* W, long row0, int n0  , char* smem) {
;     ...
; #pragma unroll
;   for (int m = 0; m < 8; ++m)
; #pragma unroll
;     for (int pr = 0; pr < 2; ++pr) {
;       const int cl = (wc * 2 + pr) * 16 + l15;
; #pragma unroll
;       for (int j = 0; j < 4; ++j) {
;         const int rl = wr * 128 + m * 16 + quad * 4 + j;
;         float a = acc[m][2 * pr][j], b = acc[m][2 * pr + 1][j];
;         tl[rl * 72 + cl] = f2bf(silu_(a) * b);
;       }
;     }
	v_div_fmas_f32 v1, v1, v125, v126
	v_div_fixup_f32 v1, v1, v2, v131
	v_mul_f32_e32 v1, v127, v1
	v_add_f32_e32 v2, 1.0, v124
	v_div_scale_f32 v124, s[10:11], v2, v2, v120
	v_rcp_f32_e32 v125, v124
	v_cvt_pk_bf16_f32 v1, v1, s0
	ds_write_b16 v132, v1 offset:432
	v_readlane_b32 s59, v251, 61
	v_fma_f32 v1, -v124, v125, 1.0
	v_fmac_f32_e32 v125, v1, v125
	v_div_scale_f32 v1, vcc, v120, v2, v120
	v_mul_f32_e32 v126, v1, v125
	v_fma_f32 v127, -v124, v126, v1
	v_fmac_f32_e32 v126, v127, v125
	v_fma_f32 v1, -v124, v126, v1
	v_mul_f32_e32 v124, 0xbfb8aa3b, v121
	v_exp_f32_e32 v124, v124
	v_div_fmas_f32 v1, v1, v125, v126
	v_div_fixup_f32 v1, v1, v2, v120
	v_mul_f32_e32 v1, v116, v1
	v_add_f32_e32 v2, 1.0, v124
	v_div_scale_f32 v120, s[10:11], v2, v2, v121
	v_rcp_f32_e32 v124, v120
	v_cvt_pk_bf16_f32 v1, v1, s0
	ds_write_b16 v132, v1 offset:32
	v_readlane_b32 s57, v251, 59
	v_fma_f32 v1, -v120, v124, 1.0
	v_fmac_f32_e32 v124, v1, v124
	v_div_scale_f32 v1, vcc, v121, v2, v121
	v_mul_f32_e32 v116, v1, v124
	v_fma_f32 v125, -v120, v116, v1
	v_fmac_f32_e32 v116, v125, v124
	v_fma_f32 v1, -v120, v116, v1
	v_mul_f32_e32 v120, 0xbfb8aa3b, v122
	v_exp_f32_e32 v120, v120
	v_div_fmas_f32 v1, v1, v124, v116
	v_div_fixup_f32 v1, v1, v2, v121
	v_mul_f32_e32 v1, v117, v1
	v_add_f32_e32 v2, 1.0, v120
	v_div_scale_f32 v116, s[10:11], v2, v2, v122
	v_rcp_f32_e32 v120, v116
	v_cvt_pk_bf16_f32 v1, v1, s0
	ds_write_b16 v132, v1 offset:176
	v_readlane_b32 s60, v251, 62
	v_fma_f32 v1, -v116, v120, 1.0
	v_fmac_f32_e32 v120, v1, v120
	v_div_scale_f32 v1, vcc, v122, v2, v122
	v_mul_f32_e32 v117, v1, v120
	v_fma_f32 v121, -v116, v117, v1
	v_fmac_f32_e32 v117, v121, v120
	v_fma_f32 v1, -v116, v117, v1
	v_mul_f32_e32 v116, 0xbfb8aa3b, v123
	v_exp_f32_e32 v116, v116
	v_div_fmas_f32 v1, v1, v120, v117
	v_div_fixup_f32 v1, v1, v2, v122
	v_mul_f32_e32 v1, v118, v1
	v_add_f32_e32 v2, 1.0, v116
	v_div_scale_f32 v116, s[10:11], v2, v2, v123
	v_rcp_f32_e32 v117, v116
	v_cvt_pk_bf16_f32 v1, v1, s0
	ds_write_b16 v132, v1 offset:320
	v_readlane_b32 s61, v251, 63
	v_fma_f32 v1, -v116, v117, 1.0
	v_fmac_f32_e32 v117, v1, v117
	v_div_scale_f32 v1, vcc, v123, v2, v123
	v_mul_f32_e32 v118, v1, v117
	v_fma_f32 v120, -v116, v118, v1
	v_fmac_f32_e32 v118, v120, v117
	v_fma_f32 v1, -v116, v118, v1
	v_mul_f32_e32 v116, 0xbfb8aa3b, v112
	v_exp_f32_e32 v116, v116
	v_div_fmas_f32 v1, v1, v117, v118
	v_div_fixup_f32 v1, v1, v2, v123
	v_mul_f32_e32 v1, v119, v1
	v_add_f32_e32 v2, 1.0, v116
	v_div_scale_f32 v116, s[10:11], v2, v2, v112
	v_rcp_f32_e32 v117, v116
	v_cvt_pk_bf16_f32 v1, v1, s0
	ds_write_b16 v132, v1 offset:464
	v_readlane_b32 s62, v252, 0
	v_fma_f32 v1, -v116, v117, 1.0
	v_fmac_f32_e32 v117, v1, v117
	v_div_scale_f32 v1, vcc, v112, v2, v112
	v_mul_f32_e32 v118, v1, v117
	v_fma_f32 v119, -v116, v118, v1
	v_fmac_f32_e32 v118, v119, v117
	v_fma_f32 v1, -v116, v118, v1
	v_mul_f32_e32 v116, 0xbfb8aa3b, v113
	v_exp_f32_e32 v116, v116
	v_div_fmas_f32 v1, v1, v117, v118
	v_div_fixup_f32 v1, v1, v2, v112
	v_mul_f32_e32 v1, v108, v1
	v_add_f32_e32 v2, 1.0, v116
	v_div_scale_f32 v112, s[10:11], v2, v2, v113
	v_rcp_f32_e32 v116, v112
	v_cvt_pk_bf16_f32 v1, v1, s0
	ds_write_b16 v132, v1 offset:2304
	v_readlane_b32 s63, v252, 1
	v_fma_f32 v1, -v112, v116, 1.0
	v_fmac_f32_e32 v116, v1, v116
	v_div_scale_f32 v1, vcc, v113, v2, v113
	v_mul_f32_e32 v108, v1, v116
	v_fma_f32 v117, -v112, v108, v1
	v_fmac_f32_e32 v108, v117, v116
	v_fma_f32 v1, -v112, v108, v1
	v_mul_f32_e32 v112, 0xbfb8aa3b, v114
	v_exp_f32_e32 v112, v112
	v_div_fmas_f32 v1, v1, v116, v108
	v_div_fixup_f32 v1, v1, v2, v113
	v_mul_f32_e32 v1, v109, v1
	v_add_f32_e32 v2, 1.0, v112
	v_div_scale_f32 v108, s[10:11], v2, v2, v114
	v_rcp_f32_e32 v112, v108
	v_cvt_pk_bf16_f32 v1, v1, s0
	ds_write_b16 v132, v1 offset:2448
	v_readlane_b32 s64, v252, 2
	v_fma_f32 v1, -v108, v112, 1.0
	v_fmac_f32_e32 v112, v1, v112
	v_div_scale_f32 v1, vcc, v114, v2, v114
	v_mul_f32_e32 v109, v1, v112
	v_fma_f32 v113, -v108, v109, v1
	v_fmac_f32_e32 v109, v113, v112
	v_fma_f32 v1, -v108, v109, v1
	v_mul_f32_e32 v108, 0xbfb8aa3b, v115
	v_exp_f32_e32 v108, v108
	v_div_fmas_f32 v1, v1, v112, v109
	v_div_fixup_f32 v1, v1, v2, v114
	v_mul_f32_e32 v1, v110, v1
	v_add_f32_e32 v2, 1.0, v108
	v_div_scale_f32 v108, s[10:11], v2, v2, v115
	v_rcp_f32_e32 v109, v108
	v_cvt_pk_bf16_f32 v1, v1, s0
	ds_write_b16 v132, v1 offset:2592
	v_readlane_b32 s65, v252, 3
	v_fma_f32 v1, -v108, v109, 1.0
	v_fmac_f32_e32 v109, v1, v109
	v_div_scale_f32 v1, vcc, v115, v2, v115
	v_mul_f32_e32 v110, v1, v109
	v_fma_f32 v112, -v108, v110, v1
	v_fmac_f32_e32 v110, v112, v109
	v_fma_f32 v1, -v108, v110, v1
	v_mul_f32_e32 v108, 0xbfb8aa3b, v104
	v_exp_f32_e32 v108, v108
	v_div_fmas_f32 v1, v1, v109, v110
	v_div_fixup_f32 v1, v1, v2, v115
	v_mul_f32_e32 v1, v111, v1
	v_add_f32_e32 v2, 1.0, v108
	v_div_scale_f32 v108, s[10:11], v2, v2, v104
	v_rcp_f32_e32 v109, v108
	v_cvt_pk_bf16_f32 v1, v1, s0
	ds_write_b16 v132, v1 offset:2736
	v_readlane_b32 s66, v252, 4
	v_fma_f32 v1, -v108, v109, 1.0
	v_fmac_f32_e32 v109, v1, v109
	v_div_scale_f32 v1, vcc, v104, v2, v104
	v_mul_f32_e32 v110, v1, v109
	v_fma_f32 v111, -v108, v110, v1
	v_fmac_f32_e32 v110, v111, v109
	v_fma_f32 v1, -v108, v110, v1
	v_mul_f32_e32 v108, 0xbfb8aa3b, v105
	v_exp_f32_e32 v108, v108
	v_div_fmas_f32 v1, v1, v109, v110
	v_div_fixup_f32 v1, v1, v2, v104
	v_mul_f32_e32 v1, v100, v1
	v_add_f32_e32 v2, 1.0, v108
	v_div_scale_f32 v104, s[10:11], v2, v2, v105
	v_rcp_f32_e32 v108, v104
	v_cvt_pk_bf16_f32 v1, v1, s0
	ds_write_b16 v132, v1 offset:2336
	v_readlane_b32 s67, v252, 5
	v_fma_f32 v1, -v104, v108, 1.0
	v_fmac_f32_e32 v108, v1, v108
; DEVI float silu_(float x) { return x / (1.f + __expf(-x)); }
; DEVI void ffn1_tile256(const P& p, const bf* W, long row0, int n0  , char* smem) {
;     ...
; #pragma unroll
;   for (int m = 0; m < 8; ++m)
; #pragma unroll
;     for (int pr = 0; pr < 2; ++pr) {
;       const int cl = (wc * 2 + pr) * 16 + l15;
; #pragma unroll
;       for (int j = 0; j < 4; ++j) {
;         const int rl = wr * 128 + m * 16 + quad * 4 + j;
;         float a = acc[m][2 * pr][j], b = acc[m][2 * pr + 1][j];
;         tl[rl * 72 + cl] = f2bf(silu_(a) * b);
;       }
;     }
	v_div_scale_f32 v1, vcc, v105, v2, v105
	v_mul_f32_e32 v100, v1, v108
	v_fma_f32 v109, -v104, v100, v1
	v_fmac_f32_e32 v100, v109, v108
	v_fma_f32 v1, -v104, v100, v1
	v_mul_f32_e32 v104, 0xbfb8aa3b, v106
	v_exp_f32_e32 v104, v104
	v_div_fmas_f32 v1, v1, v108, v100
	v_div_fixup_f32 v1, v1, v2, v105
	v_mul_f32_e32 v1, v101, v1
	v_add_f32_e32 v2, 1.0, v104
	v_div_scale_f32 v100, s[10:11], v2, v2, v106
	v_rcp_f32_e32 v104, v100
	v_cvt_pk_bf16_f32 v1, v1, s0
	ds_write_b16 v132, v1 offset:2480
	v_readlane_b32 s68, v252, 6
	v_fma_f32 v1, -v100, v104, 1.0
	v_fmac_f32_e32 v104, v1, v104
	v_div_scale_f32 v1, vcc, v106, v2, v106
	v_mul_f32_e32 v101, v1, v104
	v_fma_f32 v105, -v100, v101, v1
	v_fmac_f32_e32 v101, v105, v104
	v_fma_f32 v1, -v100, v101, v1
	v_mul_f32_e32 v100, 0xbfb8aa3b, v107
	v_exp_f32_e32 v100, v100
	v_div_fmas_f32 v1, v1, v104, v101
	v_div_fixup_f32 v1, v1, v2, v106
	v_mul_f32_e32 v1, v102, v1
	v_add_f32_e32 v2, 1.0, v100
	v_div_scale_f32 v100, s[10:11], v2, v2, v107
	v_rcp_f32_e32 v101, v100
	v_cvt_pk_bf16_f32 v1, v1, s0
	ds_write_b16 v132, v1 offset:2624
	v_readlane_b32 s69, v252, 7
	v_fma_f32 v1, -v100, v101, 1.0
	v_fmac_f32_e32 v101, v1, v101
	v_div_scale_f32 v1, vcc, v107, v2, v107
	v_mul_f32_e32 v102, v1, v101
	v_fma_f32 v104, -v100, v102, v1
	v_fmac_f32_e32 v102, v104, v101
	v_fma_f32 v1, -v100, v102, v1
	v_mul_f32_e32 v100, 0xbfb8aa3b, v96
	v_exp_f32_e32 v100, v100
	v_div_fmas_f32 v1, v1, v101, v102
	v_div_fixup_f32 v1, v1, v2, v107
	v_mul_f32_e32 v1, v103, v1
	v_add_f32_e32 v2, 1.0, v100
	v_div_scale_f32 v100, s[10:11], v2, v2, v96
	v_rcp_f32_e32 v101, v100
	v_cvt_pk_bf16_f32 v1, v1, s0
	ds_write_b16 v132, v1 offset:2768
	v_readlane_b32 s70, v252, 8
	v_fma_f32 v1, -v100, v101, 1.0
	v_fmac_f32_e32 v101, v1, v101
	v_div_scale_f32 v1, vcc, v96, v2, v96
	v_mul_f32_e32 v102, v1, v101
	v_fma_f32 v103, -v100, v102, v1
	v_fmac_f32_e32 v102, v103, v101
	v_fma_f32 v1, -v100, v102, v1
	v_mul_f32_e32 v100, 0xbfb8aa3b, v97
	v_exp_f32_e32 v100, v100
	v_div_fmas_f32 v1, v1, v101, v102
	v_div_fixup_f32 v1, v1, v2, v96
	v_mul_f32_e32 v1, v92, v1
	v_add_f32_e32 v2, 1.0, v100
	v_div_scale_f32 v96, s[10:11], v2, v2, v97
	v_rcp_f32_e32 v100, v96
	v_cvt_pk_bf16_f32 v1, v1, s0
	ds_write_b16 v132, v1 offset:4608
	v_readlane_b32 s71, v252, 9
	v_fma_f32 v1, -v96, v100, 1.0
	v_fmac_f32_e32 v100, v1, v100
	v_div_scale_f32 v1, vcc, v97, v2, v97
	v_mul_f32_e32 v92, v1, v100
	v_fma_f32 v101, -v96, v92, v1
	v_fmac_f32_e32 v92, v101, v100
	v_fma_f32 v1, -v96, v92, v1
	v_mul_f32_e32 v96, 0xbfb8aa3b, v98
	v_exp_f32_e32 v96, v96
	v_div_fmas_f32 v1, v1, v100, v92
	v_div_fixup_f32 v1, v1, v2, v97
	v_mul_f32_e32 v1, v93, v1
	v_add_f32_e32 v2, 1.0, v96
	v_div_scale_f32 v92, s[10:11], v2, v2, v98
	v_rcp_f32_e32 v96, v92
	v_cvt_pk_bf16_f32 v1, v1, s0
	ds_write_b16 v132, v1 offset:4752
	v_fma_f32 v1, -v92, v96, 1.0
	v_fmac_f32_e32 v96, v1, v96
	v_div_scale_f32 v1, vcc, v98, v2, v98
	v_mul_f32_e32 v93, v1, v96
	v_fma_f32 v97, -v92, v93, v1
	v_fmac_f32_e32 v93, v97, v96
	v_fma_f32 v1, -v92, v93, v1
	v_mul_f32_e32 v92, 0xbfb8aa3b, v99
	v_exp_f32_e32 v92, v92
	v_div_fmas_f32 v1, v1, v96, v93
	v_div_fixup_f32 v1, v1, v2, v98
	v_mul_f32_e32 v1, v94, v1
	v_add_f32_e32 v2, 1.0, v92
	v_div_scale_f32 v92, s[10:11], v2, v2, v99
	v_rcp_f32_e32 v93, v92
	v_cvt_pk_bf16_f32 v1, v1, s0
	ds_write_b16 v132, v1 offset:4896
	v_fma_f32 v1, -v92, v93, 1.0
	v_fmac_f32_e32 v93, v1, v93
	v_div_scale_f32 v1, vcc, v99, v2, v99
	v_mul_f32_e32 v94, v1, v93
	v_fma_f32 v96, -v92, v94, v1
	v_fmac_f32_e32 v94, v96, v93
	v_fma_f32 v1, -v92, v94, v1
	v_mul_f32_e32 v92, 0xbfb8aa3b, v88
	v_exp_f32_e32 v92, v92
	v_div_fmas_f32 v1, v1, v93, v94
	v_div_fixup_f32 v1, v1, v2, v99
	v_mul_f32_e32 v1, v95, v1
	v_add_f32_e32 v2, 1.0, v92
	v_div_scale_f32 v92, s[10:11], v2, v2, v88
	v_rcp_f32_e32 v93, v92
	v_cvt_pk_bf16_f32 v1, v1, s0
	ds_write_b16 v132, v1 offset:5040
	v_fma_f32 v1, -v92, v93, 1.0
	v_fmac_f32_e32 v93, v1, v93
	v_div_scale_f32 v1, vcc, v88, v2, v88
	v_mul_f32_e32 v94, v1, v93
	v_fma_f32 v95, -v92, v94, v1
	v_fmac_f32_e32 v94, v95, v93
	v_fma_f32 v1, -v92, v94, v1
	v_mul_f32_e32 v92, 0xbfb8aa3b, v89
	v_exp_f32_e32 v92, v92
	v_div_fmas_f32 v1, v1, v93, v94
	v_div_fixup_f32 v1, v1, v2, v88
	v_mul_f32_e32 v1, v84, v1
	v_add_f32_e32 v2, 1.0, v92
	v_div_scale_f32 v88, s[10:11], v2, v2, v89
	v_rcp_f32_e32 v92, v88
	v_cvt_pk_bf16_f32 v1, v1, s0
	ds_write_b16 v132, v1 offset:4640
	v_fma_f32 v1, -v88, v92, 1.0
	v_fmac_f32_e32 v92, v1, v92
	v_div_scale_f32 v1, vcc, v89, v2, v89
	v_mul_f32_e32 v84, v1, v92
	v_fma_f32 v93, -v88, v84, v1
	v_fmac_f32_e32 v84, v93, v92
	v_fma_f32 v1, -v88, v84, v1
	v_mul_f32_e32 v88, 0xbfb8aa3b, v90
	v_exp_f32_e32 v88, v88
	v_div_fmas_f32 v1, v1, v92, v84
	v_div_fixup_f32 v1, v1, v2, v89
	v_mul_f32_e32 v1, v85, v1
	v_add_f32_e32 v2, 1.0, v88
	v_div_scale_f32 v84, s[10:11], v2, v2, v90
	v_rcp_f32_e32 v88, v84
	v_cvt_pk_bf16_f32 v1, v1, s0
	ds_write_b16 v132, v1 offset:4784
	v_fma_f32 v1, -v84, v88, 1.0
	v_fmac_f32_e32 v88, v1, v88
	v_div_scale_f32 v1, vcc, v90, v2, v90
	v_mul_f32_e32 v85, v1, v88
	v_fma_f32 v89, -v84, v85, v1
	v_fmac_f32_e32 v85, v89, v88
	v_fma_f32 v1, -v84, v85, v1
	v_mul_f32_e32 v84, 0xbfb8aa3b, v91
	v_exp_f32_e32 v84, v84
	v_div_fmas_f32 v1, v1, v88, v85
	v_div_fixup_f32 v1, v1, v2, v90
	v_mul_f32_e32 v1, v86, v1
	v_add_f32_e32 v2, 1.0, v84
	v_div_scale_f32 v84, s[10:11], v2, v2, v91
	v_rcp_f32_e32 v85, v84
	v_cvt_pk_bf16_f32 v1, v1, s0
	ds_write_b16 v132, v1 offset:4928
	v_fma_f32 v1, -v84, v85, 1.0
	v_fmac_f32_e32 v85, v1, v85
	v_div_scale_f32 v1, vcc, v91, v2, v91
	v_mul_f32_e32 v86, v1, v85
	v_fma_f32 v88, -v84, v86, v1
	v_fmac_f32_e32 v86, v88, v85
; DEVI float silu_(float x) { return x / (1.f + __expf(-x)); }
; DEVI void ffn1_tile256(const P& p, const bf* W, long row0, int n0  , char* smem) {
;     ...
; #pragma unroll
;   for (int m = 0; m < 8; ++m)
; #pragma unroll
;     for (int pr = 0; pr < 2; ++pr) {
;       const int cl = (wc * 2 + pr) * 16 + l15;
; #pragma unroll
;       for (int j = 0; j < 4; ++j) {
;         const int rl = wr * 128 + m * 16 + quad * 4 + j;
;         float a = acc[m][2 * pr][j], b = acc[m][2 * pr + 1][j];
;         tl[rl * 72 + cl] = f2bf(silu_(a) * b);
;       }
;     }
	v_fma_f32 v1, -v84, v86, v1
	v_mul_f32_e32 v84, 0xbfb8aa3b, v80
	v_exp_f32_e32 v84, v84
	v_div_fmas_f32 v1, v1, v85, v86
	v_div_fixup_f32 v1, v1, v2, v91
	v_mul_f32_e32 v1, v87, v1
	v_add_f32_e32 v2, 1.0, v84
	v_div_scale_f32 v84, s[10:11], v2, v2, v80
	v_rcp_f32_e32 v85, v84
	v_cvt_pk_bf16_f32 v1, v1, s0
	ds_write_b16 v132, v1 offset:5072
	v_fma_f32 v1, -v84, v85, 1.0
	v_fmac_f32_e32 v85, v1, v85
	v_div_scale_f32 v1, vcc, v80, v2, v80
	v_mul_f32_e32 v86, v1, v85
	v_fma_f32 v87, -v84, v86, v1
	v_fmac_f32_e32 v86, v87, v85
	v_fma_f32 v1, -v84, v86, v1
	v_mul_f32_e32 v84, 0xbfb8aa3b, v81
	v_exp_f32_e32 v84, v84
	v_div_fmas_f32 v1, v1, v85, v86
	v_div_fixup_f32 v1, v1, v2, v80
	v_mul_f32_e32 v1, v76, v1
	v_add_f32_e32 v2, 1.0, v84
	v_div_scale_f32 v80, s[10:11], v2, v2, v81
	v_rcp_f32_e32 v84, v80
	v_cvt_pk_bf16_f32 v1, v1, s0
	ds_write_b16 v132, v1 offset:6912
	v_fma_f32 v1, -v80, v84, 1.0
	v_fmac_f32_e32 v84, v1, v84
	v_div_scale_f32 v1, vcc, v81, v2, v81
	v_mul_f32_e32 v76, v1, v84
	v_fma_f32 v85, -v80, v76, v1
	v_fmac_f32_e32 v76, v85, v84
	v_fma_f32 v1, -v80, v76, v1
	v_mul_f32_e32 v80, 0xbfb8aa3b, v82
	v_exp_f32_e32 v80, v80
	v_div_fmas_f32 v1, v1, v84, v76
	v_div_fixup_f32 v1, v1, v2, v81
	v_mul_f32_e32 v1, v77, v1
	v_add_f32_e32 v2, 1.0, v80
	v_div_scale_f32 v76, s[10:11], v2, v2, v82
	v_rcp_f32_e32 v80, v76
	v_cvt_pk_bf16_f32 v1, v1, s0
	ds_write_b16 v132, v1 offset:7056
	v_fma_f32 v1, -v76, v80, 1.0
	v_fmac_f32_e32 v80, v1, v80
	v_div_scale_f32 v1, vcc, v82, v2, v82
	v_mul_f32_e32 v77, v1, v80
	v_fma_f32 v81, -v76, v77, v1
	v_fmac_f32_e32 v77, v81, v80
	v_fma_f32 v1, -v76, v77, v1
	v_mul_f32_e32 v76, 0xbfb8aa3b, v83
	v_exp_f32_e32 v76, v76
	v_div_fmas_f32 v1, v1, v80, v77
	v_div_fixup_f32 v1, v1, v2, v82
	v_mul_f32_e32 v1, v78, v1
	v_add_f32_e32 v2, 1.0, v76
	v_div_scale_f32 v76, s[10:11], v2, v2, v83
	v_rcp_f32_e32 v77, v76
	v_cvt_pk_bf16_f32 v1, v1, s0
	ds_write_b16 v132, v1 offset:7200
	v_fma_f32 v1, -v76, v77, 1.0
	v_fmac_f32_e32 v77, v1, v77
	v_div_scale_f32 v1, vcc, v83, v2, v83
	v_mul_f32_e32 v78, v1, v77
	v_fma_f32 v80, -v76, v78, v1
	v_fmac_f32_e32 v78, v80, v77
	v_fma_f32 v1, -v76, v78, v1
	v_mul_f32_e32 v76, 0xbfb8aa3b, v72
	v_exp_f32_e32 v76, v76
	v_div_fmas_f32 v1, v1, v77, v78
	v_div_fixup_f32 v1, v1, v2, v83
	v_mul_f32_e32 v1, v79, v1
	v_add_f32_e32 v2, 1.0, v76
	v_div_scale_f32 v76, s[10:11], v2, v2, v72
	v_rcp_f32_e32 v77, v76
	v_cvt_pk_bf16_f32 v1, v1, s0
	ds_write_b16 v132, v1 offset:7344
	v_fma_f32 v1, -v76, v77, 1.0
	v_fmac_f32_e32 v77, v1, v77
	v_div_scale_f32 v1, vcc, v72, v2, v72
	v_mul_f32_e32 v78, v1, v77
	v_fma_f32 v79, -v76, v78, v1
	v_fmac_f32_e32 v78, v79, v77
	v_fma_f32 v1, -v76, v78, v1
	v_mul_f32_e32 v76, 0xbfb8aa3b, v73
	v_exp_f32_e32 v76, v76
	v_div_fmas_f32 v1, v1, v77, v78
	v_div_fixup_f32 v1, v1, v2, v72
	v_mul_f32_e32 v1, v68, v1
	v_add_f32_e32 v2, 1.0, v76
	v_div_scale_f32 v72, s[10:11], v2, v2, v73
	v_rcp_f32_e32 v76, v72
	v_cvt_pk_bf16_f32 v1, v1, s0
	ds_write_b16 v132, v1 offset:6944
	v_fma_f32 v1, -v72, v76, 1.0
	v_fmac_f32_e32 v76, v1, v76
	v_div_scale_f32 v1, vcc, v73, v2, v73
	v_mul_f32_e32 v68, v1, v76
	v_fma_f32 v77, -v72, v68, v1
	v_fmac_f32_e32 v68, v77, v76
	v_fma_f32 v1, -v72, v68, v1
	v_mul_f32_e32 v72, 0xbfb8aa3b, v74
	v_exp_f32_e32 v72, v72
	v_div_fmas_f32 v1, v1, v76, v68
	v_div_fixup_f32 v1, v1, v2, v73
	v_mul_f32_e32 v1, v69, v1
	v_add_f32_e32 v2, 1.0, v72
	v_div_scale_f32 v68, s[10:11], v2, v2, v74
	v_rcp_f32_e32 v72, v68
	v_cvt_pk_bf16_f32 v1, v1, s0
	ds_write_b16 v132, v1 offset:7088
	v_fma_f32 v1, -v68, v72, 1.0
	v_fmac_f32_e32 v72, v1, v72
	v_div_scale_f32 v1, vcc, v74, v2, v74
	v_mul_f32_e32 v69, v1, v72
	v_fma_f32 v73, -v68, v69, v1
	v_fmac_f32_e32 v69, v73, v72
	v_fma_f32 v1, -v68, v69, v1
	v_mul_f32_e32 v68, 0xbfb8aa3b, v75
	v_exp_f32_e32 v68, v68
	v_div_fmas_f32 v1, v1, v72, v69
	v_div_fixup_f32 v1, v1, v2, v74
	v_mul_f32_e32 v1, v70, v1
	v_add_f32_e32 v2, 1.0, v68
	v_div_scale_f32 v68, s[10:11], v2, v2, v75
	v_rcp_f32_e32 v69, v68
	v_cvt_pk_bf16_f32 v1, v1, s0
	ds_write_b16 v132, v1 offset:7232
	v_fma_f32 v1, -v68, v69, 1.0
	v_fmac_f32_e32 v69, v1, v69
	v_div_scale_f32 v1, vcc, v75, v2, v75
	v_mul_f32_e32 v70, v1, v69
	v_fma_f32 v72, -v68, v70, v1
	v_fmac_f32_e32 v70, v72, v69
	v_fma_f32 v1, -v68, v70, v1
	v_mul_f32_e32 v68, 0xbfb8aa3b, v64
	v_exp_f32_e32 v68, v68
	v_div_fmas_f32 v1, v1, v69, v70
	v_div_fixup_f32 v1, v1, v2, v75
	v_mul_f32_e32 v1, v71, v1
	v_add_f32_e32 v2, 1.0, v68
	v_div_scale_f32 v68, s[10:11], v2, v2, v64
	v_rcp_f32_e32 v69, v68
	v_cvt_pk_bf16_f32 v1, v1, s0
	ds_write_b16 v132, v1 offset:7376
	v_fma_f32 v1, -v68, v69, 1.0
	v_fmac_f32_e32 v69, v1, v69
	v_div_scale_f32 v1, vcc, v64, v2, v64
	v_mul_f32_e32 v70, v1, v69
	v_fma_f32 v71, -v68, v70, v1
	v_fmac_f32_e32 v70, v71, v69
	v_fma_f32 v1, -v68, v70, v1
	v_mul_f32_e32 v68, 0xbfb8aa3b, v65
	v_exp_f32_e32 v68, v68
	v_div_fmas_f32 v1, v1, v69, v70
	v_div_fixup_f32 v1, v1, v2, v64
	v_mul_f32_e32 v1, v60, v1
	v_add_f32_e32 v2, 1.0, v68
	v_div_scale_f32 v64, s[10:11], v2, v2, v65
	v_rcp_f32_e32 v68, v64
	v_cvt_pk_bf16_f32 v1, v1, s0
	ds_write_b16 v132, v1 offset:9216
	v_fma_f32 v1, -v64, v68, 1.0
	v_fmac_f32_e32 v68, v1, v68
	v_div_scale_f32 v1, vcc, v65, v2, v65
	v_mul_f32_e32 v60, v1, v68
	v_fma_f32 v69, -v64, v60, v1
	v_fmac_f32_e32 v60, v69, v68
	v_fma_f32 v1, -v64, v60, v1
	v_mul_f32_e32 v64, 0xbfb8aa3b, v66
	v_exp_f32_e32 v64, v64
	v_div_fmas_f32 v1, v1, v68, v60
	v_div_fixup_f32 v1, v1, v2, v65
	v_mul_f32_e32 v1, v61, v1
	v_add_f32_e32 v2, 1.0, v64
	v_div_scale_f32 v60, s[10:11], v2, v2, v66
	v_rcp_f32_e32 v64, v60
	v_cvt_pk_bf16_f32 v1, v1, s0
	ds_write_b16 v132, v1 offset:9360
; DEVI float silu_(float x) { return x / (1.f + __expf(-x)); }
; DEVI void ffn1_tile256(const P& p, const bf* W, long row0, int n0  , char* smem) {
;     ...
; #pragma unroll
;   for (int m = 0; m < 8; ++m)
; #pragma unroll
;     for (int pr = 0; pr < 2; ++pr) {
;       const int cl = (wc * 2 + pr) * 16 + l15;
; #pragma unroll
;       for (int j = 0; j < 4; ++j) {
;         const int rl = wr * 128 + m * 16 + quad * 4 + j;
;         float a = acc[m][2 * pr][j], b = acc[m][2 * pr + 1][j];
;         tl[rl * 72 + cl] = f2bf(silu_(a) * b);
;       }
;     }
	v_fma_f32 v1, -v60, v64, 1.0
	v_fmac_f32_e32 v64, v1, v64
	v_div_scale_f32 v1, vcc, v66, v2, v66
	v_mul_f32_e32 v61, v1, v64
	v_fma_f32 v65, -v60, v61, v1
	v_fmac_f32_e32 v61, v65, v64
	v_fma_f32 v1, -v60, v61, v1
	v_mul_f32_e32 v60, 0xbfb8aa3b, v67
	v_exp_f32_e32 v60, v60
	v_div_fmas_f32 v1, v1, v64, v61
	v_div_fixup_f32 v1, v1, v2, v66
	v_mul_f32_e32 v1, v62, v1
	v_add_f32_e32 v2, 1.0, v60
	v_div_scale_f32 v60, s[10:11], v2, v2, v67
	v_rcp_f32_e32 v61, v60
	v_cvt_pk_bf16_f32 v1, v1, s0
	ds_write_b16 v132, v1 offset:9504
	v_fma_f32 v1, -v60, v61, 1.0
	v_fmac_f32_e32 v61, v1, v61
	v_div_scale_f32 v1, vcc, v67, v2, v67
	v_mul_f32_e32 v62, v1, v61
	v_fma_f32 v64, -v60, v62, v1
	v_fmac_f32_e32 v62, v64, v61
	v_fma_f32 v1, -v60, v62, v1
	v_mul_f32_e32 v60, 0xbfb8aa3b, v56
	v_exp_f32_e32 v60, v60
	v_div_fmas_f32 v1, v1, v61, v62
	v_div_fixup_f32 v1, v1, v2, v67
	v_mul_f32_e32 v1, v63, v1
	v_add_f32_e32 v2, 1.0, v60
	v_div_scale_f32 v60, s[10:11], v2, v2, v56
	v_rcp_f32_e32 v61, v60
	v_cvt_pk_bf16_f32 v1, v1, s0
	ds_write_b16 v132, v1 offset:9648
	v_fma_f32 v1, -v60, v61, 1.0
	v_fmac_f32_e32 v61, v1, v61
	v_div_scale_f32 v1, vcc, v56, v2, v56
	v_mul_f32_e32 v62, v1, v61
	v_fma_f32 v63, -v60, v62, v1
	v_fmac_f32_e32 v62, v63, v61
	v_fma_f32 v1, -v60, v62, v1
	v_mul_f32_e32 v60, 0xbfb8aa3b, v57
	v_exp_f32_e32 v60, v60
	v_div_fmas_f32 v1, v1, v61, v62
	v_div_fixup_f32 v1, v1, v2, v56
	v_mul_f32_e32 v1, v52, v1
	v_add_f32_e32 v2, 1.0, v60
	v_div_scale_f32 v56, s[10:11], v2, v2, v57
	v_rcp_f32_e32 v60, v56
	v_cvt_pk_bf16_f32 v1, v1, s0
	ds_write_b16 v132, v1 offset:9248
	v_fma_f32 v1, -v56, v60, 1.0
	v_fmac_f32_e32 v60, v1, v60
	v_div_scale_f32 v1, vcc, v57, v2, v57
	v_mul_f32_e32 v52, v1, v60
	v_fma_f32 v61, -v56, v52, v1
	v_fmac_f32_e32 v52, v61, v60
	v_fma_f32 v1, -v56, v52, v1
	v_mul_f32_e32 v56, 0xbfb8aa3b, v58
	v_exp_f32_e32 v56, v56
	v_div_fmas_f32 v1, v1, v60, v52
	v_div_fixup_f32 v1, v1, v2, v57
	v_mul_f32_e32 v1, v53, v1
	v_add_f32_e32 v2, 1.0, v56
	v_div_scale_f32 v52, s[10:11], v2, v2, v58
	v_rcp_f32_e32 v56, v52
	v_cvt_pk_bf16_f32 v1, v1, s0
	ds_write_b16 v132, v1 offset:9392
	v_fma_f32 v1, -v52, v56, 1.0
	v_fmac_f32_e32 v56, v1, v56
	v_div_scale_f32 v1, vcc, v58, v2, v58
	v_mul_f32_e32 v53, v1, v56
	v_fma_f32 v57, -v52, v53, v1
	v_fmac_f32_e32 v53, v57, v56
	v_fma_f32 v1, -v52, v53, v1
	v_mul_f32_e32 v52, 0xbfb8aa3b, v59
	v_exp_f32_e32 v52, v52
	v_div_fmas_f32 v1, v1, v56, v53
	v_div_fixup_f32 v1, v1, v2, v58
	v_mul_f32_e32 v1, v54, v1
	v_add_f32_e32 v2, 1.0, v52
	v_div_scale_f32 v52, s[10:11], v2, v2, v59
	v_rcp_f32_e32 v53, v52
	v_cvt_pk_bf16_f32 v1, v1, s0
	ds_write_b16 v132, v1 offset:9536
	v_fma_f32 v1, -v52, v53, 1.0
	v_fmac_f32_e32 v53, v1, v53
	v_div_scale_f32 v1, vcc, v59, v2, v59
	v_mul_f32_e32 v54, v1, v53
	v_fma_f32 v56, -v52, v54, v1
	v_fmac_f32_e32 v54, v56, v53
	v_fma_f32 v1, -v52, v54, v1
	v_mul_f32_e32 v52, 0xbfb8aa3b, v48
	v_exp_f32_e32 v52, v52
	v_div_fmas_f32 v1, v1, v53, v54
	v_div_fixup_f32 v1, v1, v2, v59
	v_mul_f32_e32 v1, v55, v1
	v_add_f32_e32 v2, 1.0, v52
	v_div_scale_f32 v52, s[10:11], v2, v2, v48
	v_rcp_f32_e32 v53, v52
	v_cvt_pk_bf16_f32 v1, v1, s0
	ds_write_b16 v132, v1 offset:9680
	v_fma_f32 v1, -v52, v53, 1.0
	v_fmac_f32_e32 v53, v1, v53
	v_div_scale_f32 v1, vcc, v48, v2, v48
	v_mul_f32_e32 v54, v1, v53
	v_fma_f32 v55, -v52, v54, v1
	v_fmac_f32_e32 v54, v55, v53
	v_fma_f32 v1, -v52, v54, v1
	v_mul_f32_e32 v52, 0xbfb8aa3b, v49
	v_exp_f32_e32 v52, v52
	v_div_fmas_f32 v1, v1, v53, v54
	v_div_fixup_f32 v1, v1, v2, v48
	v_mul_f32_e32 v1, v44, v1
	v_add_f32_e32 v2, 1.0, v52
	v_div_scale_f32 v48, s[10:11], v2, v2, v49
	v_rcp_f32_e32 v52, v48
	v_cvt_pk_bf16_f32 v1, v1, s0
	ds_write_b16 v132, v1 offset:11520
	v_fma_f32 v1, -v48, v52, 1.0
	v_fmac_f32_e32 v52, v1, v52
	v_div_scale_f32 v1, vcc, v49, v2, v49
	v_mul_f32_e32 v44, v1, v52
	v_fma_f32 v53, -v48, v44, v1
	v_fmac_f32_e32 v44, v53, v52
	v_fma_f32 v1, -v48, v44, v1
	v_mul_f32_e32 v48, 0xbfb8aa3b, v50
	v_exp_f32_e32 v48, v48
	v_div_fmas_f32 v1, v1, v52, v44
	v_div_fixup_f32 v1, v1, v2, v49
	v_mul_f32_e32 v1, v45, v1
	v_add_f32_e32 v2, 1.0, v48
	v_div_scale_f32 v44, s[10:11], v2, v2, v50
	v_rcp_f32_e32 v48, v44
	v_cvt_pk_bf16_f32 v1, v1, s0
	ds_write_b16 v132, v1 offset:11664
	v_fma_f32 v1, -v44, v48, 1.0
	v_fmac_f32_e32 v48, v1, v48
	v_div_scale_f32 v1, vcc, v50, v2, v50
	v_mul_f32_e32 v45, v1, v48
	v_fma_f32 v49, -v44, v45, v1
	v_fmac_f32_e32 v45, v49, v48
	v_fma_f32 v1, -v44, v45, v1
	v_mul_f32_e32 v44, 0xbfb8aa3b, v51
	v_exp_f32_e32 v44, v44
	v_div_fmas_f32 v1, v1, v48, v45
	v_div_fixup_f32 v1, v1, v2, v50
	v_mul_f32_e32 v1, v46, v1
	v_add_f32_e32 v2, 1.0, v44
	v_div_scale_f32 v44, s[10:11], v2, v2, v51
	v_rcp_f32_e32 v45, v44
	v_cvt_pk_bf16_f32 v1, v1, s0
	ds_write_b16 v132, v1 offset:11808
	v_fma_f32 v1, -v44, v45, 1.0
	v_fmac_f32_e32 v45, v1, v45
	v_div_scale_f32 v1, vcc, v51, v2, v51
	v_mul_f32_e32 v46, v1, v45
	v_fma_f32 v48, -v44, v46, v1
	v_fmac_f32_e32 v46, v48, v45
	v_fma_f32 v1, -v44, v46, v1
	v_mul_f32_e32 v44, 0xbfb8aa3b, v40
	v_exp_f32_e32 v44, v44
	v_div_fmas_f32 v1, v1, v45, v46
	v_div_fixup_f32 v1, v1, v2, v51
	v_mul_f32_e32 v1, v47, v1
	v_add_f32_e32 v2, 1.0, v44
	v_div_scale_f32 v44, s[10:11], v2, v2, v40
	v_rcp_f32_e32 v45, v44
	v_cvt_pk_bf16_f32 v1, v1, s0
	ds_write_b16 v132, v1 offset:11952
	v_fma_f32 v1, -v44, v45, 1.0
	v_fmac_f32_e32 v45, v1, v45
	v_div_scale_f32 v1, vcc, v40, v2, v40
	v_mul_f32_e32 v46, v1, v45
	v_fma_f32 v47, -v44, v46, v1
	v_fmac_f32_e32 v46, v47, v45
	v_fma_f32 v1, -v44, v46, v1
	v_mul_f32_e32 v44, 0xbfb8aa3b, v41
	v_exp_f32_e32 v44, v44
	v_div_fmas_f32 v1, v1, v45, v46
	v_div_fixup_f32 v1, v1, v2, v40
; DEVI float silu_(float x) { return x / (1.f + __expf(-x)); }
; DEVI void ffn1_tile256(const P& p, const bf* W, long row0, int n0  , char* smem) {
;     ...
; #pragma unroll
;   for (int m = 0; m < 8; ++m)
; #pragma unroll
;     for (int pr = 0; pr < 2; ++pr) {
;       const int cl = (wc * 2 + pr) * 16 + l15;
; #pragma unroll
;       for (int j = 0; j < 4; ++j) {
;         const int rl = wr * 128 + m * 16 + quad * 4 + j;
;         float a = acc[m][2 * pr][j], b = acc[m][2 * pr + 1][j];
;         tl[rl * 72 + cl] = f2bf(silu_(a) * b);
;       }
;     }
	v_mul_f32_e32 v1, v36, v1
	v_add_f32_e32 v2, 1.0, v44
	v_div_scale_f32 v40, s[10:11], v2, v2, v41
	v_rcp_f32_e32 v44, v40
	v_cvt_pk_bf16_f32 v1, v1, s0
	ds_write_b16 v132, v1 offset:11552
	v_fma_f32 v1, -v40, v44, 1.0
	v_fmac_f32_e32 v44, v1, v44
	v_div_scale_f32 v1, vcc, v41, v2, v41
	v_mul_f32_e32 v36, v1, v44
	v_fma_f32 v45, -v40, v36, v1
	v_fmac_f32_e32 v36, v45, v44
	v_fma_f32 v1, -v40, v36, v1
	v_mul_f32_e32 v40, 0xbfb8aa3b, v42
	v_exp_f32_e32 v40, v40
	v_div_fmas_f32 v1, v1, v44, v36
	v_div_fixup_f32 v1, v1, v2, v41
	v_mul_f32_e32 v1, v37, v1
	v_add_f32_e32 v2, 1.0, v40
	v_div_scale_f32 v36, s[10:11], v2, v2, v42
	v_rcp_f32_e32 v40, v36
	v_cvt_pk_bf16_f32 v1, v1, s0
	ds_write_b16 v132, v1 offset:11696
	v_fma_f32 v1, -v36, v40, 1.0
	v_fmac_f32_e32 v40, v1, v40
	v_div_scale_f32 v1, vcc, v42, v2, v42
	v_mul_f32_e32 v37, v1, v40
	v_fma_f32 v41, -v36, v37, v1
	v_fmac_f32_e32 v37, v41, v40
	v_fma_f32 v1, -v36, v37, v1
	v_mul_f32_e32 v36, 0xbfb8aa3b, v43
	v_exp_f32_e32 v36, v36
	v_div_fmas_f32 v1, v1, v40, v37
	v_div_fixup_f32 v1, v1, v2, v42
	v_mul_f32_e32 v1, v38, v1
	v_add_f32_e32 v2, 1.0, v36
	v_div_scale_f32 v36, s[10:11], v2, v2, v43
	v_rcp_f32_e32 v37, v36
	v_cvt_pk_bf16_f32 v1, v1, s0
	ds_write_b16 v132, v1 offset:11840
	v_fma_f32 v1, -v36, v37, 1.0
	v_fmac_f32_e32 v37, v1, v37
	v_div_scale_f32 v1, vcc, v43, v2, v43
	v_mul_f32_e32 v38, v1, v37
	v_fma_f32 v40, -v36, v38, v1
	v_fmac_f32_e32 v38, v40, v37
	v_fma_f32 v1, -v36, v38, v1
	v_mul_f32_e32 v36, 0xbfb8aa3b, v32
	v_exp_f32_e32 v36, v36
	v_div_fmas_f32 v1, v1, v37, v38
	v_div_fixup_f32 v1, v1, v2, v43
	v_mul_f32_e32 v1, v39, v1
	v_add_f32_e32 v2, 1.0, v36
	v_div_scale_f32 v36, s[10:11], v2, v2, v32
	v_rcp_f32_e32 v37, v36
	v_cvt_pk_bf16_f32 v1, v1, s0
	ds_write_b16 v132, v1 offset:11984
	v_fma_f32 v1, -v36, v37, 1.0
	v_fmac_f32_e32 v37, v1, v37
	v_div_scale_f32 v1, vcc, v32, v2, v32
	v_mul_f32_e32 v38, v1, v37
	v_fma_f32 v39, -v36, v38, v1
	v_fmac_f32_e32 v38, v39, v37
	v_fma_f32 v1, -v36, v38, v1
	v_mul_f32_e32 v36, 0xbfb8aa3b, v33
	v_exp_f32_e32 v36, v36
	v_div_fmas_f32 v1, v1, v37, v38
	v_div_fixup_f32 v1, v1, v2, v32
	v_mul_f32_e32 v1, v28, v1
	v_add_f32_e32 v2, 1.0, v36
	v_div_scale_f32 v32, s[10:11], v2, v2, v33
	v_rcp_f32_e32 v36, v32
	v_cvt_pk_bf16_f32 v1, v1, s0
	ds_write_b16 v132, v1 offset:13824
	v_fma_f32 v1, -v32, v36, 1.0
	v_fmac_f32_e32 v36, v1, v36
	v_div_scale_f32 v1, vcc, v33, v2, v33
	v_mul_f32_e32 v28, v1, v36
	v_fma_f32 v37, -v32, v28, v1
	v_fmac_f32_e32 v28, v37, v36
	v_fma_f32 v1, -v32, v28, v1
	v_mul_f32_e32 v32, 0xbfb8aa3b, v34
	v_exp_f32_e32 v32, v32
	v_div_fmas_f32 v1, v1, v36, v28
	v_div_fixup_f32 v1, v1, v2, v33
	v_mul_f32_e32 v1, v29, v1
	v_add_f32_e32 v2, 1.0, v32
	v_div_scale_f32 v28, s[10:11], v2, v2, v34
	v_rcp_f32_e32 v32, v28
	v_cvt_pk_bf16_f32 v1, v1, s0
	ds_write_b16 v132, v1 offset:13968
	v_fma_f32 v1, -v28, v32, 1.0
	v_fmac_f32_e32 v32, v1, v32
	v_div_scale_f32 v1, vcc, v34, v2, v34
	v_mul_f32_e32 v29, v1, v32
	v_fma_f32 v33, -v28, v29, v1
	v_fmac_f32_e32 v29, v33, v32
	v_fma_f32 v1, -v28, v29, v1
	v_mul_f32_e32 v28, 0xbfb8aa3b, v35
	v_exp_f32_e32 v28, v28
	v_div_fmas_f32 v1, v1, v32, v29
	v_div_fixup_f32 v1, v1, v2, v34
	v_mul_f32_e32 v1, v30, v1
	v_add_f32_e32 v2, 1.0, v28
	v_div_scale_f32 v28, s[10:11], v2, v2, v35
	v_rcp_f32_e32 v29, v28
	v_cvt_pk_bf16_f32 v1, v1, s0
	ds_write_b16 v132, v1 offset:14112
	v_fma_f32 v1, -v28, v29, 1.0
	v_fmac_f32_e32 v29, v1, v29
	v_div_scale_f32 v1, vcc, v35, v2, v35
	v_mul_f32_e32 v30, v1, v29
	v_fma_f32 v32, -v28, v30, v1
	v_fmac_f32_e32 v30, v32, v29
	v_fma_f32 v1, -v28, v30, v1
	v_mul_f32_e32 v28, 0xbfb8aa3b, v24
	v_exp_f32_e32 v28, v28
	v_div_fmas_f32 v1, v1, v29, v30
	v_div_fixup_f32 v1, v1, v2, v35
	v_mul_f32_e32 v1, v31, v1
	v_add_f32_e32 v2, 1.0, v28
	v_div_scale_f32 v28, s[10:11], v2, v2, v24
	v_rcp_f32_e32 v29, v28
	v_cvt_pk_bf16_f32 v1, v1, s0
	ds_write_b16 v132, v1 offset:14256
	v_fma_f32 v1, -v28, v29, 1.0
	v_fmac_f32_e32 v29, v1, v29
	v_div_scale_f32 v1, vcc, v24, v2, v24
	v_mul_f32_e32 v30, v1, v29
	v_fma_f32 v31, -v28, v30, v1
	v_fmac_f32_e32 v30, v31, v29
	v_fma_f32 v1, -v28, v30, v1
	v_mul_f32_e32 v28, 0xbfb8aa3b, v25
	v_exp_f32_e32 v28, v28
	v_div_fmas_f32 v1, v1, v29, v30
	v_div_fixup_f32 v1, v1, v2, v24
	v_mul_f32_e32 v1, v20, v1
	v_add_f32_e32 v2, 1.0, v28
	v_div_scale_f32 v24, s[10:11], v2, v2, v25
	v_rcp_f32_e32 v28, v24
	v_cvt_pk_bf16_f32 v1, v1, s0
	ds_write_b16 v132, v1 offset:13856
	v_fma_f32 v1, -v24, v28, 1.0
	v_fmac_f32_e32 v28, v1, v28
	v_div_scale_f32 v1, vcc, v25, v2, v25
	v_mul_f32_e32 v20, v1, v28
	v_fma_f32 v29, -v24, v20, v1
	v_fmac_f32_e32 v20, v29, v28
	v_fma_f32 v1, -v24, v20, v1
	v_mul_f32_e32 v24, 0xbfb8aa3b, v26
	v_exp_f32_e32 v24, v24
	v_div_fmas_f32 v1, v1, v28, v20
	v_div_fixup_f32 v1, v1, v2, v25
	v_mul_f32_e32 v1, v21, v1
	v_add_f32_e32 v2, 1.0, v24
	v_div_scale_f32 v20, s[10:11], v2, v2, v26
	v_rcp_f32_e32 v24, v20
	v_cvt_pk_bf16_f32 v1, v1, s0
	ds_write_b16 v132, v1 offset:14000
	v_fma_f32 v1, -v20, v24, 1.0
	v_fmac_f32_e32 v24, v1, v24
	v_div_scale_f32 v1, vcc, v26, v2, v26
	v_mul_f32_e32 v21, v1, v24
	v_fma_f32 v25, -v20, v21, v1
	v_fmac_f32_e32 v21, v25, v24
	v_fma_f32 v1, -v20, v21, v1
	v_mul_f32_e32 v20, 0xbfb8aa3b, v27
	v_exp_f32_e32 v20, v20
	v_div_fmas_f32 v1, v1, v24, v21
	v_div_fixup_f32 v1, v1, v2, v26
	v_mul_f32_e32 v1, v22, v1
	v_add_f32_e32 v2, 1.0, v20
	v_div_scale_f32 v20, s[10:11], v2, v2, v27
	v_rcp_f32_e32 v21, v20
	v_cvt_pk_bf16_f32 v1, v1, s0
	ds_write_b16 v132, v1 offset:14144
	v_fma_f32 v1, -v20, v21, 1.0
	v_fmac_f32_e32 v21, v1, v21
	v_div_scale_f32 v1, vcc, v27, v2, v27
	v_mul_f32_e32 v22, v1, v21
	v_fma_f32 v24, -v20, v22, v1
; DEVI float silu_(float x) { return x / (1.f + __expf(-x)); }
; DEVI void ffn1_tile256(const P& p, const bf* W, long row0, int n0  , char* smem) {
;     ...
; #pragma unroll
;   for (int m = 0; m < 8; ++m)
; #pragma unroll
;     for (int pr = 0; pr < 2; ++pr) {
;       const int cl = (wc * 2 + pr) * 16 + l15;
; #pragma unroll
;       for (int j = 0; j < 4; ++j) {
;         const int rl = wr * 128 + m * 16 + quad * 4 + j;
;         float a = acc[m][2 * pr][j], b = acc[m][2 * pr + 1][j];
;         tl[rl * 72 + cl] = f2bf(silu_(a) * b);
;       }
;     }
;   __syncthreads();
;   tile_store256<64>(smem, p.UZ, DFF, row0, n0 / 2);
	v_fmac_f32_e32 v22, v24, v21
	v_fma_f32 v1, -v20, v22, v1
	v_mul_f32_e32 v20, 0xbfb8aa3b, v16
	v_exp_f32_e32 v20, v20
	v_div_fmas_f32 v1, v1, v21, v22
	v_div_fixup_f32 v1, v1, v2, v27
	v_mul_f32_e32 v1, v23, v1
	v_add_f32_e32 v2, 1.0, v20
	v_div_scale_f32 v20, s[10:11], v2, v2, v16
	v_rcp_f32_e32 v21, v20
	v_cvt_pk_bf16_f32 v1, v1, s0
	ds_write_b16 v132, v1 offset:14288
	v_fma_f32 v1, -v20, v21, 1.0
	v_fmac_f32_e32 v21, v1, v21
	v_div_scale_f32 v1, vcc, v16, v2, v16
	v_mul_f32_e32 v22, v1, v21
	v_fma_f32 v23, -v20, v22, v1
	v_fmac_f32_e32 v22, v23, v21
	v_fma_f32 v1, -v20, v22, v1
	v_mul_f32_e32 v20, 0xbfb8aa3b, v17
	v_exp_f32_e32 v20, v20
	v_div_fmas_f32 v1, v1, v21, v22
	v_div_fixup_f32 v1, v1, v2, v16
	v_mul_f32_e32 v1, v12, v1
	v_add_f32_e32 v2, 1.0, v20
	v_div_scale_f32 v16, s[10:11], v2, v2, v17
	v_rcp_f32_e32 v20, v16
	v_cvt_pk_bf16_f32 v1, v1, s0
	ds_write_b16 v132, v1 offset:16128
	v_fma_f32 v1, -v16, v20, 1.0
	v_fmac_f32_e32 v20, v1, v20
	v_div_scale_f32 v1, vcc, v17, v2, v17
	v_mul_f32_e32 v12, v1, v20
	v_fma_f32 v21, -v16, v12, v1
	v_fmac_f32_e32 v12, v21, v20
	v_fma_f32 v1, -v16, v12, v1
	v_mul_f32_e32 v16, 0xbfb8aa3b, v18
	v_exp_f32_e32 v16, v16
	v_div_fmas_f32 v1, v1, v20, v12
	v_div_fixup_f32 v1, v1, v2, v17
	v_mul_f32_e32 v1, v13, v1
	v_add_f32_e32 v2, 1.0, v16
	v_div_scale_f32 v12, s[10:11], v2, v2, v18
	v_rcp_f32_e32 v16, v12
	v_cvt_pk_bf16_f32 v1, v1, s0
	ds_write_b16 v132, v1 offset:16272
	v_fma_f32 v1, -v12, v16, 1.0
	v_fmac_f32_e32 v16, v1, v16
	v_div_scale_f32 v1, vcc, v18, v2, v18
	v_mul_f32_e32 v13, v1, v16
	v_fma_f32 v17, -v12, v13, v1
	v_fmac_f32_e32 v13, v17, v16
	v_fma_f32 v1, -v12, v13, v1
	v_mul_f32_e32 v12, 0xbfb8aa3b, v19
	v_exp_f32_e32 v12, v12
	v_div_fmas_f32 v1, v1, v16, v13
	v_div_fixup_f32 v1, v1, v2, v18
	v_mul_f32_e32 v1, v14, v1
	v_add_f32_e32 v2, 1.0, v12
	v_div_scale_f32 v12, s[10:11], v2, v2, v19
	v_rcp_f32_e32 v13, v12
	v_cvt_pk_bf16_f32 v1, v1, s0
	ds_write_b16 v132, v1 offset:16416
	v_fma_f32 v1, -v12, v13, 1.0
	v_fmac_f32_e32 v13, v1, v13
	v_div_scale_f32 v1, vcc, v19, v2, v19
	v_mul_f32_e32 v14, v1, v13
	v_fma_f32 v16, -v12, v14, v1
	v_fmac_f32_e32 v14, v16, v13
	v_fma_f32 v1, -v12, v14, v1
	v_mul_f32_e32 v12, 0xbfb8aa3b, v8
	v_exp_f32_e32 v12, v12
	v_div_fmas_f32 v1, v1, v13, v14
	v_div_fixup_f32 v1, v1, v2, v19
	v_mul_f32_e32 v1, v15, v1
	v_add_f32_e32 v2, 1.0, v12
	v_div_scale_f32 v12, s[10:11], v2, v2, v8
	v_rcp_f32_e32 v13, v12
	v_cvt_pk_bf16_f32 v1, v1, s0
	ds_write_b16 v132, v1 offset:16560
	v_fma_f32 v1, -v12, v13, 1.0
	v_fmac_f32_e32 v13, v1, v13
	v_div_scale_f32 v1, vcc, v8, v2, v8
	v_mul_f32_e32 v14, v1, v13
	v_fma_f32 v15, -v12, v14, v1
	v_fmac_f32_e32 v14, v15, v13
	v_fma_f32 v1, -v12, v14, v1
	v_mul_f32_e32 v12, 0xbfb8aa3b, v9
	v_exp_f32_e32 v12, v12
	v_div_fmas_f32 v1, v1, v13, v14
	v_div_fixup_f32 v1, v1, v2, v8
	v_mul_f32_e32 v1, v4, v1
	v_add_f32_e32 v2, 1.0, v12
	v_div_scale_f32 v8, s[10:11], v2, v2, v9
	v_rcp_f32_e32 v12, v8
	v_cvt_pk_bf16_f32 v1, v1, s0
	ds_write_b16 v132, v1 offset:16160
	v_fma_f32 v1, -v8, v12, 1.0
	v_fmac_f32_e32 v12, v1, v12
	v_div_scale_f32 v1, vcc, v9, v2, v9
	v_mul_f32_e32 v4, v1, v12
	v_fma_f32 v13, -v8, v4, v1
	v_fmac_f32_e32 v4, v13, v12
	v_fma_f32 v1, -v8, v4, v1
	v_mul_f32_e32 v8, 0xbfb8aa3b, v10
	v_exp_f32_e32 v8, v8
	v_div_fmas_f32 v1, v1, v12, v4
	v_div_fixup_f32 v1, v1, v2, v9
	v_mul_f32_e32 v1, v5, v1
	v_add_f32_e32 v2, 1.0, v8
	v_div_scale_f32 v4, s[10:11], v2, v2, v10
	v_rcp_f32_e32 v8, v4
	v_cvt_pk_bf16_f32 v1, v1, s0
	ds_write_b16 v132, v1 offset:16304
	v_fma_f32 v1, -v4, v8, 1.0
	v_fmac_f32_e32 v8, v1, v8
	v_div_scale_f32 v1, vcc, v10, v2, v10
	v_mul_f32_e32 v5, v1, v8
	v_fma_f32 v9, -v4, v5, v1
	v_fmac_f32_e32 v5, v9, v8
	v_fma_f32 v1, -v4, v5, v1
	v_mul_f32_e32 v4, 0xbfb8aa3b, v11
	v_exp_f32_e32 v4, v4
	v_div_fmas_f32 v1, v1, v8, v5
	v_div_fixup_f32 v1, v1, v2, v10
	v_mul_f32_e32 v1, v6, v1
	v_add_f32_e32 v2, 1.0, v4
	v_div_scale_f32 v4, s[10:11], v2, v2, v11
	v_rcp_f32_e32 v5, v4
	v_cvt_pk_bf16_f32 v1, v1, s0
	ds_write_b16 v132, v1 offset:16448
	s_ashr_i32 s10, s38, 1
	v_fma_f32 v1, -v4, v5, 1.0
	v_fmac_f32_e32 v5, v1, v5
	v_div_scale_f32 v1, vcc, v11, v2, v11
	v_mul_f32_e32 v6, v1, v5
	v_fma_f32 v8, -v4, v6, v1
	v_fmac_f32_e32 v6, v8, v5
	v_fma_f32 v1, -v4, v6, v1
	v_div_fmas_f32 v1, v1, v5, v6
	v_div_fixup_f32 v1, v1, v2, v11
	v_mul_f32_e32 v1, v7, v1
	v_cvt_pk_bf16_f32 v1, v1, s0
	ds_write_b16 v132, v1 offset:16592
	v_mov_b32_e32 v1, v178
	s_waitcnt lgkmcnt(0)
	s_barrier
; DEVI int get_tid() { int t = threadIdx.x; asm volatile("" : "+v"(t)); return t; }
; template <int BN>
; DEVI void tile_store256(const char* smem, bf* __restrict__ C, long ldc, long row0, int col0) {
;   constexpr int LDT = BN + 8;
;   constexpr int CPR = BN / 8;
;   const int tid = get_tid();
; #pragma unroll
;   for (int i = 0; i < CPR; ++i) {
;     const int q = tid + 256 * i;
;     const int r = q / CPR, c = q - r * CPR;
;     u32x4 v = *reinterpret_cast<const u32x4*>(smem + (r * LDT + c * 8) * 2);
;     *reinterpret_cast<u32x4*>(C + (row0 + r) * ldc + col0 + c * 8) = v;
;   }
; }
; DEVI void phase_ffn1(const P& p, int f, char* smem) {
;     ...
;   for (int v = blockIdx.x; v < 128 * 44; v += gridDim.x) {
;     int m2, nt;
;     lat_tile_map256(v, 44, m2, nt);
;     ffn1_tile256(p, W, lat_row0_256(m2), nt * 128, smem);
	s_ashr_i32 s11, s10, 31
	v_ashrrev_i32_e32 v2, 31, v1
	v_lshrrev_b32_e32 v2, 29, v2
	s_lshl_b64 s[10:11], s[10:11], 1
	v_add_u32_e32 v2, v1, v2
	s_add_u32 s10, s58, s10
	v_ashrrev_i32_e32 v8, 3, v2
	s_addc_u32 s11, s59, s11
	v_lshlrev_b32_e32 v4, 6, v8
	v_lshlrev_b32_e32 v5, 3, v1
	v_ashrrev_i32_e32 v9, 31, v8
	v_mul_lo_u32 v2, v8, s80
	v_sub_u32_e32 v10, v5, v4
	v_lshl_add_u64 v[8:9], s[34:35], 0, v[8:9]
	v_mov_b64_e32 v[12:13], s[10:11]
	v_add_lshl_u32 v2, v10, v2, 1
	v_mad_u64_u32 v[14:15], s[10:11], v8, s31, v[12:13]
	ds_read_b128 v[4:7], v2
	v_mov_b32_e32 v2, v15
	v_mad_u64_u32 v[8:9], s[10:11], v9, s31, v[2:3]
	v_add_u32_e32 v2, 0x100, v1
	v_mov_b32_e32 v15, v8
	v_ashrrev_i32_e32 v8, 31, v2
	v_lshrrev_b32_e32 v8, 29, v8
	v_add_u32_e32 v8, v2, v8
	v_ashrrev_i32_e32 v16, 3, v8
	v_ashrrev_i32_e32 v11, 31, v10
	v_lshlrev_b32_e32 v9, 6, v16
	v_lshlrev_b32_e32 v2, 3, v2
	v_lshl_add_u64 v[14:15], v[10:11], 1, v[14:15]
	v_mul_lo_u32 v8, v16, s80
	v_sub_u32_e32 v18, v2, v9
	v_ashrrev_i32_e32 v17, 31, v16
	v_add_lshl_u32 v2, v18, v8, 1
	s_waitcnt lgkmcnt(0)
	global_store_dwordx4 v[14:15], v[4:7], off
	ds_read_b128 v[8:11], v2
	v_ashrrev_i32_e32 v19, 31, v18
	v_lshl_add_u64 v[4:5], s[34:35], 0, v[16:17]
	v_mad_u64_u32 v[6:7], s[10:11], v4, s31, v[12:13]
	v_mov_b32_e32 v2, v7
	v_mad_u64_u32 v[4:5], s[10:11], v5, s31, v[2:3]
	v_mov_b32_e32 v7, v4
	v_lshl_add_u64 v[4:5], v[18:19], 1, v[6:7]
	v_add_u32_e32 v2, 0x200, v1
	s_waitcnt lgkmcnt(0)
	global_store_dwordx4 v[4:5], v[8:11], off
	v_ashrrev_i32_e32 v4, 31, v2
	v_lshrrev_b32_e32 v4, 29, v4
	v_add_u32_e32 v4, v2, v4
	v_ashrrev_i32_e32 v8, 3, v4
	v_lshlrev_b32_e32 v5, 6, v8
	v_lshlrev_b32_e32 v2, 3, v2
	v_ashrrev_i32_e32 v9, 31, v8
	v_mul_lo_u32 v4, v8, s80
	v_sub_u32_e32 v10, v2, v5
	v_lshl_add_u64 v[8:9], s[34:35], 0, v[8:9]
	v_add_lshl_u32 v2, v10, v4, 1
	v_mad_u64_u32 v[14:15], s[10:11], v8, s31, v[12:13]
	ds_read_b128 v[4:7], v2
	v_mov_b32_e32 v2, v15
	v_mad_u64_u32 v[8:9], s[10:11], v9, s31, v[2:3]
	v_add_u32_e32 v2, 0x300, v1
	v_mov_b32_e32 v15, v8
	v_ashrrev_i32_e32 v8, 31, v2
	v_lshrrev_b32_e32 v8, 29, v8
	v_add_u32_e32 v8, v2, v8
	v_ashrrev_i32_e32 v16, 3, v8
	v_ashrrev_i32_e32 v11, 31, v10
	v_lshlrev_b32_e32 v9, 6, v16
	v_lshlrev_b32_e32 v2, 3, v2
	v_lshl_add_u64 v[14:15], v[10:11], 1, v[14:15]
	v_mul_lo_u32 v8, v16, s80
	v_sub_u32_e32 v18, v2, v9
	v_ashrrev_i32_e32 v17, 31, v16
	v_add_lshl_u32 v2, v18, v8, 1
	s_waitcnt lgkmcnt(0)
	global_store_dwordx4 v[14:15], v[4:7], off
	ds_read_b128 v[8:11], v2
	v_ashrrev_i32_e32 v19, 31, v18
	v_lshl_add_u64 v[4:5], s[34:35], 0, v[16:17]
	v_mad_u64_u32 v[6:7], s[10:11], v4, s31, v[12:13]
	v_mov_b32_e32 v2, v7
	v_mad_u64_u32 v[4:5], s[10:11], v5, s31, v[2:3]
	v_mov_b32_e32 v7, v4
	v_lshl_add_u64 v[4:5], v[18:19], 1, v[6:7]
	v_add_u32_e32 v2, 0x400, v1
	s_waitcnt lgkmcnt(0)
	global_store_dwordx4 v[4:5], v[8:11], off
	v_ashrrev_i32_e32 v4, 31, v2
	v_lshrrev_b32_e32 v4, 29, v4
	v_add_u32_e32 v4, v2, v4
	v_ashrrev_i32_e32 v8, 3, v4
	v_lshlrev_b32_e32 v5, 6, v8
	v_lshlrev_b32_e32 v2, 3, v2
	v_ashrrev_i32_e32 v9, 31, v8
	v_mul_lo_u32 v4, v8, s80
	v_sub_u32_e32 v10, v2, v5
	v_lshl_add_u64 v[8:9], s[34:35], 0, v[8:9]
	v_add_lshl_u32 v2, v10, v4, 1
	v_mad_u64_u32 v[14:15], s[10:11], v8, s31, v[12:13]
	ds_read_b128 v[4:7], v2
	v_mov_b32_e32 v2, v15
	v_mad_u64_u32 v[8:9], s[10:11], v9, s31, v[2:3]
	v_add_u32_e32 v2, 0x500, v1
	v_mov_b32_e32 v15, v8
	v_ashrrev_i32_e32 v8, 31, v2
	v_lshrrev_b32_e32 v8, 29, v8
	v_add_u32_e32 v8, v2, v8
	v_ashrrev_i32_e32 v16, 3, v8
	v_ashrrev_i32_e32 v11, 31, v10
	v_lshlrev_b32_e32 v9, 6, v16
	v_lshlrev_b32_e32 v2, 3, v2
	v_lshl_add_u64 v[14:15], v[10:11], 1, v[14:15]
	v_mul_lo_u32 v8, v16, s80
	v_sub_u32_e32 v18, v2, v9
	v_ashrrev_i32_e32 v17, 31, v16
	v_add_lshl_u32 v2, v18, v8, 1
	s_waitcnt lgkmcnt(0)
	global_store_dwordx4 v[14:15], v[4:7], off
	ds_read_b128 v[8:11], v2
	v_ashrrev_i32_e32 v19, 31, v18
	v_lshl_add_u64 v[4:5], s[34:35], 0, v[16:17]
	v_mad_u64_u32 v[6:7], s[10:11], v4, s31, v[12:13]
	v_mov_b32_e32 v2, v7
	v_mad_u64_u32 v[4:5], s[10:11], v5, s31, v[2:3]
	v_mov_b32_e32 v7, v4
	v_lshl_add_u64 v[4:5], v[18:19], 1, v[6:7]
	v_add_u32_e32 v2, 0x600, v1
	s_waitcnt lgkmcnt(0)
	global_store_dwordx4 v[4:5], v[8:11], off
	v_ashrrev_i32_e32 v4, 31, v2
	v_lshrrev_b32_e32 v4, 29, v4
	v_add_u32_e32 v4, v2, v4
	v_ashrrev_i32_e32 v8, 3, v4
	v_lshlrev_b32_e32 v5, 6, v8
	v_lshlrev_b32_e32 v2, 3, v2
	v_ashrrev_i32_e32 v9, 31, v8
	v_mul_lo_u32 v4, v8, s80
	v_sub_u32_e32 v10, v2, v5
	v_lshl_add_u64 v[8:9], s[34:35], 0, v[8:9]
	v_add_lshl_u32 v2, v10, v4, 1
	v_mad_u64_u32 v[14:15], s[10:11], v8, s31, v[12:13]
	ds_read_b128 v[4:7], v2
	v_mov_b32_e32 v2, v15
	v_add_u32_e32 v1, 0x700, v1
	v_mad_u64_u32 v[8:9], s[10:11], v9, s31, v[2:3]
	v_ashrrev_i32_e32 v2, 31, v1
	v_lshrrev_b32_e32 v2, 29, v2
	v_add_u32_e32 v2, v1, v2
	v_mov_b32_e32 v15, v8
	v_ashrrev_i32_e32 v11, 31, v10
	v_ashrrev_i32_e32 v16, 3, v2
	v_lshl_add_u64 v[14:15], v[10:11], 1, v[14:15]
	v_lshlrev_b32_e32 v8, 6, v16
	v_lshlrev_b32_e32 v1, 3, v1
	v_ashrrev_i32_e32 v17, 31, v16
	v_mul_lo_u32 v2, v16, s80
	v_sub_u32_e32 v18, v1, v8
	s_waitcnt lgkmcnt(0)
	global_store_dwordx4 v[14:15], v[4:7], off
	v_add_lshl_u32 v1, v18, v2, 1
	ds_read_b128 v[8:11], v1
	v_lshl_add_u64 v[4:5], s[34:35], 0, v[16:17]
	v_mad_u64_u32 v[6:7], s[10:11], v4, s31, v[12:13]
	v_mov_b32_e32 v2, v7
	v_mad_u64_u32 v[4:5], s[10:11], v5, s31, v[2:3]
	v_readlane_b32 s10, v252, 59
	v_mov_b32_e32 v7, v4
	v_ashrrev_i32_e32 v19, 31, v18
	s_add_i32 s2, s2, s10
	v_lshl_add_u64 v[4:5], v[18:19], 1, v[6:7]
	s_cmpk_gt_i32 s2, 0x15ff
	s_waitcnt lgkmcnt(0)
	global_store_dwordx4 v[4:5], v[8:11], off
	s_barrier
	v_readlane_b32 s11, v252, 60
	s_cbranch_scc0 .LBB0_935
